# baseline (speedup 1.0000x reference)
; #define STAGE_A(b, h, kt) { const u16* ap_ = A + (size_t)((h) * ahalf + (unsigned)(kt) * 64u); glds16(ap_ + ao0, l0 + SA_(b, h)); glds16(ap_ + ao1, l0 + SA_(b, h) + 8192); }
; #define STAGE_B(b, h, kt) { const u16* bp_ = ((h) ? B1 : B0) + (unsigned)(kt) * 64u; glds16(bp_ + bo0, l0 + SB_(b, h)); glds16(bp_ + bo1, l0 + SB_(b, h) + 8192); }
; #define LDA(dst, b, h) _Pragma("unroll") for (int m = 0; m < 4; ++m) _Pragma("unroll") for (int k = 0; k < 2; ++k) \
;     dst[m][k] = *(const bf16x8*)(lds + SA_(b, h) + lds_byte(wr * 64 + m * 16 + fr, k * 32 + fq * 8));
; #define LDB(dst, b, h) _Pragma("unroll") for (int n = 0; n < 2; ++n) _Pragma("unroll") for (int k = 0; k < 2; ++k) \
;     dst[n][k] = *(const bf16x8*)(lds + SB_(b, h) + lds_byte(wc * 32 + n * 16 + fr, k * 32 + fq * 8));
; #define MMA(ai, bj, At_, Bt_) { __builtin_amdgcn_s_setprio(1); \
;     _Pragma("unroll") for (int m = 0; m < 4; ++m) _Pragma("unroll") for (int n = 0; n < 2; ++n) _Pragma("unroll") for (int k = 0; k < 2; ++k) \
;       acc[ai][bj][m][n] = MFMA16(Bt_[n][k], At_[m][k], acc[ai][bj][m][n]); \
;     __builtin_amdgcn_s_setprio(0); }
; #define WAIT_V(n) asm volatile("s_waitcnt vmcnt(" #n ")" ::: "memory");
; #define WAIT_L(n) asm volatile("s_waitcnt lgkmcnt(" #n ")" ::: "memory");
; #define BAR __builtin_amdgcn_s_barrier();
; #define SCHED __builtin_amdgcn_sched_barrier(0);
; DI void gemm256(const u16* __restrict__ A, int lda, const u16* __restrict__ B0, const u16* __restrict__ B1, int ldb, int nt, acc_t& acc, char* lds) {
;     ...
;   for (int t = 0; t < nt - 2; t += 2) {
;     LDB(Bq0, 0, 0) SCHED LDA(At, 0, 0) STAGE_A(1, 1, t + 1)
;     WAIT_L(8) BAR WAIT_L(0) MMA(0, 0, At, Bq0) BAR SCHED
;     LDB(Bq1, 0, 1) STAGE_B(0, 0, t + 2)
;     BAR WAIT_L(0) MMA(0, 1, At, Bq1) BAR
;     LDA(At, 0, 1) STAGE_A(0, 0, t + 2)
;     BAR WAIT_L(0) MMA(1, 0, At, Bq0) BAR SCHED
;     STAGE_B(0, 1, t + 2)
;     WAIT_V(6) BAR MMA(1, 1, At, Bq1) BAR
;     LDB(Bq0, 1, 0) SCHED LDA(At, 1, 0) STAGE_A(0, 1, t + 2)
;     WAIT_L(8) BAR WAIT_L(0) MMA(0, 0, At, Bq0) BAR SCHED
;     LDB(Bq1, 1, 1) STAGE_B(1, 0, t + 3)
;     BAR WAIT_L(0) MMA(0, 1, At, Bq1) BAR
;     LDA(At, 1, 1) STAGE_A(1, 0, t + 3)
;     BAR WAIT_L(0) MMA(1, 0, At, Bq0) BAR SCHED
;     STAGE_B(1, 1, t + 3)
;     WAIT_V(6) BAR MMA(1, 1, At, Bq1) BAR
;   }
.LBB0_168:
	ds_read_b128 v[142:145], v166
	ds_read_b128 v[170:173], v166 offset:1024
	ds_read_b128 v[174:177], v166 offset:2048
	ds_read_b128 v[178:181], v166 offset:3072
	v_lshl_add_u64 v[222:223], s[22:23], 0, v[136:137]
	v_readfirstlane_b32 s7, v167
	v_lshl_add_u64 v[168:169], v[222:223], 0, s[0:1]
	s_mov_b32 m0, s7
	ds_read_b128 v[182:185], v148
	ds_read_b128 v[190:193], v147
	ds_read_b128 v[198:201], v146
	ds_read_b128 v[206:209], v141
	global_load_lds_dwordx4 v[168:169], off
	v_add_u32_e32 v168, 0xe000, v149
	v_lshl_add_u64 v[224:225], s[22:23], 0, v[138:139]
	v_readfirstlane_b32 s7, v168
	v_lshl_add_u64 v[216:217], v[224:225], 0, s[0:1]
	s_mov_b32 m0, s7
	s_nop 0
	global_load_lds_dwordx4 v[216:217], off
	s_waitcnt lgkmcnt(4)
	s_barrier
	s_waitcnt lgkmcnt(0)
	ds_read_b128 v[186:189], v148 offset:1024
	ds_read_b128 v[194:197], v147 offset:1024
	ds_read_b128 v[202:205], v146 offset:1024
	ds_read_b128 v[210:213], v141 offset:1024
	v_mfma_f32_16x16x32_bf16 v[126:129], v[142:145], v[182:185], v[126:129]
	v_mfma_f32_16x16x32_bf16 v[122:125], v[174:177], v[182:185], v[122:125]
	v_mfma_f32_16x16x32_bf16 v[118:121], v[142:145], v[190:193], v[118:121]
	v_mfma_f32_16x16x32_bf16 v[114:117], v[174:177], v[190:193], v[114:117]
	v_mfma_f32_16x16x32_bf16 v[110:113], v[142:145], v[198:201], v[110:113]
	v_mfma_f32_16x16x32_bf16 v[106:109], v[174:177], v[198:201], v[106:109]
	v_mfma_f32_16x16x32_bf16 v[102:105], v[142:145], v[206:209], v[102:105]
	v_mfma_f32_16x16x32_bf16 v[98:101], v[174:177], v[206:209], v[98:101]
	s_waitcnt lgkmcnt(0)
	v_mfma_f32_16x16x32_bf16 v[126:129], v[170:173], v[186:189], v[126:129]
	v_mfma_f32_16x16x32_bf16 v[122:125], v[178:181], v[186:189], v[122:125]
	v_mfma_f32_16x16x32_bf16 v[118:121], v[170:173], v[194:197], v[118:121]
	v_mfma_f32_16x16x32_bf16 v[114:117], v[178:181], v[194:197], v[114:117]
	v_mfma_f32_16x16x32_bf16 v[110:113], v[170:173], v[202:205], v[110:113]
	v_mfma_f32_16x16x32_bf16 v[106:109], v[178:181], v[202:205], v[106:109]
	v_mfma_f32_16x16x32_bf16 v[102:105], v[170:173], v[210:213], v[102:105]
	v_mfma_f32_16x16x32_bf16 v[98:101], v[178:181], v[210:213], v[98:101]
	s_barrier
	v_lshl_add_u64 v[238:239], s[22:23], 0, v[132:133]
	v_readfirstlane_b32 s7, v151
	v_lshl_add_u64 v[240:241], v[238:239], 0, s[28:29]
	s_mov_b32 m0, s7
	ds_read_b128 v[216:219], v165
	ds_read_b128 v[226:229], v165 offset:1024
	ds_read_b128 v[230:233], v165 offset:2048
	ds_read_b128 v[234:237], v165 offset:3072
	global_load_lds_dwordx4 v[240:241], off
	v_lshl_add_u64 v[240:241], s[22:23], 0, v[134:135]
	v_readfirstlane_b32 s7, v152
	v_lshl_add_u64 v[242:243], v[240:241], 0, s[28:29]
	s_mov_b32 m0, s7
	s_nop 0
	global_load_lds_dwordx4 v[242:243], off
	s_barrier
	s_waitcnt lgkmcnt(0)
	v_mfma_f32_16x16x32_bf16 v[94:97], v[216:219], v[182:185], v[94:97]
	v_mfma_f32_16x16x32_bf16 v[90:93], v[230:233], v[182:185], v[90:93]
	v_mfma_f32_16x16x32_bf16 v[86:89], v[216:219], v[190:193], v[86:89]
	v_mfma_f32_16x16x32_bf16 v[82:85], v[230:233], v[190:193], v[82:85]
	v_mfma_f32_16x16x32_bf16 v[78:81], v[216:219], v[198:201], v[78:81]
	v_mfma_f32_16x16x32_bf16 v[74:77], v[230:233], v[198:201], v[74:77]
	v_mfma_f32_16x16x32_bf16 v[70:73], v[216:219], v[206:209], v[70:73]
	v_mfma_f32_16x16x32_bf16 v[66:69], v[230:233], v[206:209], v[66:69]
	v_mfma_f32_16x16x32_bf16 v[94:97], v[226:229], v[186:189], v[94:97]
	v_mfma_f32_16x16x32_bf16 v[90:93], v[234:237], v[186:189], v[90:93]
	v_mfma_f32_16x16x32_bf16 v[86:89], v[226:229], v[194:197], v[86:89]
	v_mfma_f32_16x16x32_bf16 v[82:85], v[234:237], v[194:197], v[82:85]
	v_mfma_f32_16x16x32_bf16 v[78:81], v[226:229], v[202:205], v[78:81]
	v_mfma_f32_16x16x32_bf16 v[74:77], v[234:237], v[202:205], v[74:77]
	v_mfma_f32_16x16x32_bf16 v[70:73], v[226:229], v[210:213], v[70:73]
	v_mfma_f32_16x16x32_bf16 v[66:69], v[234:237], v[210:213], v[66:69]
	v_readfirstlane_b32 s7, v149
	v_lshl_add_u64 v[242:243], v[222:223], 0, s[20:21]
	s_mov_b32 m0, s7
	v_readfirstlane_b32 s7, v153
	s_barrier
	ds_read_b128 v[182:185], v148 offset:16384
	ds_read_b128 v[190:193], v147 offset:16384
	ds_read_b128 v[198:201], v146 offset:16384
	ds_read_b128 v[206:209], v141 offset:16384
	global_load_lds_dwordx4 v[242:243], off
	v_lshl_add_u64 v[242:243], v[224:225], 0, s[20:21]
	s_mov_b32 m0, s7
	s_nop 0
	global_load_lds_dwordx4 v[242:243], off
	s_barrier
	s_waitcnt lgkmcnt(0)
	ds_read_b128 v[186:189], v148 offset:17408
	ds_read_b128 v[194:197], v147 offset:17408
	ds_read_b128 v[202:205], v146 offset:17408
	ds_read_b128 v[210:213], v141 offset:17408
	v_mfma_f32_16x16x32_bf16 v[60:63], v[142:145], v[182:185], v[60:63]
	v_mfma_f32_16x16x32_bf16 v[56:59], v[174:177], v[182:185], v[56:59]
	v_mfma_f32_16x16x32_bf16 v[52:55], v[142:145], v[190:193], v[52:55]
	v_mfma_f32_16x16x32_bf16 v[48:51], v[174:177], v[190:193], v[48:51]
	v_mfma_f32_16x16x32_bf16 v[44:47], v[142:145], v[198:201], v[44:47]
	v_mfma_f32_16x16x32_bf16 v[40:43], v[174:177], v[198:201], v[40:43]
	v_mfma_f32_16x16x32_bf16 v[36:39], v[142:145], v[206:209], v[36:39]
	v_mfma_f32_16x16x32_bf16 v[32:35], v[174:177], v[206:209], v[32:35]
	s_waitcnt lgkmcnt(0)
	v_mfma_f32_16x16x32_bf16 v[60:63], v[170:173], v[186:189], v[60:63]
	v_mfma_f32_16x16x32_bf16 v[56:59], v[178:181], v[186:189], v[56:59]
	v_mfma_f32_16x16x32_bf16 v[52:55], v[170:173], v[194:197], v[52:55]
	v_mfma_f32_16x16x32_bf16 v[48:51], v[178:181], v[194:197], v[48:51]
	v_mfma_f32_16x16x32_bf16 v[44:47], v[170:173], v[202:205], v[44:47]
	v_mfma_f32_16x16x32_bf16 v[40:43], v[178:181], v[202:205], v[40:43]
	v_mfma_f32_16x16x32_bf16 v[36:39], v[170:173], v[210:213], v[36:39]
	v_mfma_f32_16x16x32_bf16 v[32:35], v[178:181], v[210:213], v[32:35]
	s_barrier
; #define STAGE_A(b, h, kt) { const u16* ap_ = A + (size_t)((h) * ahalf + (unsigned)(kt) * 64u); glds16(ap_ + ao0, l0 + SA_(b, h)); glds16(ap_ + ao1, l0 + SA_(b, h) + 8192); }
; #define STAGE_B(b, h, kt) { const u16* bp_ = ((h) ? B1 : B0) + (unsigned)(kt) * 64u; glds16(bp_ + bo0, l0 + SB_(b, h)); glds16(bp_ + bo1, l0 + SB_(b, h) + 8192); }
; #define LDA(dst, b, h) _Pragma("unroll") for (int m = 0; m < 4; ++m) _Pragma("unroll") for (int k = 0; k < 2; ++k) \
;     dst[m][k] = *(const bf16x8*)(lds + SA_(b, h) + lds_byte(wr * 64 + m * 16 + fr, k * 32 + fq * 8));
; #define LDB(dst, b, h) _Pragma("unroll") for (int n = 0; n < 2; ++n) _Pragma("unroll") for (int k = 0; k < 2; ++k) \
;     dst[n][k] = *(const bf16x8*)(lds + SB_(b, h) + lds_byte(wc * 32 + n * 16 + fr, k * 32 + fq * 8));
; #define MMA(ai, bj, At_, Bt_) { __builtin_amdgcn_s_setprio(1); \
;     _Pragma("unroll") for (int m = 0; m < 4; ++m) _Pragma("unroll") for (int n = 0; n < 2; ++n) _Pragma("unroll") for (int k = 0; k < 2; ++k) \
;       acc[ai][bj][m][n] = MFMA16(Bt_[n][k], At_[m][k], acc[ai][bj][m][n]); \
;     __builtin_amdgcn_s_setprio(0); }
; #define WAIT_V(n) asm volatile("s_waitcnt vmcnt(" #n ")" ::: "memory");
; #define WAIT_L(n) asm volatile("s_waitcnt lgkmcnt(" #n ")" ::: "memory");
; #define BAR __builtin_amdgcn_s_barrier();
; #define SCHED __builtin_amdgcn_sched_barrier(0);
; DI void gemm256(const u16* __restrict__ A, int lda, const u16* __restrict__ B0, const u16* __restrict__ B1, int ldb, int nt, acc_t& acc, char* lds) {
;     ...
;   for (int t = 0; t < nt - 2; t += 2) {
;     LDB(Bq0, 0, 0) SCHED LDA(At, 0, 0) STAGE_A(1, 1, t + 1)
;     WAIT_L(8) BAR WAIT_L(0) MMA(0, 0, At, Bq0) BAR SCHED
;     LDB(Bq1, 0, 1) STAGE_B(0, 0, t + 2)
;     BAR WAIT_L(0) MMA(0, 1, At, Bq1) BAR
;     LDA(At, 0, 1) STAGE_A(0, 0, t + 2)
;     BAR WAIT_L(0) MMA(1, 0, At, Bq0) BAR SCHED
;     STAGE_B(0, 1, t + 2)
;     WAIT_V(6) BAR MMA(1, 1, At, Bq1) BAR
;     LDB(Bq0, 1, 0) SCHED LDA(At, 1, 0) STAGE_A(0, 1, t + 2)
;     WAIT_L(8) BAR WAIT_L(0) MMA(0, 0, At, Bq0) BAR SCHED
;     LDB(Bq1, 1, 1) STAGE_B(1, 0, t + 3)
;     BAR WAIT_L(0) MMA(0, 1, At, Bq1) BAR
;     LDA(At, 1, 1) STAGE_A(1, 0, t + 3)
;     BAR WAIT_L(0) MMA(1, 0, At, Bq0) BAR SCHED
;     STAGE_B(1, 1, t + 3)
;     WAIT_V(6) BAR MMA(1, 1, At, Bq1) BAR
;   }
	v_readfirstlane_b32 s7, v154
	v_lshl_add_u64 v[142:143], v[238:239], 0, s[36:37]
	s_mov_b32 m0, s7
	v_readfirstlane_b32 s7, v156
	global_load_lds_dwordx4 v[142:143], off
	v_lshl_add_u64 v[142:143], v[240:241], 0, s[36:37]
	s_mov_b32 m0, s7
	s_nop 0
	global_load_lds_dwordx4 v[142:143], off
	s_waitcnt vmcnt(6)
	s_barrier
	v_mfma_f32_16x16x32_bf16 v[28:31], v[216:219], v[182:185], v[28:31]
	v_mfma_f32_16x16x32_bf16 v[24:27], v[230:233], v[182:185], v[24:27]
	v_mfma_f32_16x16x32_bf16 v[20:23], v[216:219], v[190:193], v[20:23]
	v_mfma_f32_16x16x32_bf16 v[16:19], v[230:233], v[190:193], v[16:19]
	v_mfma_f32_16x16x32_bf16 v[12:15], v[216:219], v[198:201], v[12:15]
	v_mfma_f32_16x16x32_bf16 v[8:11], v[230:233], v[198:201], v[8:11]
	v_mfma_f32_16x16x32_bf16 v[4:7], v[216:219], v[206:209], v[4:7]
	v_mfma_f32_16x16x32_bf16 v[0:3], v[230:233], v[206:209], v[0:3]
	v_mfma_f32_16x16x32_bf16 v[28:31], v[226:229], v[186:189], v[28:31]
	v_mfma_f32_16x16x32_bf16 v[24:27], v[234:237], v[186:189], v[24:27]
	v_mfma_f32_16x16x32_bf16 v[20:23], v[226:229], v[194:197], v[20:23]
	v_mfma_f32_16x16x32_bf16 v[16:19], v[234:237], v[194:197], v[16:19]
	v_mfma_f32_16x16x32_bf16 v[12:15], v[226:229], v[202:205], v[12:15]
	v_mfma_f32_16x16x32_bf16 v[8:11], v[234:237], v[202:205], v[8:11]
	v_mfma_f32_16x16x32_bf16 v[4:7], v[226:229], v[210:213], v[4:7]
	v_mfma_f32_16x16x32_bf16 v[0:3], v[234:237], v[210:213], v[0:3]
	s_barrier
	ds_read_b128 v[142:145], v155
	ds_read_b128 v[170:173], v155 offset:1024
	ds_read_b128 v[174:177], v155 offset:2048
	ds_read_b128 v[178:181], v155 offset:3072
	v_readfirstlane_b32 s7, v157
	v_lshl_add_u64 v[216:217], v[222:223], 0, s[24:25]
	s_mov_b32 m0, s7
	v_readfirstlane_b32 s7, v158
	ds_read_b128 v[182:185], v148 offset:32768
	ds_read_b128 v[190:193], v147 offset:32768
	ds_read_b128 v[198:201], v146 offset:32768
	ds_read_b128 v[206:209], v141 offset:32768
	global_load_lds_dwordx4 v[216:217], off
	v_lshl_add_u64 v[216:217], v[224:225], 0, s[24:25]
	s_mov_b32 m0, s7
	s_nop 0
	global_load_lds_dwordx4 v[216:217], off
	s_waitcnt lgkmcnt(4)
	s_barrier
	s_waitcnt lgkmcnt(0)
	ds_read_b128 v[186:189], v148 offset:33792
	ds_read_b128 v[194:197], v147 offset:33792
	ds_read_b128 v[202:205], v146 offset:33792
	ds_read_b128 v[210:213], v141 offset:33792
	v_mfma_f32_16x16x32_bf16 v[126:129], v[142:145], v[182:185], v[126:129]
	v_mfma_f32_16x16x32_bf16 v[122:125], v[174:177], v[182:185], v[122:125]
	v_mfma_f32_16x16x32_bf16 v[118:121], v[142:145], v[190:193], v[118:121]
	v_mfma_f32_16x16x32_bf16 v[114:117], v[174:177], v[190:193], v[114:117]
	v_mfma_f32_16x16x32_bf16 v[110:113], v[142:145], v[198:201], v[110:113]
	v_mfma_f32_16x16x32_bf16 v[106:109], v[174:177], v[198:201], v[106:109]
	v_mfma_f32_16x16x32_bf16 v[102:105], v[142:145], v[206:209], v[102:105]
	v_mfma_f32_16x16x32_bf16 v[98:101], v[174:177], v[206:209], v[98:101]
	s_waitcnt lgkmcnt(0)
	v_mfma_f32_16x16x32_bf16 v[126:129], v[170:173], v[186:189], v[126:129]
	v_mfma_f32_16x16x32_bf16 v[122:125], v[178:181], v[186:189], v[122:125]
	v_mfma_f32_16x16x32_bf16 v[118:121], v[170:173], v[194:197], v[118:121]
	v_mfma_f32_16x16x32_bf16 v[114:117], v[178:181], v[194:197], v[114:117]
	v_mfma_f32_16x16x32_bf16 v[110:113], v[170:173], v[202:205], v[110:113]
	v_mfma_f32_16x16x32_bf16 v[106:109], v[178:181], v[202:205], v[106:109]
	v_mfma_f32_16x16x32_bf16 v[102:105], v[170:173], v[210:213], v[102:105]
	v_mfma_f32_16x16x32_bf16 v[98:101], v[178:181], v[210:213], v[98:101]
	s_barrier
	v_readfirstlane_b32 s7, v159
	v_lshl_add_u64 v[242:243], v[238:239], 0, s[26:27]
	s_mov_b32 m0, s7
	v_readfirstlane_b32 s7, v160
	ds_read_b128 v[216:219], v150
	ds_read_b128 v[226:229], v150 offset:1024
	ds_read_b128 v[230:233], v150 offset:2048
	ds_read_b128 v[234:237], v150 offset:3072
	global_load_lds_dwordx4 v[242:243], off
	v_lshl_add_u64 v[242:243], v[240:241], 0, s[26:27]
	s_mov_b32 m0, s7
	s_nop 0
	global_load_lds_dwordx4 v[242:243], off
	s_barrier
	s_waitcnt lgkmcnt(0)
	v_mfma_f32_16x16x32_bf16 v[94:97], v[216:219], v[182:185], v[94:97]
	v_mfma_f32_16x16x32_bf16 v[90:93], v[230:233], v[182:185], v[90:93]
	v_mfma_f32_16x16x32_bf16 v[86:89], v[216:219], v[190:193], v[86:89]
	v_mfma_f32_16x16x32_bf16 v[82:85], v[230:233], v[190:193], v[82:85]
	v_mfma_f32_16x16x32_bf16 v[78:81], v[216:219], v[198:201], v[78:81]
	v_mfma_f32_16x16x32_bf16 v[74:77], v[230:233], v[198:201], v[74:77]
	v_mfma_f32_16x16x32_bf16 v[70:73], v[216:219], v[206:209], v[70:73]
	v_mfma_f32_16x16x32_bf16 v[66:69], v[230:233], v[206:209], v[66:69]
	v_mfma_f32_16x16x32_bf16 v[94:97], v[226:229], v[186:189], v[94:97]
	v_mfma_f32_16x16x32_bf16 v[90:93], v[234:237], v[186:189], v[90:93]
	v_mfma_f32_16x16x32_bf16 v[86:89], v[226:229], v[194:197], v[86:89]
	v_mfma_f32_16x16x32_bf16 v[82:85], v[234:237], v[194:197], v[82:85]
	v_mfma_f32_16x16x32_bf16 v[78:81], v[226:229], v[202:205], v[78:81]
	v_mfma_f32_16x16x32_bf16 v[74:77], v[234:237], v[202:205], v[74:77]
	v_mfma_f32_16x16x32_bf16 v[70:73], v[226:229], v[210:213], v[70:73]
	v_mfma_f32_16x16x32_bf16 v[66:69], v[234:237], v[210:213], v[66:69]
	v_readfirstlane_b32 s7, v161
	v_lshl_add_u64 v[222:223], v[222:223], 0, s[34:35]
	s_mov_b32 m0, s7
	v_readfirstlane_b32 s7, v162
	s_barrier
	ds_read_b128 v[182:185], v148 offset:49152
	ds_read_b128 v[190:193], v147 offset:49152
	ds_read_b128 v[198:201], v146 offset:49152
	ds_read_b128 v[206:209], v141 offset:49152
	global_load_lds_dwordx4 v[222:223], off
	v_lshl_add_u64 v[222:223], v[224:225], 0, s[34:35]
	s_mov_b32 m0, s7
	s_nop 0
	global_load_lds_dwordx4 v[222:223], off
	s_barrier
; #define STAGE_A(b, h, kt) { const u16* ap_ = A + (size_t)((h) * ahalf + (unsigned)(kt) * 64u); glds16(ap_ + ao0, l0 + SA_(b, h)); glds16(ap_ + ao1, l0 + SA_(b, h) + 8192); }
; #define STAGE_B(b, h, kt) { const u16* bp_ = ((h) ? B1 : B0) + (unsigned)(kt) * 64u; glds16(bp_ + bo0, l0 + SB_(b, h)); glds16(bp_ + bo1, l0 + SB_(b, h) + 8192); }
; #define LDA(dst, b, h) _Pragma("unroll") for (int m = 0; m < 4; ++m) _Pragma("unroll") for (int k = 0; k < 2; ++k) \
;     dst[m][k] = *(const bf16x8*)(lds + SA_(b, h) + lds_byte(wr * 64 + m * 16 + fr, k * 32 + fq * 8));
; #define LDB(dst, b, h) _Pragma("unroll") for (int n = 0; n < 2; ++n) _Pragma("unroll") for (int k = 0; k < 2; ++k) \
;     dst[n][k] = *(const bf16x8*)(lds + SB_(b, h) + lds_byte(wc * 32 + n * 16 + fr, k * 32 + fq * 8));
; #define MMA(ai, bj, At_, Bt_) { __builtin_amdgcn_s_setprio(1); \
;     _Pragma("unroll") for (int m = 0; m < 4; ++m) _Pragma("unroll") for (int n = 0; n < 2; ++n) _Pragma("unroll") for (int k = 0; k < 2; ++k) \
;       acc[ai][bj][m][n] = MFMA16(Bt_[n][k], At_[m][k], acc[ai][bj][m][n]); \
;     __builtin_amdgcn_s_setprio(0); }
; DI void gemm256(const u16* __restrict__ A, int lda, const u16* __restrict__ B0, const u16* __restrict__ B1, int ldb, int nt, acc_t& acc, char* lds) {
;     ...
;   for (int t = 0; t < nt - 2; t += 2) {
;     LDB(Bq0, 0, 0) SCHED LDA(At, 0, 0) STAGE_A(1, 1, t + 1)
;     WAIT_L(8) BAR WAIT_L(0) MMA(0, 0, At, Bq0) BAR SCHED
;     LDB(Bq1, 0, 1) STAGE_B(0, 0, t + 2)
;     BAR WAIT_L(0) MMA(0, 1, At, Bq1) BAR
;     LDA(At, 0, 1) STAGE_A(0, 0, t + 2)
;     BAR WAIT_L(0) MMA(1, 0, At, Bq0) BAR SCHED
;     STAGE_B(0, 1, t + 2)
;     WAIT_V(6) BAR MMA(1, 1, At, Bq1) BAR
;     LDB(Bq0, 1, 0) SCHED LDA(At, 1, 0) STAGE_A(0, 1, t + 2)
;     WAIT_L(8) BAR WAIT_L(0) MMA(0, 0, At, Bq0) BAR SCHED
;     LDB(Bq1, 1, 1) STAGE_B(1, 0, t + 3)
;     BAR WAIT_L(0) MMA(0, 1, At, Bq1) BAR
;     LDA(At, 1, 1) STAGE_A(1, 0, t + 3)
;     BAR WAIT_L(0) MMA(1, 0, At, Bq0) BAR SCHED
;     STAGE_B(1, 1, t + 3)
;     WAIT_V(6) BAR MMA(1, 1, At, Bq1) BAR
;   }
;   { LDB(Bq0, 0, 0) LDA(At, 0, 0) STAGE_A(1, 1, nt - 1)
;     BAR WAIT_L(0) MMA(0, 0, At, Bq0) BAR
;     LDB(Bq1, 0, 1) BAR WAIT_L(0) MMA(0, 1, At, Bq1) BAR
;     LDA(At, 0, 1) WAIT_V(4) BAR WAIT_L(0) MMA(1, 0, At, Bq0) MMA(1, 1, At, Bq1) BAR }
;   { LDB(Bq0, 1, 0) LDA(At, 1, 0) WAIT_V(2) BAR WAIT_L(0) MMA(0, 0, At, Bq0) BAR
	s_waitcnt lgkmcnt(0)
	ds_read_b128 v[186:189], v148 offset:50176
	ds_read_b128 v[194:197], v147 offset:50176
	ds_read_b128 v[202:205], v146 offset:50176
	ds_read_b128 v[210:213], v141 offset:50176
	v_mfma_f32_16x16x32_bf16 v[60:63], v[142:145], v[182:185], v[60:63]
	v_mfma_f32_16x16x32_bf16 v[56:59], v[174:177], v[182:185], v[56:59]
	v_mfma_f32_16x16x32_bf16 v[52:55], v[142:145], v[190:193], v[52:55]
	v_mfma_f32_16x16x32_bf16 v[48:51], v[174:177], v[190:193], v[48:51]
	v_mfma_f32_16x16x32_bf16 v[44:47], v[142:145], v[198:201], v[44:47]
	v_mfma_f32_16x16x32_bf16 v[40:43], v[174:177], v[198:201], v[40:43]
	v_mfma_f32_16x16x32_bf16 v[36:39], v[142:145], v[206:209], v[36:39]
	v_mfma_f32_16x16x32_bf16 v[32:35], v[174:177], v[206:209], v[32:35]
	s_waitcnt lgkmcnt(0)
	v_mfma_f32_16x16x32_bf16 v[60:63], v[170:173], v[186:189], v[60:63]
	v_mfma_f32_16x16x32_bf16 v[56:59], v[178:181], v[186:189], v[56:59]
	v_mfma_f32_16x16x32_bf16 v[52:55], v[170:173], v[194:197], v[52:55]
	v_mfma_f32_16x16x32_bf16 v[48:51], v[178:181], v[194:197], v[48:51]
	v_mfma_f32_16x16x32_bf16 v[44:47], v[170:173], v[202:205], v[44:47]
	v_mfma_f32_16x16x32_bf16 v[40:43], v[178:181], v[202:205], v[40:43]
	v_mfma_f32_16x16x32_bf16 v[36:39], v[170:173], v[210:213], v[36:39]
	v_mfma_f32_16x16x32_bf16 v[32:35], v[178:181], v[210:213], v[32:35]
	s_barrier
	v_readfirstlane_b32 s7, v163
	v_lshl_add_u64 v[142:143], v[238:239], 0, s[38:39]
	s_mov_b32 m0, s7
	v_readfirstlane_b32 s7, v164
	global_load_lds_dwordx4 v[142:143], off
	v_lshl_add_u64 v[142:143], v[240:241], 0, s[38:39]
	s_mov_b32 m0, s7
	s_nop 0
	global_load_lds_dwordx4 v[142:143], off
	s_waitcnt vmcnt(6)
	s_barrier
	v_mfma_f32_16x16x32_bf16 v[28:31], v[216:219], v[182:185], v[28:31]
	v_mfma_f32_16x16x32_bf16 v[24:27], v[230:233], v[182:185], v[24:27]
	v_mfma_f32_16x16x32_bf16 v[20:23], v[216:219], v[190:193], v[20:23]
	v_mfma_f32_16x16x32_bf16 v[16:19], v[230:233], v[190:193], v[16:19]
	v_mfma_f32_16x16x32_bf16 v[12:15], v[216:219], v[198:201], v[12:15]
	v_mfma_f32_16x16x32_bf16 v[8:11], v[230:233], v[198:201], v[8:11]
	v_mfma_f32_16x16x32_bf16 v[4:7], v[216:219], v[206:209], v[4:7]
	v_mfma_f32_16x16x32_bf16 v[0:3], v[230:233], v[206:209], v[0:3]
	v_mfma_f32_16x16x32_bf16 v[28:31], v[226:229], v[186:189], v[28:31]
	v_mfma_f32_16x16x32_bf16 v[24:27], v[234:237], v[186:189], v[24:27]
	v_mfma_f32_16x16x32_bf16 v[20:23], v[226:229], v[194:197], v[20:23]
	v_mfma_f32_16x16x32_bf16 v[16:19], v[234:237], v[194:197], v[16:19]
	v_mfma_f32_16x16x32_bf16 v[12:15], v[226:229], v[202:205], v[12:15]
	v_mfma_f32_16x16x32_bf16 v[8:11], v[234:237], v[202:205], v[8:11]
	v_mfma_f32_16x16x32_bf16 v[4:7], v[226:229], v[210:213], v[4:7]
	v_mfma_f32_16x16x32_bf16 v[0:3], v[234:237], v[210:213], v[0:3]
	s_add_i32 s3, s3, 2
	s_add_u32 s22, s22, 0x100
	s_addc_u32 s23, s23, 0
	s_cmp_lt_u32 s3, 12
	s_barrier
	s_cbranch_scc1 .LBB0_168
	s_add_u32 s8, s8, 0x40780
	s_addc_u32 s9, s9, 0
	v_readfirstlane_b32 s3, v167
	v_lshl_add_u64 v[152:153], v[64:65], 1, s[8:9]
	s_mov_b32 m0, s3
	v_readfirstlane_b32 s3, v168
	ds_read_b128 v[132:135], v166
	ds_read_b128 v[136:139], v166 offset:1024
	ds_read_b128 v[142:145], v166 offset:2048
	ds_read_b128 v[156:159], v166 offset:3072
	ds_read_b128 v[160:163], v148
	ds_read_b128 v[170:173], v148 offset:1024
	ds_read_b128 v[174:177], v147
	ds_read_b128 v[178:181], v147 offset:1024
	ds_read_b128 v[182:185], v146
	ds_read_b128 v[186:189], v146 offset:1024
	ds_read_b128 v[190:193], v141
	ds_read_b128 v[194:197], v141 offset:1024
	global_load_lds_dwordx4 v[152:153], off
	v_lshl_add_u64 v[130:131], v[130:131], 1, s[8:9]
	s_mov_b32 m0, s3
	s_nop 0
	global_load_lds_dwordx4 v[130:131], off
	s_barrier
	s_waitcnt lgkmcnt(0)
	v_mfma_f32_16x16x32_bf16 v[126:129], v[132:135], v[160:163], v[126:129]
	v_mfma_f32_16x16x32_bf16 v[122:125], v[142:145], v[160:163], v[122:125]
	v_mfma_f32_16x16x32_bf16 v[118:121], v[132:135], v[174:177], v[118:121]
	v_mfma_f32_16x16x32_bf16 v[114:117], v[142:145], v[174:177], v[114:117]
	v_mfma_f32_16x16x32_bf16 v[102:105], v[132:135], v[190:193], v[102:105]
	v_mfma_f32_16x16x32_bf16 v[98:101], v[142:145], v[190:193], v[98:101]
	v_mfma_f32_16x16x32_bf16 v[126:129], v[136:139], v[170:173], v[126:129]
	v_mfma_f32_16x16x32_bf16 v[122:125], v[156:159], v[170:173], v[122:125]
	v_mfma_f32_16x16x32_bf16 v[118:121], v[136:139], v[178:181], v[118:121]
	v_mfma_f32_16x16x32_bf16 v[114:117], v[156:159], v[178:181], v[114:117]
	v_mfma_f32_16x16x32_bf16 v[110:113], v[132:135], v[182:185], v[110:113]
	v_mfma_f32_16x16x32_bf16 v[106:109], v[142:145], v[182:185], v[106:109]
	v_mfma_f32_16x16x32_bf16 v[102:105], v[136:139], v[194:197], v[102:105]
	v_mfma_f32_16x16x32_bf16 v[98:101], v[156:159], v[194:197], v[98:101]
	v_mfma_f32_16x16x32_bf16 v[166:169], v[136:139], v[186:189], v[110:113]
	v_mfma_f32_16x16x32_bf16 v[198:201], v[156:159], v[186:189], v[106:109]
	s_barrier
	s_nop 1
	ds_read_b128 v[106:109], v165
	ds_read_b128 v[110:113], v165 offset:1024
	ds_read_b128 v[202:205], v165 offset:2048
	ds_read_b128 v[206:209], v165 offset:3072
	s_barrier
	s_waitcnt lgkmcnt(0)
	v_mfma_f32_16x16x32_bf16 v[86:89], v[106:109], v[174:177], v[86:89]
	v_mfma_f32_16x16x32_bf16 v[82:85], v[202:205], v[174:177], v[82:85]
	v_mfma_f32_16x16x32_bf16 v[70:73], v[106:109], v[190:193], v[70:73]
	v_mfma_f32_16x16x32_bf16 v[66:69], v[202:205], v[190:193], v[66:69]
	v_mfma_f32_16x16x32_bf16 v[94:97], v[106:109], v[160:163], v[94:97]
	v_mfma_f32_16x16x32_bf16 v[90:93], v[202:205], v[160:163], v[90:93]
	v_mfma_f32_16x16x32_bf16 v[86:89], v[110:113], v[178:181], v[86:89]
	v_mfma_f32_16x16x32_bf16 v[82:85], v[206:209], v[178:181], v[82:85]
	v_mfma_f32_16x16x32_bf16 v[78:81], v[106:109], v[182:185], v[78:81]
	v_mfma_f32_16x16x32_bf16 v[74:77], v[202:205], v[182:185], v[74:77]
	v_mfma_f32_16x16x32_bf16 v[70:73], v[110:113], v[194:197], v[70:73]
	v_mfma_f32_16x16x32_bf16 v[66:69], v[206:209], v[194:197], v[66:69]
	v_mfma_f32_16x16x32_bf16 v[210:213], v[110:113], v[170:173], v[94:97]
	v_mfma_f32_16x16x32_bf16 v[160:163], v[206:209], v[170:173], v[90:93]
	v_mfma_f32_16x16x32_bf16 v[170:173], v[110:113], v[186:189], v[78:81]
	v_mfma_f32_16x16x32_bf16 v[174:177], v[206:209], v[186:189], v[74:77]
	s_barrier
; #define STAGE_A(b, h, kt) { const u16* ap_ = A + (size_t)((h) * ahalf + (unsigned)(kt) * 64u); glds16(ap_ + ao0, l0 + SA_(b, h)); glds16(ap_ + ao1, l0 + SA_(b, h) + 8192); }
; #define LDA(dst, b, h) _Pragma("unroll") for (int m = 0; m < 4; ++m) _Pragma("unroll") for (int k = 0; k < 2; ++k) \
;     dst[m][k] = *(const bf16x8*)(lds + SA_(b, h) + lds_byte(wr * 64 + m * 16 + fr, k * 32 + fq * 8));
; #define LDB(dst, b, h) _Pragma("unroll") for (int n = 0; n < 2; ++n) _Pragma("unroll") for (int k = 0; k < 2; ++k) \
;     dst[n][k] = *(const bf16x8*)(lds + SB_(b, h) + lds_byte(wc * 32 + n * 16 + fr, k * 32 + fq * 8));
; #define MMA(ai, bj, At_, Bt_) { __builtin_amdgcn_s_setprio(1); \
;     _Pragma("unroll") for (int m = 0; m < 4; ++m) _Pragma("unroll") for (int n = 0; n < 2; ++n) _Pragma("unroll") for (int k = 0; k < 2; ++k) \
;       acc[ai][bj][m][n] = MFMA16(Bt_[n][k], At_[m][k], acc[ai][bj][m][n]); \
;     __builtin_amdgcn_s_setprio(0); }
; #define WAIT_V(n) asm volatile("s_waitcnt vmcnt(" #n ")" ::: "memory");
; #define WAIT_L(n) asm volatile("s_waitcnt lgkmcnt(" #n ")" ::: "memory");
; #define BAR __builtin_amdgcn_s_barrier();
; DI void gemm256(const u16* __restrict__ A, int lda, const u16* __restrict__ B0, const u16* __restrict__ B1, int ldb, int nt, acc_t& acc, char* lds) {
;     ...
;   { LDB(Bq0, 0, 0) LDA(At, 0, 0) STAGE_A(1, 1, nt - 1)
;     BAR WAIT_L(0) MMA(0, 0, At, Bq0) BAR
;     LDB(Bq1, 0, 1) BAR WAIT_L(0) MMA(0, 1, At, Bq1) BAR
;     LDA(At, 0, 1) WAIT_V(4) BAR WAIT_L(0) MMA(1, 0, At, Bq0) MMA(1, 1, At, Bq1) BAR }
;   { LDB(Bq0, 1, 0) LDA(At, 1, 0) WAIT_V(2) BAR WAIT_L(0) MMA(0, 0, At, Bq0) BAR
	s_nop 0
	ds_read_b128 v[74:77], v148 offset:16384
	ds_read_b128 v[78:81], v148 offset:17408
	ds_read_b128 v[90:93], v147 offset:16384
	ds_read_b128 v[94:97], v147 offset:17408
	ds_read_b128 v[178:181], v146 offset:16384
	ds_read_b128 v[182:185], v146 offset:17408
	ds_read_b128 v[186:189], v141 offset:16384
	ds_read_b128 v[190:193], v141 offset:17408
	s_waitcnt vmcnt(4)
	s_barrier
	s_waitcnt lgkmcnt(0)
	v_mfma_f32_16x16x32_bf16 v[60:63], v[132:135], v[74:77], v[60:63]
	v_mfma_f32_16x16x32_bf16 v[56:59], v[142:145], v[74:77], v[56:59]
	v_mfma_f32_16x16x32_bf16 v[52:55], v[132:135], v[90:93], v[52:55]
	v_mfma_f32_16x16x32_bf16 v[48:51], v[142:145], v[90:93], v[48:51]
	v_mfma_f32_16x16x32_bf16 v[36:39], v[132:135], v[186:189], v[36:39]
	v_mfma_f32_16x16x32_bf16 v[32:35], v[142:145], v[186:189], v[32:35]
	v_mfma_f32_16x16x32_bf16 v[60:63], v[136:139], v[78:81], v[60:63]
	v_mfma_f32_16x16x32_bf16 v[56:59], v[156:159], v[78:81], v[56:59]
	v_mfma_f32_16x16x32_bf16 v[52:55], v[136:139], v[94:97], v[52:55]
	v_mfma_f32_16x16x32_bf16 v[48:51], v[156:159], v[94:97], v[48:51]
	v_mfma_f32_16x16x32_bf16 v[44:47], v[132:135], v[178:181], v[44:47]
	v_mfma_f32_16x16x32_bf16 v[40:43], v[142:145], v[178:181], v[40:43]
	v_mfma_f32_16x16x32_bf16 v[36:39], v[136:139], v[190:193], v[36:39]
	v_mfma_f32_16x16x32_bf16 v[32:35], v[156:159], v[190:193], v[32:35]
	v_mfma_f32_16x16x32_bf16 v[194:197], v[136:139], v[182:185], v[44:47]
	v_mfma_f32_16x16x32_bf16 v[216:219], v[156:159], v[182:185], v[40:43]
	v_mfma_f32_16x16x32_bf16 v[20:23], v[106:109], v[90:93], v[20:23]
	v_mfma_f32_16x16x32_bf16 v[16:19], v[202:205], v[90:93], v[16:19]
	v_mfma_f32_16x16x32_bf16 v[4:7], v[106:109], v[186:189], v[4:7]
	v_mfma_f32_16x16x32_bf16 v[0:3], v[202:205], v[186:189], v[0:3]
	v_mfma_f32_16x16x32_bf16 v[28:31], v[106:109], v[74:77], v[28:31]
	v_mfma_f32_16x16x32_bf16 v[24:27], v[202:205], v[74:77], v[24:27]
	v_mfma_f32_16x16x32_bf16 v[20:23], v[110:113], v[94:97], v[20:23]
	v_mfma_f32_16x16x32_bf16 v[16:19], v[206:209], v[94:97], v[16:19]
	v_mfma_f32_16x16x32_bf16 v[12:15], v[106:109], v[178:181], v[12:15]
	v_mfma_f32_16x16x32_bf16 v[8:11], v[202:205], v[178:181], v[8:11]
	v_mfma_f32_16x16x32_bf16 v[4:7], v[110:113], v[190:193], v[4:7]
	v_mfma_f32_16x16x32_bf16 v[0:3], v[206:209], v[190:193], v[0:3]
	v_mfma_f32_16x16x32_bf16 v[130:133], v[110:113], v[78:81], v[28:31]
	v_mfma_f32_16x16x32_bf16 v[134:137], v[206:209], v[78:81], v[24:27]
	v_mfma_f32_16x16x32_bf16 v[142:145], v[110:113], v[182:185], v[12:15]
	v_mfma_f32_16x16x32_bf16 v[156:159], v[206:209], v[182:185], v[8:11]
	s_barrier
	s_nop 0
	ds_read_b128 v[8:11], v155
	ds_read_b128 v[12:15], v155 offset:1024
	ds_read_b128 v[178:181], v155 offset:2048
	ds_read_b128 v[152:155], v155 offset:3072
	ds_read_b128 v[24:27], v148 offset:32768
	ds_read_b128 v[28:31], v148 offset:33792
	ds_read_b128 v[40:43], v147 offset:32768
	ds_read_b128 v[44:47], v147 offset:33792
	ds_read_b128 v[182:185], v146 offset:32768
	ds_read_b128 v[186:189], v146 offset:33792
	ds_read_b128 v[190:193], v141 offset:32768
	ds_read_b128 v[202:205], v141 offset:33792
	s_waitcnt vmcnt(2)
	s_barrier
	s_waitcnt lgkmcnt(0)
	v_mfma_f32_16x16x32_bf16 v[74:77], v[8:11], v[24:27], v[126:129]
	v_mfma_f32_16x16x32_bf16 v[126:129], v[12:15], v[28:31], v[74:77]
	v_mfma_f32_16x16x32_bf16 v[74:77], v[178:181], v[24:27], v[122:125]
	v_mfma_f32_16x16x32_bf16 v[122:125], v[152:155], v[28:31], v[74:77]
	v_mfma_f32_16x16x32_bf16 v[74:77], v[8:11], v[40:43], v[118:121]
	v_mfma_f32_16x16x32_bf16 v[110:113], v[12:15], v[44:47], v[74:77]
	v_mfma_f32_16x16x32_bf16 v[74:77], v[178:181], v[40:43], v[114:117]
	v_mfma_f32_16x16x32_bf16 v[106:109], v[152:155], v[44:47], v[74:77]
	v_mfma_f32_16x16x32_bf16 v[74:77], v[8:11], v[182:185], v[166:169]
	v_mfma_f32_16x16x32_bf16 v[94:97], v[12:15], v[186:189], v[74:77]
	v_mfma_f32_16x16x32_bf16 v[74:77], v[178:181], v[182:185], v[198:201]
	v_mfma_f32_16x16x32_bf16 v[90:93], v[152:155], v[186:189], v[74:77]
	v_mfma_f32_16x16x32_bf16 v[74:77], v[8:11], v[190:193], v[102:105]
	v_mfma_f32_16x16x32_bf16 v[78:81], v[12:15], v[202:205], v[74:77]
	v_mfma_f32_16x16x32_bf16 v[74:77], v[178:181], v[190:193], v[98:101]
	v_mfma_f32_16x16x32_bf16 v[74:77], v[152:155], v[202:205], v[74:77]
	s_barrier
; #define LDA(dst, b, h) _Pragma("unroll") for (int m = 0; m < 4; ++m) _Pragma("unroll") for (int k = 0; k < 2; ++k) \
;     dst[m][k] = *(const bf16x8*)(lds + SA_(b, h) + lds_byte(wr * 64 + m * 16 + fr, k * 32 + fq * 8));
; #define LDB(dst, b, h) _Pragma("unroll") for (int n = 0; n < 2; ++n) _Pragma("unroll") for (int k = 0; k < 2; ++k) \
;     dst[n][k] = *(const bf16x8*)(lds + SB_(b, h) + lds_byte(wc * 32 + n * 16 + fr, k * 32 + fq * 8));
; #define MMA(ai, bj, At_, Bt_) { __builtin_amdgcn_s_setprio(1); \
;     _Pragma("unroll") for (int m = 0; m < 4; ++m) _Pragma("unroll") for (int n = 0; n < 2; ++n) _Pragma("unroll") for (int k = 0; k < 2; ++k) \
;       acc[ai][bj][m][n] = MFMA16(Bt_[n][k], At_[m][k], acc[ai][bj][m][n]); \
;     __builtin_amdgcn_s_setprio(0); }
; #define WAIT_V(n) asm volatile("s_waitcnt vmcnt(" #n ")" ::: "memory");
; #define WAIT_L(n) asm volatile("s_waitcnt lgkmcnt(" #n ")" ::: "memory");
; #define BAR __builtin_amdgcn_s_barrier();
; DI void gemm256(const u16* __restrict__ A, int lda, const u16* __restrict__ B0, const u16* __restrict__ B1, int ldb, int nt, acc_t& acc, char* lds) {
;     ...
;   { LDB(Bq0, 1, 0) LDA(At, 1, 0) WAIT_V(2) BAR WAIT_L(0) MMA(0, 0, At, Bq0) BAR
;     LDB(Bq1, 1, 1) WAIT_V(0) BAR WAIT_L(0) MMA(0, 1, At, Bq1) BAR
;     LDA(At, 1, 1) BAR WAIT_L(0) MMA(1, 0, At, Bq0) MMA(1, 1, At, Bq1) BAR }
;   if (wr == 0) BAR
	ds_read_b128 v[164:167], v150
	ds_read_b128 v[198:201], v150 offset:1024
	ds_read_b128 v[206:209], v150 offset:2048
	ds_read_b128 v[226:229], v150 offset:3072
	s_waitcnt vmcnt(0)
	s_barrier
	s_waitcnt lgkmcnt(0)
	v_mfma_f32_16x16x32_bf16 v[98:101], v[164:167], v[24:27], v[210:213]
	v_mfma_f32_16x16x32_bf16 v[24:27], v[206:209], v[24:27], v[160:163]
	v_mfma_f32_16x16x32_bf16 v[114:117], v[226:229], v[28:31], v[24:27]
	v_mfma_f32_16x16x32_bf16 v[24:27], v[164:167], v[40:43], v[86:89]
	v_mfma_f32_16x16x32_bf16 v[102:105], v[198:201], v[44:47], v[24:27]
	v_mfma_f32_16x16x32_bf16 v[24:27], v[206:209], v[40:43], v[82:85]
	v_mfma_f32_16x16x32_bf16 v[118:121], v[198:201], v[28:31], v[98:101]
	v_mfma_f32_16x16x32_bf16 v[98:101], v[226:229], v[44:47], v[24:27]
	v_mfma_f32_16x16x32_bf16 v[24:27], v[164:167], v[182:185], v[170:173]
	v_mfma_f32_16x16x32_bf16 v[86:89], v[198:201], v[186:189], v[24:27]
	v_mfma_f32_16x16x32_bf16 v[24:27], v[206:209], v[182:185], v[174:177]
	v_mfma_f32_16x16x32_bf16 v[82:85], v[226:229], v[186:189], v[24:27]
	v_mfma_f32_16x16x32_bf16 v[24:27], v[164:167], v[190:193], v[70:73]
	v_mfma_f32_16x16x32_bf16 v[70:73], v[198:201], v[202:205], v[24:27]
	v_mfma_f32_16x16x32_bf16 v[24:27], v[206:209], v[190:193], v[66:69]
	v_mfma_f32_16x16x32_bf16 v[66:69], v[226:229], v[202:205], v[24:27]
	s_barrier
	ds_read_b128 v[160:163], v148 offset:49152
	ds_read_b128 v[148:151], v148 offset:50176
	ds_read_b128 v[168:171], v147 offset:49152
	ds_read_b128 v[172:175], v147 offset:50176
	ds_read_b128 v[182:185], v146 offset:49152
	ds_read_b128 v[186:189], v146 offset:50176
	ds_read_b128 v[190:193], v141 offset:49152
	ds_read_b128 v[202:205], v141 offset:50176
	s_barrier
	s_waitcnt lgkmcnt(0)
	v_mfma_f32_16x16x32_bf16 v[24:27], v[8:11], v[160:163], v[60:63]
	v_mfma_f32_16x16x32_bf16 v[60:63], v[12:15], v[148:151], v[24:27]
	v_mfma_f32_16x16x32_bf16 v[24:27], v[178:181], v[160:163], v[56:59]
	v_mfma_f32_16x16x32_bf16 v[56:59], v[152:155], v[148:151], v[24:27]
	v_mfma_f32_16x16x32_bf16 v[24:27], v[8:11], v[168:171], v[52:55]
	v_mfma_f32_16x16x32_bf16 v[44:47], v[12:15], v[172:175], v[24:27]
	v_mfma_f32_16x16x32_bf16 v[24:27], v[178:181], v[168:171], v[48:51]
	v_mfma_f32_16x16x32_bf16 v[40:43], v[152:155], v[172:175], v[24:27]
	v_mfma_f32_16x16x32_bf16 v[24:27], v[8:11], v[182:185], v[194:197]
	v_mfma_f32_16x16x32_bf16 v[8:11], v[8:11], v[190:193], v[36:39]
	v_mfma_f32_16x16x32_bf16 v[28:31], v[12:15], v[186:189], v[24:27]
	v_mfma_f32_16x16x32_bf16 v[24:27], v[178:181], v[182:185], v[216:219]
	v_mfma_f32_16x16x32_bf16 v[12:15], v[12:15], v[202:205], v[8:11]
	v_mfma_f32_16x16x32_bf16 v[8:11], v[178:181], v[190:193], v[32:35]
	v_mfma_f32_16x16x32_bf16 v[24:27], v[152:155], v[186:189], v[24:27]
	v_mfma_f32_16x16x32_bf16 v[8:11], v[152:155], v[202:205], v[8:11]
	v_mfma_f32_16x16x32_bf16 v[32:35], v[164:167], v[160:163], v[130:133]
	v_mfma_f32_16x16x32_bf16 v[52:55], v[198:201], v[148:151], v[32:35]
	v_mfma_f32_16x16x32_bf16 v[32:35], v[206:209], v[160:163], v[134:137]
	v_mfma_f32_16x16x32_bf16 v[16:19], v[206:209], v[168:171], v[16:19]
	v_mfma_f32_16x16x32_bf16 v[48:51], v[226:229], v[148:151], v[32:35]
	v_mfma_f32_16x16x32_bf16 v[20:23], v[164:167], v[168:171], v[20:23]
	v_mfma_f32_16x16x32_bf16 v[32:35], v[226:229], v[172:175], v[16:19]
	v_mfma_f32_16x16x32_bf16 v[16:19], v[164:167], v[182:185], v[142:145]
	v_mfma_f32_16x16x32_bf16 v[36:39], v[198:201], v[172:175], v[20:23]
	v_mfma_f32_16x16x32_bf16 v[20:23], v[198:201], v[186:189], v[16:19]
	v_mfma_f32_16x16x32_bf16 v[16:19], v[206:209], v[182:185], v[156:159]
	v_mfma_f32_16x16x32_bf16 v[4:7], v[164:167], v[190:193], v[4:7]
	v_mfma_f32_16x16x32_bf16 v[0:3], v[206:209], v[190:193], v[0:3]
	v_mfma_f32_16x16x32_bf16 v[16:19], v[226:229], v[186:189], v[16:19]
	v_mfma_f32_16x16x32_bf16 v[4:7], v[198:201], v[202:205], v[4:7]
	v_mfma_f32_16x16x32_bf16 v[0:3], v[226:229], v[202:205], v[0:3]
	s_movk_i32 s3, 0x100
	v_cmp_gt_u32_e32 vcc, s3, v140
	s_barrier
	s_and_saveexec_b64 s[8:9], vcc
	s_cbranch_execz .LBB0_171
	s_barrier

; #define STAGE_A(b, h, kt) { const u16* ap_ = A + (size_t)((h) * ahalf + (unsigned)(kt) * 64u); glds16(ap_ + ao0, l0 + SA_(b, h)); glds16(ap_ + ao1, l0 + SA_(b, h) + 8192); }
; #define STAGE_B(b, h, kt) { const u16* bp_ = ((h) ? B1 : B0) + (unsigned)(kt) * 64u; glds16(bp_ + bo0, l0 + SB_(b, h)); glds16(bp_ + bo1, l0 + SB_(b, h) + 8192); }
; #define LDA(dst, b, h) _Pragma("unroll") for (int m = 0; m < 4; ++m) _Pragma("unroll") for (int k = 0; k < 2; ++k) \
;     dst[m][k] = *(const bf16x8*)(lds + SA_(b, h) + lds_byte(wr * 64 + m * 16 + fr, k * 32 + fq * 8));
; #define LDB(dst, b, h) _Pragma("unroll") for (int n = 0; n < 2; ++n) _Pragma("unroll") for (int k = 0; k < 2; ++k) \
;     dst[n][k] = *(const bf16x8*)(lds + SB_(b, h) + lds_byte(wc * 32 + n * 16 + fr, k * 32 + fq * 8));
; #define MMA(ai, bj, At_, Bt_) { __builtin_amdgcn_s_setprio(1); \
;     _Pragma("unroll") for (int m = 0; m < 4; ++m) _Pragma("unroll") for (int n = 0; n < 2; ++n) _Pragma("unroll") for (int k = 0; k < 2; ++k) \
;       acc[ai][bj][m][n] = MFMA16(Bt_[n][k], At_[m][k], acc[ai][bj][m][n]); \
;     __builtin_amdgcn_s_setprio(0); }
; #define WAIT_V(n) asm volatile("s_waitcnt vmcnt(" #n ")" ::: "memory");
; #define WAIT_L(n) asm volatile("s_waitcnt lgkmcnt(" #n ")" ::: "memory");
; #define BAR __builtin_amdgcn_s_barrier();
; #define SCHED __builtin_amdgcn_sched_barrier(0);
; DI void gemm256(const u16* __restrict__ A, int lda, const u16* __restrict__ B0, const u16* __restrict__ B1, int ldb, int nt, acc_t& acc, char* lds) {
;     ...
;   for (int t = 0; t < nt - 2; t += 2) {
;     LDB(Bq0, 0, 0) SCHED LDA(At, 0, 0) STAGE_A(1, 1, t + 1)
;     WAIT_L(8) BAR WAIT_L(0) MMA(0, 0, At, Bq0) BAR SCHED
;     LDB(Bq1, 0, 1) STAGE_B(0, 0, t + 2)
;     BAR WAIT_L(0) MMA(0, 1, At, Bq1) BAR
;     LDA(At, 0, 1) STAGE_A(0, 0, t + 2)
;     BAR WAIT_L(0) MMA(1, 0, At, Bq0) BAR SCHED
;     STAGE_B(0, 1, t + 2)
;     WAIT_V(6) BAR MMA(1, 1, At, Bq1) BAR
;     LDB(Bq0, 1, 0) SCHED LDA(At, 1, 0) STAGE_A(0, 1, t + 2)
;     WAIT_L(8) BAR WAIT_L(0) MMA(0, 0, At, Bq0) BAR SCHED
;     LDB(Bq1, 1, 1) STAGE_B(1, 0, t + 3)
;     BAR WAIT_L(0) MMA(0, 1, At, Bq1) BAR
;     LDA(At, 1, 1) STAGE_A(1, 0, t + 3)
;     BAR WAIT_L(0) MMA(1, 0, At, Bq0) BAR SCHED
;     STAGE_B(1, 1, t + 3)
;     WAIT_V(6) BAR MMA(1, 1, At, Bq1) BAR
;   }
.LBB0_564:
	ds_read_b128 v[170:173], v166
	ds_read_b128 v[174:177], v166 offset:1024
	ds_read_b128 v[178:181], v166 offset:2048
	ds_read_b128 v[182:185], v166 offset:3072
	v_lshl_add_u64 v[142:143], s[22:23], 0, v[138:139]
	v_readfirstlane_b32 s3, v167
	v_lshl_add_u64 v[144:145], v[142:143], 0, s[38:39]
	s_mov_b32 m0, s3
	ds_read_b128 v[186:189], v148
	ds_read_b128 v[194:197], v147
	ds_read_b128 v[202:205], v146
	ds_read_b128 v[210:213], v141
	global_load_lds_dwordx4 v[144:145], off
	v_lshl_add_u64 v[144:145], s[22:23], 0, v[136:137]
	v_readfirstlane_b32 s3, v168
	v_lshl_add_u64 v[216:217], v[144:145], 0, s[38:39]
	s_mov_b32 m0, s3
	s_nop 0
	global_load_lds_dwordx4 v[216:217], off
	s_waitcnt lgkmcnt(4)
	s_barrier
	s_waitcnt lgkmcnt(0)
	ds_read_b128 v[190:193], v148 offset:1024
	ds_read_b128 v[198:201], v147 offset:1024
	ds_read_b128 v[206:209], v146 offset:1024
	ds_read_b128 v[226:229], v141 offset:1024
	v_mfma_f32_16x16x32_bf16 v[126:129], v[170:173], v[186:189], v[126:129]
	v_mfma_f32_16x16x32_bf16 v[122:125], v[178:181], v[186:189], v[122:125]
	v_mfma_f32_16x16x32_bf16 v[118:121], v[170:173], v[194:197], v[118:121]
	v_mfma_f32_16x16x32_bf16 v[114:117], v[178:181], v[194:197], v[114:117]
	v_mfma_f32_16x16x32_bf16 v[110:113], v[170:173], v[202:205], v[110:113]
	v_mfma_f32_16x16x32_bf16 v[106:109], v[178:181], v[202:205], v[106:109]
	v_mfma_f32_16x16x32_bf16 v[102:105], v[170:173], v[210:213], v[102:105]
	v_mfma_f32_16x16x32_bf16 v[98:101], v[178:181], v[210:213], v[98:101]
	s_waitcnt lgkmcnt(0)
	v_mfma_f32_16x16x32_bf16 v[126:129], v[174:177], v[190:193], v[126:129]
	v_mfma_f32_16x16x32_bf16 v[122:125], v[182:185], v[190:193], v[122:125]
	v_mfma_f32_16x16x32_bf16 v[118:121], v[174:177], v[198:201], v[118:121]
	v_mfma_f32_16x16x32_bf16 v[114:117], v[182:185], v[198:201], v[114:117]
	v_mfma_f32_16x16x32_bf16 v[110:113], v[174:177], v[206:209], v[110:113]
	v_mfma_f32_16x16x32_bf16 v[106:109], v[182:185], v[206:209], v[106:109]
	v_mfma_f32_16x16x32_bf16 v[102:105], v[174:177], v[226:229], v[102:105]
	v_mfma_f32_16x16x32_bf16 v[98:101], v[182:185], v[226:229], v[98:101]
	s_barrier
	v_lshl_add_u64 v[216:217], s[22:23], 0, v[132:133]
	v_readfirstlane_b32 s3, v150
	v_lshl_add_u64 v[218:219], v[216:217], 0, s[20:21]
	s_mov_b32 m0, s3
	ds_read_b128 v[230:233], v165
	ds_read_b128 v[234:237], v165 offset:1024
	ds_read_b128 v[238:241], v165 offset:2048
	ds_read_b128 v[242:245], v165 offset:3072
	global_load_lds_dwordx4 v[218:219], off
	v_lshl_add_u64 v[218:219], s[22:23], 0, v[134:135]
	v_readfirstlane_b32 s3, v152
	v_lshl_add_u64 v[222:223], v[218:219], 0, s[20:21]
	s_mov_b32 m0, s3
	s_nop 0
	global_load_lds_dwordx4 v[222:223], off
	s_barrier
	s_waitcnt lgkmcnt(0)
	v_mfma_f32_16x16x32_bf16 v[94:97], v[230:233], v[186:189], v[94:97]
	v_mfma_f32_16x16x32_bf16 v[90:93], v[238:241], v[186:189], v[90:93]
	v_mfma_f32_16x16x32_bf16 v[86:89], v[230:233], v[194:197], v[86:89]
	v_mfma_f32_16x16x32_bf16 v[82:85], v[238:241], v[194:197], v[82:85]
	v_mfma_f32_16x16x32_bf16 v[78:81], v[230:233], v[202:205], v[78:81]
	v_mfma_f32_16x16x32_bf16 v[74:77], v[238:241], v[202:205], v[74:77]
	v_mfma_f32_16x16x32_bf16 v[70:73], v[230:233], v[210:213], v[70:73]
	v_mfma_f32_16x16x32_bf16 v[66:69], v[238:241], v[210:213], v[66:69]
	v_mfma_f32_16x16x32_bf16 v[94:97], v[234:237], v[190:193], v[94:97]
	v_mfma_f32_16x16x32_bf16 v[90:93], v[242:245], v[190:193], v[90:93]
	v_mfma_f32_16x16x32_bf16 v[86:89], v[234:237], v[198:201], v[86:89]
	v_mfma_f32_16x16x32_bf16 v[82:85], v[242:245], v[198:201], v[82:85]
	v_mfma_f32_16x16x32_bf16 v[78:81], v[234:237], v[206:209], v[78:81]
	v_mfma_f32_16x16x32_bf16 v[74:77], v[242:245], v[206:209], v[74:77]
	v_mfma_f32_16x16x32_bf16 v[70:73], v[234:237], v[226:229], v[70:73]
	v_mfma_f32_16x16x32_bf16 v[66:69], v[242:245], v[226:229], v[66:69]
	v_readfirstlane_b32 s3, v149
	v_lshl_add_u64 v[222:223], v[142:143], 0, s[28:29]
	s_mov_b32 m0, s3
	v_readfirstlane_b32 s3, v153
	s_barrier
	ds_read_b128 v[186:189], v148 offset:16384
	ds_read_b128 v[194:197], v147 offset:16384
	ds_read_b128 v[202:205], v146 offset:16384
	ds_read_b128 v[210:213], v141 offset:16384
	global_load_lds_dwordx4 v[222:223], off
	v_lshl_add_u64 v[222:223], v[144:145], 0, s[28:29]
	s_mov_b32 m0, s3
	s_nop 0
	global_load_lds_dwordx4 v[222:223], off
	s_barrier
	s_waitcnt lgkmcnt(0)
	ds_read_b128 v[190:193], v148 offset:17408
	ds_read_b128 v[198:201], v147 offset:17408
	ds_read_b128 v[206:209], v146 offset:17408
	ds_read_b128 v[226:229], v141 offset:17408
	v_mfma_f32_16x16x32_bf16 v[60:63], v[170:173], v[186:189], v[60:63]
	v_mfma_f32_16x16x32_bf16 v[56:59], v[178:181], v[186:189], v[56:59]
	v_mfma_f32_16x16x32_bf16 v[52:55], v[170:173], v[194:197], v[52:55]
	v_mfma_f32_16x16x32_bf16 v[48:51], v[178:181], v[194:197], v[48:51]
	v_mfma_f32_16x16x32_bf16 v[44:47], v[170:173], v[202:205], v[44:47]
	v_mfma_f32_16x16x32_bf16 v[40:43], v[178:181], v[202:205], v[40:43]
	v_mfma_f32_16x16x32_bf16 v[36:39], v[170:173], v[210:213], v[36:39]
	v_mfma_f32_16x16x32_bf16 v[32:35], v[178:181], v[210:213], v[32:35]
	s_waitcnt lgkmcnt(0)
	v_mfma_f32_16x16x32_bf16 v[60:63], v[174:177], v[190:193], v[60:63]
	v_mfma_f32_16x16x32_bf16 v[56:59], v[182:185], v[190:193], v[56:59]
	v_mfma_f32_16x16x32_bf16 v[52:55], v[174:177], v[198:201], v[52:55]
	v_mfma_f32_16x16x32_bf16 v[48:51], v[182:185], v[198:201], v[48:51]
	v_mfma_f32_16x16x32_bf16 v[44:47], v[174:177], v[206:209], v[44:47]
	v_mfma_f32_16x16x32_bf16 v[40:43], v[182:185], v[206:209], v[40:43]
	v_mfma_f32_16x16x32_bf16 v[36:39], v[174:177], v[226:229], v[36:39]
	v_mfma_f32_16x16x32_bf16 v[32:35], v[182:185], v[226:229], v[32:35]
	s_barrier
; #define STAGE_A(b, h, kt) { const u16* ap_ = A + (size_t)((h) * ahalf + (unsigned)(kt) * 64u); glds16(ap_ + ao0, l0 + SA_(b, h)); glds16(ap_ + ao1, l0 + SA_(b, h) + 8192); }
; #define STAGE_B(b, h, kt) { const u16* bp_ = ((h) ? B1 : B0) + (unsigned)(kt) * 64u; glds16(bp_ + bo0, l0 + SB_(b, h)); glds16(bp_ + bo1, l0 + SB_(b, h) + 8192); }
; #define LDA(dst, b, h) _Pragma("unroll") for (int m = 0; m < 4; ++m) _Pragma("unroll") for (int k = 0; k < 2; ++k) \
;     dst[m][k] = *(const bf16x8*)(lds + SA_(b, h) + lds_byte(wr * 64 + m * 16 + fr, k * 32 + fq * 8));
; #define LDB(dst, b, h) _Pragma("unroll") for (int n = 0; n < 2; ++n) _Pragma("unroll") for (int k = 0; k < 2; ++k) \
;     dst[n][k] = *(const bf16x8*)(lds + SB_(b, h) + lds_byte(wc * 32 + n * 16 + fr, k * 32 + fq * 8));
; #define MMA(ai, bj, At_, Bt_) { __builtin_amdgcn_s_setprio(1); \
;     _Pragma("unroll") for (int m = 0; m < 4; ++m) _Pragma("unroll") for (int n = 0; n < 2; ++n) _Pragma("unroll") for (int k = 0; k < 2; ++k) \
;       acc[ai][bj][m][n] = MFMA16(Bt_[n][k], At_[m][k], acc[ai][bj][m][n]); \
;     __builtin_amdgcn_s_setprio(0); }
; #define WAIT_V(n) asm volatile("s_waitcnt vmcnt(" #n ")" ::: "memory");
; #define WAIT_L(n) asm volatile("s_waitcnt lgkmcnt(" #n ")" ::: "memory");
; #define BAR __builtin_amdgcn_s_barrier();
; #define SCHED __builtin_amdgcn_sched_barrier(0);
; DI void gemm256(const u16* __restrict__ A, int lda, const u16* __restrict__ B0, const u16* __restrict__ B1, int ldb, int nt, acc_t& acc, char* lds) {
;     ...
;   for (int t = 0; t < nt - 2; t += 2) {
;     LDB(Bq0, 0, 0) SCHED LDA(At, 0, 0) STAGE_A(1, 1, t + 1)
;     WAIT_L(8) BAR WAIT_L(0) MMA(0, 0, At, Bq0) BAR SCHED
;     LDB(Bq1, 0, 1) STAGE_B(0, 0, t + 2)
;     BAR WAIT_L(0) MMA(0, 1, At, Bq1) BAR
;     LDA(At, 0, 1) STAGE_A(0, 0, t + 2)
;     BAR WAIT_L(0) MMA(1, 0, At, Bq0) BAR SCHED
;     STAGE_B(0, 1, t + 2)
;     WAIT_V(6) BAR MMA(1, 1, At, Bq1) BAR
;     LDB(Bq0, 1, 0) SCHED LDA(At, 1, 0) STAGE_A(0, 1, t + 2)
;     WAIT_L(8) BAR WAIT_L(0) MMA(0, 0, At, Bq0) BAR SCHED
;     LDB(Bq1, 1, 1) STAGE_B(1, 0, t + 3)
;     BAR WAIT_L(0) MMA(0, 1, At, Bq1) BAR
;     LDA(At, 1, 1) STAGE_A(1, 0, t + 3)
;     BAR WAIT_L(0) MMA(1, 0, At, Bq0) BAR SCHED
;     STAGE_B(1, 1, t + 3)
;     WAIT_V(6) BAR MMA(1, 1, At, Bq1) BAR
;   }
	v_readfirstlane_b32 s3, v154
	v_lshl_add_u64 v[170:171], v[216:217], 0, s[24:25]
	s_mov_b32 m0, s3
	v_readfirstlane_b32 s3, v155
	global_load_lds_dwordx4 v[170:171], off
	v_lshl_add_u64 v[170:171], v[218:219], 0, s[24:25]
	s_mov_b32 m0, s3
	s_nop 0
	global_load_lds_dwordx4 v[170:171], off
	s_waitcnt vmcnt(6)
	s_barrier
	v_mfma_f32_16x16x32_bf16 v[28:31], v[230:233], v[186:189], v[28:31]
	v_mfma_f32_16x16x32_bf16 v[24:27], v[238:241], v[186:189], v[24:27]
	v_mfma_f32_16x16x32_bf16 v[20:23], v[230:233], v[194:197], v[20:23]
	v_mfma_f32_16x16x32_bf16 v[16:19], v[238:241], v[194:197], v[16:19]
	v_mfma_f32_16x16x32_bf16 v[12:15], v[230:233], v[202:205], v[12:15]
	v_mfma_f32_16x16x32_bf16 v[8:11], v[238:241], v[202:205], v[8:11]
	v_mfma_f32_16x16x32_bf16 v[4:7], v[230:233], v[210:213], v[4:7]
	v_mfma_f32_16x16x32_bf16 v[0:3], v[238:241], v[210:213], v[0:3]
	v_mfma_f32_16x16x32_bf16 v[28:31], v[234:237], v[190:193], v[28:31]
	v_mfma_f32_16x16x32_bf16 v[24:27], v[242:245], v[190:193], v[24:27]
	v_mfma_f32_16x16x32_bf16 v[20:23], v[234:237], v[198:201], v[20:23]
	v_mfma_f32_16x16x32_bf16 v[16:19], v[242:245], v[198:201], v[16:19]
	v_mfma_f32_16x16x32_bf16 v[12:15], v[234:237], v[206:209], v[12:15]
	v_mfma_f32_16x16x32_bf16 v[8:11], v[242:245], v[206:209], v[8:11]
	v_mfma_f32_16x16x32_bf16 v[4:7], v[234:237], v[226:229], v[4:7]
	v_mfma_f32_16x16x32_bf16 v[0:3], v[242:245], v[226:229], v[0:3]
	s_barrier
	ds_read_b128 v[170:173], v156
	ds_read_b128 v[174:177], v156 offset:1024
	ds_read_b128 v[178:181], v156 offset:2048
	ds_read_b128 v[182:185], v156 offset:3072
	v_readfirstlane_b32 s3, v157
	v_lshl_add_u64 v[222:223], v[142:143], 0, s[36:37]
	s_mov_b32 m0, s3
	v_readfirstlane_b32 s3, v158
	ds_read_b128 v[186:189], v148 offset:32768
	ds_read_b128 v[194:197], v147 offset:32768
	ds_read_b128 v[202:205], v146 offset:32768
	ds_read_b128 v[210:213], v141 offset:32768
	global_load_lds_dwordx4 v[222:223], off
	v_lshl_add_u64 v[222:223], v[144:145], 0, s[36:37]
	s_mov_b32 m0, s3
	s_nop 0
	global_load_lds_dwordx4 v[222:223], off
	s_waitcnt lgkmcnt(4)
	s_barrier
	s_waitcnt lgkmcnt(0)
	ds_read_b128 v[190:193], v148 offset:33792
	ds_read_b128 v[198:201], v147 offset:33792
	ds_read_b128 v[206:209], v146 offset:33792
	ds_read_b128 v[226:229], v141 offset:33792
	v_mfma_f32_16x16x32_bf16 v[126:129], v[170:173], v[186:189], v[126:129]
	v_mfma_f32_16x16x32_bf16 v[122:125], v[178:181], v[186:189], v[122:125]
	v_mfma_f32_16x16x32_bf16 v[118:121], v[170:173], v[194:197], v[118:121]
	v_mfma_f32_16x16x32_bf16 v[114:117], v[178:181], v[194:197], v[114:117]
	v_mfma_f32_16x16x32_bf16 v[110:113], v[170:173], v[202:205], v[110:113]
	v_mfma_f32_16x16x32_bf16 v[106:109], v[178:181], v[202:205], v[106:109]
	v_mfma_f32_16x16x32_bf16 v[102:105], v[170:173], v[210:213], v[102:105]
	v_mfma_f32_16x16x32_bf16 v[98:101], v[178:181], v[210:213], v[98:101]
	s_waitcnt lgkmcnt(0)
	v_mfma_f32_16x16x32_bf16 v[126:129], v[174:177], v[190:193], v[126:129]
	v_mfma_f32_16x16x32_bf16 v[122:125], v[182:185], v[190:193], v[122:125]
	v_mfma_f32_16x16x32_bf16 v[118:121], v[174:177], v[198:201], v[118:121]
	v_mfma_f32_16x16x32_bf16 v[114:117], v[182:185], v[198:201], v[114:117]
	v_mfma_f32_16x16x32_bf16 v[110:113], v[174:177], v[206:209], v[110:113]
	v_mfma_f32_16x16x32_bf16 v[106:109], v[182:185], v[206:209], v[106:109]
	v_mfma_f32_16x16x32_bf16 v[102:105], v[174:177], v[226:229], v[102:105]
	v_mfma_f32_16x16x32_bf16 v[98:101], v[182:185], v[226:229], v[98:101]
	s_barrier
	v_readfirstlane_b32 s3, v159
	v_lshl_add_u64 v[222:223], v[216:217], 0, s[34:35]
	s_mov_b32 m0, s3
	v_readfirstlane_b32 s3, v160
	ds_read_b128 v[230:233], v151
	ds_read_b128 v[234:237], v151 offset:1024
	ds_read_b128 v[238:241], v151 offset:2048
	ds_read_b128 v[242:245], v151 offset:3072
	global_load_lds_dwordx4 v[222:223], off
	v_lshl_add_u64 v[222:223], v[218:219], 0, s[34:35]
	s_mov_b32 m0, s3
	s_nop 0
	global_load_lds_dwordx4 v[222:223], off
	s_barrier
	s_waitcnt lgkmcnt(0)
	v_mfma_f32_16x16x32_bf16 v[94:97], v[230:233], v[186:189], v[94:97]
	v_mfma_f32_16x16x32_bf16 v[90:93], v[238:241], v[186:189], v[90:93]
	v_mfma_f32_16x16x32_bf16 v[86:89], v[230:233], v[194:197], v[86:89]
	v_mfma_f32_16x16x32_bf16 v[82:85], v[238:241], v[194:197], v[82:85]
	v_mfma_f32_16x16x32_bf16 v[78:81], v[230:233], v[202:205], v[78:81]
	v_mfma_f32_16x16x32_bf16 v[74:77], v[238:241], v[202:205], v[74:77]
	v_mfma_f32_16x16x32_bf16 v[70:73], v[230:233], v[210:213], v[70:73]
	v_mfma_f32_16x16x32_bf16 v[66:69], v[238:241], v[210:213], v[66:69]
	v_mfma_f32_16x16x32_bf16 v[94:97], v[234:237], v[190:193], v[94:97]
	v_mfma_f32_16x16x32_bf16 v[90:93], v[242:245], v[190:193], v[90:93]
	v_mfma_f32_16x16x32_bf16 v[86:89], v[234:237], v[198:201], v[86:89]
	v_mfma_f32_16x16x32_bf16 v[82:85], v[242:245], v[198:201], v[82:85]
	v_mfma_f32_16x16x32_bf16 v[78:81], v[234:237], v[206:209], v[78:81]
	v_mfma_f32_16x16x32_bf16 v[74:77], v[242:245], v[206:209], v[74:77]
	v_mfma_f32_16x16x32_bf16 v[70:73], v[234:237], v[226:229], v[70:73]
	v_mfma_f32_16x16x32_bf16 v[66:69], v[242:245], v[226:229], v[66:69]
	v_readfirstlane_b32 s3, v161
	v_lshl_add_u64 v[142:143], v[142:143], 0, s[26:27]
	s_mov_b32 m0, s3
	v_readfirstlane_b32 s3, v162
	s_barrier
	ds_read_b128 v[186:189], v148 offset:49152
	ds_read_b128 v[194:197], v147 offset:49152
	ds_read_b128 v[202:205], v146 offset:49152
	ds_read_b128 v[210:213], v141 offset:49152
	global_load_lds_dwordx4 v[142:143], off
	v_lshl_add_u64 v[142:143], v[144:145], 0, s[26:27]
	s_mov_b32 m0, s3
	s_nop 0
	global_load_lds_dwordx4 v[142:143], off
	s_barrier
; #define STAGE_A(b, h, kt) { const u16* ap_ = A + (size_t)((h) * ahalf + (unsigned)(kt) * 64u); glds16(ap_ + ao0, l0 + SA_(b, h)); glds16(ap_ + ao1, l0 + SA_(b, h) + 8192); }
; #define STAGE_B(b, h, kt) { const u16* bp_ = ((h) ? B1 : B0) + (unsigned)(kt) * 64u; glds16(bp_ + bo0, l0 + SB_(b, h)); glds16(bp_ + bo1, l0 + SB_(b, h) + 8192); }
; #define LDA(dst, b, h) _Pragma("unroll") for (int m = 0; m < 4; ++m) _Pragma("unroll") for (int k = 0; k < 2; ++k) \
;     dst[m][k] = *(const bf16x8*)(lds + SA_(b, h) + lds_byte(wr * 64 + m * 16 + fr, k * 32 + fq * 8));
; #define LDB(dst, b, h) _Pragma("unroll") for (int n = 0; n < 2; ++n) _Pragma("unroll") for (int k = 0; k < 2; ++k) \
;     dst[n][k] = *(const bf16x8*)(lds + SB_(b, h) + lds_byte(wc * 32 + n * 16 + fr, k * 32 + fq * 8));
; #define MMA(ai, bj, At_, Bt_) { __builtin_amdgcn_s_setprio(1); \
;     _Pragma("unroll") for (int m = 0; m < 4; ++m) _Pragma("unroll") for (int n = 0; n < 2; ++n) _Pragma("unroll") for (int k = 0; k < 2; ++k) \
;       acc[ai][bj][m][n] = MFMA16(Bt_[n][k], At_[m][k], acc[ai][bj][m][n]); \
;     __builtin_amdgcn_s_setprio(0); }
; #define WAIT_V(n) asm volatile("s_waitcnt vmcnt(" #n ")" ::: "memory");
; #define WAIT_L(n) asm volatile("s_waitcnt lgkmcnt(" #n ")" ::: "memory");
; #define BAR __builtin_amdgcn_s_barrier();
; #define SCHED __builtin_amdgcn_sched_barrier(0);
; DI void gemm256(const u16* __restrict__ A, int lda, const u16* __restrict__ B0, const u16* __restrict__ B1, int ldb, int nt, acc_t& acc, char* lds) {
;     ...
;     BAR WAIT_L(0) MMA(1, 0, At, Bq0) BAR SCHED
;     STAGE_B(1, 1, t + 3)
;     WAIT_V(6) BAR MMA(1, 1, At, Bq1) BAR
;   }
;   { LDB(Bq0, 0, 0) LDA(At, 0, 0) STAGE_A(1, 1, nt - 1)
;     BAR WAIT_L(0) MMA(0, 0, At, Bq0) BAR
;     LDB(Bq1, 0, 1) BAR WAIT_L(0) MMA(0, 1, At, Bq1) BAR
	s_waitcnt lgkmcnt(0)
	ds_read_b128 v[190:193], v148 offset:50176
	ds_read_b128 v[198:201], v147 offset:50176
	ds_read_b128 v[206:209], v146 offset:50176
	ds_read_b128 v[226:229], v141 offset:50176
	v_mfma_f32_16x16x32_bf16 v[60:63], v[170:173], v[186:189], v[60:63]
	v_mfma_f32_16x16x32_bf16 v[56:59], v[178:181], v[186:189], v[56:59]
	v_mfma_f32_16x16x32_bf16 v[52:55], v[170:173], v[194:197], v[52:55]
	v_mfma_f32_16x16x32_bf16 v[48:51], v[178:181], v[194:197], v[48:51]
	v_mfma_f32_16x16x32_bf16 v[44:47], v[170:173], v[202:205], v[44:47]
	v_mfma_f32_16x16x32_bf16 v[40:43], v[178:181], v[202:205], v[40:43]
	v_mfma_f32_16x16x32_bf16 v[36:39], v[170:173], v[210:213], v[36:39]
	v_mfma_f32_16x16x32_bf16 v[32:35], v[178:181], v[210:213], v[32:35]
	s_waitcnt lgkmcnt(0)
	v_mfma_f32_16x16x32_bf16 v[60:63], v[174:177], v[190:193], v[60:63]
	v_mfma_f32_16x16x32_bf16 v[56:59], v[182:185], v[190:193], v[56:59]
	v_mfma_f32_16x16x32_bf16 v[52:55], v[174:177], v[198:201], v[52:55]
	v_mfma_f32_16x16x32_bf16 v[48:51], v[182:185], v[198:201], v[48:51]
	v_mfma_f32_16x16x32_bf16 v[44:47], v[174:177], v[206:209], v[44:47]
	v_mfma_f32_16x16x32_bf16 v[40:43], v[182:185], v[206:209], v[40:43]
	v_mfma_f32_16x16x32_bf16 v[36:39], v[174:177], v[226:229], v[36:39]
	v_mfma_f32_16x16x32_bf16 v[32:35], v[182:185], v[226:229], v[32:35]
	s_barrier
	v_readfirstlane_b32 s3, v163
	v_lshl_add_u64 v[142:143], v[216:217], 0, s[50:51]
	s_mov_b32 m0, s3
	v_readfirstlane_b32 s3, v164
	global_load_lds_dwordx4 v[142:143], off
	v_lshl_add_u64 v[142:143], v[218:219], 0, s[50:51]
	s_mov_b32 m0, s3
	s_nop 0
	global_load_lds_dwordx4 v[142:143], off
	s_waitcnt vmcnt(6)
	s_barrier
	v_mfma_f32_16x16x32_bf16 v[28:31], v[230:233], v[186:189], v[28:31]
	v_mfma_f32_16x16x32_bf16 v[24:27], v[238:241], v[186:189], v[24:27]
	v_mfma_f32_16x16x32_bf16 v[20:23], v[230:233], v[194:197], v[20:23]
	v_mfma_f32_16x16x32_bf16 v[16:19], v[238:241], v[194:197], v[16:19]
	v_mfma_f32_16x16x32_bf16 v[12:15], v[230:233], v[202:205], v[12:15]
	v_mfma_f32_16x16x32_bf16 v[8:11], v[238:241], v[202:205], v[8:11]
	v_mfma_f32_16x16x32_bf16 v[4:7], v[230:233], v[210:213], v[4:7]
	v_mfma_f32_16x16x32_bf16 v[0:3], v[238:241], v[210:213], v[0:3]
	v_mfma_f32_16x16x32_bf16 v[28:31], v[234:237], v[190:193], v[28:31]
	v_mfma_f32_16x16x32_bf16 v[24:27], v[242:245], v[190:193], v[24:27]
	v_mfma_f32_16x16x32_bf16 v[20:23], v[234:237], v[198:201], v[20:23]
	v_mfma_f32_16x16x32_bf16 v[16:19], v[242:245], v[198:201], v[16:19]
	v_mfma_f32_16x16x32_bf16 v[12:15], v[234:237], v[206:209], v[12:15]
	v_mfma_f32_16x16x32_bf16 v[8:11], v[242:245], v[206:209], v[8:11]
	v_mfma_f32_16x16x32_bf16 v[4:7], v[234:237], v[226:229], v[4:7]
	v_mfma_f32_16x16x32_bf16 v[0:3], v[242:245], v[226:229], v[0:3]
	s_add_i32 s2, s2, 2
	s_add_u32 s22, s22, 0x100
	s_addc_u32 s23, s23, 0
	s_cmp_lt_u32 s2, 12
	s_barrier
	s_cbranch_scc1 .LBB0_564
	s_add_u32 s2, s8, 0x40780
	s_addc_u32 s3, s9, 0
	v_readfirstlane_b32 s7, v167
	v_lshl_add_u64 v[142:143], v[64:65], 1, s[2:3]
	s_mov_b32 m0, s7
	v_lshl_add_u64 v[130:131], v[130:131], 1, s[2:3]
	v_readfirstlane_b32 s2, v168
	ds_read_b128 v[132:135], v166
	ds_read_b128 v[136:139], v166 offset:1024
	ds_read_b128 v[152:155], v166 offset:2048
	ds_read_b128 v[158:161], v166 offset:3072
	ds_read_b128 v[170:173], v148
	ds_read_b128 v[174:177], v148 offset:1024
	ds_read_b128 v[178:181], v147
	ds_read_b128 v[182:185], v147 offset:1024
	ds_read_b128 v[186:189], v146
	ds_read_b128 v[190:193], v146 offset:1024
	ds_read_b128 v[194:197], v141
	ds_read_b128 v[198:201], v141 offset:1024
	global_load_lds_dwordx4 v[142:143], off
	s_mov_b32 m0, s2
	s_nop 0
	global_load_lds_dwordx4 v[130:131], off
	s_barrier
	s_waitcnt lgkmcnt(0)
	v_mfma_f32_16x16x32_bf16 v[126:129], v[132:135], v[170:173], v[126:129]
	v_mfma_f32_16x16x32_bf16 v[122:125], v[152:155], v[170:173], v[122:125]
	v_mfma_f32_16x16x32_bf16 v[118:121], v[132:135], v[178:181], v[118:121]
	v_mfma_f32_16x16x32_bf16 v[114:117], v[152:155], v[178:181], v[114:117]
	v_mfma_f32_16x16x32_bf16 v[110:113], v[132:135], v[186:189], v[110:113]
	v_mfma_f32_16x16x32_bf16 v[106:109], v[152:155], v[186:189], v[106:109]
	v_mfma_f32_16x16x32_bf16 v[102:105], v[132:135], v[194:197], v[102:105]
	v_mfma_f32_16x16x32_bf16 v[98:101], v[152:155], v[194:197], v[98:101]
	v_mfma_f32_16x16x32_bf16 v[126:129], v[136:139], v[174:177], v[126:129]
	v_mfma_f32_16x16x32_bf16 v[122:125], v[158:161], v[174:177], v[122:125]
	v_mfma_f32_16x16x32_bf16 v[118:121], v[136:139], v[182:185], v[118:121]
	v_mfma_f32_16x16x32_bf16 v[114:117], v[158:161], v[182:185], v[114:117]
	v_mfma_f32_16x16x32_bf16 v[110:113], v[136:139], v[190:193], v[110:113]
	v_mfma_f32_16x16x32_bf16 v[106:109], v[158:161], v[190:193], v[106:109]
	v_mfma_f32_16x16x32_bf16 v[102:105], v[136:139], v[198:201], v[102:105]
	v_mfma_f32_16x16x32_bf16 v[98:101], v[158:161], v[198:201], v[98:101]
	s_barrier
	ds_read_b128 v[166:169], v165
	ds_read_b128 v[202:205], v165 offset:1024
	ds_read_b128 v[206:209], v165 offset:2048
	ds_read_b128 v[162:165], v165 offset:3072
	s_barrier
	s_waitcnt lgkmcnt(0)
	v_mfma_f32_16x16x32_bf16 v[94:97], v[166:169], v[170:173], v[94:97]
	v_mfma_f32_16x16x32_bf16 v[90:93], v[206:209], v[170:173], v[90:93]
	v_mfma_f32_16x16x32_bf16 v[86:89], v[166:169], v[178:181], v[86:89]
	v_mfma_f32_16x16x32_bf16 v[82:85], v[206:209], v[178:181], v[82:85]
	v_mfma_f32_16x16x32_bf16 v[78:81], v[166:169], v[186:189], v[78:81]
	v_mfma_f32_16x16x32_bf16 v[74:77], v[206:209], v[186:189], v[74:77]
	v_mfma_f32_16x16x32_bf16 v[70:73], v[166:169], v[194:197], v[70:73]
	v_mfma_f32_16x16x32_bf16 v[66:69], v[206:209], v[194:197], v[66:69]
	v_mfma_f32_16x16x32_bf16 v[94:97], v[202:205], v[174:177], v[94:97]
	v_mfma_f32_16x16x32_bf16 v[90:93], v[162:165], v[174:177], v[90:93]
	v_mfma_f32_16x16x32_bf16 v[86:89], v[202:205], v[182:185], v[86:89]
	v_mfma_f32_16x16x32_bf16 v[82:85], v[162:165], v[182:185], v[82:85]
	v_mfma_f32_16x16x32_bf16 v[78:81], v[202:205], v[190:193], v[78:81]
	v_mfma_f32_16x16x32_bf16 v[74:77], v[162:165], v[190:193], v[74:77]
	v_mfma_f32_16x16x32_bf16 v[70:73], v[202:205], v[198:201], v[70:73]
	v_mfma_f32_16x16x32_bf16 v[66:69], v[162:165], v[198:201], v[66:69]
	s_barrier
; #define LDA(dst, b, h) _Pragma("unroll") for (int m = 0; m < 4; ++m) _Pragma("unroll") for (int k = 0; k < 2; ++k) \
;     dst[m][k] = *(const bf16x8*)(lds + SA_(b, h) + lds_byte(wr * 64 + m * 16 + fr, k * 32 + fq * 8));
; #define LDB(dst, b, h) _Pragma("unroll") for (int n = 0; n < 2; ++n) _Pragma("unroll") for (int k = 0; k < 2; ++k) \
;     dst[n][k] = *(const bf16x8*)(lds + SB_(b, h) + lds_byte(wc * 32 + n * 16 + fr, k * 32 + fq * 8));
; #define MMA(ai, bj, At_, Bt_) { __builtin_amdgcn_s_setprio(1); \
;     _Pragma("unroll") for (int m = 0; m < 4; ++m) _Pragma("unroll") for (int n = 0; n < 2; ++n) _Pragma("unroll") for (int k = 0; k < 2; ++k) \
;       acc[ai][bj][m][n] = MFMA16(Bt_[n][k], At_[m][k], acc[ai][bj][m][n]); \
;     __builtin_amdgcn_s_setprio(0); }
; #define WAIT_V(n) asm volatile("s_waitcnt vmcnt(" #n ")" ::: "memory");
; #define WAIT_L(n) asm volatile("s_waitcnt lgkmcnt(" #n ")" ::: "memory");
; #define BAR __builtin_amdgcn_s_barrier();
; DI void gemm256(const u16* __restrict__ A, int lda, const u16* __restrict__ B0, const u16* __restrict__ B1, int ldb, int nt, acc_t& acc, char* lds) {
;     ...
;     LDA(At, 0, 1) WAIT_V(4) BAR WAIT_L(0) MMA(1, 0, At, Bq0) MMA(1, 1, At, Bq1) BAR }
;   { LDB(Bq0, 1, 0) LDA(At, 1, 0) WAIT_V(2) BAR WAIT_L(0) MMA(0, 0, At, Bq0) BAR
	ds_read_b128 v[170:173], v148 offset:16384
	ds_read_b128 v[174:177], v148 offset:17408
	ds_read_b128 v[178:181], v147 offset:16384
	ds_read_b128 v[182:185], v147 offset:17408
	ds_read_b128 v[186:189], v146 offset:16384
	ds_read_b128 v[190:193], v146 offset:17408
	ds_read_b128 v[194:197], v141 offset:16384
	ds_read_b128 v[198:201], v141 offset:17408
	s_waitcnt vmcnt(4)
	s_barrier
	s_waitcnt lgkmcnt(0)
	v_mfma_f32_16x16x32_bf16 v[60:63], v[132:135], v[170:173], v[60:63]
	v_mfma_f32_16x16x32_bf16 v[52:55], v[132:135], v[178:181], v[52:55]
	v_mfma_f32_16x16x32_bf16 v[44:47], v[132:135], v[186:189], v[44:47]
	v_mfma_f32_16x16x32_bf16 v[36:39], v[132:135], v[194:197], v[36:39]
	v_mfma_f32_16x16x32_bf16 v[32:35], v[152:155], v[194:197], v[32:35]
	v_mfma_f32_16x16x32_bf16 v[60:63], v[136:139], v[174:177], v[60:63]
	v_mfma_f32_16x16x32_bf16 v[56:59], v[152:155], v[170:173], v[56:59]
	v_mfma_f32_16x16x32_bf16 v[210:213], v[136:139], v[182:185], v[52:55]
	v_mfma_f32_16x16x32_bf16 v[48:51], v[152:155], v[178:181], v[48:51]
	v_mfma_f32_16x16x32_bf16 v[230:233], v[136:139], v[190:193], v[44:47]
	v_mfma_f32_16x16x32_bf16 v[40:43], v[152:155], v[186:189], v[40:43]
	v_mfma_f32_16x16x32_bf16 v[130:133], v[136:139], v[198:201], v[36:39]
	v_mfma_f32_16x16x32_bf16 v[134:137], v[158:161], v[198:201], v[32:35]
	v_mfma_f32_16x16x32_bf16 v[56:59], v[158:161], v[174:177], v[56:59]
	v_mfma_f32_16x16x32_bf16 v[226:229], v[158:161], v[182:185], v[48:51]
	v_mfma_f32_16x16x32_bf16 v[234:237], v[158:161], v[190:193], v[40:43]
	v_mfma_f32_16x16x32_bf16 v[28:31], v[166:169], v[170:173], v[28:31]
	v_mfma_f32_16x16x32_bf16 v[24:27], v[206:209], v[170:173], v[24:27]
	v_mfma_f32_16x16x32_bf16 v[20:23], v[166:169], v[178:181], v[20:23]
	v_mfma_f32_16x16x32_bf16 v[16:19], v[206:209], v[178:181], v[16:19]
	v_mfma_f32_16x16x32_bf16 v[12:15], v[166:169], v[186:189], v[12:15]
	v_mfma_f32_16x16x32_bf16 v[8:11], v[206:209], v[186:189], v[8:11]
	v_mfma_f32_16x16x32_bf16 v[4:7], v[166:169], v[194:197], v[4:7]
	v_mfma_f32_16x16x32_bf16 v[0:3], v[206:209], v[194:197], v[0:3]
	v_mfma_f32_16x16x32_bf16 v[152:155], v[202:205], v[174:177], v[28:31]
	v_mfma_f32_16x16x32_bf16 v[158:161], v[162:165], v[174:177], v[24:27]
	v_mfma_f32_16x16x32_bf16 v[170:173], v[202:205], v[182:185], v[20:23]
	v_mfma_f32_16x16x32_bf16 v[174:177], v[162:165], v[182:185], v[16:19]
	v_mfma_f32_16x16x32_bf16 v[178:181], v[202:205], v[190:193], v[12:15]
	v_mfma_f32_16x16x32_bf16 v[182:185], v[162:165], v[190:193], v[8:11]
	v_mfma_f32_16x16x32_bf16 v[166:169], v[202:205], v[198:201], v[4:7]
	v_mfma_f32_16x16x32_bf16 v[162:165], v[162:165], v[198:201], v[0:3]
	s_barrier
	ds_read_b128 v[186:189], v156
	ds_read_b128 v[190:193], v156 offset:1024
	ds_read_b128 v[194:197], v156 offset:2048
	ds_read_b128 v[198:201], v156 offset:3072
	ds_read_b128 v[32:35], v148 offset:32768
	ds_read_b128 v[36:39], v148 offset:33792
	ds_read_b128 v[44:47], v147 offset:32768
	ds_read_b128 v[202:205], v147 offset:33792
	ds_read_b128 v[206:209], v146 offset:32768
	ds_read_b128 v[238:241], v146 offset:33792
	ds_read_b128 v[242:245], v141 offset:32768
	ds_read_b128 v[246:249], v141 offset:33792
	s_waitcnt vmcnt(2)
	s_barrier
	s_waitcnt lgkmcnt(0)
	v_mfma_f32_16x16x32_bf16 v[0:3], v[186:189], v[32:35], v[126:129]
	v_mfma_f32_16x16x32_bf16 v[28:31], v[190:193], v[36:39], v[0:3]
	v_mfma_f32_16x16x32_bf16 v[0:3], v[194:197], v[32:35], v[122:125]
	v_mfma_f32_16x16x32_bf16 v[24:27], v[198:201], v[36:39], v[0:3]
	v_mfma_f32_16x16x32_bf16 v[0:3], v[186:189], v[44:47], v[118:121]
	v_mfma_f32_16x16x32_bf16 v[16:19], v[190:193], v[202:205], v[0:3]
	v_mfma_f32_16x16x32_bf16 v[0:3], v[194:197], v[44:47], v[114:117]
	v_mfma_f32_16x16x32_bf16 v[20:23], v[198:201], v[202:205], v[0:3]
	v_mfma_f32_16x16x32_bf16 v[0:3], v[186:189], v[206:209], v[110:113]
	v_mfma_f32_16x16x32_bf16 v[8:11], v[190:193], v[238:241], v[0:3]
	v_mfma_f32_16x16x32_bf16 v[0:3], v[194:197], v[206:209], v[106:109]
	v_mfma_f32_16x16x32_bf16 v[12:15], v[198:201], v[238:241], v[0:3]
	v_mfma_f32_16x16x32_bf16 v[0:3], v[186:189], v[242:245], v[102:105]
	v_mfma_f32_16x16x32_bf16 v[4:7], v[194:197], v[242:245], v[98:101]
	v_mfma_f32_16x16x32_bf16 v[0:3], v[190:193], v[246:249], v[0:3]
	v_mfma_f32_16x16x32_bf16 v[4:7], v[198:201], v[246:249], v[4:7]
	s_barrier
; #define LDA(dst, b, h) _Pragma("unroll") for (int m = 0; m < 4; ++m) _Pragma("unroll") for (int k = 0; k < 2; ++k) \
;     dst[m][k] = *(const bf16x8*)(lds + SA_(b, h) + lds_byte(wr * 64 + m * 16 + fr, k * 32 + fq * 8));
; #define LDB(dst, b, h) _Pragma("unroll") for (int n = 0; n < 2; ++n) _Pragma("unroll") for (int k = 0; k < 2; ++k) \
;     dst[n][k] = *(const bf16x8*)(lds + SB_(b, h) + lds_byte(wc * 32 + n * 16 + fr, k * 32 + fq * 8));
; #define MMA(ai, bj, At_, Bt_) { __builtin_amdgcn_s_setprio(1); \
;     _Pragma("unroll") for (int m = 0; m < 4; ++m) _Pragma("unroll") for (int n = 0; n < 2; ++n) _Pragma("unroll") for (int k = 0; k < 2; ++k) \
;       acc[ai][bj][m][n] = MFMA16(Bt_[n][k], At_[m][k], acc[ai][bj][m][n]); \
;     __builtin_amdgcn_s_setprio(0); }
; #define WAIT_V(n) asm volatile("s_waitcnt vmcnt(" #n ")" ::: "memory");
; #define WAIT_L(n) asm volatile("s_waitcnt lgkmcnt(" #n ")" ::: "memory");
; #define BAR __builtin_amdgcn_s_barrier();
; DI void gemm256(const u16* __restrict__ A, int lda, const u16* __restrict__ B0, const u16* __restrict__ B1, int ldb, int nt, acc_t& acc, char* lds) {
;     ...
;   { LDB(Bq0, 1, 0) LDA(At, 1, 0) WAIT_V(2) BAR WAIT_L(0) MMA(0, 0, At, Bq0) BAR
;     LDB(Bq1, 1, 1) WAIT_V(0) BAR WAIT_L(0) MMA(0, 1, At, Bq1) BAR
;     LDA(At, 1, 1) BAR WAIT_L(0) MMA(1, 0, At, Bq0) MMA(1, 1, At, Bq1) BAR }
;   if (wr == 0) BAR
;   __syncthreads();
	ds_read_b128 v[106:109], v151
	ds_read_b128 v[110:113], v151 offset:1024
	ds_read_b128 v[142:145], v151 offset:2048
	ds_read_b128 v[216:219], v151 offset:3072
	s_waitcnt vmcnt(0)
	s_barrier
	s_waitcnt lgkmcnt(0)
	v_mfma_f32_16x16x32_bf16 v[40:43], v[106:109], v[32:35], v[94:97]
	v_mfma_f32_16x16x32_bf16 v[32:35], v[142:145], v[32:35], v[90:93]
	v_mfma_f32_16x16x32_bf16 v[52:55], v[216:219], v[36:39], v[32:35]
	v_mfma_f32_16x16x32_bf16 v[32:35], v[106:109], v[44:47], v[86:89]
	v_mfma_f32_16x16x32_bf16 v[48:51], v[110:113], v[36:39], v[40:43]
	v_mfma_f32_16x16x32_bf16 v[40:43], v[110:113], v[202:205], v[32:35]
	v_mfma_f32_16x16x32_bf16 v[32:35], v[142:145], v[44:47], v[82:85]
	v_mfma_f32_16x16x32_bf16 v[44:47], v[216:219], v[202:205], v[32:35]
	v_mfma_f32_16x16x32_bf16 v[32:35], v[106:109], v[206:209], v[78:81]
	v_mfma_f32_16x16x32_bf16 v[36:39], v[110:113], v[238:241], v[32:35]
	v_mfma_f32_16x16x32_bf16 v[32:35], v[142:145], v[206:209], v[74:77]
	v_mfma_f32_16x16x32_bf16 v[78:81], v[216:219], v[238:241], v[32:35]
	v_mfma_f32_16x16x32_bf16 v[32:35], v[106:109], v[242:245], v[70:73]
	v_mfma_f32_16x16x32_bf16 v[66:69], v[142:145], v[242:245], v[66:69]
	v_mfma_f32_16x16x32_bf16 v[32:35], v[110:113], v[246:249], v[32:35]
	v_mfma_f32_16x16x32_bf16 v[66:69], v[216:219], v[246:249], v[66:69]
	s_barrier
	ds_read_b128 v[114:117], v148 offset:49152
	ds_read_b128 v[118:121], v148 offset:50176
	ds_read_b128 v[126:129], v147 offset:49152
	ds_read_b128 v[148:151], v147 offset:50176
	ds_read_b128 v[202:205], v146 offset:49152
	ds_read_b128 v[206:209], v146 offset:50176
	ds_read_b128 v[238:241], v141 offset:49152
	ds_read_b128 v[242:245], v141 offset:50176
	s_barrier
	s_waitcnt lgkmcnt(0)
	v_mfma_f32_16x16x32_bf16 v[56:59], v[194:197], v[114:117], v[56:59]
	v_mfma_f32_16x16x32_bf16 v[102:105], v[198:201], v[118:121], v[56:59]
	v_mfma_f32_16x16x32_bf16 v[56:59], v[186:189], v[126:129], v[210:213]
	v_mfma_f32_16x16x32_bf16 v[90:93], v[190:193], v[148:151], v[56:59]
	v_mfma_f32_16x16x32_bf16 v[56:59], v[194:197], v[126:129], v[226:229]
	v_mfma_f32_16x16x32_bf16 v[94:97], v[198:201], v[148:151], v[56:59]
	v_mfma_f32_16x16x32_bf16 v[56:59], v[186:189], v[202:205], v[230:233]
	v_mfma_f32_16x16x32_bf16 v[82:85], v[190:193], v[206:209], v[56:59]
	v_mfma_f32_16x16x32_bf16 v[56:59], v[194:197], v[202:205], v[234:237]
	v_mfma_f32_16x16x32_bf16 v[86:89], v[198:201], v[206:209], v[56:59]
	v_mfma_f32_16x16x32_bf16 v[56:59], v[186:189], v[238:241], v[130:133]
	v_mfma_f32_16x16x32_bf16 v[60:63], v[186:189], v[114:117], v[60:63]
	v_mfma_f32_16x16x32_bf16 v[70:73], v[190:193], v[242:245], v[56:59]
	v_mfma_f32_16x16x32_bf16 v[56:59], v[194:197], v[238:241], v[134:137]
	v_mfma_f32_16x16x32_bf16 v[98:101], v[190:193], v[118:121], v[60:63]
	v_mfma_f32_16x16x32_bf16 v[74:77], v[198:201], v[242:245], v[56:59]
	v_mfma_f32_16x16x32_bf16 v[56:59], v[106:109], v[114:117], v[152:155]
	v_mfma_f32_16x16x32_bf16 v[130:133], v[110:113], v[118:121], v[56:59]
	v_mfma_f32_16x16x32_bf16 v[56:59], v[142:145], v[114:117], v[158:161]
	v_mfma_f32_16x16x32_bf16 v[134:137], v[216:219], v[118:121], v[56:59]
	v_mfma_f32_16x16x32_bf16 v[56:59], v[106:109], v[126:129], v[170:173]
	v_mfma_f32_16x16x32_bf16 v[122:125], v[110:113], v[148:151], v[56:59]
	v_mfma_f32_16x16x32_bf16 v[56:59], v[142:145], v[126:129], v[174:177]
	v_mfma_f32_16x16x32_bf16 v[126:129], v[216:219], v[148:151], v[56:59]
	v_mfma_f32_16x16x32_bf16 v[56:59], v[106:109], v[202:205], v[178:181]
	v_mfma_f32_16x16x32_bf16 v[114:117], v[110:113], v[206:209], v[56:59]
	v_mfma_f32_16x16x32_bf16 v[56:59], v[142:145], v[202:205], v[182:185]
	v_mfma_f32_16x16x32_bf16 v[118:121], v[216:219], v[206:209], v[56:59]
	v_mfma_f32_16x16x32_bf16 v[56:59], v[106:109], v[238:241], v[166:169]
	v_mfma_f32_16x16x32_bf16 v[106:109], v[110:113], v[242:245], v[56:59]
	v_mfma_f32_16x16x32_bf16 v[56:59], v[142:145], v[238:241], v[162:165]
	v_mfma_f32_16x16x32_bf16 v[110:113], v[216:219], v[242:245], v[56:59]
	s_movk_i32 s2, 0x100
	v_cmp_gt_u32_e32 vcc, s2, v140
	s_barrier
	s_and_saveexec_b64 s[8:9], vcc
	s_mov_b32 s69, 0x800000
	s_mov_b32 s75, 0x3f317217
	s_mov_b32 s92, 0x7f800000
	s_cbranch_execz .LBB0_567
	s_barrier

; #define STAGE_A(b, h, kt) { const u16* ap_ = A + (size_t)((h) * ahalf + (unsigned)(kt) * 64u); glds16(ap_ + ao0, l0 + SA_(b, h)); glds16(ap_ + ao1, l0 + SA_(b, h) + 8192); }
; #define STAGE_B(b, h, kt) { const u16* bp_ = ((h) ? B1 : B0) + (unsigned)(kt) * 64u; glds16(bp_ + bo0, l0 + SB_(b, h)); glds16(bp_ + bo1, l0 + SB_(b, h) + 8192); }
; #define LDA(dst, b, h) _Pragma("unroll") for (int m = 0; m < 4; ++m) _Pragma("unroll") for (int k = 0; k < 2; ++k) \
;     dst[m][k] = *(const bf16x8*)(lds + SA_(b, h) + lds_byte(wr * 64 + m * 16 + fr, k * 32 + fq * 8));
; #define LDB(dst, b, h) _Pragma("unroll") for (int n = 0; n < 2; ++n) _Pragma("unroll") for (int k = 0; k < 2; ++k) \
;     dst[n][k] = *(const bf16x8*)(lds + SB_(b, h) + lds_byte(wc * 32 + n * 16 + fr, k * 32 + fq * 8));
; #define MMA(ai, bj, At_, Bt_) { __builtin_amdgcn_s_setprio(1); \
;     _Pragma("unroll") for (int m = 0; m < 4; ++m) _Pragma("unroll") for (int n = 0; n < 2; ++n) _Pragma("unroll") for (int k = 0; k < 2; ++k) \
;       acc[ai][bj][m][n] = MFMA16(Bt_[n][k], At_[m][k], acc[ai][bj][m][n]); \
;     __builtin_amdgcn_s_setprio(0); }
; #define WAIT_L(n) asm volatile("s_waitcnt lgkmcnt(" #n ")" ::: "memory");
; #define BAR __builtin_amdgcn_s_barrier();
; #define SCHED __builtin_amdgcn_sched_barrier(0);
; DI void gemm256(const u16* __restrict__ A, int lda, const u16* __restrict__ B0, const u16* __restrict__ B1, int ldb, int nt, acc_t& acc, char* lds) {
;     ...
;   for (int t = 0; t < nt - 2; t += 2) {
;     LDB(Bq0, 0, 0) SCHED LDA(At, 0, 0) STAGE_A(1, 1, t + 1)
;     WAIT_L(8) BAR WAIT_L(0) MMA(0, 0, At, Bq0) BAR SCHED
;     LDB(Bq1, 0, 1) STAGE_B(0, 0, t + 2)
;     BAR WAIT_L(0) MMA(0, 1, At, Bq1) BAR
;     LDA(At, 0, 1) STAGE_A(0, 0, t + 2)
;     BAR WAIT_L(0) MMA(1, 0, At, Bq0) BAR SCHED
.LBB0_973:
	ds_read_b128 v[142:145], v166
	ds_read_b128 v[170:173], v166 offset:1024
	ds_read_b128 v[174:177], v166 offset:2048
	ds_read_b128 v[178:181], v166 offset:3072
	v_lshl_add_u64 v[222:223], s[22:23], 0, v[136:137]
	v_readfirstlane_b32 s19, v167
	v_lshl_add_u64 v[168:169], v[222:223], 0, s[0:1]
	s_mov_b32 m0, s19
	ds_read_b128 v[182:185], v148
	ds_read_b128 v[190:193], v147
	ds_read_b128 v[198:201], v146
	ds_read_b128 v[206:209], v141
	global_load_lds_dwordx4 v[168:169], off
	v_add_u32_e32 v168, 0xe000, v149
	v_lshl_add_u64 v[224:225], s[22:23], 0, v[138:139]
	v_readfirstlane_b32 s19, v168
	v_lshl_add_u64 v[216:217], v[224:225], 0, s[0:1]
	s_mov_b32 m0, s19
	s_nop 0
	global_load_lds_dwordx4 v[216:217], off
	s_waitcnt lgkmcnt(4)
	s_barrier
	s_waitcnt lgkmcnt(0)
	ds_read_b128 v[186:189], v148 offset:1024
	ds_read_b128 v[194:197], v147 offset:1024
	ds_read_b128 v[202:205], v146 offset:1024
	ds_read_b128 v[210:213], v141 offset:1024
	v_mfma_f32_16x16x32_bf16 v[126:129], v[142:145], v[182:185], v[126:129]
	v_mfma_f32_16x16x32_bf16 v[122:125], v[174:177], v[182:185], v[122:125]
	v_mfma_f32_16x16x32_bf16 v[118:121], v[142:145], v[190:193], v[118:121]
	v_mfma_f32_16x16x32_bf16 v[114:117], v[174:177], v[190:193], v[114:117]
	v_mfma_f32_16x16x32_bf16 v[110:113], v[142:145], v[198:201], v[110:113]
	v_mfma_f32_16x16x32_bf16 v[106:109], v[174:177], v[198:201], v[106:109]
	v_mfma_f32_16x16x32_bf16 v[102:105], v[142:145], v[206:209], v[102:105]
	v_mfma_f32_16x16x32_bf16 v[98:101], v[174:177], v[206:209], v[98:101]
	s_waitcnt lgkmcnt(0)
	v_mfma_f32_16x16x32_bf16 v[126:129], v[170:173], v[186:189], v[126:129]
	v_mfma_f32_16x16x32_bf16 v[122:125], v[178:181], v[186:189], v[122:125]
	v_mfma_f32_16x16x32_bf16 v[118:121], v[170:173], v[194:197], v[118:121]
	v_mfma_f32_16x16x32_bf16 v[114:117], v[178:181], v[194:197], v[114:117]
	v_mfma_f32_16x16x32_bf16 v[110:113], v[170:173], v[202:205], v[110:113]
	v_mfma_f32_16x16x32_bf16 v[106:109], v[178:181], v[202:205], v[106:109]
	v_mfma_f32_16x16x32_bf16 v[102:105], v[170:173], v[210:213], v[102:105]
	v_mfma_f32_16x16x32_bf16 v[98:101], v[178:181], v[210:213], v[98:101]
	s_barrier
	v_lshl_add_u64 v[238:239], s[22:23], 0, v[132:133]
	v_readfirstlane_b32 s19, v150
	v_lshl_add_u64 v[240:241], v[238:239], 0, s[28:29]
	s_mov_b32 m0, s19
	ds_read_b128 v[216:219], v165
	ds_read_b128 v[226:229], v165 offset:1024
	ds_read_b128 v[230:233], v165 offset:2048
	ds_read_b128 v[234:237], v165 offset:3072
	global_load_lds_dwordx4 v[240:241], off
	v_lshl_add_u64 v[240:241], s[22:23], 0, v[134:135]
	v_readfirstlane_b32 s19, v151
	v_lshl_add_u64 v[242:243], v[240:241], 0, s[28:29]
	s_mov_b32 m0, s19
	s_nop 0
	global_load_lds_dwordx4 v[242:243], off
	s_barrier
	s_waitcnt lgkmcnt(0)
	v_mfma_f32_16x16x32_bf16 v[94:97], v[216:219], v[182:185], v[94:97]
	v_mfma_f32_16x16x32_bf16 v[90:93], v[230:233], v[182:185], v[90:93]
	v_mfma_f32_16x16x32_bf16 v[86:89], v[216:219], v[190:193], v[86:89]
	v_mfma_f32_16x16x32_bf16 v[82:85], v[230:233], v[190:193], v[82:85]
	v_mfma_f32_16x16x32_bf16 v[78:81], v[216:219], v[198:201], v[78:81]
	v_mfma_f32_16x16x32_bf16 v[74:77], v[230:233], v[198:201], v[74:77]
	v_mfma_f32_16x16x32_bf16 v[70:73], v[216:219], v[206:209], v[70:73]
	v_mfma_f32_16x16x32_bf16 v[66:69], v[230:233], v[206:209], v[66:69]
	v_mfma_f32_16x16x32_bf16 v[94:97], v[226:229], v[186:189], v[94:97]
	v_mfma_f32_16x16x32_bf16 v[90:93], v[234:237], v[186:189], v[90:93]
	v_mfma_f32_16x16x32_bf16 v[86:89], v[226:229], v[194:197], v[86:89]
	v_mfma_f32_16x16x32_bf16 v[82:85], v[234:237], v[194:197], v[82:85]
	v_mfma_f32_16x16x32_bf16 v[78:81], v[226:229], v[202:205], v[78:81]
	v_mfma_f32_16x16x32_bf16 v[74:77], v[234:237], v[202:205], v[74:77]
	v_mfma_f32_16x16x32_bf16 v[70:73], v[226:229], v[210:213], v[70:73]
	v_mfma_f32_16x16x32_bf16 v[66:69], v[234:237], v[210:213], v[66:69]
	v_readfirstlane_b32 s19, v149
	v_lshl_add_u64 v[242:243], v[222:223], 0, s[20:21]
	s_mov_b32 m0, s19
	v_readfirstlane_b32 s19, v153
	s_barrier
	ds_read_b128 v[182:185], v148 offset:16384
	ds_read_b128 v[190:193], v147 offset:16384
	ds_read_b128 v[198:201], v146 offset:16384
	ds_read_b128 v[206:209], v141 offset:16384
	global_load_lds_dwordx4 v[242:243], off
	v_lshl_add_u64 v[242:243], v[224:225], 0, s[20:21]
	s_mov_b32 m0, s19
	s_nop 0
	global_load_lds_dwordx4 v[242:243], off
	s_barrier
	s_waitcnt lgkmcnt(0)
	ds_read_b128 v[186:189], v148 offset:17408
	ds_read_b128 v[194:197], v147 offset:17408
	ds_read_b128 v[202:205], v146 offset:17408
	ds_read_b128 v[210:213], v141 offset:17408
	v_mfma_f32_16x16x32_bf16 v[60:63], v[142:145], v[182:185], v[60:63]
	v_mfma_f32_16x16x32_bf16 v[56:59], v[174:177], v[182:185], v[56:59]
	v_mfma_f32_16x16x32_bf16 v[52:55], v[142:145], v[190:193], v[52:55]
	v_mfma_f32_16x16x32_bf16 v[48:51], v[174:177], v[190:193], v[48:51]
	v_mfma_f32_16x16x32_bf16 v[44:47], v[142:145], v[198:201], v[44:47]
	v_mfma_f32_16x16x32_bf16 v[40:43], v[174:177], v[198:201], v[40:43]
	v_mfma_f32_16x16x32_bf16 v[36:39], v[142:145], v[206:209], v[36:39]
	v_mfma_f32_16x16x32_bf16 v[32:35], v[174:177], v[206:209], v[32:35]
	s_waitcnt lgkmcnt(0)
	v_mfma_f32_16x16x32_bf16 v[60:63], v[170:173], v[186:189], v[60:63]
	v_mfma_f32_16x16x32_bf16 v[56:59], v[178:181], v[186:189], v[56:59]
	v_mfma_f32_16x16x32_bf16 v[52:55], v[170:173], v[194:197], v[52:55]
	v_mfma_f32_16x16x32_bf16 v[48:51], v[178:181], v[194:197], v[48:51]
	v_mfma_f32_16x16x32_bf16 v[44:47], v[170:173], v[202:205], v[44:47]
	v_mfma_f32_16x16x32_bf16 v[40:43], v[178:181], v[202:205], v[40:43]
	v_mfma_f32_16x16x32_bf16 v[36:39], v[170:173], v[210:213], v[36:39]
	v_mfma_f32_16x16x32_bf16 v[32:35], v[178:181], v[210:213], v[32:35]
	s_barrier
; #define STAGE_A(b, h, kt) { const u16* ap_ = A + (size_t)((h) * ahalf + (unsigned)(kt) * 64u); glds16(ap_ + ao0, l0 + SA_(b, h)); glds16(ap_ + ao1, l0 + SA_(b, h) + 8192); }
; #define STAGE_B(b, h, kt) { const u16* bp_ = ((h) ? B1 : B0) + (unsigned)(kt) * 64u; glds16(bp_ + bo0, l0 + SB_(b, h)); glds16(bp_ + bo1, l0 + SB_(b, h) + 8192); }
; #define LDA(dst, b, h) _Pragma("unroll") for (int m = 0; m < 4; ++m) _Pragma("unroll") for (int k = 0; k < 2; ++k) \
;     dst[m][k] = *(const bf16x8*)(lds + SA_(b, h) + lds_byte(wr * 64 + m * 16 + fr, k * 32 + fq * 8));
; #define LDB(dst, b, h) _Pragma("unroll") for (int n = 0; n < 2; ++n) _Pragma("unroll") for (int k = 0; k < 2; ++k) \
;     dst[n][k] = *(const bf16x8*)(lds + SB_(b, h) + lds_byte(wc * 32 + n * 16 + fr, k * 32 + fq * 8));
; #define MMA(ai, bj, At_, Bt_) { __builtin_amdgcn_s_setprio(1); \
;     _Pragma("unroll") for (int m = 0; m < 4; ++m) _Pragma("unroll") for (int n = 0; n < 2; ++n) _Pragma("unroll") for (int k = 0; k < 2; ++k) \
;       acc[ai][bj][m][n] = MFMA16(Bt_[n][k], At_[m][k], acc[ai][bj][m][n]); \
;     __builtin_amdgcn_s_setprio(0); }
; #define WAIT_V(n) asm volatile("s_waitcnt vmcnt(" #n ")" ::: "memory");
; #define WAIT_L(n) asm volatile("s_waitcnt lgkmcnt(" #n ")" ::: "memory");
; #define BAR __builtin_amdgcn_s_barrier();
; #define SCHED __builtin_amdgcn_sched_barrier(0);
; DI void gemm256(const u16* __restrict__ A, int lda, const u16* __restrict__ B0, const u16* __restrict__ B1, int ldb, int nt, acc_t& acc, char* lds) {
;     ...
;     STAGE_B(0, 1, t + 2)
;     WAIT_V(6) BAR MMA(1, 1, At, Bq1) BAR
;     LDB(Bq0, 1, 0) SCHED LDA(At, 1, 0) STAGE_A(0, 1, t + 2)
;     WAIT_L(8) BAR WAIT_L(0) MMA(0, 0, At, Bq0) BAR SCHED
;     LDB(Bq1, 1, 1) STAGE_B(1, 0, t + 3)
;     BAR WAIT_L(0) MMA(0, 1, At, Bq1) BAR
;     LDA(At, 1, 1) STAGE_A(1, 0, t + 3)
	v_readfirstlane_b32 s19, v154
	v_lshl_add_u64 v[142:143], v[238:239], 0, s[44:45]
	s_mov_b32 m0, s19
	v_readfirstlane_b32 s19, v155
	global_load_lds_dwordx4 v[142:143], off
	v_lshl_add_u64 v[142:143], v[240:241], 0, s[44:45]
	s_mov_b32 m0, s19
	s_nop 0
	global_load_lds_dwordx4 v[142:143], off
	s_waitcnt vmcnt(6)
	s_barrier
	v_mfma_f32_16x16x32_bf16 v[28:31], v[216:219], v[182:185], v[28:31]
	v_mfma_f32_16x16x32_bf16 v[24:27], v[230:233], v[182:185], v[24:27]
	v_mfma_f32_16x16x32_bf16 v[20:23], v[216:219], v[190:193], v[20:23]
	v_mfma_f32_16x16x32_bf16 v[16:19], v[230:233], v[190:193], v[16:19]
	v_mfma_f32_16x16x32_bf16 v[12:15], v[216:219], v[198:201], v[12:15]
	v_mfma_f32_16x16x32_bf16 v[8:11], v[230:233], v[198:201], v[8:11]
	v_mfma_f32_16x16x32_bf16 v[4:7], v[216:219], v[206:209], v[4:7]
	v_mfma_f32_16x16x32_bf16 v[0:3], v[230:233], v[206:209], v[0:3]
	v_mfma_f32_16x16x32_bf16 v[28:31], v[226:229], v[186:189], v[28:31]
	v_mfma_f32_16x16x32_bf16 v[24:27], v[234:237], v[186:189], v[24:27]
	v_mfma_f32_16x16x32_bf16 v[20:23], v[226:229], v[194:197], v[20:23]
	v_mfma_f32_16x16x32_bf16 v[16:19], v[234:237], v[194:197], v[16:19]
	v_mfma_f32_16x16x32_bf16 v[12:15], v[226:229], v[202:205], v[12:15]
	v_mfma_f32_16x16x32_bf16 v[8:11], v[234:237], v[202:205], v[8:11]
	v_mfma_f32_16x16x32_bf16 v[4:7], v[226:229], v[210:213], v[4:7]
	v_mfma_f32_16x16x32_bf16 v[0:3], v[234:237], v[210:213], v[0:3]
	s_barrier
	ds_read_b128 v[142:145], v156
	ds_read_b128 v[170:173], v156 offset:1024
	ds_read_b128 v[174:177], v156 offset:2048
	ds_read_b128 v[178:181], v156 offset:3072
	v_readfirstlane_b32 s19, v157
	v_lshl_add_u64 v[216:217], v[222:223], 0, s[24:25]
	s_mov_b32 m0, s19
	v_readfirstlane_b32 s19, v158
	ds_read_b128 v[182:185], v148 offset:32768
	ds_read_b128 v[190:193], v147 offset:32768
	ds_read_b128 v[198:201], v146 offset:32768
	ds_read_b128 v[206:209], v141 offset:32768
	global_load_lds_dwordx4 v[216:217], off
	v_lshl_add_u64 v[216:217], v[224:225], 0, s[24:25]
	s_mov_b32 m0, s19
	s_nop 0
	global_load_lds_dwordx4 v[216:217], off
	s_waitcnt lgkmcnt(4)
	s_barrier
	s_waitcnt lgkmcnt(0)
	ds_read_b128 v[186:189], v148 offset:33792
	ds_read_b128 v[194:197], v147 offset:33792
	ds_read_b128 v[202:205], v146 offset:33792
	ds_read_b128 v[210:213], v141 offset:33792
	v_mfma_f32_16x16x32_bf16 v[126:129], v[142:145], v[182:185], v[126:129]
	v_mfma_f32_16x16x32_bf16 v[122:125], v[174:177], v[182:185], v[122:125]
	v_mfma_f32_16x16x32_bf16 v[118:121], v[142:145], v[190:193], v[118:121]
	v_mfma_f32_16x16x32_bf16 v[114:117], v[174:177], v[190:193], v[114:117]
	v_mfma_f32_16x16x32_bf16 v[110:113], v[142:145], v[198:201], v[110:113]
	v_mfma_f32_16x16x32_bf16 v[106:109], v[174:177], v[198:201], v[106:109]
	v_mfma_f32_16x16x32_bf16 v[102:105], v[142:145], v[206:209], v[102:105]
	v_mfma_f32_16x16x32_bf16 v[98:101], v[174:177], v[206:209], v[98:101]
	s_waitcnt lgkmcnt(0)
	v_mfma_f32_16x16x32_bf16 v[126:129], v[170:173], v[186:189], v[126:129]
	v_mfma_f32_16x16x32_bf16 v[122:125], v[178:181], v[186:189], v[122:125]
	v_mfma_f32_16x16x32_bf16 v[118:121], v[170:173], v[194:197], v[118:121]
	v_mfma_f32_16x16x32_bf16 v[114:117], v[178:181], v[194:197], v[114:117]
	v_mfma_f32_16x16x32_bf16 v[110:113], v[170:173], v[202:205], v[110:113]
	v_mfma_f32_16x16x32_bf16 v[106:109], v[178:181], v[202:205], v[106:109]
	v_mfma_f32_16x16x32_bf16 v[102:105], v[170:173], v[210:213], v[102:105]
	v_mfma_f32_16x16x32_bf16 v[98:101], v[178:181], v[210:213], v[98:101]
	s_barrier
	v_readfirstlane_b32 s19, v159
	v_lshl_add_u64 v[242:243], v[238:239], 0, s[48:49]
	s_mov_b32 m0, s19
	v_readfirstlane_b32 s19, v160
	ds_read_b128 v[216:219], v152
	ds_read_b128 v[226:229], v152 offset:1024
	ds_read_b128 v[230:233], v152 offset:2048
	ds_read_b128 v[234:237], v152 offset:3072
	global_load_lds_dwordx4 v[242:243], off
	v_lshl_add_u64 v[242:243], v[240:241], 0, s[48:49]
	s_mov_b32 m0, s19
	s_nop 0
	global_load_lds_dwordx4 v[242:243], off
	s_barrier
	s_waitcnt lgkmcnt(0)
	v_mfma_f32_16x16x32_bf16 v[94:97], v[216:219], v[182:185], v[94:97]
	v_mfma_f32_16x16x32_bf16 v[90:93], v[230:233], v[182:185], v[90:93]
	v_mfma_f32_16x16x32_bf16 v[86:89], v[216:219], v[190:193], v[86:89]
	v_mfma_f32_16x16x32_bf16 v[82:85], v[230:233], v[190:193], v[82:85]
	v_mfma_f32_16x16x32_bf16 v[78:81], v[216:219], v[198:201], v[78:81]
	v_mfma_f32_16x16x32_bf16 v[74:77], v[230:233], v[198:201], v[74:77]
	v_mfma_f32_16x16x32_bf16 v[70:73], v[216:219], v[206:209], v[70:73]
	v_mfma_f32_16x16x32_bf16 v[66:69], v[230:233], v[206:209], v[66:69]
	v_mfma_f32_16x16x32_bf16 v[94:97], v[226:229], v[186:189], v[94:97]
	v_mfma_f32_16x16x32_bf16 v[90:93], v[234:237], v[186:189], v[90:93]
	v_mfma_f32_16x16x32_bf16 v[86:89], v[226:229], v[194:197], v[86:89]
	v_mfma_f32_16x16x32_bf16 v[82:85], v[234:237], v[194:197], v[82:85]
	v_mfma_f32_16x16x32_bf16 v[78:81], v[226:229], v[202:205], v[78:81]
	v_mfma_f32_16x16x32_bf16 v[74:77], v[234:237], v[202:205], v[74:77]
	v_mfma_f32_16x16x32_bf16 v[70:73], v[226:229], v[210:213], v[70:73]
	v_mfma_f32_16x16x32_bf16 v[66:69], v[234:237], v[210:213], v[66:69]
	v_readfirstlane_b32 s19, v161
	v_lshl_add_u64 v[222:223], v[222:223], 0, s[34:35]
	s_mov_b32 m0, s19
	v_readfirstlane_b32 s19, v162
	s_barrier
	ds_read_b128 v[182:185], v148 offset:49152
	ds_read_b128 v[190:193], v147 offset:49152
	ds_read_b128 v[198:201], v146 offset:49152
	ds_read_b128 v[206:209], v141 offset:49152
	global_load_lds_dwordx4 v[222:223], off
	v_lshl_add_u64 v[222:223], v[224:225], 0, s[34:35]
	s_mov_b32 m0, s19
	s_nop 0
	global_load_lds_dwordx4 v[222:223], off
	s_barrier
; #define STAGE_A(b, h, kt) { const u16* ap_ = A + (size_t)((h) * ahalf + (unsigned)(kt) * 64u); glds16(ap_ + ao0, l0 + SA_(b, h)); glds16(ap_ + ao1, l0 + SA_(b, h) + 8192); }
; #define STAGE_B(b, h, kt) { const u16* bp_ = ((h) ? B1 : B0) + (unsigned)(kt) * 64u; glds16(bp_ + bo0, l0 + SB_(b, h)); glds16(bp_ + bo1, l0 + SB_(b, h) + 8192); }
; #define LDA(dst, b, h) _Pragma("unroll") for (int m = 0; m < 4; ++m) _Pragma("unroll") for (int k = 0; k < 2; ++k) \
;     dst[m][k] = *(const bf16x8*)(lds + SA_(b, h) + lds_byte(wr * 64 + m * 16 + fr, k * 32 + fq * 8));
; #define LDB(dst, b, h) _Pragma("unroll") for (int n = 0; n < 2; ++n) _Pragma("unroll") for (int k = 0; k < 2; ++k) \
;     dst[n][k] = *(const bf16x8*)(lds + SB_(b, h) + lds_byte(wc * 32 + n * 16 + fr, k * 32 + fq * 8));
; #define MMA(ai, bj, At_, Bt_) { __builtin_amdgcn_s_setprio(1); \
;     _Pragma("unroll") for (int m = 0; m < 4; ++m) _Pragma("unroll") for (int n = 0; n < 2; ++n) _Pragma("unroll") for (int k = 0; k < 2; ++k) \
;       acc[ai][bj][m][n] = MFMA16(Bt_[n][k], At_[m][k], acc[ai][bj][m][n]); \
;     __builtin_amdgcn_s_setprio(0); }
; #define WAIT_V(n) asm volatile("s_waitcnt vmcnt(" #n ")" ::: "memory");
; #define WAIT_L(n) asm volatile("s_waitcnt lgkmcnt(" #n ")" ::: "memory");
; #define BAR __builtin_amdgcn_s_barrier();
; #define SCHED __builtin_amdgcn_sched_barrier(0);
; DI void gemm256(const u16* __restrict__ A, int lda, const u16* __restrict__ B0, const u16* __restrict__ B1, int ldb, int nt, acc_t& acc, char* lds) {
;     ...
;     BAR WAIT_L(0) MMA(1, 0, At, Bq0) BAR SCHED
;     STAGE_B(1, 1, t + 3)
;     WAIT_V(6) BAR MMA(1, 1, At, Bq1) BAR
;   }
;   { LDB(Bq0, 0, 0) LDA(At, 0, 0) STAGE_A(1, 1, nt - 1)
;     BAR WAIT_L(0) MMA(0, 0, At, Bq0) BAR
;     LDB(Bq1, 0, 1) BAR WAIT_L(0) MMA(0, 1, At, Bq1) BAR
	s_waitcnt lgkmcnt(0)
	ds_read_b128 v[186:189], v148 offset:50176
	ds_read_b128 v[194:197], v147 offset:50176
	ds_read_b128 v[202:205], v146 offset:50176
	ds_read_b128 v[210:213], v141 offset:50176
	v_mfma_f32_16x16x32_bf16 v[60:63], v[142:145], v[182:185], v[60:63]
	v_mfma_f32_16x16x32_bf16 v[56:59], v[174:177], v[182:185], v[56:59]
	v_mfma_f32_16x16x32_bf16 v[52:55], v[142:145], v[190:193], v[52:55]
	v_mfma_f32_16x16x32_bf16 v[48:51], v[174:177], v[190:193], v[48:51]
	v_mfma_f32_16x16x32_bf16 v[44:47], v[142:145], v[198:201], v[44:47]
	v_mfma_f32_16x16x32_bf16 v[40:43], v[174:177], v[198:201], v[40:43]
	v_mfma_f32_16x16x32_bf16 v[36:39], v[142:145], v[206:209], v[36:39]
	v_mfma_f32_16x16x32_bf16 v[32:35], v[174:177], v[206:209], v[32:35]
	s_waitcnt lgkmcnt(0)
	v_mfma_f32_16x16x32_bf16 v[60:63], v[170:173], v[186:189], v[60:63]
	v_mfma_f32_16x16x32_bf16 v[56:59], v[178:181], v[186:189], v[56:59]
	v_mfma_f32_16x16x32_bf16 v[52:55], v[170:173], v[194:197], v[52:55]
	v_mfma_f32_16x16x32_bf16 v[48:51], v[178:181], v[194:197], v[48:51]
	v_mfma_f32_16x16x32_bf16 v[44:47], v[170:173], v[202:205], v[44:47]
	v_mfma_f32_16x16x32_bf16 v[40:43], v[178:181], v[202:205], v[40:43]
	v_mfma_f32_16x16x32_bf16 v[36:39], v[170:173], v[210:213], v[36:39]
	v_mfma_f32_16x16x32_bf16 v[32:35], v[178:181], v[210:213], v[32:35]
	s_barrier
	v_readfirstlane_b32 s19, v163
	v_lshl_add_u64 v[142:143], v[238:239], 0, s[54:55]
	s_mov_b32 m0, s19
	v_readfirstlane_b32 s19, v164
	global_load_lds_dwordx4 v[142:143], off
	v_lshl_add_u64 v[142:143], v[240:241], 0, s[54:55]
	s_mov_b32 m0, s19
	s_nop 0
	global_load_lds_dwordx4 v[142:143], off
	s_waitcnt vmcnt(6)
	s_barrier
	v_mfma_f32_16x16x32_bf16 v[28:31], v[216:219], v[182:185], v[28:31]
	v_mfma_f32_16x16x32_bf16 v[24:27], v[230:233], v[182:185], v[24:27]
	v_mfma_f32_16x16x32_bf16 v[20:23], v[216:219], v[190:193], v[20:23]
	v_mfma_f32_16x16x32_bf16 v[16:19], v[230:233], v[190:193], v[16:19]
	v_mfma_f32_16x16x32_bf16 v[12:15], v[216:219], v[198:201], v[12:15]
	v_mfma_f32_16x16x32_bf16 v[8:11], v[230:233], v[198:201], v[8:11]
	v_mfma_f32_16x16x32_bf16 v[4:7], v[216:219], v[206:209], v[4:7]
	v_mfma_f32_16x16x32_bf16 v[0:3], v[230:233], v[206:209], v[0:3]
	v_mfma_f32_16x16x32_bf16 v[28:31], v[226:229], v[186:189], v[28:31]
	v_mfma_f32_16x16x32_bf16 v[24:27], v[234:237], v[186:189], v[24:27]
	v_mfma_f32_16x16x32_bf16 v[20:23], v[226:229], v[194:197], v[20:23]
	v_mfma_f32_16x16x32_bf16 v[16:19], v[234:237], v[194:197], v[16:19]
	v_mfma_f32_16x16x32_bf16 v[12:15], v[226:229], v[202:205], v[12:15]
	v_mfma_f32_16x16x32_bf16 v[8:11], v[234:237], v[202:205], v[8:11]
	v_mfma_f32_16x16x32_bf16 v[4:7], v[226:229], v[210:213], v[4:7]
	v_mfma_f32_16x16x32_bf16 v[0:3], v[234:237], v[210:213], v[0:3]
	s_add_i32 s7, s7, 2
	s_add_u32 s22, s22, 0x100
	s_addc_u32 s23, s23, 0
	s_cmp_lt_u32 s7, 12
	s_barrier
	s_cbranch_scc1 .LBB0_973
	s_add_u32 s54, s50, 0x40780
	s_addc_u32 s55, s51, 0
	v_readfirstlane_b32 s7, v167
	v_lshl_add_u64 v[150:151], v[64:65], 1, s[54:55]
	s_mov_b32 m0, s7
	v_readfirstlane_b32 s7, v168
	ds_read_b128 v[132:135], v166
	ds_read_b128 v[136:139], v166 offset:1024
	ds_read_b128 v[142:145], v166 offset:2048
	ds_read_b128 v[158:161], v166 offset:3072
	ds_read_b128 v[170:173], v148
	ds_read_b128 v[174:177], v148 offset:1024
	ds_read_b128 v[178:181], v147
	ds_read_b128 v[182:185], v147 offset:1024
	ds_read_b128 v[186:189], v146
	ds_read_b128 v[190:193], v146 offset:1024
	ds_read_b128 v[194:197], v141
	ds_read_b128 v[198:201], v141 offset:1024
	global_load_lds_dwordx4 v[150:151], off
	v_lshl_add_u64 v[130:131], v[130:131], 1, s[54:55]
	s_mov_b32 m0, s7
	s_nop 0
	global_load_lds_dwordx4 v[130:131], off
	s_barrier
	s_waitcnt lgkmcnt(0)
	v_mfma_f32_16x16x32_bf16 v[126:129], v[132:135], v[170:173], v[126:129]
	v_mfma_f32_16x16x32_bf16 v[122:125], v[142:145], v[170:173], v[122:125]
	v_mfma_f32_16x16x32_bf16 v[118:121], v[132:135], v[178:181], v[118:121]
	v_mfma_f32_16x16x32_bf16 v[114:117], v[142:145], v[178:181], v[114:117]
	v_mfma_f32_16x16x32_bf16 v[102:105], v[132:135], v[194:197], v[102:105]
	v_mfma_f32_16x16x32_bf16 v[98:101], v[142:145], v[194:197], v[98:101]
	v_mfma_f32_16x16x32_bf16 v[126:129], v[136:139], v[174:177], v[126:129]
	v_mfma_f32_16x16x32_bf16 v[122:125], v[158:161], v[174:177], v[122:125]
	v_mfma_f32_16x16x32_bf16 v[118:121], v[136:139], v[182:185], v[118:121]
	v_mfma_f32_16x16x32_bf16 v[114:117], v[158:161], v[182:185], v[114:117]
	v_mfma_f32_16x16x32_bf16 v[110:113], v[132:135], v[186:189], v[110:113]
	v_mfma_f32_16x16x32_bf16 v[106:109], v[142:145], v[186:189], v[106:109]
	v_mfma_f32_16x16x32_bf16 v[102:105], v[136:139], v[198:201], v[102:105]
	v_mfma_f32_16x16x32_bf16 v[98:101], v[158:161], v[198:201], v[98:101]
	v_mfma_f32_16x16x32_bf16 v[166:169], v[136:139], v[190:193], v[110:113]
	v_mfma_f32_16x16x32_bf16 v[202:205], v[158:161], v[190:193], v[106:109]
	s_barrier
	s_nop 1
	ds_read_b128 v[106:109], v165
	ds_read_b128 v[110:113], v165 offset:1024
	ds_read_b128 v[206:209], v165 offset:2048
	ds_read_b128 v[162:165], v165 offset:3072
	s_barrier
	s_waitcnt lgkmcnt(0)
	v_mfma_f32_16x16x32_bf16 v[86:89], v[106:109], v[178:181], v[86:89]
	v_mfma_f32_16x16x32_bf16 v[82:85], v[206:209], v[178:181], v[82:85]
	v_mfma_f32_16x16x32_bf16 v[70:73], v[106:109], v[194:197], v[70:73]
	v_mfma_f32_16x16x32_bf16 v[66:69], v[206:209], v[194:197], v[66:69]
	v_mfma_f32_16x16x32_bf16 v[94:97], v[106:109], v[170:173], v[94:97]
	v_mfma_f32_16x16x32_bf16 v[90:93], v[206:209], v[170:173], v[90:93]
	v_mfma_f32_16x16x32_bf16 v[86:89], v[110:113], v[182:185], v[86:89]
	v_mfma_f32_16x16x32_bf16 v[82:85], v[162:165], v[182:185], v[82:85]
	v_mfma_f32_16x16x32_bf16 v[78:81], v[106:109], v[186:189], v[78:81]
	v_mfma_f32_16x16x32_bf16 v[74:77], v[206:209], v[186:189], v[74:77]
	v_mfma_f32_16x16x32_bf16 v[70:73], v[110:113], v[198:201], v[70:73]
	v_mfma_f32_16x16x32_bf16 v[66:69], v[162:165], v[198:201], v[66:69]
	v_mfma_f32_16x16x32_bf16 v[210:213], v[110:113], v[174:177], v[94:97]
	v_mfma_f32_16x16x32_bf16 v[170:173], v[162:165], v[174:177], v[90:93]
	v_mfma_f32_16x16x32_bf16 v[174:177], v[110:113], v[190:193], v[78:81]
	v_mfma_f32_16x16x32_bf16 v[178:181], v[162:165], v[190:193], v[74:77]
	s_barrier
; #define LDA(dst, b, h) _Pragma("unroll") for (int m = 0; m < 4; ++m) _Pragma("unroll") for (int k = 0; k < 2; ++k) \
;     dst[m][k] = *(const bf16x8*)(lds + SA_(b, h) + lds_byte(wr * 64 + m * 16 + fr, k * 32 + fq * 8));
; #define LDB(dst, b, h) _Pragma("unroll") for (int n = 0; n < 2; ++n) _Pragma("unroll") for (int k = 0; k < 2; ++k) \
;     dst[n][k] = *(const bf16x8*)(lds + SB_(b, h) + lds_byte(wc * 32 + n * 16 + fr, k * 32 + fq * 8));
; #define MMA(ai, bj, At_, Bt_) { __builtin_amdgcn_s_setprio(1); \
;     _Pragma("unroll") for (int m = 0; m < 4; ++m) _Pragma("unroll") for (int n = 0; n < 2; ++n) _Pragma("unroll") for (int k = 0; k < 2; ++k) \
;       acc[ai][bj][m][n] = MFMA16(Bt_[n][k], At_[m][k], acc[ai][bj][m][n]); \
;     __builtin_amdgcn_s_setprio(0); }
; #define WAIT_V(n) asm volatile("s_waitcnt vmcnt(" #n ")" ::: "memory");
; #define WAIT_L(n) asm volatile("s_waitcnt lgkmcnt(" #n ")" ::: "memory");
; #define BAR __builtin_amdgcn_s_barrier();
; DI void gemm256(const u16* __restrict__ A, int lda, const u16* __restrict__ B0, const u16* __restrict__ B1, int ldb, int nt, acc_t& acc, char* lds) {
;     ...
;     LDA(At, 0, 1) WAIT_V(4) BAR WAIT_L(0) MMA(1, 0, At, Bq0) MMA(1, 1, At, Bq1) BAR }
;   { LDB(Bq0, 1, 0) LDA(At, 1, 0) WAIT_V(2) BAR WAIT_L(0) MMA(0, 0, At, Bq0) BAR
	s_nop 0
	ds_read_b128 v[74:77], v148 offset:16384
	ds_read_b128 v[78:81], v148 offset:17408
	ds_read_b128 v[90:93], v147 offset:16384
	ds_read_b128 v[94:97], v147 offset:17408
	ds_read_b128 v[182:185], v146 offset:16384
	ds_read_b128 v[186:189], v146 offset:17408
	ds_read_b128 v[190:193], v141 offset:16384
	ds_read_b128 v[194:197], v141 offset:17408
	s_waitcnt vmcnt(4)
	s_barrier
	s_waitcnt lgkmcnt(0)
	v_mfma_f32_16x16x32_bf16 v[60:63], v[132:135], v[74:77], v[60:63]
	v_mfma_f32_16x16x32_bf16 v[56:59], v[142:145], v[74:77], v[56:59]
	v_mfma_f32_16x16x32_bf16 v[52:55], v[132:135], v[90:93], v[52:55]
	v_mfma_f32_16x16x32_bf16 v[48:51], v[142:145], v[90:93], v[48:51]
	v_mfma_f32_16x16x32_bf16 v[36:39], v[132:135], v[190:193], v[36:39]
	v_mfma_f32_16x16x32_bf16 v[32:35], v[142:145], v[190:193], v[32:35]
	v_mfma_f32_16x16x32_bf16 v[60:63], v[136:139], v[78:81], v[60:63]
	v_mfma_f32_16x16x32_bf16 v[56:59], v[158:161], v[78:81], v[56:59]
	v_mfma_f32_16x16x32_bf16 v[52:55], v[136:139], v[94:97], v[52:55]
	v_mfma_f32_16x16x32_bf16 v[48:51], v[158:161], v[94:97], v[48:51]
	v_mfma_f32_16x16x32_bf16 v[44:47], v[132:135], v[182:185], v[44:47]
	v_mfma_f32_16x16x32_bf16 v[40:43], v[142:145], v[182:185], v[40:43]
	v_mfma_f32_16x16x32_bf16 v[36:39], v[136:139], v[194:197], v[36:39]
	v_mfma_f32_16x16x32_bf16 v[32:35], v[158:161], v[194:197], v[32:35]
	v_mfma_f32_16x16x32_bf16 v[198:201], v[136:139], v[186:189], v[44:47]
	v_mfma_f32_16x16x32_bf16 v[216:219], v[158:161], v[186:189], v[40:43]
	v_mfma_f32_16x16x32_bf16 v[20:23], v[106:109], v[90:93], v[20:23]
	v_mfma_f32_16x16x32_bf16 v[16:19], v[206:209], v[90:93], v[16:19]
	v_mfma_f32_16x16x32_bf16 v[4:7], v[106:109], v[190:193], v[4:7]
	v_mfma_f32_16x16x32_bf16 v[0:3], v[206:209], v[190:193], v[0:3]
	v_mfma_f32_16x16x32_bf16 v[28:31], v[106:109], v[74:77], v[28:31]
	v_mfma_f32_16x16x32_bf16 v[24:27], v[206:209], v[74:77], v[24:27]
	v_mfma_f32_16x16x32_bf16 v[20:23], v[110:113], v[94:97], v[20:23]
	v_mfma_f32_16x16x32_bf16 v[16:19], v[162:165], v[94:97], v[16:19]
	v_mfma_f32_16x16x32_bf16 v[12:15], v[106:109], v[182:185], v[12:15]
	v_mfma_f32_16x16x32_bf16 v[8:11], v[206:209], v[182:185], v[8:11]
	v_mfma_f32_16x16x32_bf16 v[4:7], v[110:113], v[194:197], v[4:7]
	v_mfma_f32_16x16x32_bf16 v[0:3], v[162:165], v[194:197], v[0:3]
	v_mfma_f32_16x16x32_bf16 v[130:133], v[110:113], v[78:81], v[28:31]
	v_mfma_f32_16x16x32_bf16 v[134:137], v[162:165], v[78:81], v[24:27]
	v_mfma_f32_16x16x32_bf16 v[142:145], v[110:113], v[186:189], v[12:15]
	v_mfma_f32_16x16x32_bf16 v[158:161], v[162:165], v[186:189], v[8:11]
	s_barrier
	s_nop 0
	ds_read_b128 v[8:11], v156
	ds_read_b128 v[12:15], v156 offset:1024
	ds_read_b128 v[162:165], v156 offset:2048
	ds_read_b128 v[154:157], v156 offset:3072
	ds_read_b128 v[24:27], v148 offset:32768
	ds_read_b128 v[28:31], v148 offset:33792
	ds_read_b128 v[40:43], v147 offset:32768
	ds_read_b128 v[44:47], v147 offset:33792
	ds_read_b128 v[182:185], v146 offset:32768
	ds_read_b128 v[186:189], v146 offset:33792
	ds_read_b128 v[190:193], v141 offset:32768
	ds_read_b128 v[194:197], v141 offset:33792
	s_waitcnt vmcnt(2)
	s_barrier
	s_waitcnt lgkmcnt(0)
	v_mfma_f32_16x16x32_bf16 v[74:77], v[8:11], v[24:27], v[126:129]
	v_mfma_f32_16x16x32_bf16 v[126:129], v[12:15], v[28:31], v[74:77]
	v_mfma_f32_16x16x32_bf16 v[74:77], v[162:165], v[24:27], v[122:125]
	v_mfma_f32_16x16x32_bf16 v[122:125], v[154:157], v[28:31], v[74:77]
	v_mfma_f32_16x16x32_bf16 v[74:77], v[8:11], v[40:43], v[118:121]
	v_mfma_f32_16x16x32_bf16 v[110:113], v[12:15], v[44:47], v[74:77]
	v_mfma_f32_16x16x32_bf16 v[74:77], v[162:165], v[40:43], v[114:117]
	v_mfma_f32_16x16x32_bf16 v[106:109], v[154:157], v[44:47], v[74:77]
	v_mfma_f32_16x16x32_bf16 v[74:77], v[8:11], v[182:185], v[166:169]
	v_mfma_f32_16x16x32_bf16 v[94:97], v[12:15], v[186:189], v[74:77]
	v_mfma_f32_16x16x32_bf16 v[74:77], v[162:165], v[182:185], v[202:205]
	v_mfma_f32_16x16x32_bf16 v[90:93], v[154:157], v[186:189], v[74:77]
	v_mfma_f32_16x16x32_bf16 v[74:77], v[8:11], v[190:193], v[102:105]
	v_mfma_f32_16x16x32_bf16 v[78:81], v[12:15], v[194:197], v[74:77]
	v_mfma_f32_16x16x32_bf16 v[74:77], v[162:165], v[190:193], v[98:101]
	v_mfma_f32_16x16x32_bf16 v[74:77], v[154:157], v[194:197], v[74:77]
	s_barrier
; #define LDA(dst, b, h) _Pragma("unroll") for (int m = 0; m < 4; ++m) _Pragma("unroll") for (int k = 0; k < 2; ++k) \
;     dst[m][k] = *(const bf16x8*)(lds + SA_(b, h) + lds_byte(wr * 64 + m * 16 + fr, k * 32 + fq * 8));
; #define LDB(dst, b, h) _Pragma("unroll") for (int n = 0; n < 2; ++n) _Pragma("unroll") for (int k = 0; k < 2; ++k) \
;     dst[n][k] = *(const bf16x8*)(lds + SB_(b, h) + lds_byte(wc * 32 + n * 16 + fr, k * 32 + fq * 8));
; #define MMA(ai, bj, At_, Bt_) { __builtin_amdgcn_s_setprio(1); \
;     _Pragma("unroll") for (int m = 0; m < 4; ++m) _Pragma("unroll") for (int n = 0; n < 2; ++n) _Pragma("unroll") for (int k = 0; k < 2; ++k) \
;       acc[ai][bj][m][n] = MFMA16(Bt_[n][k], At_[m][k], acc[ai][bj][m][n]); \
;     __builtin_amdgcn_s_setprio(0); }
; #define WAIT_V(n) asm volatile("s_waitcnt vmcnt(" #n ")" ::: "memory");
; #define WAIT_L(n) asm volatile("s_waitcnt lgkmcnt(" #n ")" ::: "memory");
; #define BAR __builtin_amdgcn_s_barrier();
; DI void gemm256(const u16* __restrict__ A, int lda, const u16* __restrict__ B0, const u16* __restrict__ B1, int ldb, int nt, acc_t& acc, char* lds) {
;     ...
;   { LDB(Bq0, 1, 0) LDA(At, 1, 0) WAIT_V(2) BAR WAIT_L(0) MMA(0, 0, At, Bq0) BAR
;     LDB(Bq1, 1, 1) WAIT_V(0) BAR WAIT_L(0) MMA(0, 1, At, Bq1) BAR
;     LDA(At, 1, 1) BAR WAIT_L(0) MMA(1, 0, At, Bq0) MMA(1, 1, At, Bq1) BAR }
;   if (wr == 0) BAR
;   __syncthreads();
	ds_read_b128 v[166:169], v152
	ds_read_b128 v[202:205], v152 offset:1024
	ds_read_b128 v[206:209], v152 offset:2048
	ds_read_b128 v[150:153], v152 offset:3072
	s_waitcnt vmcnt(0)
	s_barrier
	s_waitcnt lgkmcnt(0)
	v_mfma_f32_16x16x32_bf16 v[98:101], v[166:169], v[24:27], v[210:213]
	v_mfma_f32_16x16x32_bf16 v[24:27], v[206:209], v[24:27], v[170:173]
	v_mfma_f32_16x16x32_bf16 v[114:117], v[150:153], v[28:31], v[24:27]
	v_mfma_f32_16x16x32_bf16 v[24:27], v[166:169], v[40:43], v[86:89]
	v_mfma_f32_16x16x32_bf16 v[102:105], v[202:205], v[44:47], v[24:27]
	v_mfma_f32_16x16x32_bf16 v[24:27], v[206:209], v[40:43], v[82:85]
	v_mfma_f32_16x16x32_bf16 v[118:121], v[202:205], v[28:31], v[98:101]
	v_mfma_f32_16x16x32_bf16 v[98:101], v[150:153], v[44:47], v[24:27]
	v_mfma_f32_16x16x32_bf16 v[24:27], v[166:169], v[182:185], v[174:177]
	v_mfma_f32_16x16x32_bf16 v[86:89], v[202:205], v[186:189], v[24:27]
	v_mfma_f32_16x16x32_bf16 v[24:27], v[206:209], v[182:185], v[178:181]
	v_mfma_f32_16x16x32_bf16 v[82:85], v[150:153], v[186:189], v[24:27]
	v_mfma_f32_16x16x32_bf16 v[24:27], v[166:169], v[190:193], v[70:73]
	v_mfma_f32_16x16x32_bf16 v[70:73], v[202:205], v[194:197], v[24:27]
	v_mfma_f32_16x16x32_bf16 v[24:27], v[206:209], v[190:193], v[66:69]
	v_mfma_f32_16x16x32_bf16 v[66:69], v[150:153], v[194:197], v[24:27]
	s_barrier
	ds_read_b128 v[170:173], v148 offset:49152
	ds_read_b128 v[174:177], v148 offset:50176
	ds_read_b128 v[178:181], v147 offset:49152
	ds_read_b128 v[182:185], v147 offset:50176
	ds_read_b128 v[186:189], v146 offset:49152
	ds_read_b128 v[146:149], v146 offset:50176
	ds_read_b128 v[190:193], v141 offset:49152
	ds_read_b128 v[194:197], v141 offset:50176
	s_barrier
	s_waitcnt lgkmcnt(0)
	v_mfma_f32_16x16x32_bf16 v[24:27], v[8:11], v[170:173], v[60:63]
	v_mfma_f32_16x16x32_bf16 v[60:63], v[12:15], v[174:177], v[24:27]
	v_mfma_f32_16x16x32_bf16 v[24:27], v[162:165], v[170:173], v[56:59]
	v_mfma_f32_16x16x32_bf16 v[56:59], v[154:157], v[174:177], v[24:27]
	v_mfma_f32_16x16x32_bf16 v[24:27], v[8:11], v[178:181], v[52:55]
	v_mfma_f32_16x16x32_bf16 v[44:47], v[12:15], v[182:185], v[24:27]
	v_mfma_f32_16x16x32_bf16 v[24:27], v[162:165], v[178:181], v[48:51]
	v_mfma_f32_16x16x32_bf16 v[40:43], v[154:157], v[182:185], v[24:27]
	v_mfma_f32_16x16x32_bf16 v[24:27], v[8:11], v[186:189], v[198:201]
	v_mfma_f32_16x16x32_bf16 v[8:11], v[8:11], v[190:193], v[36:39]
	v_mfma_f32_16x16x32_bf16 v[28:31], v[12:15], v[146:149], v[24:27]
	v_mfma_f32_16x16x32_bf16 v[24:27], v[162:165], v[186:189], v[216:219]
	v_mfma_f32_16x16x32_bf16 v[12:15], v[12:15], v[194:197], v[8:11]
	v_mfma_f32_16x16x32_bf16 v[8:11], v[162:165], v[190:193], v[32:35]
	v_mfma_f32_16x16x32_bf16 v[24:27], v[154:157], v[146:149], v[24:27]
	v_mfma_f32_16x16x32_bf16 v[8:11], v[154:157], v[194:197], v[8:11]
	v_mfma_f32_16x16x32_bf16 v[32:35], v[166:169], v[170:173], v[130:133]
	v_mfma_f32_16x16x32_bf16 v[52:55], v[202:205], v[174:177], v[32:35]
	v_mfma_f32_16x16x32_bf16 v[32:35], v[206:209], v[170:173], v[134:137]
	v_mfma_f32_16x16x32_bf16 v[16:19], v[206:209], v[178:181], v[16:19]
	v_mfma_f32_16x16x32_bf16 v[48:51], v[150:153], v[174:177], v[32:35]
	v_mfma_f32_16x16x32_bf16 v[20:23], v[166:169], v[178:181], v[20:23]
	v_mfma_f32_16x16x32_bf16 v[32:35], v[150:153], v[182:185], v[16:19]
	v_mfma_f32_16x16x32_bf16 v[16:19], v[166:169], v[186:189], v[142:145]
	v_mfma_f32_16x16x32_bf16 v[36:39], v[202:205], v[182:185], v[20:23]
	v_mfma_f32_16x16x32_bf16 v[20:23], v[202:205], v[146:149], v[16:19]
	v_mfma_f32_16x16x32_bf16 v[16:19], v[206:209], v[186:189], v[158:161]
	v_mfma_f32_16x16x32_bf16 v[4:7], v[166:169], v[190:193], v[4:7]
	v_mfma_f32_16x16x32_bf16 v[0:3], v[206:209], v[190:193], v[0:3]
	v_mfma_f32_16x16x32_bf16 v[16:19], v[150:153], v[146:149], v[16:19]
	v_mfma_f32_16x16x32_bf16 v[4:7], v[202:205], v[194:197], v[4:7]
	v_mfma_f32_16x16x32_bf16 v[0:3], v[150:153], v[194:197], v[0:3]
	s_movk_i32 s7, 0x100
	v_cmp_gt_u32_e32 vcc, s7, v140
	s_barrier
	s_and_saveexec_b64 s[22:23], vcc
	s_cbranch_execz .LBB0_976
	s_barrier

; #define STAGE_A(b, h, kt) { const u16* ap_ = A + (size_t)((h) * ahalf + (unsigned)(kt) * 64u); glds16(ap_ + ao0, l0 + SA_(b, h)); glds16(ap_ + ao1, l0 + SA_(b, h) + 8192); }
; #define STAGE_B(b, h, kt) { const u16* bp_ = ((h) ? B1 : B0) + (unsigned)(kt) * 64u; glds16(bp_ + bo0, l0 + SB_(b, h)); glds16(bp_ + bo1, l0 + SB_(b, h) + 8192); }
; #define LDA(dst, b, h) _Pragma("unroll") for (int m = 0; m < 4; ++m) _Pragma("unroll") for (int k = 0; k < 2; ++k) \
;     dst[m][k] = *(const bf16x8*)(lds + SA_(b, h) + lds_byte(wr * 64 + m * 16 + fr, k * 32 + fq * 8));
; #define LDB(dst, b, h) _Pragma("unroll") for (int n = 0; n < 2; ++n) _Pragma("unroll") for (int k = 0; k < 2; ++k) \
;     dst[n][k] = *(const bf16x8*)(lds + SB_(b, h) + lds_byte(wc * 32 + n * 16 + fr, k * 32 + fq * 8));
; #define MMA(ai, bj, At_, Bt_) { __builtin_amdgcn_s_setprio(1); \
;     _Pragma("unroll") for (int m = 0; m < 4; ++m) _Pragma("unroll") for (int n = 0; n < 2; ++n) _Pragma("unroll") for (int k = 0; k < 2; ++k) \
;       acc[ai][bj][m][n] = MFMA16(Bt_[n][k], At_[m][k], acc[ai][bj][m][n]); \
;     __builtin_amdgcn_s_setprio(0); }
; #define WAIT_L(n) asm volatile("s_waitcnt lgkmcnt(" #n ")" ::: "memory");
; #define BAR __builtin_amdgcn_s_barrier();
; #define SCHED __builtin_amdgcn_sched_barrier(0);
; DI void gemm256(const u16* __restrict__ A, int lda, const u16* __restrict__ B0, const u16* __restrict__ B1, int ldb, int nt, acc_t& acc, char* lds) {
;     ...
;   for (int t = 0; t < nt - 2; t += 2) {
;     LDB(Bq0, 0, 0) SCHED LDA(At, 0, 0) STAGE_A(1, 1, t + 1)
;     WAIT_L(8) BAR WAIT_L(0) MMA(0, 0, At, Bq0) BAR SCHED
;     LDB(Bq1, 0, 1) STAGE_B(0, 0, t + 2)
;     BAR WAIT_L(0) MMA(0, 1, At, Bq1) BAR
;     LDA(At, 0, 1) STAGE_A(0, 0, t + 2)
;     BAR WAIT_L(0) MMA(1, 0, At, Bq0) BAR SCHED
.LBB0_979:
	ds_read_b128 v[142:145], v166
	ds_read_b128 v[170:173], v166 offset:1024
	ds_read_b128 v[174:177], v166 offset:2048
	ds_read_b128 v[178:181], v166 offset:3072
	v_lshl_add_u64 v[222:223], s[8:9], 0, v[136:137]
	v_readfirstlane_b32 s3, v167
	v_lshl_add_u64 v[168:169], v[222:223], 0, s[76:77]
	s_mov_b32 m0, s3
	ds_read_b128 v[182:185], v148
	ds_read_b128 v[190:193], v147
	ds_read_b128 v[198:201], v146
	ds_read_b128 v[206:209], v141
	global_load_lds_dwordx4 v[168:169], off
	v_add_u32_e32 v168, 0xe000, v149
	v_lshl_add_u64 v[224:225], s[8:9], 0, v[138:139]
	v_readfirstlane_b32 s3, v168
	v_lshl_add_u64 v[216:217], v[224:225], 0, s[76:77]
	s_mov_b32 m0, s3
	s_nop 0
	global_load_lds_dwordx4 v[216:217], off
	s_waitcnt lgkmcnt(4)
	s_barrier
	s_waitcnt lgkmcnt(0)
	ds_read_b128 v[186:189], v148 offset:1024
	ds_read_b128 v[194:197], v147 offset:1024
	ds_read_b128 v[202:205], v146 offset:1024
	ds_read_b128 v[210:213], v141 offset:1024
	v_mfma_f32_16x16x32_bf16 v[126:129], v[142:145], v[182:185], v[126:129]
	v_mfma_f32_16x16x32_bf16 v[122:125], v[174:177], v[182:185], v[122:125]
	v_mfma_f32_16x16x32_bf16 v[118:121], v[142:145], v[190:193], v[118:121]
	v_mfma_f32_16x16x32_bf16 v[114:117], v[174:177], v[190:193], v[114:117]
	v_mfma_f32_16x16x32_bf16 v[110:113], v[142:145], v[198:201], v[110:113]
	v_mfma_f32_16x16x32_bf16 v[106:109], v[174:177], v[198:201], v[106:109]
	v_mfma_f32_16x16x32_bf16 v[102:105], v[142:145], v[206:209], v[102:105]
	v_mfma_f32_16x16x32_bf16 v[98:101], v[174:177], v[206:209], v[98:101]
	s_waitcnt lgkmcnt(0)
	v_mfma_f32_16x16x32_bf16 v[126:129], v[170:173], v[186:189], v[126:129]
	v_mfma_f32_16x16x32_bf16 v[122:125], v[178:181], v[186:189], v[122:125]
	v_mfma_f32_16x16x32_bf16 v[118:121], v[170:173], v[194:197], v[118:121]
	v_mfma_f32_16x16x32_bf16 v[114:117], v[178:181], v[194:197], v[114:117]
	v_mfma_f32_16x16x32_bf16 v[110:113], v[170:173], v[202:205], v[110:113]
	v_mfma_f32_16x16x32_bf16 v[106:109], v[178:181], v[202:205], v[106:109]
	v_mfma_f32_16x16x32_bf16 v[102:105], v[170:173], v[210:213], v[102:105]
	v_mfma_f32_16x16x32_bf16 v[98:101], v[178:181], v[210:213], v[98:101]
	s_barrier
	v_lshl_add_u64 v[238:239], s[8:9], 0, v[132:133]
	v_readfirstlane_b32 s3, v150
	v_lshl_add_u64 v[240:241], v[238:239], 0, s[22:23]
	s_mov_b32 m0, s3
	ds_read_b128 v[216:219], v165
	ds_read_b128 v[226:229], v165 offset:1024
	ds_read_b128 v[230:233], v165 offset:2048
	ds_read_b128 v[234:237], v165 offset:3072
	global_load_lds_dwordx4 v[240:241], off
	v_lshl_add_u64 v[240:241], s[8:9], 0, v[134:135]
	v_readfirstlane_b32 s3, v152
	v_lshl_add_u64 v[242:243], v[240:241], 0, s[22:23]
	s_mov_b32 m0, s3
	s_nop 0
	global_load_lds_dwordx4 v[242:243], off
	s_barrier
	s_waitcnt lgkmcnt(0)
	v_mfma_f32_16x16x32_bf16 v[94:97], v[216:219], v[182:185], v[94:97]
	v_mfma_f32_16x16x32_bf16 v[90:93], v[230:233], v[182:185], v[90:93]
	v_mfma_f32_16x16x32_bf16 v[86:89], v[216:219], v[190:193], v[86:89]
	v_mfma_f32_16x16x32_bf16 v[82:85], v[230:233], v[190:193], v[82:85]
	v_mfma_f32_16x16x32_bf16 v[78:81], v[216:219], v[198:201], v[78:81]
	v_mfma_f32_16x16x32_bf16 v[74:77], v[230:233], v[198:201], v[74:77]
	v_mfma_f32_16x16x32_bf16 v[70:73], v[216:219], v[206:209], v[70:73]
	v_mfma_f32_16x16x32_bf16 v[66:69], v[230:233], v[206:209], v[66:69]
	v_mfma_f32_16x16x32_bf16 v[94:97], v[226:229], v[186:189], v[94:97]
	v_mfma_f32_16x16x32_bf16 v[90:93], v[234:237], v[186:189], v[90:93]
	v_mfma_f32_16x16x32_bf16 v[86:89], v[226:229], v[194:197], v[86:89]
	v_mfma_f32_16x16x32_bf16 v[82:85], v[234:237], v[194:197], v[82:85]
	v_mfma_f32_16x16x32_bf16 v[78:81], v[226:229], v[202:205], v[78:81]
	v_mfma_f32_16x16x32_bf16 v[74:77], v[234:237], v[202:205], v[74:77]
	v_mfma_f32_16x16x32_bf16 v[70:73], v[226:229], v[210:213], v[70:73]
	v_mfma_f32_16x16x32_bf16 v[66:69], v[234:237], v[210:213], v[66:69]
	v_readfirstlane_b32 s3, v149
	v_lshl_add_u64 v[242:243], v[222:223], 0, s[80:81]
	s_mov_b32 m0, s3
	v_readfirstlane_b32 s3, v153
	s_barrier
	ds_read_b128 v[182:185], v148 offset:16384
	ds_read_b128 v[190:193], v147 offset:16384
	ds_read_b128 v[198:201], v146 offset:16384
	ds_read_b128 v[206:209], v141 offset:16384
	global_load_lds_dwordx4 v[242:243], off
	v_lshl_add_u64 v[242:243], v[224:225], 0, s[80:81]
	s_mov_b32 m0, s3
	s_nop 0
	global_load_lds_dwordx4 v[242:243], off
	s_barrier
	s_waitcnt lgkmcnt(0)
	ds_read_b128 v[186:189], v148 offset:17408
	ds_read_b128 v[194:197], v147 offset:17408
	ds_read_b128 v[202:205], v146 offset:17408
	ds_read_b128 v[210:213], v141 offset:17408
	v_mfma_f32_16x16x32_bf16 v[60:63], v[142:145], v[182:185], v[60:63]
	v_mfma_f32_16x16x32_bf16 v[56:59], v[174:177], v[182:185], v[56:59]
	v_mfma_f32_16x16x32_bf16 v[52:55], v[142:145], v[190:193], v[52:55]
	v_mfma_f32_16x16x32_bf16 v[48:51], v[174:177], v[190:193], v[48:51]
	v_mfma_f32_16x16x32_bf16 v[44:47], v[142:145], v[198:201], v[44:47]
	v_mfma_f32_16x16x32_bf16 v[40:43], v[174:177], v[198:201], v[40:43]
	v_mfma_f32_16x16x32_bf16 v[36:39], v[142:145], v[206:209], v[36:39]
	v_mfma_f32_16x16x32_bf16 v[32:35], v[174:177], v[206:209], v[32:35]
	s_waitcnt lgkmcnt(0)
	v_mfma_f32_16x16x32_bf16 v[60:63], v[170:173], v[186:189], v[60:63]
	v_mfma_f32_16x16x32_bf16 v[56:59], v[178:181], v[186:189], v[56:59]
	v_mfma_f32_16x16x32_bf16 v[52:55], v[170:173], v[194:197], v[52:55]
	v_mfma_f32_16x16x32_bf16 v[48:51], v[178:181], v[194:197], v[48:51]
	v_mfma_f32_16x16x32_bf16 v[44:47], v[170:173], v[202:205], v[44:47]
	v_mfma_f32_16x16x32_bf16 v[40:43], v[178:181], v[202:205], v[40:43]
	v_mfma_f32_16x16x32_bf16 v[36:39], v[170:173], v[210:213], v[36:39]
	v_mfma_f32_16x16x32_bf16 v[32:35], v[178:181], v[210:213], v[32:35]
	s_barrier
; #define STAGE_A(b, h, kt) { const u16* ap_ = A + (size_t)((h) * ahalf + (unsigned)(kt) * 64u); glds16(ap_ + ao0, l0 + SA_(b, h)); glds16(ap_ + ao1, l0 + SA_(b, h) + 8192); }
; #define STAGE_B(b, h, kt) { const u16* bp_ = ((h) ? B1 : B0) + (unsigned)(kt) * 64u; glds16(bp_ + bo0, l0 + SB_(b, h)); glds16(bp_ + bo1, l0 + SB_(b, h) + 8192); }
; #define LDA(dst, b, h) _Pragma("unroll") for (int m = 0; m < 4; ++m) _Pragma("unroll") for (int k = 0; k < 2; ++k) \
;     dst[m][k] = *(const bf16x8*)(lds + SA_(b, h) + lds_byte(wr * 64 + m * 16 + fr, k * 32 + fq * 8));
; #define LDB(dst, b, h) _Pragma("unroll") for (int n = 0; n < 2; ++n) _Pragma("unroll") for (int k = 0; k < 2; ++k) \
;     dst[n][k] = *(const bf16x8*)(lds + SB_(b, h) + lds_byte(wc * 32 + n * 16 + fr, k * 32 + fq * 8));
; #define MMA(ai, bj, At_, Bt_) { __builtin_amdgcn_s_setprio(1); \
;     _Pragma("unroll") for (int m = 0; m < 4; ++m) _Pragma("unroll") for (int n = 0; n < 2; ++n) _Pragma("unroll") for (int k = 0; k < 2; ++k) \
;       acc[ai][bj][m][n] = MFMA16(Bt_[n][k], At_[m][k], acc[ai][bj][m][n]); \
;     __builtin_amdgcn_s_setprio(0); }
; #define WAIT_V(n) asm volatile("s_waitcnt vmcnt(" #n ")" ::: "memory");
; #define WAIT_L(n) asm volatile("s_waitcnt lgkmcnt(" #n ")" ::: "memory");
; #define BAR __builtin_amdgcn_s_barrier();
; #define SCHED __builtin_amdgcn_sched_barrier(0);
; DI void gemm256(const u16* __restrict__ A, int lda, const u16* __restrict__ B0, const u16* __restrict__ B1, int ldb, int nt, acc_t& acc, char* lds) {
;     ...
;     STAGE_B(0, 1, t + 2)
;     WAIT_V(6) BAR MMA(1, 1, At, Bq1) BAR
;     LDB(Bq0, 1, 0) SCHED LDA(At, 1, 0) STAGE_A(0, 1, t + 2)
;     WAIT_L(8) BAR WAIT_L(0) MMA(0, 0, At, Bq0) BAR SCHED
;     LDB(Bq1, 1, 1) STAGE_B(1, 0, t + 3)
;     BAR WAIT_L(0) MMA(0, 1, At, Bq1) BAR
;     LDA(At, 1, 1) STAGE_A(1, 0, t + 3)
	v_readfirstlane_b32 s3, v154
	v_lshl_add_u64 v[142:143], v[238:239], 0, s[28:29]
	s_mov_b32 m0, s3
	v_readfirstlane_b32 s3, v155
	global_load_lds_dwordx4 v[142:143], off
	v_lshl_add_u64 v[142:143], v[240:241], 0, s[28:29]
	s_mov_b32 m0, s3
	s_nop 0
	global_load_lds_dwordx4 v[142:143], off
	s_waitcnt vmcnt(6)
	s_barrier
	v_mfma_f32_16x16x32_bf16 v[28:31], v[216:219], v[182:185], v[28:31]
	v_mfma_f32_16x16x32_bf16 v[24:27], v[230:233], v[182:185], v[24:27]
	v_mfma_f32_16x16x32_bf16 v[20:23], v[216:219], v[190:193], v[20:23]
	v_mfma_f32_16x16x32_bf16 v[16:19], v[230:233], v[190:193], v[16:19]
	v_mfma_f32_16x16x32_bf16 v[12:15], v[216:219], v[198:201], v[12:15]
	v_mfma_f32_16x16x32_bf16 v[8:11], v[230:233], v[198:201], v[8:11]
	v_mfma_f32_16x16x32_bf16 v[4:7], v[216:219], v[206:209], v[4:7]
	v_mfma_f32_16x16x32_bf16 v[0:3], v[230:233], v[206:209], v[0:3]
	v_mfma_f32_16x16x32_bf16 v[28:31], v[226:229], v[186:189], v[28:31]
	v_mfma_f32_16x16x32_bf16 v[24:27], v[234:237], v[186:189], v[24:27]
	v_mfma_f32_16x16x32_bf16 v[20:23], v[226:229], v[194:197], v[20:23]
	v_mfma_f32_16x16x32_bf16 v[16:19], v[234:237], v[194:197], v[16:19]
	v_mfma_f32_16x16x32_bf16 v[12:15], v[226:229], v[202:205], v[12:15]
	v_mfma_f32_16x16x32_bf16 v[8:11], v[234:237], v[202:205], v[8:11]
	v_mfma_f32_16x16x32_bf16 v[4:7], v[226:229], v[210:213], v[4:7]
	v_mfma_f32_16x16x32_bf16 v[0:3], v[234:237], v[210:213], v[0:3]
	s_barrier
	ds_read_b128 v[142:145], v156
	ds_read_b128 v[170:173], v156 offset:1024
	ds_read_b128 v[174:177], v156 offset:2048
	ds_read_b128 v[178:181], v156 offset:3072
	v_readfirstlane_b32 s3, v157
	v_lshl_add_u64 v[216:217], v[222:223], 0, s[4:5]
	s_mov_b32 m0, s3
	v_readfirstlane_b32 s3, v158
	ds_read_b128 v[182:185], v148 offset:32768
	ds_read_b128 v[190:193], v147 offset:32768
	ds_read_b128 v[198:201], v146 offset:32768
	ds_read_b128 v[206:209], v141 offset:32768
	global_load_lds_dwordx4 v[216:217], off
	v_lshl_add_u64 v[216:217], v[224:225], 0, s[4:5]
	s_mov_b32 m0, s3
	s_nop 0
	global_load_lds_dwordx4 v[216:217], off
	s_waitcnt lgkmcnt(4)
	s_barrier
	s_waitcnt lgkmcnt(0)
	ds_read_b128 v[186:189], v148 offset:33792
	ds_read_b128 v[194:197], v147 offset:33792
	ds_read_b128 v[202:205], v146 offset:33792
	ds_read_b128 v[210:213], v141 offset:33792
	v_mfma_f32_16x16x32_bf16 v[126:129], v[142:145], v[182:185], v[126:129]
	v_mfma_f32_16x16x32_bf16 v[122:125], v[174:177], v[182:185], v[122:125]
	v_mfma_f32_16x16x32_bf16 v[118:121], v[142:145], v[190:193], v[118:121]
	v_mfma_f32_16x16x32_bf16 v[114:117], v[174:177], v[190:193], v[114:117]
	v_mfma_f32_16x16x32_bf16 v[110:113], v[142:145], v[198:201], v[110:113]
	v_mfma_f32_16x16x32_bf16 v[106:109], v[174:177], v[198:201], v[106:109]
	v_mfma_f32_16x16x32_bf16 v[102:105], v[142:145], v[206:209], v[102:105]
	v_mfma_f32_16x16x32_bf16 v[98:101], v[174:177], v[206:209], v[98:101]
	s_waitcnt lgkmcnt(0)
	v_mfma_f32_16x16x32_bf16 v[126:129], v[170:173], v[186:189], v[126:129]
	v_mfma_f32_16x16x32_bf16 v[122:125], v[178:181], v[186:189], v[122:125]
	v_mfma_f32_16x16x32_bf16 v[118:121], v[170:173], v[194:197], v[118:121]
	v_mfma_f32_16x16x32_bf16 v[114:117], v[178:181], v[194:197], v[114:117]
	v_mfma_f32_16x16x32_bf16 v[110:113], v[170:173], v[202:205], v[110:113]
	v_mfma_f32_16x16x32_bf16 v[106:109], v[178:181], v[202:205], v[106:109]
	v_mfma_f32_16x16x32_bf16 v[102:105], v[170:173], v[210:213], v[102:105]
	v_mfma_f32_16x16x32_bf16 v[98:101], v[178:181], v[210:213], v[98:101]
	s_barrier
	v_readfirstlane_b32 s3, v159
	v_lshl_add_u64 v[242:243], v[238:239], 0, s[64:65]
	s_mov_b32 m0, s3
	v_readfirstlane_b32 s3, v160
	ds_read_b128 v[216:219], v151
	ds_read_b128 v[226:229], v151 offset:1024
	ds_read_b128 v[230:233], v151 offset:2048
	ds_read_b128 v[234:237], v151 offset:3072
	global_load_lds_dwordx4 v[242:243], off
	v_lshl_add_u64 v[242:243], v[240:241], 0, s[64:65]
	s_mov_b32 m0, s3
	s_nop 0
	global_load_lds_dwordx4 v[242:243], off
	s_barrier
	s_waitcnt lgkmcnt(0)
	v_mfma_f32_16x16x32_bf16 v[94:97], v[216:219], v[182:185], v[94:97]
	v_mfma_f32_16x16x32_bf16 v[90:93], v[230:233], v[182:185], v[90:93]
	v_mfma_f32_16x16x32_bf16 v[86:89], v[216:219], v[190:193], v[86:89]
	v_mfma_f32_16x16x32_bf16 v[82:85], v[230:233], v[190:193], v[82:85]
	v_mfma_f32_16x16x32_bf16 v[78:81], v[216:219], v[198:201], v[78:81]
	v_mfma_f32_16x16x32_bf16 v[74:77], v[230:233], v[198:201], v[74:77]
	v_mfma_f32_16x16x32_bf16 v[70:73], v[216:219], v[206:209], v[70:73]
	v_mfma_f32_16x16x32_bf16 v[66:69], v[230:233], v[206:209], v[66:69]
	v_mfma_f32_16x16x32_bf16 v[94:97], v[226:229], v[186:189], v[94:97]
	v_mfma_f32_16x16x32_bf16 v[90:93], v[234:237], v[186:189], v[90:93]
	v_mfma_f32_16x16x32_bf16 v[86:89], v[226:229], v[194:197], v[86:89]
	v_mfma_f32_16x16x32_bf16 v[82:85], v[234:237], v[194:197], v[82:85]
	v_mfma_f32_16x16x32_bf16 v[78:81], v[226:229], v[202:205], v[78:81]
	v_mfma_f32_16x16x32_bf16 v[74:77], v[234:237], v[202:205], v[74:77]
	v_mfma_f32_16x16x32_bf16 v[70:73], v[226:229], v[210:213], v[70:73]
	v_mfma_f32_16x16x32_bf16 v[66:69], v[234:237], v[210:213], v[66:69]
	v_readfirstlane_b32 s3, v161
	v_lshl_add_u64 v[222:223], v[222:223], 0, s[30:31]
	s_mov_b32 m0, s3
	v_readfirstlane_b32 s3, v162
	s_barrier
	ds_read_b128 v[182:185], v148 offset:49152
	ds_read_b128 v[190:193], v147 offset:49152
	ds_read_b128 v[198:201], v146 offset:49152
	ds_read_b128 v[206:209], v141 offset:49152
	global_load_lds_dwordx4 v[222:223], off
	v_lshl_add_u64 v[222:223], v[224:225], 0, s[30:31]
	s_mov_b32 m0, s3
	s_nop 0
	global_load_lds_dwordx4 v[222:223], off
	s_barrier
; #define STAGE_A(b, h, kt) { const u16* ap_ = A + (size_t)((h) * ahalf + (unsigned)(kt) * 64u); glds16(ap_ + ao0, l0 + SA_(b, h)); glds16(ap_ + ao1, l0 + SA_(b, h) + 8192); }
; #define STAGE_B(b, h, kt) { const u16* bp_ = ((h) ? B1 : B0) + (unsigned)(kt) * 64u; glds16(bp_ + bo0, l0 + SB_(b, h)); glds16(bp_ + bo1, l0 + SB_(b, h) + 8192); }
; #define LDA(dst, b, h) _Pragma("unroll") for (int m = 0; m < 4; ++m) _Pragma("unroll") for (int k = 0; k < 2; ++k) \
;     dst[m][k] = *(const bf16x8*)(lds + SA_(b, h) + lds_byte(wr * 64 + m * 16 + fr, k * 32 + fq * 8));
; #define LDB(dst, b, h) _Pragma("unroll") for (int n = 0; n < 2; ++n) _Pragma("unroll") for (int k = 0; k < 2; ++k) \
;     dst[n][k] = *(const bf16x8*)(lds + SB_(b, h) + lds_byte(wc * 32 + n * 16 + fr, k * 32 + fq * 8));
; #define MMA(ai, bj, At_, Bt_) { __builtin_amdgcn_s_setprio(1); \
;     _Pragma("unroll") for (int m = 0; m < 4; ++m) _Pragma("unroll") for (int n = 0; n < 2; ++n) _Pragma("unroll") for (int k = 0; k < 2; ++k) \
;       acc[ai][bj][m][n] = MFMA16(Bt_[n][k], At_[m][k], acc[ai][bj][m][n]); \
;     __builtin_amdgcn_s_setprio(0); }
; #define WAIT_V(n) asm volatile("s_waitcnt vmcnt(" #n ")" ::: "memory");
; #define WAIT_L(n) asm volatile("s_waitcnt lgkmcnt(" #n ")" ::: "memory");
; #define BAR __builtin_amdgcn_s_barrier();
; #define SCHED __builtin_amdgcn_sched_barrier(0);
; DI void gemm256(const u16* __restrict__ A, int lda, const u16* __restrict__ B0, const u16* __restrict__ B1, int ldb, int nt, acc_t& acc, char* lds) {
;     ...
;     BAR WAIT_L(0) MMA(1, 0, At, Bq0) BAR SCHED
;     STAGE_B(1, 1, t + 3)
;     WAIT_V(6) BAR MMA(1, 1, At, Bq1) BAR
;   }
;   { LDB(Bq0, 0, 0) LDA(At, 0, 0) STAGE_A(1, 1, nt - 1)
;     BAR WAIT_L(0) MMA(0, 0, At, Bq0) BAR
;     LDB(Bq1, 0, 1) BAR WAIT_L(0) MMA(0, 1, At, Bq1) BAR
	s_waitcnt lgkmcnt(0)
	ds_read_b128 v[186:189], v148 offset:50176
	ds_read_b128 v[194:197], v147 offset:50176
	ds_read_b128 v[202:205], v146 offset:50176
	ds_read_b128 v[210:213], v141 offset:50176
	v_mfma_f32_16x16x32_bf16 v[60:63], v[142:145], v[182:185], v[60:63]
	v_mfma_f32_16x16x32_bf16 v[56:59], v[174:177], v[182:185], v[56:59]
	v_mfma_f32_16x16x32_bf16 v[52:55], v[142:145], v[190:193], v[52:55]
	v_mfma_f32_16x16x32_bf16 v[48:51], v[174:177], v[190:193], v[48:51]
	v_mfma_f32_16x16x32_bf16 v[44:47], v[142:145], v[198:201], v[44:47]
	v_mfma_f32_16x16x32_bf16 v[40:43], v[174:177], v[198:201], v[40:43]
	v_mfma_f32_16x16x32_bf16 v[36:39], v[142:145], v[206:209], v[36:39]
	v_mfma_f32_16x16x32_bf16 v[32:35], v[174:177], v[206:209], v[32:35]
	s_waitcnt lgkmcnt(0)
	v_mfma_f32_16x16x32_bf16 v[60:63], v[170:173], v[186:189], v[60:63]
	v_mfma_f32_16x16x32_bf16 v[56:59], v[178:181], v[186:189], v[56:59]
	v_mfma_f32_16x16x32_bf16 v[52:55], v[170:173], v[194:197], v[52:55]
	v_mfma_f32_16x16x32_bf16 v[48:51], v[178:181], v[194:197], v[48:51]
	v_mfma_f32_16x16x32_bf16 v[44:47], v[170:173], v[202:205], v[44:47]
	v_mfma_f32_16x16x32_bf16 v[40:43], v[178:181], v[202:205], v[40:43]
	v_mfma_f32_16x16x32_bf16 v[36:39], v[170:173], v[210:213], v[36:39]
	v_mfma_f32_16x16x32_bf16 v[32:35], v[178:181], v[210:213], v[32:35]
	s_barrier
	v_readfirstlane_b32 s3, v163
	v_lshl_add_u64 v[142:143], v[238:239], 0, s[66:67]
	s_mov_b32 m0, s3
	v_readfirstlane_b32 s3, v164
	global_load_lds_dwordx4 v[142:143], off
	v_lshl_add_u64 v[142:143], v[240:241], 0, s[66:67]
	s_mov_b32 m0, s3
	s_nop 0
	global_load_lds_dwordx4 v[142:143], off
	s_waitcnt vmcnt(6)
	s_barrier
	v_mfma_f32_16x16x32_bf16 v[28:31], v[216:219], v[182:185], v[28:31]
	v_mfma_f32_16x16x32_bf16 v[24:27], v[230:233], v[182:185], v[24:27]
	v_mfma_f32_16x16x32_bf16 v[20:23], v[216:219], v[190:193], v[20:23]
	v_mfma_f32_16x16x32_bf16 v[16:19], v[230:233], v[190:193], v[16:19]
	v_mfma_f32_16x16x32_bf16 v[12:15], v[216:219], v[198:201], v[12:15]
	v_mfma_f32_16x16x32_bf16 v[8:11], v[230:233], v[198:201], v[8:11]
	v_mfma_f32_16x16x32_bf16 v[4:7], v[216:219], v[206:209], v[4:7]
	v_mfma_f32_16x16x32_bf16 v[0:3], v[230:233], v[206:209], v[0:3]
	v_mfma_f32_16x16x32_bf16 v[28:31], v[226:229], v[186:189], v[28:31]
	v_mfma_f32_16x16x32_bf16 v[24:27], v[234:237], v[186:189], v[24:27]
	v_mfma_f32_16x16x32_bf16 v[20:23], v[226:229], v[194:197], v[20:23]
	v_mfma_f32_16x16x32_bf16 v[16:19], v[234:237], v[194:197], v[16:19]
	v_mfma_f32_16x16x32_bf16 v[12:15], v[226:229], v[202:205], v[12:15]
	v_mfma_f32_16x16x32_bf16 v[8:11], v[234:237], v[202:205], v[8:11]
	v_mfma_f32_16x16x32_bf16 v[4:7], v[226:229], v[210:213], v[4:7]
	v_mfma_f32_16x16x32_bf16 v[0:3], v[234:237], v[210:213], v[0:3]
	s_add_i32 s2, s2, 2
	s_add_u32 s8, s8, 0x100
	s_addc_u32 s9, s9, 0
	s_cmp_lt_u32 s2, 4
	s_barrier
	s_cbranch_scc1 .LBB0_979
	s_add_u32 s2, s44, 0x40380
	s_addc_u32 s3, s45, 0
	v_readfirstlane_b32 s7, v167
	v_lshl_add_u64 v[162:163], v[64:65], 1, s[2:3]
	s_mov_b32 m0, s7
	v_lshl_add_u64 v[130:131], v[130:131], 1, s[2:3]
	v_readfirstlane_b32 s2, v168
	ds_read_b128 v[132:135], v166
	ds_read_b128 v[136:139], v166 offset:1024
	ds_read_b128 v[142:145], v166 offset:2048
	ds_read_b128 v[152:155], v166 offset:3072
	ds_read_b128 v[158:161], v148
	ds_read_b128 v[170:173], v148 offset:1024
	ds_read_b128 v[174:177], v147
	ds_read_b128 v[178:181], v147 offset:1024
	ds_read_b128 v[182:185], v146
	ds_read_b128 v[186:189], v146 offset:1024
	ds_read_b128 v[190:193], v141
	ds_read_b128 v[194:197], v141 offset:1024
	global_load_lds_dwordx4 v[162:163], off
	s_mov_b32 m0, s2
	s_nop 0
	global_load_lds_dwordx4 v[130:131], off
	s_barrier
	s_waitcnt lgkmcnt(0)
	v_mfma_f32_16x16x32_bf16 v[126:129], v[132:135], v[158:161], v[126:129]
	v_mfma_f32_16x16x32_bf16 v[122:125], v[142:145], v[158:161], v[122:125]
	v_mfma_f32_16x16x32_bf16 v[118:121], v[132:135], v[174:177], v[118:121]
	v_mfma_f32_16x16x32_bf16 v[114:117], v[142:145], v[174:177], v[114:117]
	v_mfma_f32_16x16x32_bf16 v[106:109], v[142:145], v[182:185], v[106:109]
	v_mfma_f32_16x16x32_bf16 v[98:101], v[142:145], v[190:193], v[98:101]
	v_mfma_f32_16x16x32_bf16 v[126:129], v[136:139], v[170:173], v[126:129]
	v_mfma_f32_16x16x32_bf16 v[122:125], v[152:155], v[170:173], v[122:125]
	v_mfma_f32_16x16x32_bf16 v[118:121], v[136:139], v[178:181], v[118:121]
	v_mfma_f32_16x16x32_bf16 v[114:117], v[152:155], v[178:181], v[114:117]
	v_mfma_f32_16x16x32_bf16 v[110:113], v[132:135], v[182:185], v[110:113]
	v_mfma_f32_16x16x32_bf16 v[106:109], v[152:155], v[186:189], v[106:109]
	v_mfma_f32_16x16x32_bf16 v[102:105], v[132:135], v[190:193], v[102:105]
	v_mfma_f32_16x16x32_bf16 v[98:101], v[152:155], v[194:197], v[98:101]
	v_mfma_f32_16x16x32_bf16 v[166:169], v[136:139], v[186:189], v[110:113]
	v_mfma_f32_16x16x32_bf16 v[198:201], v[136:139], v[194:197], v[102:105]
	s_barrier
	s_nop 2
	ds_read_b128 v[102:105], v165
	ds_read_b128 v[110:113], v165 offset:1024
	ds_read_b128 v[202:205], v165 offset:2048
	ds_read_b128 v[162:165], v165 offset:3072
	s_barrier
	s_waitcnt lgkmcnt(0)
	v_mfma_f32_16x16x32_bf16 v[90:93], v[202:205], v[158:161], v[90:93]
	v_mfma_f32_16x16x32_bf16 v[82:85], v[202:205], v[174:177], v[82:85]
	v_mfma_f32_16x16x32_bf16 v[74:77], v[202:205], v[182:185], v[74:77]
	v_mfma_f32_16x16x32_bf16 v[66:69], v[202:205], v[190:193], v[66:69]
	v_mfma_f32_16x16x32_bf16 v[94:97], v[102:105], v[158:161], v[94:97]
	v_mfma_f32_16x16x32_bf16 v[90:93], v[162:165], v[170:173], v[90:93]
	v_mfma_f32_16x16x32_bf16 v[86:89], v[102:105], v[174:177], v[86:89]
	v_mfma_f32_16x16x32_bf16 v[82:85], v[162:165], v[178:181], v[82:85]
	v_mfma_f32_16x16x32_bf16 v[78:81], v[102:105], v[182:185], v[78:81]
	v_mfma_f32_16x16x32_bf16 v[74:77], v[162:165], v[186:189], v[74:77]
	v_mfma_f32_16x16x32_bf16 v[70:73], v[102:105], v[190:193], v[70:73]
	v_mfma_f32_16x16x32_bf16 v[66:69], v[162:165], v[194:197], v[66:69]
	v_mfma_f32_16x16x32_bf16 v[206:209], v[110:113], v[170:173], v[94:97]
	v_mfma_f32_16x16x32_bf16 v[158:161], v[110:113], v[178:181], v[86:89]
	v_mfma_f32_16x16x32_bf16 v[170:173], v[110:113], v[186:189], v[78:81]
	v_mfma_f32_16x16x32_bf16 v[174:177], v[110:113], v[194:197], v[70:73]
	s_barrier
; #define LDA(dst, b, h) _Pragma("unroll") for (int m = 0; m < 4; ++m) _Pragma("unroll") for (int k = 0; k < 2; ++k) \
;     dst[m][k] = *(const bf16x8*)(lds + SA_(b, h) + lds_byte(wr * 64 + m * 16 + fr, k * 32 + fq * 8));
; #define LDB(dst, b, h) _Pragma("unroll") for (int n = 0; n < 2; ++n) _Pragma("unroll") for (int k = 0; k < 2; ++k) \
;     dst[n][k] = *(const bf16x8*)(lds + SB_(b, h) + lds_byte(wc * 32 + n * 16 + fr, k * 32 + fq * 8));
; #define MMA(ai, bj, At_, Bt_) { __builtin_amdgcn_s_setprio(1); \
;     _Pragma("unroll") for (int m = 0; m < 4; ++m) _Pragma("unroll") for (int n = 0; n < 2; ++n) _Pragma("unroll") for (int k = 0; k < 2; ++k) \
;       acc[ai][bj][m][n] = MFMA16(Bt_[n][k], At_[m][k], acc[ai][bj][m][n]); \
;     __builtin_amdgcn_s_setprio(0); }
; #define WAIT_V(n) asm volatile("s_waitcnt vmcnt(" #n ")" ::: "memory");
; #define WAIT_L(n) asm volatile("s_waitcnt lgkmcnt(" #n ")" ::: "memory");
; #define BAR __builtin_amdgcn_s_barrier();
; DI void gemm256(const u16* __restrict__ A, int lda, const u16* __restrict__ B0, const u16* __restrict__ B1, int ldb, int nt, acc_t& acc, char* lds) {
;     ...
;     LDA(At, 0, 1) WAIT_V(4) BAR WAIT_L(0) MMA(1, 0, At, Bq0) MMA(1, 1, At, Bq1) BAR }
;   { LDB(Bq0, 1, 0) LDA(At, 1, 0) WAIT_V(2) BAR WAIT_L(0) MMA(0, 0, At, Bq0) BAR
	s_nop 0
	ds_read_b128 v[70:73], v148 offset:16384
	ds_read_b128 v[78:81], v148 offset:17408
	ds_read_b128 v[86:89], v147 offset:16384
	ds_read_b128 v[94:97], v147 offset:17408
	ds_read_b128 v[178:181], v146 offset:16384
	ds_read_b128 v[182:185], v146 offset:17408
	ds_read_b128 v[186:189], v141 offset:16384
	ds_read_b128 v[190:193], v141 offset:17408
	s_waitcnt vmcnt(4)
	s_barrier
	s_waitcnt lgkmcnt(0)
	v_mfma_f32_16x16x32_bf16 v[60:63], v[132:135], v[70:73], v[60:63]
	v_mfma_f32_16x16x32_bf16 v[56:59], v[142:145], v[70:73], v[56:59]
	v_mfma_f32_16x16x32_bf16 v[52:55], v[132:135], v[86:89], v[52:55]
	v_mfma_f32_16x16x32_bf16 v[48:51], v[142:145], v[86:89], v[48:51]
	v_mfma_f32_16x16x32_bf16 v[36:39], v[132:135], v[186:189], v[36:39]
	v_mfma_f32_16x16x32_bf16 v[32:35], v[142:145], v[186:189], v[32:35]
	v_mfma_f32_16x16x32_bf16 v[60:63], v[136:139], v[78:81], v[60:63]
	v_mfma_f32_16x16x32_bf16 v[56:59], v[152:155], v[78:81], v[56:59]
	v_mfma_f32_16x16x32_bf16 v[52:55], v[136:139], v[94:97], v[52:55]
	v_mfma_f32_16x16x32_bf16 v[48:51], v[152:155], v[94:97], v[48:51]
	v_mfma_f32_16x16x32_bf16 v[44:47], v[132:135], v[178:181], v[44:47]
	v_mfma_f32_16x16x32_bf16 v[40:43], v[142:145], v[178:181], v[40:43]
	v_mfma_f32_16x16x32_bf16 v[36:39], v[136:139], v[190:193], v[36:39]
	v_mfma_f32_16x16x32_bf16 v[32:35], v[152:155], v[190:193], v[32:35]
	v_mfma_f32_16x16x32_bf16 v[194:197], v[136:139], v[182:185], v[44:47]
	v_mfma_f32_16x16x32_bf16 v[210:213], v[152:155], v[182:185], v[40:43]
	v_mfma_f32_16x16x32_bf16 v[20:23], v[102:105], v[86:89], v[20:23]
	v_mfma_f32_16x16x32_bf16 v[16:19], v[202:205], v[86:89], v[16:19]
	v_mfma_f32_16x16x32_bf16 v[4:7], v[102:105], v[186:189], v[4:7]
	v_mfma_f32_16x16x32_bf16 v[0:3], v[202:205], v[186:189], v[0:3]
	v_mfma_f32_16x16x32_bf16 v[28:31], v[102:105], v[70:73], v[28:31]
	v_mfma_f32_16x16x32_bf16 v[24:27], v[202:205], v[70:73], v[24:27]
	v_mfma_f32_16x16x32_bf16 v[20:23], v[110:113], v[94:97], v[20:23]
	v_mfma_f32_16x16x32_bf16 v[16:19], v[162:165], v[94:97], v[16:19]
	v_mfma_f32_16x16x32_bf16 v[12:15], v[102:105], v[178:181], v[12:15]
	v_mfma_f32_16x16x32_bf16 v[8:11], v[202:205], v[178:181], v[8:11]
	v_mfma_f32_16x16x32_bf16 v[4:7], v[110:113], v[190:193], v[4:7]
	v_mfma_f32_16x16x32_bf16 v[0:3], v[162:165], v[190:193], v[0:3]
	v_mfma_f32_16x16x32_bf16 v[130:133], v[110:113], v[78:81], v[28:31]
	v_mfma_f32_16x16x32_bf16 v[134:137], v[162:165], v[78:81], v[24:27]
	v_mfma_f32_16x16x32_bf16 v[142:145], v[110:113], v[182:185], v[12:15]
	v_mfma_f32_16x16x32_bf16 v[152:155], v[162:165], v[182:185], v[8:11]
	s_barrier
	s_nop 0
	ds_read_b128 v[8:11], v156
	ds_read_b128 v[12:15], v156 offset:1024
	ds_read_b128 v[162:165], v156 offset:2048
	ds_read_b128 v[178:181], v156 offset:3072
	ds_read_b128 v[24:27], v148 offset:32768
	ds_read_b128 v[28:31], v148 offset:33792
	ds_read_b128 v[40:43], v147 offset:32768
	ds_read_b128 v[44:47], v147 offset:33792
	ds_read_b128 v[182:185], v146 offset:32768
	ds_read_b128 v[186:189], v146 offset:33792
	ds_read_b128 v[190:193], v141 offset:32768
	ds_read_b128 v[202:205], v141 offset:33792
	s_waitcnt vmcnt(2)
	s_barrier
	s_waitcnt lgkmcnt(0)
	v_mfma_f32_16x16x32_bf16 v[70:73], v[8:11], v[24:27], v[126:129]
	v_mfma_f32_16x16x32_bf16 v[126:129], v[12:15], v[28:31], v[70:73]
	v_mfma_f32_16x16x32_bf16 v[70:73], v[162:165], v[24:27], v[122:125]
	v_mfma_f32_16x16x32_bf16 v[122:125], v[178:181], v[28:31], v[70:73]
	v_mfma_f32_16x16x32_bf16 v[70:73], v[8:11], v[40:43], v[118:121]
	v_mfma_f32_16x16x32_bf16 v[110:113], v[12:15], v[44:47], v[70:73]
	v_mfma_f32_16x16x32_bf16 v[70:73], v[162:165], v[40:43], v[114:117]
	v_mfma_f32_16x16x32_bf16 v[102:105], v[178:181], v[44:47], v[70:73]
	v_mfma_f32_16x16x32_bf16 v[70:73], v[8:11], v[182:185], v[166:169]
	v_mfma_f32_16x16x32_bf16 v[94:97], v[12:15], v[186:189], v[70:73]
	v_mfma_f32_16x16x32_bf16 v[70:73], v[162:165], v[182:185], v[106:109]
	v_mfma_f32_16x16x32_bf16 v[86:89], v[178:181], v[186:189], v[70:73]
	v_mfma_f32_16x16x32_bf16 v[70:73], v[8:11], v[190:193], v[198:201]
	v_mfma_f32_16x16x32_bf16 v[78:81], v[12:15], v[202:205], v[70:73]
	v_mfma_f32_16x16x32_bf16 v[70:73], v[162:165], v[190:193], v[98:101]
	v_mfma_f32_16x16x32_bf16 v[70:73], v[178:181], v[202:205], v[70:73]
	s_barrier
; #define LDA(dst, b, h) _Pragma("unroll") for (int m = 0; m < 4; ++m) _Pragma("unroll") for (int k = 0; k < 2; ++k) \
;     dst[m][k] = *(const bf16x8*)(lds + SA_(b, h) + lds_byte(wr * 64 + m * 16 + fr, k * 32 + fq * 8));
; #define LDB(dst, b, h) _Pragma("unroll") for (int n = 0; n < 2; ++n) _Pragma("unroll") for (int k = 0; k < 2; ++k) \
;     dst[n][k] = *(const bf16x8*)(lds + SB_(b, h) + lds_byte(wc * 32 + n * 16 + fr, k * 32 + fq * 8));
; #define MMA(ai, bj, At_, Bt_) { __builtin_amdgcn_s_setprio(1); \
;     _Pragma("unroll") for (int m = 0; m < 4; ++m) _Pragma("unroll") for (int n = 0; n < 2; ++n) _Pragma("unroll") for (int k = 0; k < 2; ++k) \
;       acc[ai][bj][m][n] = MFMA16(Bt_[n][k], At_[m][k], acc[ai][bj][m][n]); \
;     __builtin_amdgcn_s_setprio(0); }
; #define WAIT_V(n) asm volatile("s_waitcnt vmcnt(" #n ")" ::: "memory");
; #define WAIT_L(n) asm volatile("s_waitcnt lgkmcnt(" #n ")" ::: "memory");
; #define BAR __builtin_amdgcn_s_barrier();
; DI void gemm256(const u16* __restrict__ A, int lda, const u16* __restrict__ B0, const u16* __restrict__ B1, int ldb, int nt, acc_t& acc, char* lds) {
;     ...
;   { LDB(Bq0, 1, 0) LDA(At, 1, 0) WAIT_V(2) BAR WAIT_L(0) MMA(0, 0, At, Bq0) BAR
;     LDB(Bq1, 1, 1) WAIT_V(0) BAR WAIT_L(0) MMA(0, 1, At, Bq1) BAR
;     LDA(At, 1, 1) BAR WAIT_L(0) MMA(1, 0, At, Bq0) MMA(1, 1, At, Bq1) BAR }
;   if (wr == 0) BAR
;   __syncthreads();
	ds_read_b128 v[166:169], v151
	ds_read_b128 v[198:201], v151 offset:1024
	ds_read_b128 v[216:219], v151 offset:2048
	ds_read_b128 v[226:229], v151 offset:3072
	s_waitcnt vmcnt(0)
	s_barrier
	s_waitcnt lgkmcnt(0)
	v_mfma_f32_16x16x32_bf16 v[98:101], v[166:169], v[24:27], v[206:209]
	v_mfma_f32_16x16x32_bf16 v[24:27], v[216:219], v[24:27], v[90:93]
	v_mfma_f32_16x16x32_bf16 v[114:117], v[226:229], v[28:31], v[24:27]
	v_mfma_f32_16x16x32_bf16 v[24:27], v[166:169], v[40:43], v[158:161]
	v_mfma_f32_16x16x32_bf16 v[106:109], v[198:201], v[44:47], v[24:27]
	v_mfma_f32_16x16x32_bf16 v[24:27], v[216:219], v[40:43], v[82:85]
	v_mfma_f32_16x16x32_bf16 v[118:121], v[198:201], v[28:31], v[98:101]
	v_mfma_f32_16x16x32_bf16 v[98:101], v[226:229], v[44:47], v[24:27]
	v_mfma_f32_16x16x32_bf16 v[24:27], v[166:169], v[182:185], v[170:173]
	v_mfma_f32_16x16x32_bf16 v[90:93], v[198:201], v[186:189], v[24:27]
	v_mfma_f32_16x16x32_bf16 v[24:27], v[216:219], v[182:185], v[74:77]
	v_mfma_f32_16x16x32_bf16 v[82:85], v[226:229], v[186:189], v[24:27]
	v_mfma_f32_16x16x32_bf16 v[24:27], v[166:169], v[190:193], v[174:177]
	v_mfma_f32_16x16x32_bf16 v[74:77], v[198:201], v[202:205], v[24:27]
	v_mfma_f32_16x16x32_bf16 v[24:27], v[216:219], v[190:193], v[66:69]
	v_mfma_f32_16x16x32_bf16 v[66:69], v[226:229], v[202:205], v[24:27]
	s_barrier
	ds_read_b128 v[156:159], v148 offset:49152
	ds_read_b128 v[148:151], v148 offset:50176
	ds_read_b128 v[170:173], v147 offset:49152
	ds_read_b128 v[174:177], v147 offset:50176
	ds_read_b128 v[182:185], v146 offset:49152
	ds_read_b128 v[186:189], v146 offset:50176
	ds_read_b128 v[190:193], v141 offset:49152
	ds_read_b128 v[202:205], v141 offset:50176
	s_barrier
	s_waitcnt lgkmcnt(0)
	v_mfma_f32_16x16x32_bf16 v[24:27], v[8:11], v[156:159], v[60:63]
	v_mfma_f32_16x16x32_bf16 v[60:63], v[12:15], v[148:151], v[24:27]
	v_mfma_f32_16x16x32_bf16 v[24:27], v[162:165], v[156:159], v[56:59]
	v_mfma_f32_16x16x32_bf16 v[56:59], v[178:181], v[148:151], v[24:27]
	v_mfma_f32_16x16x32_bf16 v[24:27], v[8:11], v[170:173], v[52:55]
	v_mfma_f32_16x16x32_bf16 v[44:47], v[12:15], v[174:177], v[24:27]
	v_mfma_f32_16x16x32_bf16 v[24:27], v[162:165], v[170:173], v[48:51]
	v_mfma_f32_16x16x32_bf16 v[40:43], v[178:181], v[174:177], v[24:27]
	v_mfma_f32_16x16x32_bf16 v[24:27], v[8:11], v[182:185], v[194:197]
	v_mfma_f32_16x16x32_bf16 v[8:11], v[8:11], v[190:193], v[36:39]
	v_mfma_f32_16x16x32_bf16 v[28:31], v[12:15], v[186:189], v[24:27]
	v_mfma_f32_16x16x32_bf16 v[24:27], v[162:165], v[182:185], v[210:213]
	v_mfma_f32_16x16x32_bf16 v[12:15], v[12:15], v[202:205], v[8:11]
	v_mfma_f32_16x16x32_bf16 v[8:11], v[162:165], v[190:193], v[32:35]
	v_mfma_f32_16x16x32_bf16 v[24:27], v[178:181], v[186:189], v[24:27]
	v_mfma_f32_16x16x32_bf16 v[8:11], v[178:181], v[202:205], v[8:11]
	v_mfma_f32_16x16x32_bf16 v[32:35], v[166:169], v[156:159], v[130:133]
	v_mfma_f32_16x16x32_bf16 v[52:55], v[198:201], v[148:151], v[32:35]
	v_mfma_f32_16x16x32_bf16 v[32:35], v[216:219], v[156:159], v[134:137]
	v_mfma_f32_16x16x32_bf16 v[16:19], v[216:219], v[170:173], v[16:19]
	v_mfma_f32_16x16x32_bf16 v[48:51], v[226:229], v[148:151], v[32:35]
	v_mfma_f32_16x16x32_bf16 v[20:23], v[166:169], v[170:173], v[20:23]
	v_mfma_f32_16x16x32_bf16 v[32:35], v[226:229], v[174:177], v[16:19]
	v_mfma_f32_16x16x32_bf16 v[16:19], v[166:169], v[182:185], v[142:145]
	v_mfma_f32_16x16x32_bf16 v[36:39], v[198:201], v[174:177], v[20:23]
	v_mfma_f32_16x16x32_bf16 v[20:23], v[198:201], v[186:189], v[16:19]
	v_mfma_f32_16x16x32_bf16 v[16:19], v[216:219], v[182:185], v[152:155]
	v_mfma_f32_16x16x32_bf16 v[4:7], v[166:169], v[190:193], v[4:7]
	v_mfma_f32_16x16x32_bf16 v[0:3], v[216:219], v[190:193], v[0:3]
	v_mfma_f32_16x16x32_bf16 v[16:19], v[226:229], v[186:189], v[16:19]
	v_mfma_f32_16x16x32_bf16 v[4:7], v[198:201], v[202:205], v[4:7]
	v_mfma_f32_16x16x32_bf16 v[0:3], v[226:229], v[202:205], v[0:3]
	s_movk_i32 s2, 0x100
	v_cmp_gt_u32_e32 vcc, s2, v140
	s_barrier
	s_and_saveexec_b64 s[8:9], vcc
	s_cbranch_execz .LBB0_982
	s_barrier

; #define STAGE_A(b, h, kt) { const u16* ap_ = A + (size_t)((h) * ahalf + (unsigned)(kt) * 64u); glds16(ap_ + ao0, l0 + SA_(b, h)); glds16(ap_ + ao1, l0 + SA_(b, h) + 8192); }
; #define STAGE_B(b, h, kt) { const u16* bp_ = ((h) ? B1 : B0) + (unsigned)(kt) * 64u; glds16(bp_ + bo0, l0 + SB_(b, h)); glds16(bp_ + bo1, l0 + SB_(b, h) + 8192); }
; #define LDA(dst, b, h) _Pragma("unroll") for (int m = 0; m < 4; ++m) _Pragma("unroll") for (int k = 0; k < 2; ++k) \
;     dst[m][k] = *(const bf16x8*)(lds + SA_(b, h) + lds_byte(wr * 64 + m * 16 + fr, k * 32 + fq * 8));
; #define LDB(dst, b, h) _Pragma("unroll") for (int n = 0; n < 2; ++n) _Pragma("unroll") for (int k = 0; k < 2; ++k) \
;     dst[n][k] = *(const bf16x8*)(lds + SB_(b, h) + lds_byte(wc * 32 + n * 16 + fr, k * 32 + fq * 8));
; #define MMA(ai, bj, At_, Bt_) { __builtin_amdgcn_s_setprio(1); \
;     _Pragma("unroll") for (int m = 0; m < 4; ++m) _Pragma("unroll") for (int n = 0; n < 2; ++n) _Pragma("unroll") for (int k = 0; k < 2; ++k) \
;       acc[ai][bj][m][n] = MFMA16(Bt_[n][k], At_[m][k], acc[ai][bj][m][n]); \
;     __builtin_amdgcn_s_setprio(0); }
; #define WAIT_L(n) asm volatile("s_waitcnt lgkmcnt(" #n ")" ::: "memory");
; #define BAR __builtin_amdgcn_s_barrier();
; #define SCHED __builtin_amdgcn_sched_barrier(0);
; DI void gemm256(const u16* __restrict__ A, int lda, const u16* __restrict__ B0, const u16* __restrict__ B1, int ldb, int nt, acc_t& acc, char* lds) {
;     ...
;   for (int t = 0; t < nt - 2; t += 2) {
;     LDB(Bq0, 0, 0) SCHED LDA(At, 0, 0) STAGE_A(1, 1, t + 1)
;     WAIT_L(8) BAR WAIT_L(0) MMA(0, 0, At, Bq0) BAR SCHED
;     LDB(Bq1, 0, 1) STAGE_B(0, 0, t + 2)
;     BAR WAIT_L(0) MMA(0, 1, At, Bq1) BAR
;     LDA(At, 0, 1) STAGE_A(0, 0, t + 2)
;     BAR WAIT_L(0) MMA(1, 0, At, Bq0) BAR SCHED
.LBB0_985:
	ds_read_b128 v[142:145], v166
	ds_read_b128 v[170:173], v166 offset:1024
	ds_read_b128 v[174:177], v166 offset:2048
	ds_read_b128 v[178:181], v166 offset:3072
	v_lshl_add_u64 v[222:223], s[8:9], 0, v[136:137]
	v_readfirstlane_b32 s3, v167
	v_lshl_add_u64 v[168:169], v[222:223], 0, s[0:1]
	s_mov_b32 m0, s3
	ds_read_b128 v[182:185], v148
	ds_read_b128 v[190:193], v147
	ds_read_b128 v[198:201], v146
	ds_read_b128 v[206:209], v141
	global_load_lds_dwordx4 v[168:169], off
	v_add_u32_e32 v168, 0xe000, v150
	v_lshl_add_u64 v[224:225], s[8:9], 0, v[138:139]
	v_readfirstlane_b32 s3, v168
	v_lshl_add_u64 v[216:217], v[224:225], 0, s[0:1]
	s_mov_b32 m0, s3
	s_nop 0
	global_load_lds_dwordx4 v[216:217], off
	s_waitcnt lgkmcnt(4)
	s_barrier
	s_waitcnt lgkmcnt(0)
	ds_read_b128 v[186:189], v148 offset:1024
	ds_read_b128 v[194:197], v147 offset:1024
	ds_read_b128 v[202:205], v146 offset:1024
	ds_read_b128 v[210:213], v141 offset:1024
	v_mfma_f32_16x16x32_bf16 v[126:129], v[142:145], v[182:185], v[126:129]
	v_mfma_f32_16x16x32_bf16 v[122:125], v[174:177], v[182:185], v[122:125]
	v_mfma_f32_16x16x32_bf16 v[118:121], v[142:145], v[190:193], v[118:121]
	v_mfma_f32_16x16x32_bf16 v[114:117], v[174:177], v[190:193], v[114:117]
	v_mfma_f32_16x16x32_bf16 v[110:113], v[142:145], v[198:201], v[110:113]
	v_mfma_f32_16x16x32_bf16 v[106:109], v[174:177], v[198:201], v[106:109]
	v_mfma_f32_16x16x32_bf16 v[102:105], v[142:145], v[206:209], v[102:105]
	v_mfma_f32_16x16x32_bf16 v[98:101], v[174:177], v[206:209], v[98:101]
	s_waitcnt lgkmcnt(0)
	v_mfma_f32_16x16x32_bf16 v[126:129], v[170:173], v[186:189], v[126:129]
	v_mfma_f32_16x16x32_bf16 v[122:125], v[178:181], v[186:189], v[122:125]
	v_mfma_f32_16x16x32_bf16 v[118:121], v[170:173], v[194:197], v[118:121]
	v_mfma_f32_16x16x32_bf16 v[114:117], v[178:181], v[194:197], v[114:117]
	v_mfma_f32_16x16x32_bf16 v[110:113], v[170:173], v[202:205], v[110:113]
	v_mfma_f32_16x16x32_bf16 v[106:109], v[178:181], v[202:205], v[106:109]
	v_mfma_f32_16x16x32_bf16 v[102:105], v[170:173], v[210:213], v[102:105]
	v_mfma_f32_16x16x32_bf16 v[98:101], v[178:181], v[210:213], v[98:101]
	s_barrier
	v_lshl_add_u64 v[238:239], s[8:9], 0, v[132:133]
	v_readfirstlane_b32 s3, v151
	v_lshl_add_u64 v[240:241], v[238:239], 0, s[22:23]
	s_mov_b32 m0, s3
	ds_read_b128 v[216:219], v165
	ds_read_b128 v[226:229], v165 offset:1024
	ds_read_b128 v[230:233], v165 offset:2048
	ds_read_b128 v[234:237], v165 offset:3072
	global_load_lds_dwordx4 v[240:241], off
	v_lshl_add_u64 v[240:241], s[8:9], 0, v[134:135]
	v_readfirstlane_b32 s3, v152
	v_lshl_add_u64 v[242:243], v[240:241], 0, s[22:23]
	s_mov_b32 m0, s3
	s_nop 0
	global_load_lds_dwordx4 v[242:243], off
	s_barrier
	s_waitcnt lgkmcnt(0)
	v_mfma_f32_16x16x32_bf16 v[94:97], v[216:219], v[182:185], v[94:97]
	v_mfma_f32_16x16x32_bf16 v[90:93], v[230:233], v[182:185], v[90:93]
	v_mfma_f32_16x16x32_bf16 v[86:89], v[216:219], v[190:193], v[86:89]
	v_mfma_f32_16x16x32_bf16 v[82:85], v[230:233], v[190:193], v[82:85]
	v_mfma_f32_16x16x32_bf16 v[78:81], v[216:219], v[198:201], v[78:81]
	v_mfma_f32_16x16x32_bf16 v[74:77], v[230:233], v[198:201], v[74:77]
	v_mfma_f32_16x16x32_bf16 v[70:73], v[216:219], v[206:209], v[70:73]
	v_mfma_f32_16x16x32_bf16 v[66:69], v[230:233], v[206:209], v[66:69]
	v_mfma_f32_16x16x32_bf16 v[94:97], v[226:229], v[186:189], v[94:97]
	v_mfma_f32_16x16x32_bf16 v[90:93], v[234:237], v[186:189], v[90:93]
	v_mfma_f32_16x16x32_bf16 v[86:89], v[226:229], v[194:197], v[86:89]
	v_mfma_f32_16x16x32_bf16 v[82:85], v[234:237], v[194:197], v[82:85]
	v_mfma_f32_16x16x32_bf16 v[78:81], v[226:229], v[202:205], v[78:81]
	v_mfma_f32_16x16x32_bf16 v[74:77], v[234:237], v[202:205], v[74:77]
	v_mfma_f32_16x16x32_bf16 v[70:73], v[226:229], v[210:213], v[70:73]
	v_mfma_f32_16x16x32_bf16 v[66:69], v[234:237], v[210:213], v[66:69]
	v_readfirstlane_b32 s3, v150
	v_lshl_add_u64 v[242:243], v[222:223], 0, s[20:21]
	s_mov_b32 m0, s3
	v_readfirstlane_b32 s3, v153
	s_barrier
	ds_read_b128 v[182:185], v148 offset:16384
	ds_read_b128 v[190:193], v147 offset:16384
	ds_read_b128 v[198:201], v146 offset:16384
	ds_read_b128 v[206:209], v141 offset:16384
	global_load_lds_dwordx4 v[242:243], off
	v_lshl_add_u64 v[242:243], v[224:225], 0, s[20:21]
	s_mov_b32 m0, s3
	s_nop 0
	global_load_lds_dwordx4 v[242:243], off
	s_barrier
	s_waitcnt lgkmcnt(0)
	ds_read_b128 v[186:189], v148 offset:17408
	ds_read_b128 v[194:197], v147 offset:17408
	ds_read_b128 v[202:205], v146 offset:17408
	ds_read_b128 v[210:213], v141 offset:17408
	v_mfma_f32_16x16x32_bf16 v[60:63], v[142:145], v[182:185], v[60:63]
	v_mfma_f32_16x16x32_bf16 v[56:59], v[174:177], v[182:185], v[56:59]
	v_mfma_f32_16x16x32_bf16 v[52:55], v[142:145], v[190:193], v[52:55]
	v_mfma_f32_16x16x32_bf16 v[48:51], v[174:177], v[190:193], v[48:51]
	v_mfma_f32_16x16x32_bf16 v[44:47], v[142:145], v[198:201], v[44:47]
	v_mfma_f32_16x16x32_bf16 v[40:43], v[174:177], v[198:201], v[40:43]
	v_mfma_f32_16x16x32_bf16 v[36:39], v[142:145], v[206:209], v[36:39]
	v_mfma_f32_16x16x32_bf16 v[32:35], v[174:177], v[206:209], v[32:35]
	s_waitcnt lgkmcnt(0)
	v_mfma_f32_16x16x32_bf16 v[60:63], v[170:173], v[186:189], v[60:63]
	v_mfma_f32_16x16x32_bf16 v[56:59], v[178:181], v[186:189], v[56:59]
	v_mfma_f32_16x16x32_bf16 v[52:55], v[170:173], v[194:197], v[52:55]
	v_mfma_f32_16x16x32_bf16 v[48:51], v[178:181], v[194:197], v[48:51]
	v_mfma_f32_16x16x32_bf16 v[44:47], v[170:173], v[202:205], v[44:47]
	v_mfma_f32_16x16x32_bf16 v[40:43], v[178:181], v[202:205], v[40:43]
	v_mfma_f32_16x16x32_bf16 v[36:39], v[170:173], v[210:213], v[36:39]
	v_mfma_f32_16x16x32_bf16 v[32:35], v[178:181], v[210:213], v[32:35]
	s_barrier
; #define STAGE_A(b, h, kt) { const u16* ap_ = A + (size_t)((h) * ahalf + (unsigned)(kt) * 64u); glds16(ap_ + ao0, l0 + SA_(b, h)); glds16(ap_ + ao1, l0 + SA_(b, h) + 8192); }
; #define STAGE_B(b, h, kt) { const u16* bp_ = ((h) ? B1 : B0) + (unsigned)(kt) * 64u; glds16(bp_ + bo0, l0 + SB_(b, h)); glds16(bp_ + bo1, l0 + SB_(b, h) + 8192); }
; #define LDA(dst, b, h) _Pragma("unroll") for (int m = 0; m < 4; ++m) _Pragma("unroll") for (int k = 0; k < 2; ++k) \
;     dst[m][k] = *(const bf16x8*)(lds + SA_(b, h) + lds_byte(wr * 64 + m * 16 + fr, k * 32 + fq * 8));
; #define LDB(dst, b, h) _Pragma("unroll") for (int n = 0; n < 2; ++n) _Pragma("unroll") for (int k = 0; k < 2; ++k) \
;     dst[n][k] = *(const bf16x8*)(lds + SB_(b, h) + lds_byte(wc * 32 + n * 16 + fr, k * 32 + fq * 8));
; #define MMA(ai, bj, At_, Bt_) { __builtin_amdgcn_s_setprio(1); \
;     _Pragma("unroll") for (int m = 0; m < 4; ++m) _Pragma("unroll") for (int n = 0; n < 2; ++n) _Pragma("unroll") for (int k = 0; k < 2; ++k) \
;       acc[ai][bj][m][n] = MFMA16(Bt_[n][k], At_[m][k], acc[ai][bj][m][n]); \
;     __builtin_amdgcn_s_setprio(0); }
; #define WAIT_V(n) asm volatile("s_waitcnt vmcnt(" #n ")" ::: "memory");
; #define WAIT_L(n) asm volatile("s_waitcnt lgkmcnt(" #n ")" ::: "memory");
; #define BAR __builtin_amdgcn_s_barrier();
; #define SCHED __builtin_amdgcn_sched_barrier(0);
; DI void gemm256(const u16* __restrict__ A, int lda, const u16* __restrict__ B0, const u16* __restrict__ B1, int ldb, int nt, acc_t& acc, char* lds) {
;     ...
;     STAGE_B(0, 1, t + 2)
;     WAIT_V(6) BAR MMA(1, 1, At, Bq1) BAR
;     LDB(Bq0, 1, 0) SCHED LDA(At, 1, 0) STAGE_A(0, 1, t + 2)
;     WAIT_L(8) BAR WAIT_L(0) MMA(0, 0, At, Bq0) BAR SCHED
;     LDB(Bq1, 1, 1) STAGE_B(1, 0, t + 3)
;     BAR WAIT_L(0) MMA(0, 1, At, Bq1) BAR
;     LDA(At, 1, 1) STAGE_A(1, 0, t + 3)
	v_readfirstlane_b32 s3, v155
	v_lshl_add_u64 v[142:143], v[238:239], 0, s[28:29]
	s_mov_b32 m0, s3
	v_readfirstlane_b32 s3, v156
	global_load_lds_dwordx4 v[142:143], off
	v_lshl_add_u64 v[142:143], v[240:241], 0, s[28:29]
	s_mov_b32 m0, s3
	s_nop 0
	global_load_lds_dwordx4 v[142:143], off
	s_waitcnt vmcnt(6)
	s_barrier
	v_mfma_f32_16x16x32_bf16 v[28:31], v[216:219], v[182:185], v[28:31]
	v_mfma_f32_16x16x32_bf16 v[24:27], v[230:233], v[182:185], v[24:27]
	v_mfma_f32_16x16x32_bf16 v[20:23], v[216:219], v[190:193], v[20:23]
	v_mfma_f32_16x16x32_bf16 v[16:19], v[230:233], v[190:193], v[16:19]
	v_mfma_f32_16x16x32_bf16 v[12:15], v[216:219], v[198:201], v[12:15]
	v_mfma_f32_16x16x32_bf16 v[8:11], v[230:233], v[198:201], v[8:11]
	v_mfma_f32_16x16x32_bf16 v[4:7], v[216:219], v[206:209], v[4:7]
	v_mfma_f32_16x16x32_bf16 v[0:3], v[230:233], v[206:209], v[0:3]
	v_mfma_f32_16x16x32_bf16 v[28:31], v[226:229], v[186:189], v[28:31]
	v_mfma_f32_16x16x32_bf16 v[24:27], v[234:237], v[186:189], v[24:27]
	v_mfma_f32_16x16x32_bf16 v[20:23], v[226:229], v[194:197], v[20:23]
	v_mfma_f32_16x16x32_bf16 v[16:19], v[234:237], v[194:197], v[16:19]
	v_mfma_f32_16x16x32_bf16 v[12:15], v[226:229], v[202:205], v[12:15]
	v_mfma_f32_16x16x32_bf16 v[8:11], v[234:237], v[202:205], v[8:11]
	v_mfma_f32_16x16x32_bf16 v[4:7], v[226:229], v[210:213], v[4:7]
	v_mfma_f32_16x16x32_bf16 v[0:3], v[234:237], v[210:213], v[0:3]
	s_barrier
	ds_read_b128 v[142:145], v154
	ds_read_b128 v[170:173], v154 offset:1024
	ds_read_b128 v[174:177], v154 offset:2048
	ds_read_b128 v[178:181], v154 offset:3072
	v_readfirstlane_b32 s3, v157
	v_lshl_add_u64 v[216:217], v[222:223], 0, s[24:25]
	s_mov_b32 m0, s3
	v_readfirstlane_b32 s3, v158
	ds_read_b128 v[182:185], v148 offset:32768
	ds_read_b128 v[190:193], v147 offset:32768
	ds_read_b128 v[198:201], v146 offset:32768
	ds_read_b128 v[206:209], v141 offset:32768
	global_load_lds_dwordx4 v[216:217], off
	v_lshl_add_u64 v[216:217], v[224:225], 0, s[24:25]
	s_mov_b32 m0, s3
	s_nop 0
	global_load_lds_dwordx4 v[216:217], off
	s_waitcnt lgkmcnt(4)
	s_barrier
	s_waitcnt lgkmcnt(0)
	ds_read_b128 v[186:189], v148 offset:33792
	ds_read_b128 v[194:197], v147 offset:33792
	ds_read_b128 v[202:205], v146 offset:33792
	ds_read_b128 v[210:213], v141 offset:33792
	v_mfma_f32_16x16x32_bf16 v[126:129], v[142:145], v[182:185], v[126:129]
	v_mfma_f32_16x16x32_bf16 v[122:125], v[174:177], v[182:185], v[122:125]
	v_mfma_f32_16x16x32_bf16 v[118:121], v[142:145], v[190:193], v[118:121]
	v_mfma_f32_16x16x32_bf16 v[114:117], v[174:177], v[190:193], v[114:117]
	v_mfma_f32_16x16x32_bf16 v[110:113], v[142:145], v[198:201], v[110:113]
	v_mfma_f32_16x16x32_bf16 v[106:109], v[174:177], v[198:201], v[106:109]
	v_mfma_f32_16x16x32_bf16 v[102:105], v[142:145], v[206:209], v[102:105]
	v_mfma_f32_16x16x32_bf16 v[98:101], v[174:177], v[206:209], v[98:101]
	s_waitcnt lgkmcnt(0)
	v_mfma_f32_16x16x32_bf16 v[126:129], v[170:173], v[186:189], v[126:129]
	v_mfma_f32_16x16x32_bf16 v[122:125], v[178:181], v[186:189], v[122:125]
	v_mfma_f32_16x16x32_bf16 v[118:121], v[170:173], v[194:197], v[118:121]
	v_mfma_f32_16x16x32_bf16 v[114:117], v[178:181], v[194:197], v[114:117]
	v_mfma_f32_16x16x32_bf16 v[110:113], v[170:173], v[202:205], v[110:113]
	v_mfma_f32_16x16x32_bf16 v[106:109], v[178:181], v[202:205], v[106:109]
	v_mfma_f32_16x16x32_bf16 v[102:105], v[170:173], v[210:213], v[102:105]
	v_mfma_f32_16x16x32_bf16 v[98:101], v[178:181], v[210:213], v[98:101]
	s_barrier
	v_readfirstlane_b32 s3, v159
	v_lshl_add_u64 v[242:243], v[238:239], 0, s[46:47]
	s_mov_b32 m0, s3
	v_readfirstlane_b32 s3, v160
	ds_read_b128 v[216:219], v149
	ds_read_b128 v[226:229], v149 offset:1024
	ds_read_b128 v[230:233], v149 offset:2048
	ds_read_b128 v[234:237], v149 offset:3072
	global_load_lds_dwordx4 v[242:243], off
	v_lshl_add_u64 v[242:243], v[240:241], 0, s[46:47]
	s_mov_b32 m0, s3
	s_nop 0
	global_load_lds_dwordx4 v[242:243], off
	s_barrier
	s_waitcnt lgkmcnt(0)
	v_mfma_f32_16x16x32_bf16 v[94:97], v[216:219], v[182:185], v[94:97]
	v_mfma_f32_16x16x32_bf16 v[90:93], v[230:233], v[182:185], v[90:93]
	v_mfma_f32_16x16x32_bf16 v[86:89], v[216:219], v[190:193], v[86:89]
	v_mfma_f32_16x16x32_bf16 v[82:85], v[230:233], v[190:193], v[82:85]
	v_mfma_f32_16x16x32_bf16 v[78:81], v[216:219], v[198:201], v[78:81]
	v_mfma_f32_16x16x32_bf16 v[74:77], v[230:233], v[198:201], v[74:77]
	v_mfma_f32_16x16x32_bf16 v[70:73], v[216:219], v[206:209], v[70:73]
	v_mfma_f32_16x16x32_bf16 v[66:69], v[230:233], v[206:209], v[66:69]
	v_mfma_f32_16x16x32_bf16 v[94:97], v[226:229], v[186:189], v[94:97]
	v_mfma_f32_16x16x32_bf16 v[90:93], v[234:237], v[186:189], v[90:93]
	v_mfma_f32_16x16x32_bf16 v[86:89], v[226:229], v[194:197], v[86:89]
	v_mfma_f32_16x16x32_bf16 v[82:85], v[234:237], v[194:197], v[82:85]
	v_mfma_f32_16x16x32_bf16 v[78:81], v[226:229], v[202:205], v[78:81]
	v_mfma_f32_16x16x32_bf16 v[74:77], v[234:237], v[202:205], v[74:77]
	v_mfma_f32_16x16x32_bf16 v[70:73], v[226:229], v[210:213], v[70:73]
	v_mfma_f32_16x16x32_bf16 v[66:69], v[234:237], v[210:213], v[66:69]
	v_readfirstlane_b32 s3, v161
	v_lshl_add_u64 v[222:223], v[222:223], 0, s[34:35]
	s_mov_b32 m0, s3
	v_readfirstlane_b32 s3, v162
	s_barrier
	ds_read_b128 v[182:185], v148 offset:49152
	ds_read_b128 v[190:193], v147 offset:49152
	ds_read_b128 v[198:201], v146 offset:49152
	ds_read_b128 v[206:209], v141 offset:49152
	global_load_lds_dwordx4 v[222:223], off
	v_lshl_add_u64 v[222:223], v[224:225], 0, s[34:35]
	s_mov_b32 m0, s3
	s_nop 0
	global_load_lds_dwordx4 v[222:223], off
	s_barrier
; #define STAGE_A(b, h, kt) { const u16* ap_ = A + (size_t)((h) * ahalf + (unsigned)(kt) * 64u); glds16(ap_ + ao0, l0 + SA_(b, h)); glds16(ap_ + ao1, l0 + SA_(b, h) + 8192); }
; #define STAGE_B(b, h, kt) { const u16* bp_ = ((h) ? B1 : B0) + (unsigned)(kt) * 64u; glds16(bp_ + bo0, l0 + SB_(b, h)); glds16(bp_ + bo1, l0 + SB_(b, h) + 8192); }
; #define LDA(dst, b, h) _Pragma("unroll") for (int m = 0; m < 4; ++m) _Pragma("unroll") for (int k = 0; k < 2; ++k) \
;     dst[m][k] = *(const bf16x8*)(lds + SA_(b, h) + lds_byte(wr * 64 + m * 16 + fr, k * 32 + fq * 8));
; #define LDB(dst, b, h) _Pragma("unroll") for (int n = 0; n < 2; ++n) _Pragma("unroll") for (int k = 0; k < 2; ++k) \
;     dst[n][k] = *(const bf16x8*)(lds + SB_(b, h) + lds_byte(wc * 32 + n * 16 + fr, k * 32 + fq * 8));
; #define MMA(ai, bj, At_, Bt_) { __builtin_amdgcn_s_setprio(1); \
;     _Pragma("unroll") for (int m = 0; m < 4; ++m) _Pragma("unroll") for (int n = 0; n < 2; ++n) _Pragma("unroll") for (int k = 0; k < 2; ++k) \
;       acc[ai][bj][m][n] = MFMA16(Bt_[n][k], At_[m][k], acc[ai][bj][m][n]); \
;     __builtin_amdgcn_s_setprio(0); }
; #define WAIT_V(n) asm volatile("s_waitcnt vmcnt(" #n ")" ::: "memory");
; #define WAIT_L(n) asm volatile("s_waitcnt lgkmcnt(" #n ")" ::: "memory");
; #define BAR __builtin_amdgcn_s_barrier();
; #define SCHED __builtin_amdgcn_sched_barrier(0);
; DI void gemm256(const u16* __restrict__ A, int lda, const u16* __restrict__ B0, const u16* __restrict__ B1, int ldb, int nt, acc_t& acc, char* lds) {
;     ...
;     BAR WAIT_L(0) MMA(1, 0, At, Bq0) BAR SCHED
;     STAGE_B(1, 1, t + 3)
;     WAIT_V(6) BAR MMA(1, 1, At, Bq1) BAR
;   }
;   { LDB(Bq0, 0, 0) LDA(At, 0, 0) STAGE_A(1, 1, nt - 1)
;     BAR WAIT_L(0) MMA(0, 0, At, Bq0) BAR
;     LDB(Bq1, 0, 1) BAR WAIT_L(0) MMA(0, 1, At, Bq1) BAR
	s_waitcnt lgkmcnt(0)
	ds_read_b128 v[186:189], v148 offset:50176
	ds_read_b128 v[194:197], v147 offset:50176
	ds_read_b128 v[202:205], v146 offset:50176
	ds_read_b128 v[210:213], v141 offset:50176
	v_mfma_f32_16x16x32_bf16 v[60:63], v[142:145], v[182:185], v[60:63]
	v_mfma_f32_16x16x32_bf16 v[56:59], v[174:177], v[182:185], v[56:59]
	v_mfma_f32_16x16x32_bf16 v[52:55], v[142:145], v[190:193], v[52:55]
	v_mfma_f32_16x16x32_bf16 v[48:51], v[174:177], v[190:193], v[48:51]
	v_mfma_f32_16x16x32_bf16 v[44:47], v[142:145], v[198:201], v[44:47]
	v_mfma_f32_16x16x32_bf16 v[40:43], v[174:177], v[198:201], v[40:43]
	v_mfma_f32_16x16x32_bf16 v[36:39], v[142:145], v[206:209], v[36:39]
	v_mfma_f32_16x16x32_bf16 v[32:35], v[174:177], v[206:209], v[32:35]
	s_waitcnt lgkmcnt(0)
	v_mfma_f32_16x16x32_bf16 v[60:63], v[170:173], v[186:189], v[60:63]
	v_mfma_f32_16x16x32_bf16 v[56:59], v[178:181], v[186:189], v[56:59]
	v_mfma_f32_16x16x32_bf16 v[52:55], v[170:173], v[194:197], v[52:55]
	v_mfma_f32_16x16x32_bf16 v[48:51], v[178:181], v[194:197], v[48:51]
	v_mfma_f32_16x16x32_bf16 v[44:47], v[170:173], v[202:205], v[44:47]
	v_mfma_f32_16x16x32_bf16 v[40:43], v[178:181], v[202:205], v[40:43]
	v_mfma_f32_16x16x32_bf16 v[36:39], v[170:173], v[210:213], v[36:39]
	v_mfma_f32_16x16x32_bf16 v[32:35], v[178:181], v[210:213], v[32:35]
	s_barrier
	v_readfirstlane_b32 s3, v163
	v_lshl_add_u64 v[142:143], v[238:239], 0, s[50:51]
	s_mov_b32 m0, s3
	v_readfirstlane_b32 s3, v164
	global_load_lds_dwordx4 v[142:143], off
	v_lshl_add_u64 v[142:143], v[240:241], 0, s[50:51]
	s_mov_b32 m0, s3
	s_nop 0
	global_load_lds_dwordx4 v[142:143], off
	s_waitcnt vmcnt(6)
	s_barrier
	v_mfma_f32_16x16x32_bf16 v[28:31], v[216:219], v[182:185], v[28:31]
	v_mfma_f32_16x16x32_bf16 v[24:27], v[230:233], v[182:185], v[24:27]
	v_mfma_f32_16x16x32_bf16 v[20:23], v[216:219], v[190:193], v[20:23]
	v_mfma_f32_16x16x32_bf16 v[16:19], v[230:233], v[190:193], v[16:19]
	v_mfma_f32_16x16x32_bf16 v[12:15], v[216:219], v[198:201], v[12:15]
	v_mfma_f32_16x16x32_bf16 v[8:11], v[230:233], v[198:201], v[8:11]
	v_mfma_f32_16x16x32_bf16 v[4:7], v[216:219], v[206:209], v[4:7]
	v_mfma_f32_16x16x32_bf16 v[0:3], v[230:233], v[206:209], v[0:3]
	v_mfma_f32_16x16x32_bf16 v[28:31], v[226:229], v[186:189], v[28:31]
	v_mfma_f32_16x16x32_bf16 v[24:27], v[234:237], v[186:189], v[24:27]
	v_mfma_f32_16x16x32_bf16 v[20:23], v[226:229], v[194:197], v[20:23]
	v_mfma_f32_16x16x32_bf16 v[16:19], v[234:237], v[194:197], v[16:19]
	v_mfma_f32_16x16x32_bf16 v[12:15], v[226:229], v[202:205], v[12:15]
	v_mfma_f32_16x16x32_bf16 v[8:11], v[234:237], v[202:205], v[8:11]
	v_mfma_f32_16x16x32_bf16 v[4:7], v[226:229], v[210:213], v[4:7]
	v_mfma_f32_16x16x32_bf16 v[0:3], v[234:237], v[210:213], v[0:3]
	s_add_i32 s2, s2, 2
	s_add_u32 s8, s8, 0x100
	s_addc_u32 s9, s9, 0
	s_cmp_lt_u32 s2, 12
	s_barrier
	s_cbranch_scc1 .LBB0_985
	v_readfirstlane_b32 s2, v167
	v_lshl_add_u64 v[194:195], v[64:65], 1, s[54:55]
	s_mov_b32 m0, s2
	v_readfirstlane_b32 s2, v168
	ds_read_b128 v[132:135], v166
	ds_read_b128 v[136:139], v166 offset:1024
	ds_read_b128 v[142:145], v166 offset:2048
	ds_read_b128 v[150:153], v166 offset:3072
	ds_read_b128 v[156:159], v148
	ds_read_b128 v[160:163], v148 offset:1024
	ds_read_b128 v[170:173], v147
	ds_read_b128 v[174:177], v147 offset:1024
	ds_read_b128 v[178:181], v146
	ds_read_b128 v[182:185], v146 offset:1024
	ds_read_b128 v[186:189], v141
	ds_read_b128 v[190:193], v141 offset:1024
	global_load_lds_dwordx4 v[194:195], off
	v_lshl_add_u64 v[130:131], v[130:131], 1, s[54:55]
	s_mov_b32 m0, s2
	s_nop 0
	global_load_lds_dwordx4 v[130:131], off
	s_barrier
	s_waitcnt lgkmcnt(0)
	v_mfma_f32_16x16x32_bf16 v[126:129], v[132:135], v[156:159], v[126:129]
	v_mfma_f32_16x16x32_bf16 v[122:125], v[142:145], v[156:159], v[122:125]
	v_mfma_f32_16x16x32_bf16 v[118:121], v[132:135], v[170:173], v[118:121]
	v_mfma_f32_16x16x32_bf16 v[114:117], v[142:145], v[170:173], v[114:117]
	v_mfma_f32_16x16x32_bf16 v[102:105], v[132:135], v[186:189], v[102:105]
	v_mfma_f32_16x16x32_bf16 v[98:101], v[142:145], v[186:189], v[98:101]
	v_mfma_f32_16x16x32_bf16 v[126:129], v[136:139], v[160:163], v[126:129]
	v_mfma_f32_16x16x32_bf16 v[122:125], v[150:153], v[160:163], v[122:125]
	v_mfma_f32_16x16x32_bf16 v[118:121], v[136:139], v[174:177], v[118:121]
	v_mfma_f32_16x16x32_bf16 v[114:117], v[150:153], v[174:177], v[114:117]
	v_mfma_f32_16x16x32_bf16 v[110:113], v[132:135], v[178:181], v[110:113]
	v_mfma_f32_16x16x32_bf16 v[106:109], v[142:145], v[178:181], v[106:109]
	v_mfma_f32_16x16x32_bf16 v[102:105], v[136:139], v[190:193], v[102:105]
	v_mfma_f32_16x16x32_bf16 v[98:101], v[150:153], v[190:193], v[98:101]
	v_mfma_f32_16x16x32_bf16 v[166:169], v[136:139], v[182:185], v[110:113]
	v_mfma_f32_16x16x32_bf16 v[194:197], v[150:153], v[182:185], v[106:109]
	s_barrier
	s_nop 1
	ds_read_b128 v[106:109], v165
	ds_read_b128 v[110:113], v165 offset:1024
	ds_read_b128 v[198:201], v165 offset:2048
	ds_read_b128 v[202:205], v165 offset:3072
	s_barrier
	s_waitcnt lgkmcnt(0)
	v_mfma_f32_16x16x32_bf16 v[86:89], v[106:109], v[170:173], v[86:89]
	v_mfma_f32_16x16x32_bf16 v[82:85], v[198:201], v[170:173], v[82:85]
	v_mfma_f32_16x16x32_bf16 v[70:73], v[106:109], v[186:189], v[70:73]
	v_mfma_f32_16x16x32_bf16 v[66:69], v[198:201], v[186:189], v[66:69]
	v_mfma_f32_16x16x32_bf16 v[94:97], v[106:109], v[156:159], v[94:97]
	v_mfma_f32_16x16x32_bf16 v[90:93], v[198:201], v[156:159], v[90:93]
	v_mfma_f32_16x16x32_bf16 v[86:89], v[110:113], v[174:177], v[86:89]
	v_mfma_f32_16x16x32_bf16 v[82:85], v[202:205], v[174:177], v[82:85]
	v_mfma_f32_16x16x32_bf16 v[78:81], v[106:109], v[178:181], v[78:81]
	v_mfma_f32_16x16x32_bf16 v[74:77], v[198:201], v[178:181], v[74:77]
	v_mfma_f32_16x16x32_bf16 v[70:73], v[110:113], v[190:193], v[70:73]
	v_mfma_f32_16x16x32_bf16 v[66:69], v[202:205], v[190:193], v[66:69]
	v_mfma_f32_16x16x32_bf16 v[206:209], v[110:113], v[160:163], v[94:97]
	v_mfma_f32_16x16x32_bf16 v[156:159], v[202:205], v[160:163], v[90:93]
	v_mfma_f32_16x16x32_bf16 v[160:163], v[110:113], v[182:185], v[78:81]
	v_mfma_f32_16x16x32_bf16 v[170:173], v[202:205], v[182:185], v[74:77]
	s_barrier
; #define LDA(dst, b, h) _Pragma("unroll") for (int m = 0; m < 4; ++m) _Pragma("unroll") for (int k = 0; k < 2; ++k) \
;     dst[m][k] = *(const bf16x8*)(lds + SA_(b, h) + lds_byte(wr * 64 + m * 16 + fr, k * 32 + fq * 8));
; #define LDB(dst, b, h) _Pragma("unroll") for (int n = 0; n < 2; ++n) _Pragma("unroll") for (int k = 0; k < 2; ++k) \
;     dst[n][k] = *(const bf16x8*)(lds + SB_(b, h) + lds_byte(wc * 32 + n * 16 + fr, k * 32 + fq * 8));
; #define MMA(ai, bj, At_, Bt_) { __builtin_amdgcn_s_setprio(1); \
;     _Pragma("unroll") for (int m = 0; m < 4; ++m) _Pragma("unroll") for (int n = 0; n < 2; ++n) _Pragma("unroll") for (int k = 0; k < 2; ++k) \
;       acc[ai][bj][m][n] = MFMA16(Bt_[n][k], At_[m][k], acc[ai][bj][m][n]); \
;     __builtin_amdgcn_s_setprio(0); }
; #define WAIT_V(n) asm volatile("s_waitcnt vmcnt(" #n ")" ::: "memory");
; #define WAIT_L(n) asm volatile("s_waitcnt lgkmcnt(" #n ")" ::: "memory");
; #define BAR __builtin_amdgcn_s_barrier();
; DI void gemm256(const u16* __restrict__ A, int lda, const u16* __restrict__ B0, const u16* __restrict__ B1, int ldb, int nt, acc_t& acc, char* lds) {
;     ...
;     LDA(At, 0, 1) WAIT_V(4) BAR WAIT_L(0) MMA(1, 0, At, Bq0) MMA(1, 1, At, Bq1) BAR }
;   { LDB(Bq0, 1, 0) LDA(At, 1, 0) WAIT_V(2) BAR WAIT_L(0) MMA(0, 0, At, Bq0) BAR
	s_nop 0
	ds_read_b128 v[74:77], v148 offset:16384
	ds_read_b128 v[78:81], v148 offset:17408
	ds_read_b128 v[90:93], v147 offset:16384
	ds_read_b128 v[94:97], v147 offset:17408
	ds_read_b128 v[174:177], v146 offset:16384
	ds_read_b128 v[178:181], v146 offset:17408
	ds_read_b128 v[182:185], v141 offset:16384
	ds_read_b128 v[186:189], v141 offset:17408
	s_waitcnt vmcnt(4)
	s_barrier
	s_waitcnt lgkmcnt(0)
	v_mfma_f32_16x16x32_bf16 v[60:63], v[132:135], v[74:77], v[60:63]
	v_mfma_f32_16x16x32_bf16 v[56:59], v[142:145], v[74:77], v[56:59]
	v_mfma_f32_16x16x32_bf16 v[52:55], v[132:135], v[90:93], v[52:55]
	v_mfma_f32_16x16x32_bf16 v[48:51], v[142:145], v[90:93], v[48:51]
	v_mfma_f32_16x16x32_bf16 v[36:39], v[132:135], v[182:185], v[36:39]
	v_mfma_f32_16x16x32_bf16 v[32:35], v[142:145], v[182:185], v[32:35]
	v_mfma_f32_16x16x32_bf16 v[60:63], v[136:139], v[78:81], v[60:63]
	v_mfma_f32_16x16x32_bf16 v[56:59], v[150:153], v[78:81], v[56:59]
	v_mfma_f32_16x16x32_bf16 v[52:55], v[136:139], v[94:97], v[52:55]
	v_mfma_f32_16x16x32_bf16 v[48:51], v[150:153], v[94:97], v[48:51]
	v_mfma_f32_16x16x32_bf16 v[44:47], v[132:135], v[174:177], v[44:47]
	v_mfma_f32_16x16x32_bf16 v[40:43], v[142:145], v[174:177], v[40:43]
	v_mfma_f32_16x16x32_bf16 v[36:39], v[136:139], v[186:189], v[36:39]
	v_mfma_f32_16x16x32_bf16 v[32:35], v[150:153], v[186:189], v[32:35]
	v_mfma_f32_16x16x32_bf16 v[190:193], v[136:139], v[178:181], v[44:47]
	v_mfma_f32_16x16x32_bf16 v[210:213], v[150:153], v[178:181], v[40:43]
	v_mfma_f32_16x16x32_bf16 v[20:23], v[106:109], v[90:93], v[20:23]
	v_mfma_f32_16x16x32_bf16 v[16:19], v[198:201], v[90:93], v[16:19]
	v_mfma_f32_16x16x32_bf16 v[4:7], v[106:109], v[182:185], v[4:7]
	v_mfma_f32_16x16x32_bf16 v[0:3], v[198:201], v[182:185], v[0:3]
	v_mfma_f32_16x16x32_bf16 v[28:31], v[106:109], v[74:77], v[28:31]
	v_mfma_f32_16x16x32_bf16 v[24:27], v[198:201], v[74:77], v[24:27]
	v_mfma_f32_16x16x32_bf16 v[20:23], v[110:113], v[94:97], v[20:23]
	v_mfma_f32_16x16x32_bf16 v[16:19], v[202:205], v[94:97], v[16:19]
	v_mfma_f32_16x16x32_bf16 v[12:15], v[106:109], v[174:177], v[12:15]
	v_mfma_f32_16x16x32_bf16 v[8:11], v[198:201], v[174:177], v[8:11]
	v_mfma_f32_16x16x32_bf16 v[4:7], v[110:113], v[186:189], v[4:7]
	v_mfma_f32_16x16x32_bf16 v[0:3], v[202:205], v[186:189], v[0:3]
	v_mfma_f32_16x16x32_bf16 v[130:133], v[110:113], v[78:81], v[28:31]
	v_mfma_f32_16x16x32_bf16 v[134:137], v[202:205], v[78:81], v[24:27]
	v_mfma_f32_16x16x32_bf16 v[142:145], v[110:113], v[178:181], v[12:15]
	v_mfma_f32_16x16x32_bf16 v[150:153], v[202:205], v[178:181], v[8:11]
	s_barrier
	s_nop 0
	ds_read_b128 v[8:11], v154
	ds_read_b128 v[12:15], v154 offset:1024
	ds_read_b128 v[174:177], v154 offset:2048
	ds_read_b128 v[178:181], v154 offset:3072
	ds_read_b128 v[24:27], v148 offset:32768
	ds_read_b128 v[28:31], v148 offset:33792
	ds_read_b128 v[40:43], v147 offset:32768
	ds_read_b128 v[44:47], v147 offset:33792
	ds_read_b128 v[182:185], v146 offset:32768
	ds_read_b128 v[186:189], v146 offset:33792
	ds_read_b128 v[198:201], v141 offset:32768
	ds_read_b128 v[202:205], v141 offset:33792
	s_waitcnt vmcnt(2)
	s_barrier
	s_waitcnt lgkmcnt(0)
	v_mfma_f32_16x16x32_bf16 v[74:77], v[8:11], v[24:27], v[126:129]
	v_mfma_f32_16x16x32_bf16 v[126:129], v[12:15], v[28:31], v[74:77]
	v_mfma_f32_16x16x32_bf16 v[74:77], v[174:177], v[24:27], v[122:125]
	v_mfma_f32_16x16x32_bf16 v[122:125], v[178:181], v[28:31], v[74:77]
	v_mfma_f32_16x16x32_bf16 v[74:77], v[8:11], v[40:43], v[118:121]
	v_mfma_f32_16x16x32_bf16 v[110:113], v[12:15], v[44:47], v[74:77]
	v_mfma_f32_16x16x32_bf16 v[74:77], v[174:177], v[40:43], v[114:117]
	v_mfma_f32_16x16x32_bf16 v[106:109], v[178:181], v[44:47], v[74:77]
	v_mfma_f32_16x16x32_bf16 v[74:77], v[8:11], v[182:185], v[166:169]
	v_mfma_f32_16x16x32_bf16 v[94:97], v[12:15], v[186:189], v[74:77]
	v_mfma_f32_16x16x32_bf16 v[74:77], v[174:177], v[182:185], v[194:197]
	v_mfma_f32_16x16x32_bf16 v[90:93], v[178:181], v[186:189], v[74:77]
	v_mfma_f32_16x16x32_bf16 v[74:77], v[8:11], v[198:201], v[102:105]
	v_mfma_f32_16x16x32_bf16 v[78:81], v[12:15], v[202:205], v[74:77]
	v_mfma_f32_16x16x32_bf16 v[74:77], v[174:177], v[198:201], v[98:101]
	v_mfma_f32_16x16x32_bf16 v[74:77], v[178:181], v[202:205], v[74:77]
	s_barrier
; #define LDA(dst, b, h) _Pragma("unroll") for (int m = 0; m < 4; ++m) _Pragma("unroll") for (int k = 0; k < 2; ++k) \
;     dst[m][k] = *(const bf16x8*)(lds + SA_(b, h) + lds_byte(wr * 64 + m * 16 + fr, k * 32 + fq * 8));
; #define LDB(dst, b, h) _Pragma("unroll") for (int n = 0; n < 2; ++n) _Pragma("unroll") for (int k = 0; k < 2; ++k) \
;     dst[n][k] = *(const bf16x8*)(lds + SB_(b, h) + lds_byte(wc * 32 + n * 16 + fr, k * 32 + fq * 8));
; #define MMA(ai, bj, At_, Bt_) { __builtin_amdgcn_s_setprio(1); \
;     _Pragma("unroll") for (int m = 0; m < 4; ++m) _Pragma("unroll") for (int n = 0; n < 2; ++n) _Pragma("unroll") for (int k = 0; k < 2; ++k) \
;       acc[ai][bj][m][n] = MFMA16(Bt_[n][k], At_[m][k], acc[ai][bj][m][n]); \
;     __builtin_amdgcn_s_setprio(0); }
; #define WAIT_V(n) asm volatile("s_waitcnt vmcnt(" #n ")" ::: "memory");
; #define WAIT_L(n) asm volatile("s_waitcnt lgkmcnt(" #n ")" ::: "memory");
; #define BAR __builtin_amdgcn_s_barrier();
; DI void gemm256(const u16* __restrict__ A, int lda, const u16* __restrict__ B0, const u16* __restrict__ B1, int ldb, int nt, acc_t& acc, char* lds) {
;     ...
;   { LDB(Bq0, 1, 0) LDA(At, 1, 0) WAIT_V(2) BAR WAIT_L(0) MMA(0, 0, At, Bq0) BAR
;     LDB(Bq1, 1, 1) WAIT_V(0) BAR WAIT_L(0) MMA(0, 1, At, Bq1) BAR
;     LDA(At, 1, 1) BAR WAIT_L(0) MMA(1, 0, At, Bq0) MMA(1, 1, At, Bq1) BAR }
;   if (wr == 0) BAR
;   __syncthreads();
	ds_read_b128 v[164:167], v149
	ds_read_b128 v[194:197], v149 offset:1024
	ds_read_b128 v[216:219], v149 offset:2048
	ds_read_b128 v[226:229], v149 offset:3072
	s_waitcnt vmcnt(0)
	s_barrier
	s_waitcnt lgkmcnt(0)
	v_mfma_f32_16x16x32_bf16 v[98:101], v[164:167], v[24:27], v[206:209]
	v_mfma_f32_16x16x32_bf16 v[24:27], v[216:219], v[24:27], v[156:159]
	v_mfma_f32_16x16x32_bf16 v[114:117], v[226:229], v[28:31], v[24:27]
	v_mfma_f32_16x16x32_bf16 v[24:27], v[164:167], v[40:43], v[86:89]
	v_mfma_f32_16x16x32_bf16 v[102:105], v[194:197], v[44:47], v[24:27]
	v_mfma_f32_16x16x32_bf16 v[24:27], v[216:219], v[40:43], v[82:85]
	v_mfma_f32_16x16x32_bf16 v[118:121], v[194:197], v[28:31], v[98:101]
	v_mfma_f32_16x16x32_bf16 v[98:101], v[226:229], v[44:47], v[24:27]
	v_mfma_f32_16x16x32_bf16 v[24:27], v[164:167], v[182:185], v[160:163]
	v_mfma_f32_16x16x32_bf16 v[86:89], v[194:197], v[186:189], v[24:27]
	v_mfma_f32_16x16x32_bf16 v[24:27], v[216:219], v[182:185], v[170:173]
	v_mfma_f32_16x16x32_bf16 v[82:85], v[226:229], v[186:189], v[24:27]
	v_mfma_f32_16x16x32_bf16 v[24:27], v[164:167], v[198:201], v[70:73]
	v_mfma_f32_16x16x32_bf16 v[70:73], v[194:197], v[202:205], v[24:27]
	v_mfma_f32_16x16x32_bf16 v[24:27], v[216:219], v[198:201], v[66:69]
	v_mfma_f32_16x16x32_bf16 v[66:69], v[226:229], v[202:205], v[24:27]
	s_barrier
	ds_read_b128 v[154:157], v148 offset:49152
	ds_read_b128 v[158:161], v148 offset:50176
	ds_read_b128 v[168:171], v147 offset:49152
	ds_read_b128 v[182:185], v147 offset:50176
	ds_read_b128 v[186:189], v146 offset:49152
	ds_read_b128 v[146:149], v146 offset:50176
	ds_read_b128 v[198:201], v141 offset:49152
	ds_read_b128 v[202:205], v141 offset:50176
	s_barrier
	s_waitcnt lgkmcnt(0)
	v_mfma_f32_16x16x32_bf16 v[24:27], v[8:11], v[154:157], v[60:63]
	v_mfma_f32_16x16x32_bf16 v[60:63], v[12:15], v[158:161], v[24:27]
	v_mfma_f32_16x16x32_bf16 v[24:27], v[174:177], v[154:157], v[56:59]
	v_mfma_f32_16x16x32_bf16 v[56:59], v[178:181], v[158:161], v[24:27]
	v_mfma_f32_16x16x32_bf16 v[24:27], v[8:11], v[168:171], v[52:55]
	v_mfma_f32_16x16x32_bf16 v[44:47], v[12:15], v[182:185], v[24:27]
	v_mfma_f32_16x16x32_bf16 v[24:27], v[174:177], v[168:171], v[48:51]
	v_mfma_f32_16x16x32_bf16 v[40:43], v[178:181], v[182:185], v[24:27]
	v_mfma_f32_16x16x32_bf16 v[24:27], v[8:11], v[186:189], v[190:193]
	v_mfma_f32_16x16x32_bf16 v[8:11], v[8:11], v[198:201], v[36:39]
	v_mfma_f32_16x16x32_bf16 v[28:31], v[12:15], v[146:149], v[24:27]
	v_mfma_f32_16x16x32_bf16 v[24:27], v[174:177], v[186:189], v[210:213]
	v_mfma_f32_16x16x32_bf16 v[12:15], v[12:15], v[202:205], v[8:11]
	v_mfma_f32_16x16x32_bf16 v[8:11], v[174:177], v[198:201], v[32:35]
	v_mfma_f32_16x16x32_bf16 v[24:27], v[178:181], v[146:149], v[24:27]
	v_mfma_f32_16x16x32_bf16 v[8:11], v[178:181], v[202:205], v[8:11]
	v_mfma_f32_16x16x32_bf16 v[32:35], v[164:167], v[154:157], v[130:133]
	v_mfma_f32_16x16x32_bf16 v[52:55], v[194:197], v[158:161], v[32:35]
	v_mfma_f32_16x16x32_bf16 v[32:35], v[216:219], v[154:157], v[134:137]
	v_mfma_f32_16x16x32_bf16 v[16:19], v[216:219], v[168:171], v[16:19]
	v_mfma_f32_16x16x32_bf16 v[48:51], v[226:229], v[158:161], v[32:35]
	v_mfma_f32_16x16x32_bf16 v[20:23], v[164:167], v[168:171], v[20:23]
	v_mfma_f32_16x16x32_bf16 v[32:35], v[226:229], v[182:185], v[16:19]
	v_mfma_f32_16x16x32_bf16 v[16:19], v[164:167], v[186:189], v[142:145]
	v_mfma_f32_16x16x32_bf16 v[36:39], v[194:197], v[182:185], v[20:23]
	v_mfma_f32_16x16x32_bf16 v[20:23], v[194:197], v[146:149], v[16:19]
	v_mfma_f32_16x16x32_bf16 v[16:19], v[216:219], v[186:189], v[150:153]
	v_mfma_f32_16x16x32_bf16 v[4:7], v[164:167], v[198:201], v[4:7]
	v_mfma_f32_16x16x32_bf16 v[0:3], v[216:219], v[198:201], v[0:3]
	v_mfma_f32_16x16x32_bf16 v[16:19], v[226:229], v[146:149], v[16:19]
	v_mfma_f32_16x16x32_bf16 v[4:7], v[194:197], v[202:205], v[4:7]
	v_mfma_f32_16x16x32_bf16 v[0:3], v[226:229], v[202:205], v[0:3]
	s_movk_i32 s2, 0x100
	v_cmp_gt_u32_e32 vcc, s2, v140
	s_barrier
	s_and_saveexec_b64 s[8:9], vcc
	s_cbranch_execz .LBB0_988
	s_barrier

; #define STAGE_A(b, h, kt) { const u16* ap_ = A + (size_t)((h) * ahalf + (unsigned)(kt) * 64u); glds16(ap_ + ao0, l0 + SA_(b, h)); glds16(ap_ + ao1, l0 + SA_(b, h) + 8192); }
; #define STAGE_B(b, h, kt) { const u16* bp_ = ((h) ? B1 : B0) + (unsigned)(kt) * 64u; glds16(bp_ + bo0, l0 + SB_(b, h)); glds16(bp_ + bo1, l0 + SB_(b, h) + 8192); }
; #define LDA(dst, b, h) _Pragma("unroll") for (int m = 0; m < 4; ++m) _Pragma("unroll") for (int k = 0; k < 2; ++k) \
;     dst[m][k] = *(const bf16x8*)(lds + SA_(b, h) + lds_byte(wr * 64 + m * 16 + fr, k * 32 + fq * 8));
; #define LDB(dst, b, h) _Pragma("unroll") for (int n = 0; n < 2; ++n) _Pragma("unroll") for (int k = 0; k < 2; ++k) \
;     dst[n][k] = *(const bf16x8*)(lds + SB_(b, h) + lds_byte(wc * 32 + n * 16 + fr, k * 32 + fq * 8));
; #define MMA(ai, bj, At_, Bt_) { __builtin_amdgcn_s_setprio(1); \
;     _Pragma("unroll") for (int m = 0; m < 4; ++m) _Pragma("unroll") for (int n = 0; n < 2; ++n) _Pragma("unroll") for (int k = 0; k < 2; ++k) \
;       acc[ai][bj][m][n] = MFMA16(Bt_[n][k], At_[m][k], acc[ai][bj][m][n]); \
;     __builtin_amdgcn_s_setprio(0); }
; #define WAIT_L(n) asm volatile("s_waitcnt lgkmcnt(" #n ")" ::: "memory");
; #define BAR __builtin_amdgcn_s_barrier();
; #define SCHED __builtin_amdgcn_sched_barrier(0);
; DI void gemm256(const u16* __restrict__ A, int lda, const u16* __restrict__ B0, const u16* __restrict__ B1, int ldb, int nt, acc_t& acc, char* lds) {
;     ...
;   for (int t = 0; t < nt - 2; t += 2) {
;     LDB(Bq0, 0, 0) SCHED LDA(At, 0, 0) STAGE_A(1, 1, t + 1)
;     WAIT_L(8) BAR WAIT_L(0) MMA(0, 0, At, Bq0) BAR SCHED
;     LDB(Bq1, 0, 1) STAGE_B(0, 0, t + 2)
;     BAR WAIT_L(0) MMA(0, 1, At, Bq1) BAR
;     LDA(At, 0, 1) STAGE_A(0, 0, t + 2)
;     BAR WAIT_L(0) MMA(1, 0, At, Bq0) BAR SCHED
.LBB0_991:
	ds_read_b128 v[142:145], v166
	ds_read_b128 v[170:173], v166 offset:1024
	ds_read_b128 v[174:177], v166 offset:2048
	ds_read_b128 v[178:181], v166 offset:3072
	v_lshl_add_u64 v[222:223], s[8:9], 0, v[134:135]
	v_readfirstlane_b32 s3, v167
	v_lshl_add_u64 v[168:169], v[222:223], 0, s[22:23]
	s_mov_b32 m0, s3
	ds_read_b128 v[182:185], v148
	ds_read_b128 v[190:193], v147
	ds_read_b128 v[198:201], v146
	ds_read_b128 v[206:209], v141
	global_load_lds_dwordx4 v[168:169], off
	v_add_u32_e32 v168, 0xe000, v149
	v_lshl_add_u64 v[224:225], s[8:9], 0, v[132:133]
	v_readfirstlane_b32 s3, v168
	v_lshl_add_u64 v[216:217], v[224:225], 0, s[22:23]
	s_mov_b32 m0, s3
	s_nop 0
	global_load_lds_dwordx4 v[216:217], off
	s_waitcnt lgkmcnt(4)
	s_barrier
	s_waitcnt lgkmcnt(0)
	ds_read_b128 v[186:189], v148 offset:1024
	ds_read_b128 v[194:197], v147 offset:1024
	ds_read_b128 v[202:205], v146 offset:1024
	ds_read_b128 v[210:213], v141 offset:1024
	v_mfma_f32_16x16x32_bf16 v[126:129], v[142:145], v[182:185], v[126:129]
	v_mfma_f32_16x16x32_bf16 v[122:125], v[174:177], v[182:185], v[122:125]
	v_mfma_f32_16x16x32_bf16 v[118:121], v[142:145], v[190:193], v[118:121]
	v_mfma_f32_16x16x32_bf16 v[114:117], v[174:177], v[190:193], v[114:117]
	v_mfma_f32_16x16x32_bf16 v[110:113], v[142:145], v[198:201], v[110:113]
	v_mfma_f32_16x16x32_bf16 v[106:109], v[174:177], v[198:201], v[106:109]
	v_mfma_f32_16x16x32_bf16 v[102:105], v[142:145], v[206:209], v[102:105]
	v_mfma_f32_16x16x32_bf16 v[98:101], v[174:177], v[206:209], v[98:101]
	s_waitcnt lgkmcnt(0)
	v_mfma_f32_16x16x32_bf16 v[126:129], v[170:173], v[186:189], v[126:129]
	v_mfma_f32_16x16x32_bf16 v[122:125], v[178:181], v[186:189], v[122:125]
	v_mfma_f32_16x16x32_bf16 v[118:121], v[170:173], v[194:197], v[118:121]
	v_mfma_f32_16x16x32_bf16 v[114:117], v[178:181], v[194:197], v[114:117]
	v_mfma_f32_16x16x32_bf16 v[110:113], v[170:173], v[202:205], v[110:113]
	v_mfma_f32_16x16x32_bf16 v[106:109], v[178:181], v[202:205], v[106:109]
	v_mfma_f32_16x16x32_bf16 v[102:105], v[170:173], v[210:213], v[102:105]
	v_mfma_f32_16x16x32_bf16 v[98:101], v[178:181], v[210:213], v[98:101]
	s_barrier
	v_lshl_add_u64 v[238:239], s[8:9], 0, v[136:137]
	v_readfirstlane_b32 s3, v150
	v_lshl_add_u64 v[240:241], v[238:239], 0, s[28:29]
	s_mov_b32 m0, s3
	ds_read_b128 v[216:219], v165
	ds_read_b128 v[226:229], v165 offset:1024
	ds_read_b128 v[230:233], v165 offset:2048
	ds_read_b128 v[234:237], v165 offset:3072
	global_load_lds_dwordx4 v[240:241], off
	v_lshl_add_u64 v[240:241], s[8:9], 0, v[138:139]
	v_readfirstlane_b32 s3, v152
	v_lshl_add_u64 v[242:243], v[240:241], 0, s[28:29]
	s_mov_b32 m0, s3
	s_nop 0
	global_load_lds_dwordx4 v[242:243], off
	s_barrier
	s_waitcnt lgkmcnt(0)
	v_mfma_f32_16x16x32_bf16 v[94:97], v[216:219], v[182:185], v[94:97]
	v_mfma_f32_16x16x32_bf16 v[90:93], v[230:233], v[182:185], v[90:93]
	v_mfma_f32_16x16x32_bf16 v[86:89], v[216:219], v[190:193], v[86:89]
	v_mfma_f32_16x16x32_bf16 v[82:85], v[230:233], v[190:193], v[82:85]
	v_mfma_f32_16x16x32_bf16 v[78:81], v[216:219], v[198:201], v[78:81]
	v_mfma_f32_16x16x32_bf16 v[74:77], v[230:233], v[198:201], v[74:77]
	v_mfma_f32_16x16x32_bf16 v[70:73], v[216:219], v[206:209], v[70:73]
	v_mfma_f32_16x16x32_bf16 v[66:69], v[230:233], v[206:209], v[66:69]
	v_mfma_f32_16x16x32_bf16 v[94:97], v[226:229], v[186:189], v[94:97]
	v_mfma_f32_16x16x32_bf16 v[90:93], v[234:237], v[186:189], v[90:93]
	v_mfma_f32_16x16x32_bf16 v[86:89], v[226:229], v[194:197], v[86:89]
	v_mfma_f32_16x16x32_bf16 v[82:85], v[234:237], v[194:197], v[82:85]
	v_mfma_f32_16x16x32_bf16 v[78:81], v[226:229], v[202:205], v[78:81]
	v_mfma_f32_16x16x32_bf16 v[74:77], v[234:237], v[202:205], v[74:77]
	v_mfma_f32_16x16x32_bf16 v[70:73], v[226:229], v[210:213], v[70:73]
	v_mfma_f32_16x16x32_bf16 v[66:69], v[234:237], v[210:213], v[66:69]
	v_readfirstlane_b32 s3, v149
	v_lshl_add_u64 v[242:243], v[222:223], 0, s[42:43]
	s_mov_b32 m0, s3
	v_readfirstlane_b32 s3, v153
	s_barrier
	ds_read_b128 v[182:185], v148 offset:16384
	ds_read_b128 v[190:193], v147 offset:16384
	ds_read_b128 v[198:201], v146 offset:16384
	ds_read_b128 v[206:209], v141 offset:16384
	global_load_lds_dwordx4 v[242:243], off
	v_lshl_add_u64 v[242:243], v[224:225], 0, s[42:43]
	s_mov_b32 m0, s3
	s_nop 0
	global_load_lds_dwordx4 v[242:243], off
	s_barrier
	s_waitcnt lgkmcnt(0)
	ds_read_b128 v[186:189], v148 offset:17408
	ds_read_b128 v[194:197], v147 offset:17408
	ds_read_b128 v[202:205], v146 offset:17408
	ds_read_b128 v[210:213], v141 offset:17408
	v_mfma_f32_16x16x32_bf16 v[60:63], v[142:145], v[182:185], v[60:63]
	v_mfma_f32_16x16x32_bf16 v[56:59], v[174:177], v[182:185], v[56:59]
	v_mfma_f32_16x16x32_bf16 v[52:55], v[142:145], v[190:193], v[52:55]
	v_mfma_f32_16x16x32_bf16 v[48:51], v[174:177], v[190:193], v[48:51]
	v_mfma_f32_16x16x32_bf16 v[44:47], v[142:145], v[198:201], v[44:47]
	v_mfma_f32_16x16x32_bf16 v[40:43], v[174:177], v[198:201], v[40:43]
	v_mfma_f32_16x16x32_bf16 v[36:39], v[142:145], v[206:209], v[36:39]
	v_mfma_f32_16x16x32_bf16 v[32:35], v[174:177], v[206:209], v[32:35]
	s_waitcnt lgkmcnt(0)
	v_mfma_f32_16x16x32_bf16 v[60:63], v[170:173], v[186:189], v[60:63]
	v_mfma_f32_16x16x32_bf16 v[56:59], v[178:181], v[186:189], v[56:59]
	v_mfma_f32_16x16x32_bf16 v[52:55], v[170:173], v[194:197], v[52:55]
	v_mfma_f32_16x16x32_bf16 v[48:51], v[178:181], v[194:197], v[48:51]
	v_mfma_f32_16x16x32_bf16 v[44:47], v[170:173], v[202:205], v[44:47]
	v_mfma_f32_16x16x32_bf16 v[40:43], v[178:181], v[202:205], v[40:43]
	v_mfma_f32_16x16x32_bf16 v[36:39], v[170:173], v[210:213], v[36:39]
	v_mfma_f32_16x16x32_bf16 v[32:35], v[178:181], v[210:213], v[32:35]
	s_barrier
; #define STAGE_A(b, h, kt) { const u16* ap_ = A + (size_t)((h) * ahalf + (unsigned)(kt) * 64u); glds16(ap_ + ao0, l0 + SA_(b, h)); glds16(ap_ + ao1, l0 + SA_(b, h) + 8192); }
; #define STAGE_B(b, h, kt) { const u16* bp_ = ((h) ? B1 : B0) + (unsigned)(kt) * 64u; glds16(bp_ + bo0, l0 + SB_(b, h)); glds16(bp_ + bo1, l0 + SB_(b, h) + 8192); }
; #define LDA(dst, b, h) _Pragma("unroll") for (int m = 0; m < 4; ++m) _Pragma("unroll") for (int k = 0; k < 2; ++k) \
;     dst[m][k] = *(const bf16x8*)(lds + SA_(b, h) + lds_byte(wr * 64 + m * 16 + fr, k * 32 + fq * 8));
; #define LDB(dst, b, h) _Pragma("unroll") for (int n = 0; n < 2; ++n) _Pragma("unroll") for (int k = 0; k < 2; ++k) \
;     dst[n][k] = *(const bf16x8*)(lds + SB_(b, h) + lds_byte(wc * 32 + n * 16 + fr, k * 32 + fq * 8));
; #define MMA(ai, bj, At_, Bt_) { __builtin_amdgcn_s_setprio(1); \
;     _Pragma("unroll") for (int m = 0; m < 4; ++m) _Pragma("unroll") for (int n = 0; n < 2; ++n) _Pragma("unroll") for (int k = 0; k < 2; ++k) \
;       acc[ai][bj][m][n] = MFMA16(Bt_[n][k], At_[m][k], acc[ai][bj][m][n]); \
;     __builtin_amdgcn_s_setprio(0); }
; #define WAIT_V(n) asm volatile("s_waitcnt vmcnt(" #n ")" ::: "memory");
; #define WAIT_L(n) asm volatile("s_waitcnt lgkmcnt(" #n ")" ::: "memory");
; #define BAR __builtin_amdgcn_s_barrier();
; #define SCHED __builtin_amdgcn_sched_barrier(0);
; DI void gemm256(const u16* __restrict__ A, int lda, const u16* __restrict__ B0, const u16* __restrict__ B1, int ldb, int nt, acc_t& acc, char* lds) {
;     ...
;     STAGE_B(0, 1, t + 2)
;     WAIT_V(6) BAR MMA(1, 1, At, Bq1) BAR
;     LDB(Bq0, 1, 0) SCHED LDA(At, 1, 0) STAGE_A(0, 1, t + 2)
;     WAIT_L(8) BAR WAIT_L(0) MMA(0, 0, At, Bq0) BAR SCHED
;     LDB(Bq1, 1, 1) STAGE_B(1, 0, t + 3)
;     BAR WAIT_L(0) MMA(0, 1, At, Bq1) BAR
;     LDA(At, 1, 1) STAGE_A(1, 0, t + 3)
	v_readfirstlane_b32 s3, v154
	v_lshl_add_u64 v[142:143], v[238:239], 0, s[46:47]
	s_mov_b32 m0, s3
	v_readfirstlane_b32 s3, v156
	global_load_lds_dwordx4 v[142:143], off
	v_lshl_add_u64 v[142:143], v[240:241], 0, s[46:47]
	s_mov_b32 m0, s3
	s_nop 0
	global_load_lds_dwordx4 v[142:143], off
	s_waitcnt vmcnt(6)
	s_barrier
	v_mfma_f32_16x16x32_bf16 v[28:31], v[216:219], v[182:185], v[28:31]
	v_mfma_f32_16x16x32_bf16 v[24:27], v[230:233], v[182:185], v[24:27]
	v_mfma_f32_16x16x32_bf16 v[20:23], v[216:219], v[190:193], v[20:23]
	v_mfma_f32_16x16x32_bf16 v[16:19], v[230:233], v[190:193], v[16:19]
	v_mfma_f32_16x16x32_bf16 v[12:15], v[216:219], v[198:201], v[12:15]
	v_mfma_f32_16x16x32_bf16 v[8:11], v[230:233], v[198:201], v[8:11]
	v_mfma_f32_16x16x32_bf16 v[4:7], v[216:219], v[206:209], v[4:7]
	v_mfma_f32_16x16x32_bf16 v[0:3], v[230:233], v[206:209], v[0:3]
	v_mfma_f32_16x16x32_bf16 v[28:31], v[226:229], v[186:189], v[28:31]
	v_mfma_f32_16x16x32_bf16 v[24:27], v[234:237], v[186:189], v[24:27]
	v_mfma_f32_16x16x32_bf16 v[20:23], v[226:229], v[194:197], v[20:23]
	v_mfma_f32_16x16x32_bf16 v[16:19], v[234:237], v[194:197], v[16:19]
	v_mfma_f32_16x16x32_bf16 v[12:15], v[226:229], v[202:205], v[12:15]
	v_mfma_f32_16x16x32_bf16 v[8:11], v[234:237], v[202:205], v[8:11]
	v_mfma_f32_16x16x32_bf16 v[4:7], v[226:229], v[210:213], v[4:7]
	v_mfma_f32_16x16x32_bf16 v[0:3], v[234:237], v[210:213], v[0:3]
	s_barrier
	ds_read_b128 v[142:145], v155
	ds_read_b128 v[170:173], v155 offset:1024
	ds_read_b128 v[174:177], v155 offset:2048
	ds_read_b128 v[178:181], v155 offset:3072
	v_readfirstlane_b32 s3, v157
	v_lshl_add_u64 v[216:217], v[222:223], 0, s[48:49]
	s_mov_b32 m0, s3
	v_readfirstlane_b32 s3, v158
	ds_read_b128 v[182:185], v148 offset:32768
	ds_read_b128 v[190:193], v147 offset:32768
	ds_read_b128 v[198:201], v146 offset:32768
	ds_read_b128 v[206:209], v141 offset:32768
	global_load_lds_dwordx4 v[216:217], off
	v_lshl_add_u64 v[216:217], v[224:225], 0, s[48:49]
	s_mov_b32 m0, s3
	s_nop 0
	global_load_lds_dwordx4 v[216:217], off
	s_waitcnt lgkmcnt(4)
	s_barrier
	s_waitcnt lgkmcnt(0)
	ds_read_b128 v[186:189], v148 offset:33792
	ds_read_b128 v[194:197], v147 offset:33792
	ds_read_b128 v[202:205], v146 offset:33792
	ds_read_b128 v[210:213], v141 offset:33792
	v_mfma_f32_16x16x32_bf16 v[126:129], v[142:145], v[182:185], v[126:129]
	v_mfma_f32_16x16x32_bf16 v[122:125], v[174:177], v[182:185], v[122:125]
	v_mfma_f32_16x16x32_bf16 v[118:121], v[142:145], v[190:193], v[118:121]
	v_mfma_f32_16x16x32_bf16 v[114:117], v[174:177], v[190:193], v[114:117]
	v_mfma_f32_16x16x32_bf16 v[110:113], v[142:145], v[198:201], v[110:113]
	v_mfma_f32_16x16x32_bf16 v[106:109], v[174:177], v[198:201], v[106:109]
	v_mfma_f32_16x16x32_bf16 v[102:105], v[142:145], v[206:209], v[102:105]
	v_mfma_f32_16x16x32_bf16 v[98:101], v[174:177], v[206:209], v[98:101]
	s_waitcnt lgkmcnt(0)
	v_mfma_f32_16x16x32_bf16 v[126:129], v[170:173], v[186:189], v[126:129]
	v_mfma_f32_16x16x32_bf16 v[122:125], v[178:181], v[186:189], v[122:125]
	v_mfma_f32_16x16x32_bf16 v[118:121], v[170:173], v[194:197], v[118:121]
	v_mfma_f32_16x16x32_bf16 v[114:117], v[178:181], v[194:197], v[114:117]
	v_mfma_f32_16x16x32_bf16 v[110:113], v[170:173], v[202:205], v[110:113]
	v_mfma_f32_16x16x32_bf16 v[106:109], v[178:181], v[202:205], v[106:109]
	v_mfma_f32_16x16x32_bf16 v[102:105], v[170:173], v[210:213], v[102:105]
	v_mfma_f32_16x16x32_bf16 v[98:101], v[178:181], v[210:213], v[98:101]
	s_barrier
	v_readfirstlane_b32 s3, v159
	v_lshl_add_u64 v[242:243], v[238:239], 0, s[50:51]
	s_mov_b32 m0, s3
	v_readfirstlane_b32 s3, v160
	ds_read_b128 v[216:219], v151
	ds_read_b128 v[226:229], v151 offset:1024
	ds_read_b128 v[230:233], v151 offset:2048
	ds_read_b128 v[234:237], v151 offset:3072
	global_load_lds_dwordx4 v[242:243], off
	v_lshl_add_u64 v[242:243], v[240:241], 0, s[50:51]
	s_mov_b32 m0, s3
	s_nop 0
	global_load_lds_dwordx4 v[242:243], off
	s_barrier
	s_waitcnt lgkmcnt(0)
	v_mfma_f32_16x16x32_bf16 v[94:97], v[216:219], v[182:185], v[94:97]
	v_mfma_f32_16x16x32_bf16 v[90:93], v[230:233], v[182:185], v[90:93]
	v_mfma_f32_16x16x32_bf16 v[86:89], v[216:219], v[190:193], v[86:89]
	v_mfma_f32_16x16x32_bf16 v[82:85], v[230:233], v[190:193], v[82:85]
	v_mfma_f32_16x16x32_bf16 v[78:81], v[216:219], v[198:201], v[78:81]
	v_mfma_f32_16x16x32_bf16 v[74:77], v[230:233], v[198:201], v[74:77]
	v_mfma_f32_16x16x32_bf16 v[70:73], v[216:219], v[206:209], v[70:73]
	v_mfma_f32_16x16x32_bf16 v[66:69], v[230:233], v[206:209], v[66:69]
	v_mfma_f32_16x16x32_bf16 v[94:97], v[226:229], v[186:189], v[94:97]
	v_mfma_f32_16x16x32_bf16 v[90:93], v[234:237], v[186:189], v[90:93]
	v_mfma_f32_16x16x32_bf16 v[86:89], v[226:229], v[194:197], v[86:89]
	v_mfma_f32_16x16x32_bf16 v[82:85], v[234:237], v[194:197], v[82:85]
	v_mfma_f32_16x16x32_bf16 v[78:81], v[226:229], v[202:205], v[78:81]
	v_mfma_f32_16x16x32_bf16 v[74:77], v[234:237], v[202:205], v[74:77]
	v_mfma_f32_16x16x32_bf16 v[70:73], v[226:229], v[210:213], v[70:73]
	v_mfma_f32_16x16x32_bf16 v[66:69], v[234:237], v[210:213], v[66:69]
	v_readfirstlane_b32 s3, v161
	v_lshl_add_u64 v[222:223], v[222:223], 0, s[52:53]
	s_mov_b32 m0, s3
	v_readfirstlane_b32 s3, v162
	s_barrier
	ds_read_b128 v[182:185], v148 offset:49152
	ds_read_b128 v[190:193], v147 offset:49152
	ds_read_b128 v[198:201], v146 offset:49152
	ds_read_b128 v[206:209], v141 offset:49152
	global_load_lds_dwordx4 v[222:223], off
	v_lshl_add_u64 v[222:223], v[224:225], 0, s[52:53]
	s_mov_b32 m0, s3
	s_nop 0
	global_load_lds_dwordx4 v[222:223], off
	s_barrier
; #define STAGE_A(b, h, kt) { const u16* ap_ = A + (size_t)((h) * ahalf + (unsigned)(kt) * 64u); glds16(ap_ + ao0, l0 + SA_(b, h)); glds16(ap_ + ao1, l0 + SA_(b, h) + 8192); }
; #define STAGE_B(b, h, kt) { const u16* bp_ = ((h) ? B1 : B0) + (unsigned)(kt) * 64u; glds16(bp_ + bo0, l0 + SB_(b, h)); glds16(bp_ + bo1, l0 + SB_(b, h) + 8192); }
; #define LDA(dst, b, h) _Pragma("unroll") for (int m = 0; m < 4; ++m) _Pragma("unroll") for (int k = 0; k < 2; ++k) \
;     dst[m][k] = *(const bf16x8*)(lds + SA_(b, h) + lds_byte(wr * 64 + m * 16 + fr, k * 32 + fq * 8));
; #define LDB(dst, b, h) _Pragma("unroll") for (int n = 0; n < 2; ++n) _Pragma("unroll") for (int k = 0; k < 2; ++k) \
;     dst[n][k] = *(const bf16x8*)(lds + SB_(b, h) + lds_byte(wc * 32 + n * 16 + fr, k * 32 + fq * 8));
; #define MMA(ai, bj, At_, Bt_) { __builtin_amdgcn_s_setprio(1); \
;     _Pragma("unroll") for (int m = 0; m < 4; ++m) _Pragma("unroll") for (int n = 0; n < 2; ++n) _Pragma("unroll") for (int k = 0; k < 2; ++k) \
;       acc[ai][bj][m][n] = MFMA16(Bt_[n][k], At_[m][k], acc[ai][bj][m][n]); \
;     __builtin_amdgcn_s_setprio(0); }
; #define WAIT_V(n) asm volatile("s_waitcnt vmcnt(" #n ")" ::: "memory");
; #define WAIT_L(n) asm volatile("s_waitcnt lgkmcnt(" #n ")" ::: "memory");
; #define BAR __builtin_amdgcn_s_barrier();
; #define SCHED __builtin_amdgcn_sched_barrier(0);
; DI void gemm256(const u16* __restrict__ A, int lda, const u16* __restrict__ B0, const u16* __restrict__ B1, int ldb, int nt, acc_t& acc, char* lds) {
;     ...
;     BAR WAIT_L(0) MMA(1, 0, At, Bq0) BAR SCHED
;     STAGE_B(1, 1, t + 3)
;     WAIT_V(6) BAR MMA(1, 1, At, Bq1) BAR
;   }
;   { LDB(Bq0, 0, 0) LDA(At, 0, 0) STAGE_A(1, 1, nt - 1)
;     BAR WAIT_L(0) MMA(0, 0, At, Bq0) BAR
;     LDB(Bq1, 0, 1) BAR WAIT_L(0) MMA(0, 1, At, Bq1) BAR
	s_waitcnt lgkmcnt(0)
	ds_read_b128 v[186:189], v148 offset:50176
	ds_read_b128 v[194:197], v147 offset:50176
	ds_read_b128 v[202:205], v146 offset:50176
	ds_read_b128 v[210:213], v141 offset:50176
	v_mfma_f32_16x16x32_bf16 v[60:63], v[142:145], v[182:185], v[60:63]
	v_mfma_f32_16x16x32_bf16 v[56:59], v[174:177], v[182:185], v[56:59]
	v_mfma_f32_16x16x32_bf16 v[52:55], v[142:145], v[190:193], v[52:55]
	v_mfma_f32_16x16x32_bf16 v[48:51], v[174:177], v[190:193], v[48:51]
	v_mfma_f32_16x16x32_bf16 v[44:47], v[142:145], v[198:201], v[44:47]
	v_mfma_f32_16x16x32_bf16 v[40:43], v[174:177], v[198:201], v[40:43]
	v_mfma_f32_16x16x32_bf16 v[36:39], v[142:145], v[206:209], v[36:39]
	v_mfma_f32_16x16x32_bf16 v[32:35], v[174:177], v[206:209], v[32:35]
	s_waitcnt lgkmcnt(0)
	v_mfma_f32_16x16x32_bf16 v[60:63], v[170:173], v[186:189], v[60:63]
	v_mfma_f32_16x16x32_bf16 v[56:59], v[178:181], v[186:189], v[56:59]
	v_mfma_f32_16x16x32_bf16 v[52:55], v[170:173], v[194:197], v[52:55]
	v_mfma_f32_16x16x32_bf16 v[48:51], v[178:181], v[194:197], v[48:51]
	v_mfma_f32_16x16x32_bf16 v[44:47], v[170:173], v[202:205], v[44:47]
	v_mfma_f32_16x16x32_bf16 v[40:43], v[178:181], v[202:205], v[40:43]
	v_mfma_f32_16x16x32_bf16 v[36:39], v[170:173], v[210:213], v[36:39]
	v_mfma_f32_16x16x32_bf16 v[32:35], v[178:181], v[210:213], v[32:35]
	s_barrier
	v_readfirstlane_b32 s3, v163
	v_lshl_add_u64 v[142:143], v[238:239], 0, s[54:55]
	s_mov_b32 m0, s3
	v_readfirstlane_b32 s3, v164
	global_load_lds_dwordx4 v[142:143], off
	v_lshl_add_u64 v[142:143], v[240:241], 0, s[54:55]
	s_mov_b32 m0, s3
	s_nop 0
	global_load_lds_dwordx4 v[142:143], off
	s_waitcnt vmcnt(6)
	s_barrier
	v_mfma_f32_16x16x32_bf16 v[28:31], v[216:219], v[182:185], v[28:31]
	v_mfma_f32_16x16x32_bf16 v[24:27], v[230:233], v[182:185], v[24:27]
	v_mfma_f32_16x16x32_bf16 v[20:23], v[216:219], v[190:193], v[20:23]
	v_mfma_f32_16x16x32_bf16 v[16:19], v[230:233], v[190:193], v[16:19]
	v_mfma_f32_16x16x32_bf16 v[12:15], v[216:219], v[198:201], v[12:15]
	v_mfma_f32_16x16x32_bf16 v[8:11], v[230:233], v[198:201], v[8:11]
	v_mfma_f32_16x16x32_bf16 v[4:7], v[216:219], v[206:209], v[4:7]
	v_mfma_f32_16x16x32_bf16 v[0:3], v[230:233], v[206:209], v[0:3]
	v_mfma_f32_16x16x32_bf16 v[28:31], v[226:229], v[186:189], v[28:31]
	v_mfma_f32_16x16x32_bf16 v[24:27], v[234:237], v[186:189], v[24:27]
	v_mfma_f32_16x16x32_bf16 v[20:23], v[226:229], v[194:197], v[20:23]
	v_mfma_f32_16x16x32_bf16 v[16:19], v[234:237], v[194:197], v[16:19]
	v_mfma_f32_16x16x32_bf16 v[12:15], v[226:229], v[202:205], v[12:15]
	v_mfma_f32_16x16x32_bf16 v[8:11], v[234:237], v[202:205], v[8:11]
	v_mfma_f32_16x16x32_bf16 v[4:7], v[226:229], v[210:213], v[4:7]
	v_mfma_f32_16x16x32_bf16 v[0:3], v[234:237], v[210:213], v[0:3]
	s_add_i32 s2, s2, 2
	s_add_u32 s8, s8, 0x100
	s_addc_u32 s9, s9, 0
	s_cmp_lt_u32 s2, 4
	s_barrier
	s_cbranch_scc1 .LBB0_991
	s_add_u32 s2, s44, 0x40780
	s_addc_u32 s3, s45, 0
	v_readfirstlane_b32 s7, v167
	v_lshl_add_u64 v[152:153], v[64:65], 1, s[2:3]
	s_mov_b32 m0, s7
	v_lshl_add_u64 v[130:131], v[130:131], 1, s[2:3]
	v_readfirstlane_b32 s2, v168
	ds_read_b128 v[132:135], v166
	ds_read_b128 v[136:139], v166 offset:1024
	ds_read_b128 v[142:145], v166 offset:2048
	ds_read_b128 v[156:159], v166 offset:3072
	ds_read_b128 v[160:163], v148
	ds_read_b128 v[170:173], v148 offset:1024
	ds_read_b128 v[174:177], v147
	ds_read_b128 v[178:181], v147 offset:1024
	ds_read_b128 v[182:185], v146
	ds_read_b128 v[186:189], v146 offset:1024
	ds_read_b128 v[190:193], v141
	ds_read_b128 v[194:197], v141 offset:1024
	global_load_lds_dwordx4 v[152:153], off
	s_mov_b32 m0, s2
	s_nop 0
	global_load_lds_dwordx4 v[130:131], off
	s_barrier
	s_waitcnt lgkmcnt(0)
	v_mfma_f32_16x16x32_bf16 v[126:129], v[132:135], v[160:163], v[126:129]
	v_mfma_f32_16x16x32_bf16 v[122:125], v[142:145], v[160:163], v[122:125]
	v_mfma_f32_16x16x32_bf16 v[118:121], v[132:135], v[174:177], v[118:121]
	v_mfma_f32_16x16x32_bf16 v[114:117], v[142:145], v[174:177], v[114:117]
	v_mfma_f32_16x16x32_bf16 v[102:105], v[132:135], v[190:193], v[102:105]
	v_mfma_f32_16x16x32_bf16 v[98:101], v[142:145], v[190:193], v[98:101]
	v_mfma_f32_16x16x32_bf16 v[126:129], v[136:139], v[170:173], v[126:129]
	v_mfma_f32_16x16x32_bf16 v[122:125], v[156:159], v[170:173], v[122:125]
	v_mfma_f32_16x16x32_bf16 v[118:121], v[136:139], v[178:181], v[118:121]
	v_mfma_f32_16x16x32_bf16 v[114:117], v[156:159], v[178:181], v[114:117]
	v_mfma_f32_16x16x32_bf16 v[110:113], v[132:135], v[182:185], v[110:113]
	v_mfma_f32_16x16x32_bf16 v[106:109], v[142:145], v[182:185], v[106:109]
	v_mfma_f32_16x16x32_bf16 v[102:105], v[136:139], v[194:197], v[102:105]
	v_mfma_f32_16x16x32_bf16 v[98:101], v[156:159], v[194:197], v[98:101]
	v_mfma_f32_16x16x32_bf16 v[166:169], v[136:139], v[186:189], v[110:113]
	v_mfma_f32_16x16x32_bf16 v[198:201], v[156:159], v[186:189], v[106:109]
	s_barrier
	s_nop 1
	ds_read_b128 v[106:109], v165
	ds_read_b128 v[110:113], v165 offset:1024
	ds_read_b128 v[202:205], v165 offset:2048
	ds_read_b128 v[206:209], v165 offset:3072
	s_barrier
	s_waitcnt lgkmcnt(0)
	v_mfma_f32_16x16x32_bf16 v[86:89], v[106:109], v[174:177], v[86:89]
	v_mfma_f32_16x16x32_bf16 v[82:85], v[202:205], v[174:177], v[82:85]
	v_mfma_f32_16x16x32_bf16 v[70:73], v[106:109], v[190:193], v[70:73]
	v_mfma_f32_16x16x32_bf16 v[66:69], v[202:205], v[190:193], v[66:69]
	v_mfma_f32_16x16x32_bf16 v[94:97], v[106:109], v[160:163], v[94:97]
	v_mfma_f32_16x16x32_bf16 v[90:93], v[202:205], v[160:163], v[90:93]
	v_mfma_f32_16x16x32_bf16 v[86:89], v[110:113], v[178:181], v[86:89]
	v_mfma_f32_16x16x32_bf16 v[82:85], v[206:209], v[178:181], v[82:85]
	v_mfma_f32_16x16x32_bf16 v[78:81], v[106:109], v[182:185], v[78:81]
	v_mfma_f32_16x16x32_bf16 v[74:77], v[202:205], v[182:185], v[74:77]
	v_mfma_f32_16x16x32_bf16 v[70:73], v[110:113], v[194:197], v[70:73]
	v_mfma_f32_16x16x32_bf16 v[66:69], v[206:209], v[194:197], v[66:69]
	v_mfma_f32_16x16x32_bf16 v[210:213], v[110:113], v[170:173], v[94:97]
	v_mfma_f32_16x16x32_bf16 v[160:163], v[206:209], v[170:173], v[90:93]
	v_mfma_f32_16x16x32_bf16 v[170:173], v[110:113], v[186:189], v[78:81]
	v_mfma_f32_16x16x32_bf16 v[174:177], v[206:209], v[186:189], v[74:77]
	s_barrier
; #define LDA(dst, b, h) _Pragma("unroll") for (int m = 0; m < 4; ++m) _Pragma("unroll") for (int k = 0; k < 2; ++k) \
;     dst[m][k] = *(const bf16x8*)(lds + SA_(b, h) + lds_byte(wr * 64 + m * 16 + fr, k * 32 + fq * 8));
; #define LDB(dst, b, h) _Pragma("unroll") for (int n = 0; n < 2; ++n) _Pragma("unroll") for (int k = 0; k < 2; ++k) \
;     dst[n][k] = *(const bf16x8*)(lds + SB_(b, h) + lds_byte(wc * 32 + n * 16 + fr, k * 32 + fq * 8));
; #define MMA(ai, bj, At_, Bt_) { __builtin_amdgcn_s_setprio(1); \
;     _Pragma("unroll") for (int m = 0; m < 4; ++m) _Pragma("unroll") for (int n = 0; n < 2; ++n) _Pragma("unroll") for (int k = 0; k < 2; ++k) \
;       acc[ai][bj][m][n] = MFMA16(Bt_[n][k], At_[m][k], acc[ai][bj][m][n]); \
;     __builtin_amdgcn_s_setprio(0); }
; #define WAIT_V(n) asm volatile("s_waitcnt vmcnt(" #n ")" ::: "memory");
; #define WAIT_L(n) asm volatile("s_waitcnt lgkmcnt(" #n ")" ::: "memory");
; #define BAR __builtin_amdgcn_s_barrier();
; DI void gemm256(const u16* __restrict__ A, int lda, const u16* __restrict__ B0, const u16* __restrict__ B1, int ldb, int nt, acc_t& acc, char* lds) {
;     ...
;     LDA(At, 0, 1) WAIT_V(4) BAR WAIT_L(0) MMA(1, 0, At, Bq0) MMA(1, 1, At, Bq1) BAR }
;   { LDB(Bq0, 1, 0) LDA(At, 1, 0) WAIT_V(2) BAR WAIT_L(0) MMA(0, 0, At, Bq0) BAR
	s_nop 0
	ds_read_b128 v[74:77], v148 offset:16384
	ds_read_b128 v[78:81], v148 offset:17408
	ds_read_b128 v[90:93], v147 offset:16384
	ds_read_b128 v[94:97], v147 offset:17408
	ds_read_b128 v[178:181], v146 offset:16384
	ds_read_b128 v[182:185], v146 offset:17408
	ds_read_b128 v[186:189], v141 offset:16384
	ds_read_b128 v[190:193], v141 offset:17408
	s_waitcnt vmcnt(4)
	s_barrier
	s_waitcnt lgkmcnt(0)
	v_mfma_f32_16x16x32_bf16 v[60:63], v[132:135], v[74:77], v[60:63]
	v_mfma_f32_16x16x32_bf16 v[56:59], v[142:145], v[74:77], v[56:59]
	v_mfma_f32_16x16x32_bf16 v[52:55], v[132:135], v[90:93], v[52:55]
	v_mfma_f32_16x16x32_bf16 v[48:51], v[142:145], v[90:93], v[48:51]
	v_mfma_f32_16x16x32_bf16 v[36:39], v[132:135], v[186:189], v[36:39]
	v_mfma_f32_16x16x32_bf16 v[32:35], v[142:145], v[186:189], v[32:35]
	v_mfma_f32_16x16x32_bf16 v[60:63], v[136:139], v[78:81], v[60:63]
	v_mfma_f32_16x16x32_bf16 v[56:59], v[156:159], v[78:81], v[56:59]
	v_mfma_f32_16x16x32_bf16 v[52:55], v[136:139], v[94:97], v[52:55]
	v_mfma_f32_16x16x32_bf16 v[48:51], v[156:159], v[94:97], v[48:51]
	v_mfma_f32_16x16x32_bf16 v[44:47], v[132:135], v[178:181], v[44:47]
	v_mfma_f32_16x16x32_bf16 v[40:43], v[142:145], v[178:181], v[40:43]
	v_mfma_f32_16x16x32_bf16 v[36:39], v[136:139], v[190:193], v[36:39]
	v_mfma_f32_16x16x32_bf16 v[32:35], v[156:159], v[190:193], v[32:35]
	v_mfma_f32_16x16x32_bf16 v[194:197], v[136:139], v[182:185], v[44:47]
	v_mfma_f32_16x16x32_bf16 v[216:219], v[156:159], v[182:185], v[40:43]
	v_mfma_f32_16x16x32_bf16 v[20:23], v[106:109], v[90:93], v[20:23]
	v_mfma_f32_16x16x32_bf16 v[16:19], v[202:205], v[90:93], v[16:19]
	v_mfma_f32_16x16x32_bf16 v[4:7], v[106:109], v[186:189], v[4:7]
	v_mfma_f32_16x16x32_bf16 v[0:3], v[202:205], v[186:189], v[0:3]
	v_mfma_f32_16x16x32_bf16 v[28:31], v[106:109], v[74:77], v[28:31]
	v_mfma_f32_16x16x32_bf16 v[24:27], v[202:205], v[74:77], v[24:27]
	v_mfma_f32_16x16x32_bf16 v[20:23], v[110:113], v[94:97], v[20:23]
	v_mfma_f32_16x16x32_bf16 v[16:19], v[206:209], v[94:97], v[16:19]
	v_mfma_f32_16x16x32_bf16 v[12:15], v[106:109], v[178:181], v[12:15]
	v_mfma_f32_16x16x32_bf16 v[8:11], v[202:205], v[178:181], v[8:11]
	v_mfma_f32_16x16x32_bf16 v[4:7], v[110:113], v[190:193], v[4:7]
	v_mfma_f32_16x16x32_bf16 v[0:3], v[206:209], v[190:193], v[0:3]
	v_mfma_f32_16x16x32_bf16 v[130:133], v[110:113], v[78:81], v[28:31]
	v_mfma_f32_16x16x32_bf16 v[134:137], v[206:209], v[78:81], v[24:27]
	v_mfma_f32_16x16x32_bf16 v[142:145], v[110:113], v[182:185], v[12:15]
	v_mfma_f32_16x16x32_bf16 v[156:159], v[206:209], v[182:185], v[8:11]
	s_barrier
	s_nop 0
	ds_read_b128 v[8:11], v155
	ds_read_b128 v[12:15], v155 offset:1024
	ds_read_b128 v[178:181], v155 offset:2048
	ds_read_b128 v[152:155], v155 offset:3072
	ds_read_b128 v[24:27], v148 offset:32768
	ds_read_b128 v[28:31], v148 offset:33792
	ds_read_b128 v[40:43], v147 offset:32768
	ds_read_b128 v[44:47], v147 offset:33792
	ds_read_b128 v[182:185], v146 offset:32768
	ds_read_b128 v[186:189], v146 offset:33792
	ds_read_b128 v[190:193], v141 offset:32768
	ds_read_b128 v[202:205], v141 offset:33792
	s_waitcnt vmcnt(2)
	s_barrier
	s_waitcnt lgkmcnt(0)
	v_mfma_f32_16x16x32_bf16 v[74:77], v[8:11], v[24:27], v[126:129]
	v_mfma_f32_16x16x32_bf16 v[126:129], v[12:15], v[28:31], v[74:77]
	v_mfma_f32_16x16x32_bf16 v[74:77], v[178:181], v[24:27], v[122:125]
	v_mfma_f32_16x16x32_bf16 v[122:125], v[152:155], v[28:31], v[74:77]
	v_mfma_f32_16x16x32_bf16 v[74:77], v[8:11], v[40:43], v[118:121]
	v_mfma_f32_16x16x32_bf16 v[110:113], v[12:15], v[44:47], v[74:77]
	v_mfma_f32_16x16x32_bf16 v[74:77], v[178:181], v[40:43], v[114:117]
	v_mfma_f32_16x16x32_bf16 v[106:109], v[152:155], v[44:47], v[74:77]
	v_mfma_f32_16x16x32_bf16 v[74:77], v[8:11], v[182:185], v[166:169]
	v_mfma_f32_16x16x32_bf16 v[94:97], v[12:15], v[186:189], v[74:77]
	v_mfma_f32_16x16x32_bf16 v[74:77], v[178:181], v[182:185], v[198:201]
	v_mfma_f32_16x16x32_bf16 v[90:93], v[152:155], v[186:189], v[74:77]
	v_mfma_f32_16x16x32_bf16 v[74:77], v[8:11], v[190:193], v[102:105]
	v_mfma_f32_16x16x32_bf16 v[78:81], v[12:15], v[202:205], v[74:77]
	v_mfma_f32_16x16x32_bf16 v[74:77], v[178:181], v[190:193], v[98:101]
	v_mfma_f32_16x16x32_bf16 v[74:77], v[152:155], v[202:205], v[74:77]
	s_barrier
; #define LDA(dst, b, h) _Pragma("unroll") for (int m = 0; m < 4; ++m) _Pragma("unroll") for (int k = 0; k < 2; ++k) \
;     dst[m][k] = *(const bf16x8*)(lds + SA_(b, h) + lds_byte(wr * 64 + m * 16 + fr, k * 32 + fq * 8));
; #define LDB(dst, b, h) _Pragma("unroll") for (int n = 0; n < 2; ++n) _Pragma("unroll") for (int k = 0; k < 2; ++k) \
;     dst[n][k] = *(const bf16x8*)(lds + SB_(b, h) + lds_byte(wc * 32 + n * 16 + fr, k * 32 + fq * 8));
; #define MMA(ai, bj, At_, Bt_) { __builtin_amdgcn_s_setprio(1); \
;     _Pragma("unroll") for (int m = 0; m < 4; ++m) _Pragma("unroll") for (int n = 0; n < 2; ++n) _Pragma("unroll") for (int k = 0; k < 2; ++k) \
;       acc[ai][bj][m][n] = MFMA16(Bt_[n][k], At_[m][k], acc[ai][bj][m][n]); \
;     __builtin_amdgcn_s_setprio(0); }
; #define WAIT_V(n) asm volatile("s_waitcnt vmcnt(" #n ")" ::: "memory");
; #define WAIT_L(n) asm volatile("s_waitcnt lgkmcnt(" #n ")" ::: "memory");
; #define BAR __builtin_amdgcn_s_barrier();
; DI void gemm256(const u16* __restrict__ A, int lda, const u16* __restrict__ B0, const u16* __restrict__ B1, int ldb, int nt, acc_t& acc, char* lds) {
;     ...
;   { LDB(Bq0, 1, 0) LDA(At, 1, 0) WAIT_V(2) BAR WAIT_L(0) MMA(0, 0, At, Bq0) BAR
;     LDB(Bq1, 1, 1) WAIT_V(0) BAR WAIT_L(0) MMA(0, 1, At, Bq1) BAR
;     LDA(At, 1, 1) BAR WAIT_L(0) MMA(1, 0, At, Bq0) MMA(1, 1, At, Bq1) BAR }
;   if (wr == 0) BAR
;   __syncthreads();
	ds_read_b128 v[164:167], v151
	ds_read_b128 v[198:201], v151 offset:1024
	ds_read_b128 v[206:209], v151 offset:2048
	ds_read_b128 v[226:229], v151 offset:3072
	s_waitcnt vmcnt(0)
	s_barrier
	s_waitcnt lgkmcnt(0)
	v_mfma_f32_16x16x32_bf16 v[98:101], v[164:167], v[24:27], v[210:213]
	v_mfma_f32_16x16x32_bf16 v[24:27], v[206:209], v[24:27], v[160:163]
	v_mfma_f32_16x16x32_bf16 v[114:117], v[226:229], v[28:31], v[24:27]
	v_mfma_f32_16x16x32_bf16 v[24:27], v[164:167], v[40:43], v[86:89]
	v_mfma_f32_16x16x32_bf16 v[102:105], v[198:201], v[44:47], v[24:27]
	v_mfma_f32_16x16x32_bf16 v[24:27], v[206:209], v[40:43], v[82:85]
	v_mfma_f32_16x16x32_bf16 v[118:121], v[198:201], v[28:31], v[98:101]
	v_mfma_f32_16x16x32_bf16 v[98:101], v[226:229], v[44:47], v[24:27]
	v_mfma_f32_16x16x32_bf16 v[24:27], v[164:167], v[182:185], v[170:173]
	v_mfma_f32_16x16x32_bf16 v[86:89], v[198:201], v[186:189], v[24:27]
	v_mfma_f32_16x16x32_bf16 v[24:27], v[206:209], v[182:185], v[174:177]
	v_mfma_f32_16x16x32_bf16 v[82:85], v[226:229], v[186:189], v[24:27]
	v_mfma_f32_16x16x32_bf16 v[24:27], v[164:167], v[190:193], v[70:73]
	v_mfma_f32_16x16x32_bf16 v[70:73], v[198:201], v[202:205], v[24:27]
	v_mfma_f32_16x16x32_bf16 v[24:27], v[206:209], v[190:193], v[66:69]
	v_mfma_f32_16x16x32_bf16 v[66:69], v[226:229], v[202:205], v[24:27]
	s_barrier
	ds_read_b128 v[160:163], v148 offset:49152
	ds_read_b128 v[148:151], v148 offset:50176
	ds_read_b128 v[168:171], v147 offset:49152
	ds_read_b128 v[172:175], v147 offset:50176
	ds_read_b128 v[182:185], v146 offset:49152
	ds_read_b128 v[186:189], v146 offset:50176
	ds_read_b128 v[190:193], v141 offset:49152
	ds_read_b128 v[202:205], v141 offset:50176
	s_barrier
	s_waitcnt lgkmcnt(0)
	v_mfma_f32_16x16x32_bf16 v[24:27], v[8:11], v[160:163], v[60:63]
	v_mfma_f32_16x16x32_bf16 v[60:63], v[12:15], v[148:151], v[24:27]
	v_mfma_f32_16x16x32_bf16 v[24:27], v[178:181], v[160:163], v[56:59]
	v_mfma_f32_16x16x32_bf16 v[56:59], v[152:155], v[148:151], v[24:27]
	v_mfma_f32_16x16x32_bf16 v[24:27], v[8:11], v[168:171], v[52:55]
	v_mfma_f32_16x16x32_bf16 v[44:47], v[12:15], v[172:175], v[24:27]
	v_mfma_f32_16x16x32_bf16 v[24:27], v[178:181], v[168:171], v[48:51]
	v_mfma_f32_16x16x32_bf16 v[40:43], v[152:155], v[172:175], v[24:27]
	v_mfma_f32_16x16x32_bf16 v[24:27], v[8:11], v[182:185], v[194:197]
	v_mfma_f32_16x16x32_bf16 v[8:11], v[8:11], v[190:193], v[36:39]
	v_mfma_f32_16x16x32_bf16 v[28:31], v[12:15], v[186:189], v[24:27]
	v_mfma_f32_16x16x32_bf16 v[24:27], v[178:181], v[182:185], v[216:219]
	v_mfma_f32_16x16x32_bf16 v[12:15], v[12:15], v[202:205], v[8:11]
	v_mfma_f32_16x16x32_bf16 v[8:11], v[178:181], v[190:193], v[32:35]
	v_mfma_f32_16x16x32_bf16 v[24:27], v[152:155], v[186:189], v[24:27]
	v_mfma_f32_16x16x32_bf16 v[8:11], v[152:155], v[202:205], v[8:11]
	v_mfma_f32_16x16x32_bf16 v[32:35], v[164:167], v[160:163], v[130:133]
	v_mfma_f32_16x16x32_bf16 v[52:55], v[198:201], v[148:151], v[32:35]
	v_mfma_f32_16x16x32_bf16 v[32:35], v[206:209], v[160:163], v[134:137]
	v_mfma_f32_16x16x32_bf16 v[16:19], v[206:209], v[168:171], v[16:19]
	v_mfma_f32_16x16x32_bf16 v[48:51], v[226:229], v[148:151], v[32:35]
	v_mfma_f32_16x16x32_bf16 v[20:23], v[164:167], v[168:171], v[20:23]
	v_mfma_f32_16x16x32_bf16 v[32:35], v[226:229], v[172:175], v[16:19]
	v_mfma_f32_16x16x32_bf16 v[16:19], v[164:167], v[182:185], v[142:145]
	v_mfma_f32_16x16x32_bf16 v[36:39], v[198:201], v[172:175], v[20:23]
	v_mfma_f32_16x16x32_bf16 v[20:23], v[198:201], v[186:189], v[16:19]
	v_mfma_f32_16x16x32_bf16 v[16:19], v[206:209], v[182:185], v[156:159]
	v_mfma_f32_16x16x32_bf16 v[4:7], v[164:167], v[190:193], v[4:7]
	v_mfma_f32_16x16x32_bf16 v[0:3], v[206:209], v[190:193], v[0:3]
	v_mfma_f32_16x16x32_bf16 v[16:19], v[226:229], v[186:189], v[16:19]
	v_mfma_f32_16x16x32_bf16 v[4:7], v[198:201], v[202:205], v[4:7]
	v_mfma_f32_16x16x32_bf16 v[0:3], v[226:229], v[202:205], v[0:3]
	s_movk_i32 s2, 0x100
	v_cmp_gt_u32_e32 vcc, s2, v140
	s_barrier
	s_and_saveexec_b64 s[8:9], vcc
	s_cbranch_execz .LBB0_969
	s_barrier
	s_branch .LBB0_969

; #define STAGE_A(b, h, kt) { const u16* ap_ = A + (size_t)((h) * ahalf + (unsigned)(kt) * 64u); glds16(ap_ + ao0, l0 + SA_(b, h)); glds16(ap_ + ao1, l0 + SA_(b, h) + 8192); }
; #define STAGE_B(b, h, kt) { const u16* bp_ = ((h) ? B1 : B0) + (unsigned)(kt) * 64u; glds16(bp_ + bo0, l0 + SB_(b, h)); glds16(bp_ + bo1, l0 + SB_(b, h) + 8192); }
; #define LDA(dst, b, h) _Pragma("unroll") for (int m = 0; m < 4; ++m) _Pragma("unroll") for (int k = 0; k < 2; ++k) \
;     dst[m][k] = *(const bf16x8*)(lds + SA_(b, h) + lds_byte(wr * 64 + m * 16 + fr, k * 32 + fq * 8));
; #define LDB(dst, b, h) _Pragma("unroll") for (int n = 0; n < 2; ++n) _Pragma("unroll") for (int k = 0; k < 2; ++k) \
;     dst[n][k] = *(const bf16x8*)(lds + SB_(b, h) + lds_byte(wc * 32 + n * 16 + fr, k * 32 + fq * 8));
; #define MMA(ai, bj, At_, Bt_) { __builtin_amdgcn_s_setprio(1); \
;     _Pragma("unroll") for (int m = 0; m < 4; ++m) _Pragma("unroll") for (int n = 0; n < 2; ++n) _Pragma("unroll") for (int k = 0; k < 2; ++k) \
;       acc[ai][bj][m][n] = MFMA16(Bt_[n][k], At_[m][k], acc[ai][bj][m][n]); \
;     __builtin_amdgcn_s_setprio(0); }
; #define WAIT_L(n) asm volatile("s_waitcnt lgkmcnt(" #n ")" ::: "memory");
; #define BAR __builtin_amdgcn_s_barrier();
; #define SCHED __builtin_amdgcn_sched_barrier(0);
; DI void gemm256(const u16* __restrict__ A, int lda, const u16* __restrict__ B0, const u16* __restrict__ B1, int ldb, int nt, acc_t& acc, char* lds) {
;     ...
;   for (int t = 0; t < nt - 2; t += 2) {
;     LDB(Bq0, 0, 0) SCHED LDA(At, 0, 0) STAGE_A(1, 1, t + 1)
;     WAIT_L(8) BAR WAIT_L(0) MMA(0, 0, At, Bq0) BAR SCHED
;     LDB(Bq1, 0, 1) STAGE_B(0, 0, t + 2)
;     BAR WAIT_L(0) MMA(0, 1, At, Bq1) BAR
;     LDA(At, 0, 1) STAGE_A(0, 0, t + 2)
;     BAR WAIT_L(0) MMA(1, 0, At, Bq0) BAR SCHED
.LBB0_1053:
	ds_read_b128 v[142:145], v166
	ds_read_b128 v[170:173], v166 offset:1024
	ds_read_b128 v[174:177], v166 offset:2048
	ds_read_b128 v[178:181], v166 offset:3072
	v_lshl_add_u64 v[222:223], s[36:37], 0, v[136:137]
	v_readfirstlane_b32 s7, v167
	v_lshl_add_u64 v[168:169], v[222:223], 0, s[38:39]
	s_mov_b32 m0, s7
	ds_read_b128 v[182:185], v148
	ds_read_b128 v[190:193], v147
	ds_read_b128 v[198:201], v146
	ds_read_b128 v[206:209], v141
	global_load_lds_dwordx4 v[168:169], off
	v_add_u32_e32 v168, 0xe000, v149
	v_lshl_add_u64 v[224:225], s[36:37], 0, v[138:139]
	v_readfirstlane_b32 s7, v168
	v_lshl_add_u64 v[216:217], v[224:225], 0, s[38:39]
	s_mov_b32 m0, s7
	s_nop 0
	global_load_lds_dwordx4 v[216:217], off
	s_waitcnt lgkmcnt(4)
	s_barrier
	s_waitcnt lgkmcnt(0)
	ds_read_b128 v[186:189], v148 offset:1024
	ds_read_b128 v[194:197], v147 offset:1024
	ds_read_b128 v[202:205], v146 offset:1024
	ds_read_b128 v[210:213], v141 offset:1024
	v_mfma_f32_16x16x32_bf16 v[126:129], v[142:145], v[182:185], v[126:129]
	v_mfma_f32_16x16x32_bf16 v[122:125], v[174:177], v[182:185], v[122:125]
	v_mfma_f32_16x16x32_bf16 v[118:121], v[142:145], v[190:193], v[118:121]
	v_mfma_f32_16x16x32_bf16 v[114:117], v[174:177], v[190:193], v[114:117]
	v_mfma_f32_16x16x32_bf16 v[110:113], v[142:145], v[198:201], v[110:113]
	v_mfma_f32_16x16x32_bf16 v[106:109], v[174:177], v[198:201], v[106:109]
	v_mfma_f32_16x16x32_bf16 v[102:105], v[142:145], v[206:209], v[102:105]
	v_mfma_f32_16x16x32_bf16 v[98:101], v[174:177], v[206:209], v[98:101]
	s_waitcnt lgkmcnt(0)
	v_mfma_f32_16x16x32_bf16 v[126:129], v[170:173], v[186:189], v[126:129]
	v_mfma_f32_16x16x32_bf16 v[122:125], v[178:181], v[186:189], v[122:125]
	v_mfma_f32_16x16x32_bf16 v[118:121], v[170:173], v[194:197], v[118:121]
	v_mfma_f32_16x16x32_bf16 v[114:117], v[178:181], v[194:197], v[114:117]
	v_mfma_f32_16x16x32_bf16 v[110:113], v[170:173], v[202:205], v[110:113]
	v_mfma_f32_16x16x32_bf16 v[106:109], v[178:181], v[202:205], v[106:109]
	v_mfma_f32_16x16x32_bf16 v[102:105], v[170:173], v[210:213], v[102:105]
	v_mfma_f32_16x16x32_bf16 v[98:101], v[178:181], v[210:213], v[98:101]
	s_barrier
	v_lshl_add_u64 v[238:239], s[36:37], 0, v[132:133]
	v_readfirstlane_b32 s7, v150
	v_lshl_add_u64 v[240:241], v[238:239], 0, s[40:41]
	s_mov_b32 m0, s7
	ds_read_b128 v[216:219], v165
	ds_read_b128 v[226:229], v165 offset:1024
	ds_read_b128 v[230:233], v165 offset:2048
	ds_read_b128 v[234:237], v165 offset:3072
	global_load_lds_dwordx4 v[240:241], off
	v_lshl_add_u64 v[240:241], s[36:37], 0, v[134:135]
	v_readfirstlane_b32 s7, v152
	v_lshl_add_u64 v[242:243], v[240:241], 0, s[40:41]
	s_mov_b32 m0, s7
	s_nop 0
	global_load_lds_dwordx4 v[242:243], off
	s_barrier
	s_waitcnt lgkmcnt(0)
	v_mfma_f32_16x16x32_bf16 v[94:97], v[216:219], v[182:185], v[94:97]
	v_mfma_f32_16x16x32_bf16 v[90:93], v[230:233], v[182:185], v[90:93]
	v_mfma_f32_16x16x32_bf16 v[86:89], v[216:219], v[190:193], v[86:89]
	v_mfma_f32_16x16x32_bf16 v[82:85], v[230:233], v[190:193], v[82:85]
	v_mfma_f32_16x16x32_bf16 v[78:81], v[216:219], v[198:201], v[78:81]
	v_mfma_f32_16x16x32_bf16 v[74:77], v[230:233], v[198:201], v[74:77]
	v_mfma_f32_16x16x32_bf16 v[70:73], v[216:219], v[206:209], v[70:73]
	v_mfma_f32_16x16x32_bf16 v[66:69], v[230:233], v[206:209], v[66:69]
	v_mfma_f32_16x16x32_bf16 v[94:97], v[226:229], v[186:189], v[94:97]
	v_mfma_f32_16x16x32_bf16 v[90:93], v[234:237], v[186:189], v[90:93]
	v_mfma_f32_16x16x32_bf16 v[86:89], v[226:229], v[194:197], v[86:89]
	v_mfma_f32_16x16x32_bf16 v[82:85], v[234:237], v[194:197], v[82:85]
	v_mfma_f32_16x16x32_bf16 v[78:81], v[226:229], v[202:205], v[78:81]
	v_mfma_f32_16x16x32_bf16 v[74:77], v[234:237], v[202:205], v[74:77]
	v_mfma_f32_16x16x32_bf16 v[70:73], v[226:229], v[210:213], v[70:73]
	v_mfma_f32_16x16x32_bf16 v[66:69], v[234:237], v[210:213], v[66:69]
	v_readfirstlane_b32 s7, v149
	v_lshl_add_u64 v[242:243], v[222:223], 0, s[70:71]
	s_mov_b32 m0, s7
	v_readfirstlane_b32 s7, v153
	s_barrier
	ds_read_b128 v[182:185], v148 offset:16384
	ds_read_b128 v[190:193], v147 offset:16384
	ds_read_b128 v[198:201], v146 offset:16384
	ds_read_b128 v[206:209], v141 offset:16384
	global_load_lds_dwordx4 v[242:243], off
	v_lshl_add_u64 v[242:243], v[224:225], 0, s[70:71]
	s_mov_b32 m0, s7
	s_nop 0
	global_load_lds_dwordx4 v[242:243], off
	s_barrier
	s_waitcnt lgkmcnt(0)
	ds_read_b128 v[186:189], v148 offset:17408
	ds_read_b128 v[194:197], v147 offset:17408
	ds_read_b128 v[202:205], v146 offset:17408
	ds_read_b128 v[210:213], v141 offset:17408
	v_mfma_f32_16x16x32_bf16 v[60:63], v[142:145], v[182:185], v[60:63]
	v_mfma_f32_16x16x32_bf16 v[56:59], v[174:177], v[182:185], v[56:59]
	v_mfma_f32_16x16x32_bf16 v[52:55], v[142:145], v[190:193], v[52:55]
	v_mfma_f32_16x16x32_bf16 v[48:51], v[174:177], v[190:193], v[48:51]
	v_mfma_f32_16x16x32_bf16 v[44:47], v[142:145], v[198:201], v[44:47]
	v_mfma_f32_16x16x32_bf16 v[40:43], v[174:177], v[198:201], v[40:43]
	v_mfma_f32_16x16x32_bf16 v[36:39], v[142:145], v[206:209], v[36:39]
	v_mfma_f32_16x16x32_bf16 v[32:35], v[174:177], v[206:209], v[32:35]
	s_waitcnt lgkmcnt(0)
	v_mfma_f32_16x16x32_bf16 v[60:63], v[170:173], v[186:189], v[60:63]
	v_mfma_f32_16x16x32_bf16 v[56:59], v[178:181], v[186:189], v[56:59]
	v_mfma_f32_16x16x32_bf16 v[52:55], v[170:173], v[194:197], v[52:55]
	v_mfma_f32_16x16x32_bf16 v[48:51], v[178:181], v[194:197], v[48:51]
	v_mfma_f32_16x16x32_bf16 v[44:47], v[170:173], v[202:205], v[44:47]
	v_mfma_f32_16x16x32_bf16 v[40:43], v[178:181], v[202:205], v[40:43]
	v_mfma_f32_16x16x32_bf16 v[36:39], v[170:173], v[210:213], v[36:39]
	v_mfma_f32_16x16x32_bf16 v[32:35], v[178:181], v[210:213], v[32:35]
	s_barrier
; #define STAGE_A(b, h, kt) { const u16* ap_ = A + (size_t)((h) * ahalf + (unsigned)(kt) * 64u); glds16(ap_ + ao0, l0 + SA_(b, h)); glds16(ap_ + ao1, l0 + SA_(b, h) + 8192); }
; #define STAGE_B(b, h, kt) { const u16* bp_ = ((h) ? B1 : B0) + (unsigned)(kt) * 64u; glds16(bp_ + bo0, l0 + SB_(b, h)); glds16(bp_ + bo1, l0 + SB_(b, h) + 8192); }
; #define LDA(dst, b, h) _Pragma("unroll") for (int m = 0; m < 4; ++m) _Pragma("unroll") for (int k = 0; k < 2; ++k) \
;     dst[m][k] = *(const bf16x8*)(lds + SA_(b, h) + lds_byte(wr * 64 + m * 16 + fr, k * 32 + fq * 8));
; #define LDB(dst, b, h) _Pragma("unroll") for (int n = 0; n < 2; ++n) _Pragma("unroll") for (int k = 0; k < 2; ++k) \
;     dst[n][k] = *(const bf16x8*)(lds + SB_(b, h) + lds_byte(wc * 32 + n * 16 + fr, k * 32 + fq * 8));
; #define MMA(ai, bj, At_, Bt_) { __builtin_amdgcn_s_setprio(1); \
;     _Pragma("unroll") for (int m = 0; m < 4; ++m) _Pragma("unroll") for (int n = 0; n < 2; ++n) _Pragma("unroll") for (int k = 0; k < 2; ++k) \
;       acc[ai][bj][m][n] = MFMA16(Bt_[n][k], At_[m][k], acc[ai][bj][m][n]); \
;     __builtin_amdgcn_s_setprio(0); }
; #define WAIT_V(n) asm volatile("s_waitcnt vmcnt(" #n ")" ::: "memory");
; #define WAIT_L(n) asm volatile("s_waitcnt lgkmcnt(" #n ")" ::: "memory");
; #define BAR __builtin_amdgcn_s_barrier();
; #define SCHED __builtin_amdgcn_sched_barrier(0);
; DI void gemm256(const u16* __restrict__ A, int lda, const u16* __restrict__ B0, const u16* __restrict__ B1, int ldb, int nt, acc_t& acc, char* lds) {
;     ...
;     BAR WAIT_L(0) MMA(1, 0, At, Bq0) BAR SCHED
;     STAGE_B(0, 1, t + 2)
;     WAIT_V(6) BAR MMA(1, 1, At, Bq1) BAR
;     LDB(Bq0, 1, 0) SCHED LDA(At, 1, 0) STAGE_A(0, 1, t + 2)
;     WAIT_L(8) BAR WAIT_L(0) MMA(0, 0, At, Bq0) BAR SCHED
;     LDB(Bq1, 1, 1) STAGE_B(1, 0, t + 3)
;     BAR WAIT_L(0) MMA(0, 1, At, Bq1) BAR
;     LDA(At, 1, 1) STAGE_A(1, 0, t + 3)
;     BAR WAIT_L(0) MMA(1, 0, At, Bq0) BAR SCHED
	v_readfirstlane_b32 s7, v154
	v_lshl_add_u64 v[142:143], v[238:239], 0, s[42:43]
	s_mov_b32 m0, s7
	v_readfirstlane_b32 s7, v155
	global_load_lds_dwordx4 v[142:143], off
	v_lshl_add_u64 v[142:143], v[240:241], 0, s[42:43]
	s_mov_b32 m0, s7
	s_nop 0
	global_load_lds_dwordx4 v[142:143], off
	s_waitcnt vmcnt(6)
	s_barrier
	v_mfma_f32_16x16x32_bf16 v[28:31], v[216:219], v[182:185], v[28:31]
	v_mfma_f32_16x16x32_bf16 v[24:27], v[230:233], v[182:185], v[24:27]
	v_mfma_f32_16x16x32_bf16 v[20:23], v[216:219], v[190:193], v[20:23]
	v_mfma_f32_16x16x32_bf16 v[16:19], v[230:233], v[190:193], v[16:19]
	v_mfma_f32_16x16x32_bf16 v[12:15], v[216:219], v[198:201], v[12:15]
	v_mfma_f32_16x16x32_bf16 v[8:11], v[230:233], v[198:201], v[8:11]
	v_mfma_f32_16x16x32_bf16 v[4:7], v[216:219], v[206:209], v[4:7]
	v_mfma_f32_16x16x32_bf16 v[0:3], v[230:233], v[206:209], v[0:3]
	v_mfma_f32_16x16x32_bf16 v[28:31], v[226:229], v[186:189], v[28:31]
	v_mfma_f32_16x16x32_bf16 v[24:27], v[234:237], v[186:189], v[24:27]
	v_mfma_f32_16x16x32_bf16 v[20:23], v[226:229], v[194:197], v[20:23]
	v_mfma_f32_16x16x32_bf16 v[16:19], v[234:237], v[194:197], v[16:19]
	v_mfma_f32_16x16x32_bf16 v[12:15], v[226:229], v[202:205], v[12:15]
	v_mfma_f32_16x16x32_bf16 v[8:11], v[234:237], v[202:205], v[8:11]
	v_mfma_f32_16x16x32_bf16 v[4:7], v[226:229], v[210:213], v[4:7]
	v_mfma_f32_16x16x32_bf16 v[0:3], v[234:237], v[210:213], v[0:3]
	s_barrier
	ds_read_b128 v[142:145], v156
	ds_read_b128 v[170:173], v156 offset:1024
	ds_read_b128 v[174:177], v156 offset:2048
	ds_read_b128 v[178:181], v156 offset:3072
	v_readfirstlane_b32 s7, v157
	v_lshl_add_u64 v[216:217], v[222:223], 0, s[44:45]
	s_mov_b32 m0, s7
	v_readfirstlane_b32 s7, v158
	ds_read_b128 v[182:185], v148 offset:32768
	ds_read_b128 v[190:193], v147 offset:32768
	ds_read_b128 v[198:201], v146 offset:32768
	ds_read_b128 v[206:209], v141 offset:32768
	global_load_lds_dwordx4 v[216:217], off
	v_lshl_add_u64 v[216:217], v[224:225], 0, s[44:45]
	s_mov_b32 m0, s7
	s_nop 0
	global_load_lds_dwordx4 v[216:217], off
	s_waitcnt lgkmcnt(4)
	s_barrier
	s_waitcnt lgkmcnt(0)
	ds_read_b128 v[186:189], v148 offset:33792
	ds_read_b128 v[194:197], v147 offset:33792
	ds_read_b128 v[202:205], v146 offset:33792
	ds_read_b128 v[210:213], v141 offset:33792
	v_mfma_f32_16x16x32_bf16 v[126:129], v[142:145], v[182:185], v[126:129]
	v_mfma_f32_16x16x32_bf16 v[122:125], v[174:177], v[182:185], v[122:125]
	v_mfma_f32_16x16x32_bf16 v[118:121], v[142:145], v[190:193], v[118:121]
	v_mfma_f32_16x16x32_bf16 v[114:117], v[174:177], v[190:193], v[114:117]
	v_mfma_f32_16x16x32_bf16 v[110:113], v[142:145], v[198:201], v[110:113]
	v_mfma_f32_16x16x32_bf16 v[106:109], v[174:177], v[198:201], v[106:109]
	v_mfma_f32_16x16x32_bf16 v[102:105], v[142:145], v[206:209], v[102:105]
	v_mfma_f32_16x16x32_bf16 v[98:101], v[174:177], v[206:209], v[98:101]
	s_waitcnt lgkmcnt(0)
	v_mfma_f32_16x16x32_bf16 v[126:129], v[170:173], v[186:189], v[126:129]
	v_mfma_f32_16x16x32_bf16 v[122:125], v[178:181], v[186:189], v[122:125]
	v_mfma_f32_16x16x32_bf16 v[118:121], v[170:173], v[194:197], v[118:121]
	v_mfma_f32_16x16x32_bf16 v[114:117], v[178:181], v[194:197], v[114:117]
	v_mfma_f32_16x16x32_bf16 v[110:113], v[170:173], v[202:205], v[110:113]
	v_mfma_f32_16x16x32_bf16 v[106:109], v[178:181], v[202:205], v[106:109]
	v_mfma_f32_16x16x32_bf16 v[102:105], v[170:173], v[210:213], v[102:105]
	v_mfma_f32_16x16x32_bf16 v[98:101], v[178:181], v[210:213], v[98:101]
	s_barrier
	v_readfirstlane_b32 s7, v159
	v_lshl_add_u64 v[242:243], v[238:239], 0, s[46:47]
	s_mov_b32 m0, s7
	v_readfirstlane_b32 s7, v160
	ds_read_b128 v[216:219], v151
	ds_read_b128 v[226:229], v151 offset:1024
	ds_read_b128 v[230:233], v151 offset:2048
	ds_read_b128 v[234:237], v151 offset:3072
	global_load_lds_dwordx4 v[242:243], off
	v_lshl_add_u64 v[242:243], v[240:241], 0, s[46:47]
	s_mov_b32 m0, s7
	s_nop 0
	global_load_lds_dwordx4 v[242:243], off
	s_barrier
	s_waitcnt lgkmcnt(0)
	v_mfma_f32_16x16x32_bf16 v[94:97], v[216:219], v[182:185], v[94:97]
	v_mfma_f32_16x16x32_bf16 v[90:93], v[230:233], v[182:185], v[90:93]
	v_mfma_f32_16x16x32_bf16 v[86:89], v[216:219], v[190:193], v[86:89]
	v_mfma_f32_16x16x32_bf16 v[82:85], v[230:233], v[190:193], v[82:85]
	v_mfma_f32_16x16x32_bf16 v[78:81], v[216:219], v[198:201], v[78:81]
	v_mfma_f32_16x16x32_bf16 v[74:77], v[230:233], v[198:201], v[74:77]
	v_mfma_f32_16x16x32_bf16 v[70:73], v[216:219], v[206:209], v[70:73]
	v_mfma_f32_16x16x32_bf16 v[66:69], v[230:233], v[206:209], v[66:69]
	v_mfma_f32_16x16x32_bf16 v[94:97], v[226:229], v[186:189], v[94:97]
	v_mfma_f32_16x16x32_bf16 v[90:93], v[234:237], v[186:189], v[90:93]
	v_mfma_f32_16x16x32_bf16 v[86:89], v[226:229], v[194:197], v[86:89]
	v_mfma_f32_16x16x32_bf16 v[82:85], v[234:237], v[194:197], v[82:85]
	v_mfma_f32_16x16x32_bf16 v[78:81], v[226:229], v[202:205], v[78:81]
	v_mfma_f32_16x16x32_bf16 v[74:77], v[234:237], v[202:205], v[74:77]
	v_mfma_f32_16x16x32_bf16 v[70:73], v[226:229], v[210:213], v[70:73]
	v_mfma_f32_16x16x32_bf16 v[66:69], v[234:237], v[210:213], v[66:69]
	v_readfirstlane_b32 s7, v161
	v_lshl_add_u64 v[222:223], v[222:223], 0, s[72:73]
	s_mov_b32 m0, s7
	v_readfirstlane_b32 s7, v162
	s_barrier
	ds_read_b128 v[182:185], v148 offset:49152
	ds_read_b128 v[190:193], v147 offset:49152
	ds_read_b128 v[198:201], v146 offset:49152
	ds_read_b128 v[206:209], v141 offset:49152
	global_load_lds_dwordx4 v[222:223], off
	v_lshl_add_u64 v[222:223], v[224:225], 0, s[72:73]
	s_mov_b32 m0, s7
	s_nop 0
	global_load_lds_dwordx4 v[222:223], off
	s_barrier
; #define STAGE_A(b, h, kt) { const u16* ap_ = A + (size_t)((h) * ahalf + (unsigned)(kt) * 64u); glds16(ap_ + ao0, l0 + SA_(b, h)); glds16(ap_ + ao1, l0 + SA_(b, h) + 8192); }
; #define STAGE_B(b, h, kt) { const u16* bp_ = ((h) ? B1 : B0) + (unsigned)(kt) * 64u; glds16(bp_ + bo0, l0 + SB_(b, h)); glds16(bp_ + bo1, l0 + SB_(b, h) + 8192); }
; #define LDA(dst, b, h) _Pragma("unroll") for (int m = 0; m < 4; ++m) _Pragma("unroll") for (int k = 0; k < 2; ++k) \
;     dst[m][k] = *(const bf16x8*)(lds + SA_(b, h) + lds_byte(wr * 64 + m * 16 + fr, k * 32 + fq * 8));
; #define LDB(dst, b, h) _Pragma("unroll") for (int n = 0; n < 2; ++n) _Pragma("unroll") for (int k = 0; k < 2; ++k) \
;     dst[n][k] = *(const bf16x8*)(lds + SB_(b, h) + lds_byte(wc * 32 + n * 16 + fr, k * 32 + fq * 8));
; #define MMA(ai, bj, At_, Bt_) { __builtin_amdgcn_s_setprio(1); \
;     _Pragma("unroll") for (int m = 0; m < 4; ++m) _Pragma("unroll") for (int n = 0; n < 2; ++n) _Pragma("unroll") for (int k = 0; k < 2; ++k) \
;       acc[ai][bj][m][n] = MFMA16(Bt_[n][k], At_[m][k], acc[ai][bj][m][n]); \
;     __builtin_amdgcn_s_setprio(0); }
; #define WAIT_V(n) asm volatile("s_waitcnt vmcnt(" #n ")" ::: "memory");
; #define WAIT_L(n) asm volatile("s_waitcnt lgkmcnt(" #n ")" ::: "memory");
; #define BAR __builtin_amdgcn_s_barrier();
; #define SCHED __builtin_amdgcn_sched_barrier(0);
; DI void gemm256(const u16* __restrict__ A, int lda, const u16* __restrict__ B0, const u16* __restrict__ B1, int ldb, int nt, acc_t& acc, char* lds) {
;     ...
;     BAR WAIT_L(0) MMA(1, 0, At, Bq0) BAR SCHED
;     STAGE_B(1, 1, t + 3)
;     WAIT_V(6) BAR MMA(1, 1, At, Bq1) BAR
;   }
;   { LDB(Bq0, 0, 0) LDA(At, 0, 0) STAGE_A(1, 1, nt - 1)
;     BAR WAIT_L(0) MMA(0, 0, At, Bq0) BAR
;     LDB(Bq1, 0, 1) BAR WAIT_L(0) MMA(0, 1, At, Bq1) BAR
;     LDA(At, 0, 1) WAIT_V(4) BAR WAIT_L(0) MMA(1, 0, At, Bq0) MMA(1, 1, At, Bq1) BAR }
;   { LDB(Bq0, 1, 0) LDA(At, 1, 0) WAIT_V(2) BAR WAIT_L(0) MMA(0, 0, At, Bq0) BAR
	s_waitcnt lgkmcnt(0)
	ds_read_b128 v[186:189], v148 offset:50176
	ds_read_b128 v[194:197], v147 offset:50176
	ds_read_b128 v[202:205], v146 offset:50176
	ds_read_b128 v[210:213], v141 offset:50176
	v_mfma_f32_16x16x32_bf16 v[60:63], v[142:145], v[182:185], v[60:63]
	v_mfma_f32_16x16x32_bf16 v[56:59], v[174:177], v[182:185], v[56:59]
	v_mfma_f32_16x16x32_bf16 v[52:55], v[142:145], v[190:193], v[52:55]
	v_mfma_f32_16x16x32_bf16 v[48:51], v[174:177], v[190:193], v[48:51]
	v_mfma_f32_16x16x32_bf16 v[44:47], v[142:145], v[198:201], v[44:47]
	v_mfma_f32_16x16x32_bf16 v[40:43], v[174:177], v[198:201], v[40:43]
	v_mfma_f32_16x16x32_bf16 v[36:39], v[142:145], v[206:209], v[36:39]
	v_mfma_f32_16x16x32_bf16 v[32:35], v[174:177], v[206:209], v[32:35]
	s_waitcnt lgkmcnt(0)
	v_mfma_f32_16x16x32_bf16 v[60:63], v[170:173], v[186:189], v[60:63]
	v_mfma_f32_16x16x32_bf16 v[56:59], v[178:181], v[186:189], v[56:59]
	v_mfma_f32_16x16x32_bf16 v[52:55], v[170:173], v[194:197], v[52:55]
	v_mfma_f32_16x16x32_bf16 v[48:51], v[178:181], v[194:197], v[48:51]
	v_mfma_f32_16x16x32_bf16 v[44:47], v[170:173], v[202:205], v[44:47]
	v_mfma_f32_16x16x32_bf16 v[40:43], v[178:181], v[202:205], v[40:43]
	v_mfma_f32_16x16x32_bf16 v[36:39], v[170:173], v[210:213], v[36:39]
	v_mfma_f32_16x16x32_bf16 v[32:35], v[178:181], v[210:213], v[32:35]
	s_barrier
	v_readfirstlane_b32 s7, v163
	v_lshl_add_u64 v[142:143], v[238:239], 0, s[48:49]
	s_mov_b32 m0, s7
	v_readfirstlane_b32 s7, v164
	global_load_lds_dwordx4 v[142:143], off
	v_lshl_add_u64 v[142:143], v[240:241], 0, s[48:49]
	s_mov_b32 m0, s7
	s_nop 0
	global_load_lds_dwordx4 v[142:143], off
	s_waitcnt vmcnt(6)
	s_barrier
	v_mfma_f32_16x16x32_bf16 v[28:31], v[216:219], v[182:185], v[28:31]
	v_mfma_f32_16x16x32_bf16 v[24:27], v[230:233], v[182:185], v[24:27]
	v_mfma_f32_16x16x32_bf16 v[20:23], v[216:219], v[190:193], v[20:23]
	v_mfma_f32_16x16x32_bf16 v[16:19], v[230:233], v[190:193], v[16:19]
	v_mfma_f32_16x16x32_bf16 v[12:15], v[216:219], v[198:201], v[12:15]
	v_mfma_f32_16x16x32_bf16 v[8:11], v[230:233], v[198:201], v[8:11]
	v_mfma_f32_16x16x32_bf16 v[4:7], v[216:219], v[206:209], v[4:7]
	v_mfma_f32_16x16x32_bf16 v[0:3], v[230:233], v[206:209], v[0:3]
	v_mfma_f32_16x16x32_bf16 v[28:31], v[226:229], v[186:189], v[28:31]
	v_mfma_f32_16x16x32_bf16 v[24:27], v[234:237], v[186:189], v[24:27]
	v_mfma_f32_16x16x32_bf16 v[20:23], v[226:229], v[194:197], v[20:23]
	v_mfma_f32_16x16x32_bf16 v[16:19], v[234:237], v[194:197], v[16:19]
	v_mfma_f32_16x16x32_bf16 v[12:15], v[226:229], v[202:205], v[12:15]
	v_mfma_f32_16x16x32_bf16 v[8:11], v[234:237], v[202:205], v[8:11]
	v_mfma_f32_16x16x32_bf16 v[4:7], v[226:229], v[210:213], v[4:7]
	v_mfma_f32_16x16x32_bf16 v[0:3], v[234:237], v[210:213], v[0:3]
	s_add_i32 s3, s3, 2
	s_add_u32 s36, s36, 0x100
	s_addc_u32 s37, s37, 0
	s_cmp_lt_u32 s3, 12
	s_barrier
	s_cbranch_scc1 .LBB0_1053
	s_add_u32 s28, s28, 0x40780
	s_addc_u32 s29, s29, 0
	v_readfirstlane_b32 s3, v167
	v_lshl_add_u64 v[162:163], v[64:65], 1, s[28:29]
	s_mov_b32 m0, s3
	v_readfirstlane_b32 s3, v168
	ds_read_b128 v[132:135], v166
	ds_read_b128 v[136:139], v166 offset:1024
	ds_read_b128 v[142:145], v166 offset:2048
	ds_read_b128 v[152:155], v166 offset:3072
	ds_read_b128 v[158:161], v148
	ds_read_b128 v[170:173], v148 offset:1024
	ds_read_b128 v[174:177], v147
	ds_read_b128 v[178:181], v147 offset:1024
	ds_read_b128 v[182:185], v146
	ds_read_b128 v[186:189], v146 offset:1024
	ds_read_b128 v[190:193], v141
	ds_read_b128 v[194:197], v141 offset:1024
	global_load_lds_dwordx4 v[162:163], off
	v_lshl_add_u64 v[130:131], v[130:131], 1, s[28:29]
	s_mov_b32 m0, s3
	s_nop 0
	global_load_lds_dwordx4 v[130:131], off
	s_barrier
	s_waitcnt lgkmcnt(0)
	v_mfma_f32_16x16x32_bf16 v[126:129], v[132:135], v[158:161], v[126:129]
	v_mfma_f32_16x16x32_bf16 v[118:121], v[132:135], v[174:177], v[118:121]
	v_mfma_f32_16x16x32_bf16 v[114:117], v[142:145], v[174:177], v[114:117]
	v_mfma_f32_16x16x32_bf16 v[102:105], v[132:135], v[190:193], v[102:105]
	v_mfma_f32_16x16x32_bf16 v[98:101], v[142:145], v[190:193], v[98:101]
	v_mfma_f32_16x16x32_bf16 v[126:129], v[136:139], v[170:173], v[126:129]
	v_mfma_f32_16x16x32_bf16 v[122:125], v[142:145], v[158:161], v[122:125]
	v_mfma_f32_16x16x32_bf16 v[118:121], v[136:139], v[178:181], v[118:121]
	v_mfma_f32_16x16x32_bf16 v[114:117], v[152:155], v[178:181], v[114:117]
	v_mfma_f32_16x16x32_bf16 v[110:113], v[132:135], v[182:185], v[110:113]
	v_mfma_f32_16x16x32_bf16 v[106:109], v[142:145], v[182:185], v[106:109]
	v_mfma_f32_16x16x32_bf16 v[102:105], v[136:139], v[194:197], v[102:105]
	v_mfma_f32_16x16x32_bf16 v[98:101], v[152:155], v[194:197], v[98:101]
	v_mfma_f32_16x16x32_bf16 v[122:125], v[152:155], v[170:173], v[122:125]
	v_mfma_f32_16x16x32_bf16 v[166:169], v[136:139], v[186:189], v[110:113]
	v_mfma_f32_16x16x32_bf16 v[198:201], v[152:155], v[186:189], v[106:109]
	s_barrier
	s_nop 0
	ds_read_b128 v[106:109], v165
	ds_read_b128 v[110:113], v165 offset:1024
	ds_read_b128 v[202:205], v165 offset:2048
	ds_read_b128 v[162:165], v165 offset:3072
	s_barrier
	s_waitcnt lgkmcnt(0)
	v_mfma_f32_16x16x32_bf16 v[86:89], v[106:109], v[174:177], v[86:89]
	v_mfma_f32_16x16x32_bf16 v[82:85], v[202:205], v[174:177], v[82:85]
	v_mfma_f32_16x16x32_bf16 v[70:73], v[106:109], v[190:193], v[70:73]
	v_mfma_f32_16x16x32_bf16 v[66:69], v[202:205], v[190:193], v[66:69]
	v_mfma_f32_16x16x32_bf16 v[94:97], v[106:109], v[158:161], v[94:97]
	v_mfma_f32_16x16x32_bf16 v[90:93], v[202:205], v[158:161], v[90:93]
	v_mfma_f32_16x16x32_bf16 v[86:89], v[110:113], v[178:181], v[86:89]
	v_mfma_f32_16x16x32_bf16 v[82:85], v[162:165], v[178:181], v[82:85]
	v_mfma_f32_16x16x32_bf16 v[78:81], v[106:109], v[182:185], v[78:81]
	v_mfma_f32_16x16x32_bf16 v[74:77], v[202:205], v[182:185], v[74:77]
	v_mfma_f32_16x16x32_bf16 v[70:73], v[110:113], v[194:197], v[70:73]
	v_mfma_f32_16x16x32_bf16 v[66:69], v[162:165], v[194:197], v[66:69]
	v_mfma_f32_16x16x32_bf16 v[206:209], v[110:113], v[170:173], v[94:97]
	v_mfma_f32_16x16x32_bf16 v[158:161], v[162:165], v[170:173], v[90:93]
	v_mfma_f32_16x16x32_bf16 v[170:173], v[110:113], v[186:189], v[78:81]
	v_mfma_f32_16x16x32_bf16 v[174:177], v[162:165], v[186:189], v[74:77]
	s_barrier
; #define LDA(dst, b, h) _Pragma("unroll") for (int m = 0; m < 4; ++m) _Pragma("unroll") for (int k = 0; k < 2; ++k) \
;     dst[m][k] = *(const bf16x8*)(lds + SA_(b, h) + lds_byte(wr * 64 + m * 16 + fr, k * 32 + fq * 8));
; #define LDB(dst, b, h) _Pragma("unroll") for (int n = 0; n < 2; ++n) _Pragma("unroll") for (int k = 0; k < 2; ++k) \
;     dst[n][k] = *(const bf16x8*)(lds + SB_(b, h) + lds_byte(wc * 32 + n * 16 + fr, k * 32 + fq * 8));
; #define MMA(ai, bj, At_, Bt_) { __builtin_amdgcn_s_setprio(1); \
;     _Pragma("unroll") for (int m = 0; m < 4; ++m) _Pragma("unroll") for (int n = 0; n < 2; ++n) _Pragma("unroll") for (int k = 0; k < 2; ++k) \
;       acc[ai][bj][m][n] = MFMA16(Bt_[n][k], At_[m][k], acc[ai][bj][m][n]); \
;     __builtin_amdgcn_s_setprio(0); }
; #define WAIT_V(n) asm volatile("s_waitcnt vmcnt(" #n ")" ::: "memory");
; #define WAIT_L(n) asm volatile("s_waitcnt lgkmcnt(" #n ")" ::: "memory");
; #define BAR __builtin_amdgcn_s_barrier();
; DI void gemm256(const u16* __restrict__ A, int lda, const u16* __restrict__ B0, const u16* __restrict__ B1, int ldb, int nt, acc_t& acc, char* lds) {
;     ...
;     BAR WAIT_L(0) MMA(0, 0, At, Bq0) BAR
;     LDB(Bq1, 0, 1) BAR WAIT_L(0) MMA(0, 1, At, Bq1) BAR
;     LDA(At, 0, 1) WAIT_V(4) BAR WAIT_L(0) MMA(1, 0, At, Bq0) MMA(1, 1, At, Bq1) BAR }
;   { LDB(Bq0, 1, 0) LDA(At, 1, 0) WAIT_V(2) BAR WAIT_L(0) MMA(0, 0, At, Bq0) BAR
	s_nop 0
	ds_read_b128 v[74:77], v148 offset:16384
	ds_read_b128 v[78:81], v148 offset:17408
	ds_read_b128 v[90:93], v147 offset:16384
	ds_read_b128 v[94:97], v147 offset:17408
	ds_read_b128 v[178:181], v146 offset:16384
	ds_read_b128 v[182:185], v146 offset:17408
	ds_read_b128 v[186:189], v141 offset:16384
	ds_read_b128 v[190:193], v141 offset:17408
	s_waitcnt vmcnt(4)
	s_barrier
	s_waitcnt lgkmcnt(0)
	v_mfma_f32_16x16x32_bf16 v[60:63], v[132:135], v[74:77], v[60:63]
	v_mfma_f32_16x16x32_bf16 v[56:59], v[142:145], v[74:77], v[56:59]
	v_mfma_f32_16x16x32_bf16 v[52:55], v[132:135], v[90:93], v[52:55]
	v_mfma_f32_16x16x32_bf16 v[48:51], v[142:145], v[90:93], v[48:51]
	v_mfma_f32_16x16x32_bf16 v[36:39], v[132:135], v[186:189], v[36:39]
	v_mfma_f32_16x16x32_bf16 v[32:35], v[142:145], v[186:189], v[32:35]
	v_mfma_f32_16x16x32_bf16 v[60:63], v[136:139], v[78:81], v[60:63]
	v_mfma_f32_16x16x32_bf16 v[56:59], v[152:155], v[78:81], v[56:59]
	v_mfma_f32_16x16x32_bf16 v[52:55], v[136:139], v[94:97], v[52:55]
	v_mfma_f32_16x16x32_bf16 v[48:51], v[152:155], v[94:97], v[48:51]
	v_mfma_f32_16x16x32_bf16 v[44:47], v[132:135], v[178:181], v[44:47]
	v_mfma_f32_16x16x32_bf16 v[40:43], v[142:145], v[178:181], v[40:43]
	v_mfma_f32_16x16x32_bf16 v[36:39], v[136:139], v[190:193], v[36:39]
	v_mfma_f32_16x16x32_bf16 v[32:35], v[152:155], v[190:193], v[32:35]
	v_mfma_f32_16x16x32_bf16 v[194:197], v[136:139], v[182:185], v[44:47]
	v_mfma_f32_16x16x32_bf16 v[210:213], v[152:155], v[182:185], v[40:43]
	v_mfma_f32_16x16x32_bf16 v[20:23], v[106:109], v[90:93], v[20:23]
	v_mfma_f32_16x16x32_bf16 v[16:19], v[202:205], v[90:93], v[16:19]
	v_mfma_f32_16x16x32_bf16 v[4:7], v[106:109], v[186:189], v[4:7]
	v_mfma_f32_16x16x32_bf16 v[0:3], v[202:205], v[186:189], v[0:3]
	v_mfma_f32_16x16x32_bf16 v[28:31], v[106:109], v[74:77], v[28:31]
	v_mfma_f32_16x16x32_bf16 v[24:27], v[202:205], v[74:77], v[24:27]
	v_mfma_f32_16x16x32_bf16 v[20:23], v[110:113], v[94:97], v[20:23]
	v_mfma_f32_16x16x32_bf16 v[16:19], v[162:165], v[94:97], v[16:19]
	v_mfma_f32_16x16x32_bf16 v[12:15], v[106:109], v[178:181], v[12:15]
	v_mfma_f32_16x16x32_bf16 v[8:11], v[202:205], v[178:181], v[8:11]
	v_mfma_f32_16x16x32_bf16 v[4:7], v[110:113], v[190:193], v[4:7]
	v_mfma_f32_16x16x32_bf16 v[0:3], v[162:165], v[190:193], v[0:3]
	v_mfma_f32_16x16x32_bf16 v[134:137], v[110:113], v[78:81], v[28:31]
	v_mfma_f32_16x16x32_bf16 v[142:145], v[162:165], v[78:81], v[24:27]
	v_mfma_f32_16x16x32_bf16 v[152:155], v[110:113], v[182:185], v[12:15]
	v_mfma_f32_16x16x32_bf16 v[178:181], v[162:165], v[182:185], v[8:11]
	s_barrier
	s_nop 0
	ds_read_b128 v[8:11], v156
	ds_read_b128 v[12:15], v156 offset:1024
	ds_read_b128 v[162:165], v156 offset:2048
	ds_read_b128 v[182:185], v156 offset:3072
	ds_read_b128 v[24:27], v148 offset:32768
	ds_read_b128 v[28:31], v148 offset:33792
	ds_read_b128 v[40:43], v147 offset:32768
	ds_read_b128 v[44:47], v147 offset:33792
	ds_read_b128 v[186:189], v146 offset:32768
	ds_read_b128 v[190:193], v146 offset:33792
	ds_read_b128 v[202:205], v141 offset:32768
	ds_read_b128 v[216:219], v141 offset:33792
	s_waitcnt vmcnt(2)
	s_barrier
	s_waitcnt lgkmcnt(0)
	v_mfma_f32_16x16x32_bf16 v[74:77], v[8:11], v[24:27], v[126:129]
	v_mfma_f32_16x16x32_bf16 v[126:129], v[12:15], v[28:31], v[74:77]
	v_mfma_f32_16x16x32_bf16 v[74:77], v[162:165], v[24:27], v[122:125]
	v_mfma_f32_16x16x32_bf16 v[130:133], v[182:185], v[28:31], v[74:77]
	v_mfma_f32_16x16x32_bf16 v[74:77], v[8:11], v[40:43], v[118:121]
	v_mfma_f32_16x16x32_bf16 v[110:113], v[12:15], v[44:47], v[74:77]
	v_mfma_f32_16x16x32_bf16 v[74:77], v[162:165], v[40:43], v[114:117]
	v_mfma_f32_16x16x32_bf16 v[106:109], v[182:185], v[44:47], v[74:77]
	v_mfma_f32_16x16x32_bf16 v[74:77], v[8:11], v[186:189], v[166:169]
	v_mfma_f32_16x16x32_bf16 v[94:97], v[12:15], v[190:193], v[74:77]
	v_mfma_f32_16x16x32_bf16 v[74:77], v[162:165], v[186:189], v[198:201]
	v_mfma_f32_16x16x32_bf16 v[90:93], v[182:185], v[190:193], v[74:77]
	v_mfma_f32_16x16x32_bf16 v[74:77], v[8:11], v[202:205], v[102:105]
	v_mfma_f32_16x16x32_bf16 v[78:81], v[12:15], v[216:219], v[74:77]
	v_mfma_f32_16x16x32_bf16 v[74:77], v[162:165], v[202:205], v[98:101]
	v_mfma_f32_16x16x32_bf16 v[74:77], v[182:185], v[216:219], v[74:77]
	s_barrier
; #define LDA(dst, b, h) _Pragma("unroll") for (int m = 0; m < 4; ++m) _Pragma("unroll") for (int k = 0; k < 2; ++k) \
;     dst[m][k] = *(const bf16x8*)(lds + SA_(b, h) + lds_byte(wr * 64 + m * 16 + fr, k * 32 + fq * 8));
; #define LDB(dst, b, h) _Pragma("unroll") for (int n = 0; n < 2; ++n) _Pragma("unroll") for (int k = 0; k < 2; ++k) \
;     dst[n][k] = *(const bf16x8*)(lds + SB_(b, h) + lds_byte(wc * 32 + n * 16 + fr, k * 32 + fq * 8));
; #define MMA(ai, bj, At_, Bt_) { __builtin_amdgcn_s_setprio(1); \
;     _Pragma("unroll") for (int m = 0; m < 4; ++m) _Pragma("unroll") for (int n = 0; n < 2; ++n) _Pragma("unroll") for (int k = 0; k < 2; ++k) \
;       acc[ai][bj][m][n] = MFMA16(Bt_[n][k], At_[m][k], acc[ai][bj][m][n]); \
;     __builtin_amdgcn_s_setprio(0); }
; #define WAIT_V(n) asm volatile("s_waitcnt vmcnt(" #n ")" ::: "memory");
; #define WAIT_L(n) asm volatile("s_waitcnt lgkmcnt(" #n ")" ::: "memory");
; #define BAR __builtin_amdgcn_s_barrier();
; DI void gemm256(const u16* __restrict__ A, int lda, const u16* __restrict__ B0, const u16* __restrict__ B1, int ldb, int nt, acc_t& acc, char* lds) {
;     ...
;     LDB(Bq1, 1, 1) WAIT_V(0) BAR WAIT_L(0) MMA(0, 1, At, Bq1) BAR
;     LDA(At, 1, 1) BAR WAIT_L(0) MMA(1, 0, At, Bq0) MMA(1, 1, At, Bq1) BAR }
;   if (wr == 0) BAR
;   __syncthreads();
	ds_read_b128 v[122:125], v151
	ds_read_b128 v[166:169], v151 offset:1024
	ds_read_b128 v[198:201], v151 offset:2048
	ds_read_b128 v[226:229], v151 offset:3072
	s_waitcnt vmcnt(0)
	s_barrier
	s_waitcnt lgkmcnt(0)
	v_mfma_f32_16x16x32_bf16 v[98:101], v[122:125], v[24:27], v[206:209]
	v_mfma_f32_16x16x32_bf16 v[24:27], v[198:201], v[24:27], v[158:161]
	v_mfma_f32_16x16x32_bf16 v[114:117], v[226:229], v[28:31], v[24:27]
	v_mfma_f32_16x16x32_bf16 v[24:27], v[122:125], v[40:43], v[86:89]
	v_mfma_f32_16x16x32_bf16 v[102:105], v[166:169], v[44:47], v[24:27]
	v_mfma_f32_16x16x32_bf16 v[24:27], v[198:201], v[40:43], v[82:85]
	v_mfma_f32_16x16x32_bf16 v[118:121], v[166:169], v[28:31], v[98:101]
	v_mfma_f32_16x16x32_bf16 v[98:101], v[226:229], v[44:47], v[24:27]
	v_mfma_f32_16x16x32_bf16 v[24:27], v[122:125], v[186:189], v[170:173]
	v_mfma_f32_16x16x32_bf16 v[86:89], v[166:169], v[190:193], v[24:27]
	v_mfma_f32_16x16x32_bf16 v[24:27], v[198:201], v[186:189], v[174:177]
	v_mfma_f32_16x16x32_bf16 v[82:85], v[226:229], v[190:193], v[24:27]
	v_mfma_f32_16x16x32_bf16 v[24:27], v[122:125], v[202:205], v[70:73]
	v_mfma_f32_16x16x32_bf16 v[70:73], v[166:169], v[216:219], v[24:27]
	v_mfma_f32_16x16x32_bf16 v[24:27], v[198:201], v[202:205], v[66:69]
	v_mfma_f32_16x16x32_bf16 v[66:69], v[226:229], v[216:219], v[24:27]
	s_barrier
	ds_read_b128 v[156:159], v148 offset:49152
	ds_read_b128 v[148:151], v148 offset:50176
	ds_read_b128 v[170:173], v147 offset:49152
	ds_read_b128 v[174:177], v147 offset:50176
	ds_read_b128 v[186:189], v146 offset:49152
	ds_read_b128 v[190:193], v146 offset:50176
	ds_read_b128 v[202:205], v141 offset:49152
	ds_read_b128 v[206:209], v141 offset:50176
	s_barrier
	s_waitcnt lgkmcnt(0)
	v_mfma_f32_16x16x32_bf16 v[24:27], v[8:11], v[156:159], v[60:63]
	v_mfma_f32_16x16x32_bf16 v[60:63], v[12:15], v[148:151], v[24:27]
	v_mfma_f32_16x16x32_bf16 v[24:27], v[162:165], v[156:159], v[56:59]
	v_mfma_f32_16x16x32_bf16 v[56:59], v[182:185], v[148:151], v[24:27]
	v_mfma_f32_16x16x32_bf16 v[24:27], v[8:11], v[170:173], v[52:55]
	v_mfma_f32_16x16x32_bf16 v[44:47], v[12:15], v[174:177], v[24:27]
	v_mfma_f32_16x16x32_bf16 v[24:27], v[162:165], v[170:173], v[48:51]
	v_mfma_f32_16x16x32_bf16 v[40:43], v[182:185], v[174:177], v[24:27]
	v_mfma_f32_16x16x32_bf16 v[24:27], v[8:11], v[186:189], v[194:197]
	v_mfma_f32_16x16x32_bf16 v[8:11], v[8:11], v[202:205], v[36:39]
	v_mfma_f32_16x16x32_bf16 v[28:31], v[12:15], v[190:193], v[24:27]
	v_mfma_f32_16x16x32_bf16 v[24:27], v[162:165], v[186:189], v[210:213]
	v_mfma_f32_16x16x32_bf16 v[12:15], v[12:15], v[206:209], v[8:11]
	v_mfma_f32_16x16x32_bf16 v[8:11], v[162:165], v[202:205], v[32:35]
	v_mfma_f32_16x16x32_bf16 v[24:27], v[182:185], v[190:193], v[24:27]
	v_mfma_f32_16x16x32_bf16 v[8:11], v[182:185], v[206:209], v[8:11]
	v_mfma_f32_16x16x32_bf16 v[32:35], v[122:125], v[156:159], v[134:137]
	v_mfma_f32_16x16x32_bf16 v[52:55], v[166:169], v[148:151], v[32:35]
	v_mfma_f32_16x16x32_bf16 v[32:35], v[198:201], v[156:159], v[142:145]
	v_mfma_f32_16x16x32_bf16 v[16:19], v[198:201], v[170:173], v[16:19]
	v_mfma_f32_16x16x32_bf16 v[48:51], v[226:229], v[148:151], v[32:35]
	v_mfma_f32_16x16x32_bf16 v[20:23], v[122:125], v[170:173], v[20:23]
	v_mfma_f32_16x16x32_bf16 v[32:35], v[226:229], v[174:177], v[16:19]
	v_mfma_f32_16x16x32_bf16 v[16:19], v[122:125], v[186:189], v[152:155]
	v_mfma_f32_16x16x32_bf16 v[36:39], v[166:169], v[174:177], v[20:23]
	v_mfma_f32_16x16x32_bf16 v[20:23], v[166:169], v[190:193], v[16:19]
	v_mfma_f32_16x16x32_bf16 v[16:19], v[198:201], v[186:189], v[178:181]
	v_mfma_f32_16x16x32_bf16 v[4:7], v[122:125], v[202:205], v[4:7]
	v_mfma_f32_16x16x32_bf16 v[0:3], v[198:201], v[202:205], v[0:3]
	v_mfma_f32_16x16x32_bf16 v[16:19], v[226:229], v[190:193], v[16:19]
	v_mfma_f32_16x16x32_bf16 v[4:7], v[166:169], v[206:209], v[4:7]
	v_mfma_f32_16x16x32_bf16 v[0:3], v[226:229], v[206:209], v[0:3]
	s_movk_i32 s3, 0x100
	v_cmp_gt_u32_e32 vcc, s3, v140
	s_barrier
	s_and_saveexec_b64 s[28:29], vcc
	s_cbranch_execz .LBB0_1049
	s_barrier
	s_branch .LBB0_1049

; #define STAGE_A(b, h, kt) { const u16* ap_ = A + (size_t)((h) * ahalf + (unsigned)(kt) * 64u); glds16(ap_ + ao0, l0 + SA_(b, h)); glds16(ap_ + ao1, l0 + SA_(b, h) + 8192); }
; #define STAGE_B(b, h, kt) { const u16* bp_ = ((h) ? B1 : B0) + (unsigned)(kt) * 64u; glds16(bp_ + bo0, l0 + SB_(b, h)); glds16(bp_ + bo1, l0 + SB_(b, h) + 8192); }
; #define LDA(dst, b, h) _Pragma("unroll") for (int m = 0; m < 4; ++m) _Pragma("unroll") for (int k = 0; k < 2; ++k) \
;     dst[m][k] = *(const bf16x8*)(lds + SA_(b, h) + lds_byte(wr * 64 + m * 16 + fr, k * 32 + fq * 8));
; #define LDB(dst, b, h) _Pragma("unroll") for (int n = 0; n < 2; ++n) _Pragma("unroll") for (int k = 0; k < 2; ++k) \
;     dst[n][k] = *(const bf16x8*)(lds + SB_(b, h) + lds_byte(wc * 32 + n * 16 + fr, k * 32 + fq * 8));
; #define MMA(ai, bj, At_, Bt_) { __builtin_amdgcn_s_setprio(1); \
;     _Pragma("unroll") for (int m = 0; m < 4; ++m) _Pragma("unroll") for (int n = 0; n < 2; ++n) _Pragma("unroll") for (int k = 0; k < 2; ++k) \
;       acc[ai][bj][m][n] = MFMA16(Bt_[n][k], At_[m][k], acc[ai][bj][m][n]); \
;     __builtin_amdgcn_s_setprio(0); }
; #define WAIT_L(n) asm volatile("s_waitcnt lgkmcnt(" #n ")" ::: "memory");
; #define BAR __builtin_amdgcn_s_barrier();
; #define SCHED __builtin_amdgcn_sched_barrier(0);
; DI void gemm256(const u16* __restrict__ A, int lda, const u16* __restrict__ B0, const u16* __restrict__ B1, int ldb, int nt, acc_t& acc, char* lds) {
;     ...
;   for (int t = 0; t < nt - 2; t += 2) {
;     LDB(Bq0, 0, 0) SCHED LDA(At, 0, 0) STAGE_A(1, 1, t + 1)
;     WAIT_L(8) BAR WAIT_L(0) MMA(0, 0, At, Bq0) BAR SCHED
;     LDB(Bq1, 0, 1) STAGE_B(0, 0, t + 2)
;     BAR WAIT_L(0) MMA(0, 1, At, Bq1) BAR
;     LDA(At, 0, 1) STAGE_A(0, 0, t + 2)
;     BAR WAIT_L(0) MMA(1, 0, At, Bq0) BAR SCHED
.LBB0_1172:
	ds_read_b128 v[142:145], v166
	ds_read_b128 v[170:173], v166 offset:1024
	ds_read_b128 v[174:177], v166 offset:2048
	ds_read_b128 v[178:181], v166 offset:3072
	v_lshl_add_u64 v[222:223], s[36:37], 0, v[136:137]
	v_readfirstlane_b32 s9, v167
	v_lshl_add_u64 v[168:169], v[222:223], 0, s[76:77]
	s_mov_b32 m0, s9
	ds_read_b128 v[182:185], v148
	ds_read_b128 v[190:193], v147
	ds_read_b128 v[198:201], v146
	ds_read_b128 v[206:209], v141
	global_load_lds_dwordx4 v[168:169], off
	v_add_u32_e32 v168, 0xe000, v149
	v_lshl_add_u64 v[224:225], s[36:37], 0, v[138:139]
	v_readfirstlane_b32 s9, v168
	v_lshl_add_u64 v[216:217], v[224:225], 0, s[76:77]
	s_mov_b32 m0, s9
	s_nop 0
	global_load_lds_dwordx4 v[216:217], off
	s_waitcnt lgkmcnt(4)
	s_barrier
	s_waitcnt lgkmcnt(0)
	ds_read_b128 v[186:189], v148 offset:1024
	ds_read_b128 v[194:197], v147 offset:1024
	ds_read_b128 v[202:205], v146 offset:1024
	ds_read_b128 v[210:213], v141 offset:1024
	v_mfma_f32_16x16x32_bf16 v[126:129], v[142:145], v[182:185], v[126:129]
	v_mfma_f32_16x16x32_bf16 v[122:125], v[174:177], v[182:185], v[122:125]
	v_mfma_f32_16x16x32_bf16 v[118:121], v[142:145], v[190:193], v[118:121]
	v_mfma_f32_16x16x32_bf16 v[114:117], v[174:177], v[190:193], v[114:117]
	v_mfma_f32_16x16x32_bf16 v[110:113], v[142:145], v[198:201], v[110:113]
	v_mfma_f32_16x16x32_bf16 v[106:109], v[174:177], v[198:201], v[106:109]
	v_mfma_f32_16x16x32_bf16 v[102:105], v[142:145], v[206:209], v[102:105]
	v_mfma_f32_16x16x32_bf16 v[98:101], v[174:177], v[206:209], v[98:101]
	s_waitcnt lgkmcnt(0)
	v_mfma_f32_16x16x32_bf16 v[126:129], v[170:173], v[186:189], v[126:129]
	v_mfma_f32_16x16x32_bf16 v[122:125], v[178:181], v[186:189], v[122:125]
	v_mfma_f32_16x16x32_bf16 v[118:121], v[170:173], v[194:197], v[118:121]
	v_mfma_f32_16x16x32_bf16 v[114:117], v[178:181], v[194:197], v[114:117]
	v_mfma_f32_16x16x32_bf16 v[110:113], v[170:173], v[202:205], v[110:113]
	v_mfma_f32_16x16x32_bf16 v[106:109], v[178:181], v[202:205], v[106:109]
	v_mfma_f32_16x16x32_bf16 v[102:105], v[170:173], v[210:213], v[102:105]
	v_mfma_f32_16x16x32_bf16 v[98:101], v[178:181], v[210:213], v[98:101]
	s_barrier
	v_lshl_add_u64 v[238:239], s[36:37], 0, v[132:133]
	v_readfirstlane_b32 s9, v150
	v_lshl_add_u64 v[240:241], v[238:239], 0, s[42:43]
	s_mov_b32 m0, s9
	ds_read_b128 v[216:219], v165
	ds_read_b128 v[226:229], v165 offset:1024
	ds_read_b128 v[230:233], v165 offset:2048
	ds_read_b128 v[234:237], v165 offset:3072
	global_load_lds_dwordx4 v[240:241], off
	v_lshl_add_u64 v[240:241], s[36:37], 0, v[134:135]
	v_readfirstlane_b32 s9, v152
	v_lshl_add_u64 v[242:243], v[240:241], 0, s[42:43]
	s_mov_b32 m0, s9
	s_nop 0
	global_load_lds_dwordx4 v[242:243], off
	s_barrier
	s_waitcnt lgkmcnt(0)
	v_mfma_f32_16x16x32_bf16 v[94:97], v[216:219], v[182:185], v[94:97]
	v_mfma_f32_16x16x32_bf16 v[90:93], v[230:233], v[182:185], v[90:93]
	v_mfma_f32_16x16x32_bf16 v[86:89], v[216:219], v[190:193], v[86:89]
	v_mfma_f32_16x16x32_bf16 v[82:85], v[230:233], v[190:193], v[82:85]
	v_mfma_f32_16x16x32_bf16 v[78:81], v[216:219], v[198:201], v[78:81]
	v_mfma_f32_16x16x32_bf16 v[74:77], v[230:233], v[198:201], v[74:77]
	v_mfma_f32_16x16x32_bf16 v[70:73], v[216:219], v[206:209], v[70:73]
	v_mfma_f32_16x16x32_bf16 v[66:69], v[230:233], v[206:209], v[66:69]
	v_mfma_f32_16x16x32_bf16 v[94:97], v[226:229], v[186:189], v[94:97]
	v_mfma_f32_16x16x32_bf16 v[90:93], v[234:237], v[186:189], v[90:93]
	v_mfma_f32_16x16x32_bf16 v[86:89], v[226:229], v[194:197], v[86:89]
	v_mfma_f32_16x16x32_bf16 v[82:85], v[234:237], v[194:197], v[82:85]
	v_mfma_f32_16x16x32_bf16 v[78:81], v[226:229], v[202:205], v[78:81]
	v_mfma_f32_16x16x32_bf16 v[74:77], v[234:237], v[202:205], v[74:77]
	v_mfma_f32_16x16x32_bf16 v[70:73], v[226:229], v[210:213], v[70:73]
	v_mfma_f32_16x16x32_bf16 v[66:69], v[234:237], v[210:213], v[66:69]
	v_readfirstlane_b32 s9, v149
	v_lshl_add_u64 v[242:243], v[222:223], 0, s[80:81]
	s_mov_b32 m0, s9
	v_readfirstlane_b32 s9, v153
	s_barrier
	ds_read_b128 v[182:185], v148 offset:16384
	ds_read_b128 v[190:193], v147 offset:16384
	ds_read_b128 v[198:201], v146 offset:16384
	ds_read_b128 v[206:209], v141 offset:16384
	global_load_lds_dwordx4 v[242:243], off
	v_lshl_add_u64 v[242:243], v[224:225], 0, s[80:81]
	s_mov_b32 m0, s9
	s_nop 0
	global_load_lds_dwordx4 v[242:243], off
	s_barrier
	s_waitcnt lgkmcnt(0)
	ds_read_b128 v[186:189], v148 offset:17408
	ds_read_b128 v[194:197], v147 offset:17408
	ds_read_b128 v[202:205], v146 offset:17408
	ds_read_b128 v[210:213], v141 offset:17408
	v_mfma_f32_16x16x32_bf16 v[60:63], v[142:145], v[182:185], v[60:63]
	v_mfma_f32_16x16x32_bf16 v[56:59], v[174:177], v[182:185], v[56:59]
	v_mfma_f32_16x16x32_bf16 v[52:55], v[142:145], v[190:193], v[52:55]
	v_mfma_f32_16x16x32_bf16 v[48:51], v[174:177], v[190:193], v[48:51]
	v_mfma_f32_16x16x32_bf16 v[44:47], v[142:145], v[198:201], v[44:47]
	v_mfma_f32_16x16x32_bf16 v[40:43], v[174:177], v[198:201], v[40:43]
	v_mfma_f32_16x16x32_bf16 v[36:39], v[142:145], v[206:209], v[36:39]
	v_mfma_f32_16x16x32_bf16 v[32:35], v[174:177], v[206:209], v[32:35]
	s_waitcnt lgkmcnt(0)
	v_mfma_f32_16x16x32_bf16 v[60:63], v[170:173], v[186:189], v[60:63]
	v_mfma_f32_16x16x32_bf16 v[56:59], v[178:181], v[186:189], v[56:59]
	v_mfma_f32_16x16x32_bf16 v[52:55], v[170:173], v[194:197], v[52:55]
	v_mfma_f32_16x16x32_bf16 v[48:51], v[178:181], v[194:197], v[48:51]
	v_mfma_f32_16x16x32_bf16 v[44:47], v[170:173], v[202:205], v[44:47]
	v_mfma_f32_16x16x32_bf16 v[40:43], v[178:181], v[202:205], v[40:43]
	v_mfma_f32_16x16x32_bf16 v[36:39], v[170:173], v[210:213], v[36:39]
	v_mfma_f32_16x16x32_bf16 v[32:35], v[178:181], v[210:213], v[32:35]
	s_barrier
; #define STAGE_A(b, h, kt) { const u16* ap_ = A + (size_t)((h) * ahalf + (unsigned)(kt) * 64u); glds16(ap_ + ao0, l0 + SA_(b, h)); glds16(ap_ + ao1, l0 + SA_(b, h) + 8192); }
; #define STAGE_B(b, h, kt) { const u16* bp_ = ((h) ? B1 : B0) + (unsigned)(kt) * 64u; glds16(bp_ + bo0, l0 + SB_(b, h)); glds16(bp_ + bo1, l0 + SB_(b, h) + 8192); }
; #define LDA(dst, b, h) _Pragma("unroll") for (int m = 0; m < 4; ++m) _Pragma("unroll") for (int k = 0; k < 2; ++k) \
;     dst[m][k] = *(const bf16x8*)(lds + SA_(b, h) + lds_byte(wr * 64 + m * 16 + fr, k * 32 + fq * 8));
; #define LDB(dst, b, h) _Pragma("unroll") for (int n = 0; n < 2; ++n) _Pragma("unroll") for (int k = 0; k < 2; ++k) \
;     dst[n][k] = *(const bf16x8*)(lds + SB_(b, h) + lds_byte(wc * 32 + n * 16 + fr, k * 32 + fq * 8));
; #define MMA(ai, bj, At_, Bt_) { __builtin_amdgcn_s_setprio(1); \
;     _Pragma("unroll") for (int m = 0; m < 4; ++m) _Pragma("unroll") for (int n = 0; n < 2; ++n) _Pragma("unroll") for (int k = 0; k < 2; ++k) \
;       acc[ai][bj][m][n] = MFMA16(Bt_[n][k], At_[m][k], acc[ai][bj][m][n]); \
;     __builtin_amdgcn_s_setprio(0); }
; #define WAIT_V(n) asm volatile("s_waitcnt vmcnt(" #n ")" ::: "memory");
; #define WAIT_L(n) asm volatile("s_waitcnt lgkmcnt(" #n ")" ::: "memory");
; #define BAR __builtin_amdgcn_s_barrier();
; #define SCHED __builtin_amdgcn_sched_barrier(0);
; DI void gemm256(const u16* __restrict__ A, int lda, const u16* __restrict__ B0, const u16* __restrict__ B1, int ldb, int nt, acc_t& acc, char* lds) {
;     ...
;     BAR WAIT_L(0) MMA(1, 0, At, Bq0) BAR SCHED
;     STAGE_B(0, 1, t + 2)
;     WAIT_V(6) BAR MMA(1, 1, At, Bq1) BAR
;     LDB(Bq0, 1, 0) SCHED LDA(At, 1, 0) STAGE_A(0, 1, t + 2)
;     WAIT_L(8) BAR WAIT_L(0) MMA(0, 0, At, Bq0) BAR SCHED
;     LDB(Bq1, 1, 1) STAGE_B(1, 0, t + 3)
;     BAR WAIT_L(0) MMA(0, 1, At, Bq1) BAR
;     LDA(At, 1, 1) STAGE_A(1, 0, t + 3)
;     BAR WAIT_L(0) MMA(1, 0, At, Bq0) BAR SCHED
	v_readfirstlane_b32 s9, v154
	v_lshl_add_u64 v[142:143], v[238:239], 0, s[44:45]
	s_mov_b32 m0, s9
	v_readfirstlane_b32 s9, v155
	global_load_lds_dwordx4 v[142:143], off
	v_lshl_add_u64 v[142:143], v[240:241], 0, s[44:45]
	s_mov_b32 m0, s9
	s_nop 0
	global_load_lds_dwordx4 v[142:143], off
	s_waitcnt vmcnt(6)
	s_barrier
	v_mfma_f32_16x16x32_bf16 v[28:31], v[216:219], v[182:185], v[28:31]
	v_mfma_f32_16x16x32_bf16 v[24:27], v[230:233], v[182:185], v[24:27]
	v_mfma_f32_16x16x32_bf16 v[20:23], v[216:219], v[190:193], v[20:23]
	v_mfma_f32_16x16x32_bf16 v[16:19], v[230:233], v[190:193], v[16:19]
	v_mfma_f32_16x16x32_bf16 v[12:15], v[216:219], v[198:201], v[12:15]
	v_mfma_f32_16x16x32_bf16 v[8:11], v[230:233], v[198:201], v[8:11]
	v_mfma_f32_16x16x32_bf16 v[4:7], v[216:219], v[206:209], v[4:7]
	v_mfma_f32_16x16x32_bf16 v[0:3], v[230:233], v[206:209], v[0:3]
	v_mfma_f32_16x16x32_bf16 v[28:31], v[226:229], v[186:189], v[28:31]
	v_mfma_f32_16x16x32_bf16 v[24:27], v[234:237], v[186:189], v[24:27]
	v_mfma_f32_16x16x32_bf16 v[20:23], v[226:229], v[194:197], v[20:23]
	v_mfma_f32_16x16x32_bf16 v[16:19], v[234:237], v[194:197], v[16:19]
	v_mfma_f32_16x16x32_bf16 v[12:15], v[226:229], v[202:205], v[12:15]
	v_mfma_f32_16x16x32_bf16 v[8:11], v[234:237], v[202:205], v[8:11]
	v_mfma_f32_16x16x32_bf16 v[4:7], v[226:229], v[210:213], v[4:7]
	v_mfma_f32_16x16x32_bf16 v[0:3], v[234:237], v[210:213], v[0:3]
	s_barrier
	ds_read_b128 v[142:145], v156
	ds_read_b128 v[170:173], v156 offset:1024
	ds_read_b128 v[174:177], v156 offset:2048
	ds_read_b128 v[178:181], v156 offset:3072
	v_readfirstlane_b32 s9, v157
	v_lshl_add_u64 v[216:217], v[222:223], 0, s[4:5]
	s_mov_b32 m0, s9
	v_readfirstlane_b32 s9, v158
	ds_read_b128 v[182:185], v148 offset:32768
	ds_read_b128 v[190:193], v147 offset:32768
	ds_read_b128 v[198:201], v146 offset:32768
	ds_read_b128 v[206:209], v141 offset:32768
	global_load_lds_dwordx4 v[216:217], off
	v_lshl_add_u64 v[216:217], v[224:225], 0, s[4:5]
	s_mov_b32 m0, s9
	s_nop 0
	global_load_lds_dwordx4 v[216:217], off
	s_waitcnt lgkmcnt(4)
	s_barrier
	s_waitcnt lgkmcnt(0)
	ds_read_b128 v[186:189], v148 offset:33792
	ds_read_b128 v[194:197], v147 offset:33792
	ds_read_b128 v[202:205], v146 offset:33792
	ds_read_b128 v[210:213], v141 offset:33792
	v_mfma_f32_16x16x32_bf16 v[126:129], v[142:145], v[182:185], v[126:129]
	v_mfma_f32_16x16x32_bf16 v[122:125], v[174:177], v[182:185], v[122:125]
	v_mfma_f32_16x16x32_bf16 v[118:121], v[142:145], v[190:193], v[118:121]
	v_mfma_f32_16x16x32_bf16 v[114:117], v[174:177], v[190:193], v[114:117]
	v_mfma_f32_16x16x32_bf16 v[110:113], v[142:145], v[198:201], v[110:113]
	v_mfma_f32_16x16x32_bf16 v[106:109], v[174:177], v[198:201], v[106:109]
	v_mfma_f32_16x16x32_bf16 v[102:105], v[142:145], v[206:209], v[102:105]
	v_mfma_f32_16x16x32_bf16 v[98:101], v[174:177], v[206:209], v[98:101]
	s_waitcnt lgkmcnt(0)
	v_mfma_f32_16x16x32_bf16 v[126:129], v[170:173], v[186:189], v[126:129]
	v_mfma_f32_16x16x32_bf16 v[122:125], v[178:181], v[186:189], v[122:125]
	v_mfma_f32_16x16x32_bf16 v[118:121], v[170:173], v[194:197], v[118:121]
	v_mfma_f32_16x16x32_bf16 v[114:117], v[178:181], v[194:197], v[114:117]
	v_mfma_f32_16x16x32_bf16 v[110:113], v[170:173], v[202:205], v[110:113]
	v_mfma_f32_16x16x32_bf16 v[106:109], v[178:181], v[202:205], v[106:109]
	v_mfma_f32_16x16x32_bf16 v[102:105], v[170:173], v[210:213], v[102:105]
	v_mfma_f32_16x16x32_bf16 v[98:101], v[178:181], v[210:213], v[98:101]
	s_barrier
	v_readfirstlane_b32 s9, v159
	v_lshl_add_u64 v[242:243], v[238:239], 0, s[46:47]
	s_mov_b32 m0, s9
	v_readfirstlane_b32 s9, v160
	ds_read_b128 v[216:219], v151
	ds_read_b128 v[226:229], v151 offset:1024
	ds_read_b128 v[230:233], v151 offset:2048
	ds_read_b128 v[234:237], v151 offset:3072
	global_load_lds_dwordx4 v[242:243], off
	v_lshl_add_u64 v[242:243], v[240:241], 0, s[46:47]
	s_mov_b32 m0, s9
	s_nop 0
	global_load_lds_dwordx4 v[242:243], off
	s_barrier
	s_waitcnt lgkmcnt(0)
	v_mfma_f32_16x16x32_bf16 v[94:97], v[216:219], v[182:185], v[94:97]
	v_mfma_f32_16x16x32_bf16 v[90:93], v[230:233], v[182:185], v[90:93]
	v_mfma_f32_16x16x32_bf16 v[86:89], v[216:219], v[190:193], v[86:89]
	v_mfma_f32_16x16x32_bf16 v[82:85], v[230:233], v[190:193], v[82:85]
	v_mfma_f32_16x16x32_bf16 v[78:81], v[216:219], v[198:201], v[78:81]
	v_mfma_f32_16x16x32_bf16 v[74:77], v[230:233], v[198:201], v[74:77]
	v_mfma_f32_16x16x32_bf16 v[70:73], v[216:219], v[206:209], v[70:73]
	v_mfma_f32_16x16x32_bf16 v[66:69], v[230:233], v[206:209], v[66:69]
	v_mfma_f32_16x16x32_bf16 v[94:97], v[226:229], v[186:189], v[94:97]
	v_mfma_f32_16x16x32_bf16 v[90:93], v[234:237], v[186:189], v[90:93]
	v_mfma_f32_16x16x32_bf16 v[86:89], v[226:229], v[194:197], v[86:89]
	v_mfma_f32_16x16x32_bf16 v[82:85], v[234:237], v[194:197], v[82:85]
	v_mfma_f32_16x16x32_bf16 v[78:81], v[226:229], v[202:205], v[78:81]
	v_mfma_f32_16x16x32_bf16 v[74:77], v[234:237], v[202:205], v[74:77]
	v_mfma_f32_16x16x32_bf16 v[70:73], v[226:229], v[210:213], v[70:73]
	v_mfma_f32_16x16x32_bf16 v[66:69], v[234:237], v[210:213], v[66:69]
	v_readfirstlane_b32 s9, v161
	v_lshl_add_u64 v[222:223], v[222:223], 0, s[30:31]
	s_mov_b32 m0, s9
	v_readfirstlane_b32 s9, v162
	s_barrier
	ds_read_b128 v[182:185], v148 offset:49152
	ds_read_b128 v[190:193], v147 offset:49152
	ds_read_b128 v[198:201], v146 offset:49152
	ds_read_b128 v[206:209], v141 offset:49152
	global_load_lds_dwordx4 v[222:223], off
	v_lshl_add_u64 v[222:223], v[224:225], 0, s[30:31]
	s_mov_b32 m0, s9
	s_nop 0
	global_load_lds_dwordx4 v[222:223], off
	s_barrier
; #define STAGE_A(b, h, kt) { const u16* ap_ = A + (size_t)((h) * ahalf + (unsigned)(kt) * 64u); glds16(ap_ + ao0, l0 + SA_(b, h)); glds16(ap_ + ao1, l0 + SA_(b, h) + 8192); }
; #define STAGE_B(b, h, kt) { const u16* bp_ = ((h) ? B1 : B0) + (unsigned)(kt) * 64u; glds16(bp_ + bo0, l0 + SB_(b, h)); glds16(bp_ + bo1, l0 + SB_(b, h) + 8192); }
; #define LDA(dst, b, h) _Pragma("unroll") for (int m = 0; m < 4; ++m) _Pragma("unroll") for (int k = 0; k < 2; ++k) \
;     dst[m][k] = *(const bf16x8*)(lds + SA_(b, h) + lds_byte(wr * 64 + m * 16 + fr, k * 32 + fq * 8));
; #define LDB(dst, b, h) _Pragma("unroll") for (int n = 0; n < 2; ++n) _Pragma("unroll") for (int k = 0; k < 2; ++k) \
;     dst[n][k] = *(const bf16x8*)(lds + SB_(b, h) + lds_byte(wc * 32 + n * 16 + fr, k * 32 + fq * 8));
; #define MMA(ai, bj, At_, Bt_) { __builtin_amdgcn_s_setprio(1); \
;     _Pragma("unroll") for (int m = 0; m < 4; ++m) _Pragma("unroll") for (int n = 0; n < 2; ++n) _Pragma("unroll") for (int k = 0; k < 2; ++k) \
;       acc[ai][bj][m][n] = MFMA16(Bt_[n][k], At_[m][k], acc[ai][bj][m][n]); \
;     __builtin_amdgcn_s_setprio(0); }
; #define WAIT_V(n) asm volatile("s_waitcnt vmcnt(" #n ")" ::: "memory");
; #define WAIT_L(n) asm volatile("s_waitcnt lgkmcnt(" #n ")" ::: "memory");
; #define BAR __builtin_amdgcn_s_barrier();
; #define SCHED __builtin_amdgcn_sched_barrier(0);
; DI void gemm256(const u16* __restrict__ A, int lda, const u16* __restrict__ B0, const u16* __restrict__ B1, int ldb, int nt, acc_t& acc, char* lds) {
;     ...
;     BAR WAIT_L(0) MMA(1, 0, At, Bq0) BAR SCHED
;     STAGE_B(1, 1, t + 3)
;     WAIT_V(6) BAR MMA(1, 1, At, Bq1) BAR
;   }
;   { LDB(Bq0, 0, 0) LDA(At, 0, 0) STAGE_A(1, 1, nt - 1)
;     BAR WAIT_L(0) MMA(0, 0, At, Bq0) BAR
;     LDB(Bq1, 0, 1) BAR WAIT_L(0) MMA(0, 1, At, Bq1) BAR
;     LDA(At, 0, 1) WAIT_V(4) BAR WAIT_L(0) MMA(1, 0, At, Bq0) MMA(1, 1, At, Bq1) BAR }
;   { LDB(Bq0, 1, 0) LDA(At, 1, 0) WAIT_V(2) BAR WAIT_L(0) MMA(0, 0, At, Bq0) BAR
	s_waitcnt lgkmcnt(0)
	ds_read_b128 v[186:189], v148 offset:50176
	ds_read_b128 v[194:197], v147 offset:50176
	ds_read_b128 v[202:205], v146 offset:50176
	ds_read_b128 v[210:213], v141 offset:50176
	v_mfma_f32_16x16x32_bf16 v[60:63], v[142:145], v[182:185], v[60:63]
	v_mfma_f32_16x16x32_bf16 v[56:59], v[174:177], v[182:185], v[56:59]
	v_mfma_f32_16x16x32_bf16 v[52:55], v[142:145], v[190:193], v[52:55]
	v_mfma_f32_16x16x32_bf16 v[48:51], v[174:177], v[190:193], v[48:51]
	v_mfma_f32_16x16x32_bf16 v[44:47], v[142:145], v[198:201], v[44:47]
	v_mfma_f32_16x16x32_bf16 v[40:43], v[174:177], v[198:201], v[40:43]
	v_mfma_f32_16x16x32_bf16 v[36:39], v[142:145], v[206:209], v[36:39]
	v_mfma_f32_16x16x32_bf16 v[32:35], v[174:177], v[206:209], v[32:35]
	s_waitcnt lgkmcnt(0)
	v_mfma_f32_16x16x32_bf16 v[60:63], v[170:173], v[186:189], v[60:63]
	v_mfma_f32_16x16x32_bf16 v[56:59], v[178:181], v[186:189], v[56:59]
	v_mfma_f32_16x16x32_bf16 v[52:55], v[170:173], v[194:197], v[52:55]
	v_mfma_f32_16x16x32_bf16 v[48:51], v[178:181], v[194:197], v[48:51]
	v_mfma_f32_16x16x32_bf16 v[44:47], v[170:173], v[202:205], v[44:47]
	v_mfma_f32_16x16x32_bf16 v[40:43], v[178:181], v[202:205], v[40:43]
	v_mfma_f32_16x16x32_bf16 v[36:39], v[170:173], v[210:213], v[36:39]
	v_mfma_f32_16x16x32_bf16 v[32:35], v[178:181], v[210:213], v[32:35]
	s_barrier
	v_readfirstlane_b32 s9, v163
	v_lshl_add_u64 v[142:143], v[238:239], 0, s[48:49]
	s_mov_b32 m0, s9
	v_readfirstlane_b32 s9, v164
	global_load_lds_dwordx4 v[142:143], off
	v_lshl_add_u64 v[142:143], v[240:241], 0, s[48:49]
	s_mov_b32 m0, s9
	s_nop 0
	global_load_lds_dwordx4 v[142:143], off
	s_waitcnt vmcnt(6)
	s_barrier
	v_mfma_f32_16x16x32_bf16 v[28:31], v[216:219], v[182:185], v[28:31]
	v_mfma_f32_16x16x32_bf16 v[24:27], v[230:233], v[182:185], v[24:27]
	v_mfma_f32_16x16x32_bf16 v[20:23], v[216:219], v[190:193], v[20:23]
	v_mfma_f32_16x16x32_bf16 v[16:19], v[230:233], v[190:193], v[16:19]
	v_mfma_f32_16x16x32_bf16 v[12:15], v[216:219], v[198:201], v[12:15]
	v_mfma_f32_16x16x32_bf16 v[8:11], v[230:233], v[198:201], v[8:11]
	v_mfma_f32_16x16x32_bf16 v[4:7], v[216:219], v[206:209], v[4:7]
	v_mfma_f32_16x16x32_bf16 v[0:3], v[230:233], v[206:209], v[0:3]
	v_mfma_f32_16x16x32_bf16 v[28:31], v[226:229], v[186:189], v[28:31]
	v_mfma_f32_16x16x32_bf16 v[24:27], v[234:237], v[186:189], v[24:27]
	v_mfma_f32_16x16x32_bf16 v[20:23], v[226:229], v[194:197], v[20:23]
	v_mfma_f32_16x16x32_bf16 v[16:19], v[234:237], v[194:197], v[16:19]
	v_mfma_f32_16x16x32_bf16 v[12:15], v[226:229], v[202:205], v[12:15]
	v_mfma_f32_16x16x32_bf16 v[8:11], v[234:237], v[202:205], v[8:11]
	v_mfma_f32_16x16x32_bf16 v[4:7], v[226:229], v[210:213], v[4:7]
	v_mfma_f32_16x16x32_bf16 v[0:3], v[234:237], v[210:213], v[0:3]
	s_add_i32 s7, s7, 2
	s_add_u32 s36, s36, 0x100
	s_addc_u32 s37, s37, 0
	s_cmp_lt_u32 s7, 12
	s_barrier
	s_cbranch_scc1 .LBB0_1172
	s_add_u32 s28, s28, 0x40780
	s_addc_u32 s29, s29, 0
	v_readfirstlane_b32 s7, v167
	v_lshl_add_u64 v[162:163], v[64:65], 1, s[28:29]
	s_mov_b32 m0, s7
	v_readfirstlane_b32 s7, v168
	ds_read_b128 v[132:135], v166
	ds_read_b128 v[136:139], v166 offset:1024
	ds_read_b128 v[142:145], v166 offset:2048
	ds_read_b128 v[152:155], v166 offset:3072
	ds_read_b128 v[158:161], v148
	ds_read_b128 v[170:173], v148 offset:1024
	ds_read_b128 v[174:177], v147
	ds_read_b128 v[178:181], v147 offset:1024
	ds_read_b128 v[182:185], v146
	ds_read_b128 v[186:189], v146 offset:1024
	ds_read_b128 v[190:193], v141
	ds_read_b128 v[194:197], v141 offset:1024
	global_load_lds_dwordx4 v[162:163], off
	v_lshl_add_u64 v[130:131], v[130:131], 1, s[28:29]
	s_mov_b32 m0, s7
	s_nop 0
	global_load_lds_dwordx4 v[130:131], off
	s_barrier
	s_waitcnt lgkmcnt(0)
	v_mfma_f32_16x16x32_bf16 v[126:129], v[132:135], v[158:161], v[126:129]
	v_mfma_f32_16x16x32_bf16 v[122:125], v[142:145], v[158:161], v[122:125]
	v_mfma_f32_16x16x32_bf16 v[110:113], v[132:135], v[182:185], v[110:113]
	v_mfma_f32_16x16x32_bf16 v[106:109], v[142:145], v[182:185], v[106:109]
	v_mfma_f32_16x16x32_bf16 v[102:105], v[132:135], v[190:193], v[102:105]
	v_mfma_f32_16x16x32_bf16 v[98:101], v[142:145], v[190:193], v[98:101]
	v_mfma_f32_16x16x32_bf16 v[126:129], v[136:139], v[170:173], v[126:129]
	v_mfma_f32_16x16x32_bf16 v[122:125], v[152:155], v[170:173], v[122:125]
	v_mfma_f32_16x16x32_bf16 v[118:121], v[132:135], v[174:177], v[118:121]
	v_mfma_f32_16x16x32_bf16 v[114:117], v[142:145], v[174:177], v[114:117]
	v_mfma_f32_16x16x32_bf16 v[110:113], v[136:139], v[186:189], v[110:113]
	v_mfma_f32_16x16x32_bf16 v[106:109], v[152:155], v[186:189], v[106:109]
	v_mfma_f32_16x16x32_bf16 v[102:105], v[136:139], v[194:197], v[102:105]
	v_mfma_f32_16x16x32_bf16 v[98:101], v[152:155], v[194:197], v[98:101]
	v_mfma_f32_16x16x32_bf16 v[166:169], v[136:139], v[178:181], v[118:121]
	v_mfma_f32_16x16x32_bf16 v[198:201], v[152:155], v[178:181], v[114:117]
	s_barrier
	s_nop 0
	ds_read_b128 v[114:117], v165
	ds_read_b128 v[118:121], v165 offset:1024
	ds_read_b128 v[202:205], v165 offset:2048
	ds_read_b128 v[162:165], v165 offset:3072
	s_barrier
	s_waitcnt lgkmcnt(0)
	v_mfma_f32_16x16x32_bf16 v[94:97], v[114:117], v[158:161], v[94:97]
	v_mfma_f32_16x16x32_bf16 v[90:93], v[202:205], v[158:161], v[90:93]
	v_mfma_f32_16x16x32_bf16 v[78:81], v[114:117], v[182:185], v[78:81]
	v_mfma_f32_16x16x32_bf16 v[74:77], v[202:205], v[182:185], v[74:77]
	v_mfma_f32_16x16x32_bf16 v[70:73], v[114:117], v[190:193], v[70:73]
	v_mfma_f32_16x16x32_bf16 v[66:69], v[202:205], v[190:193], v[66:69]
	v_mfma_f32_16x16x32_bf16 v[94:97], v[118:121], v[170:173], v[94:97]
	v_mfma_f32_16x16x32_bf16 v[90:93], v[162:165], v[170:173], v[90:93]
	v_mfma_f32_16x16x32_bf16 v[86:89], v[114:117], v[174:177], v[86:89]
	v_mfma_f32_16x16x32_bf16 v[82:85], v[202:205], v[174:177], v[82:85]
	v_mfma_f32_16x16x32_bf16 v[78:81], v[118:121], v[186:189], v[78:81]
	v_mfma_f32_16x16x32_bf16 v[74:77], v[162:165], v[186:189], v[74:77]
	v_mfma_f32_16x16x32_bf16 v[70:73], v[118:121], v[194:197], v[70:73]
	v_mfma_f32_16x16x32_bf16 v[66:69], v[162:165], v[194:197], v[66:69]
	v_mfma_f32_16x16x32_bf16 v[158:161], v[118:121], v[178:181], v[86:89]
	v_mfma_f32_16x16x32_bf16 v[170:173], v[162:165], v[178:181], v[82:85]
	s_barrier
; #define LDA(dst, b, h) _Pragma("unroll") for (int m = 0; m < 4; ++m) _Pragma("unroll") for (int k = 0; k < 2; ++k) \
;     dst[m][k] = *(const bf16x8*)(lds + SA_(b, h) + lds_byte(wr * 64 + m * 16 + fr, k * 32 + fq * 8));
; #define LDB(dst, b, h) _Pragma("unroll") for (int n = 0; n < 2; ++n) _Pragma("unroll") for (int k = 0; k < 2; ++k) \
;     dst[n][k] = *(const bf16x8*)(lds + SB_(b, h) + lds_byte(wc * 32 + n * 16 + fr, k * 32 + fq * 8));
; #define MMA(ai, bj, At_, Bt_) { __builtin_amdgcn_s_setprio(1); \
;     _Pragma("unroll") for (int m = 0; m < 4; ++m) _Pragma("unroll") for (int n = 0; n < 2; ++n) _Pragma("unroll") for (int k = 0; k < 2; ++k) \
;       acc[ai][bj][m][n] = MFMA16(Bt_[n][k], At_[m][k], acc[ai][bj][m][n]); \
;     __builtin_amdgcn_s_setprio(0); }
; #define WAIT_V(n) asm volatile("s_waitcnt vmcnt(" #n ")" ::: "memory");
; #define WAIT_L(n) asm volatile("s_waitcnt lgkmcnt(" #n ")" ::: "memory");
; #define BAR __builtin_amdgcn_s_barrier();
; DI void gemm256(const u16* __restrict__ A, int lda, const u16* __restrict__ B0, const u16* __restrict__ B1, int ldb, int nt, acc_t& acc, char* lds) {
;     ...
;     BAR WAIT_L(0) MMA(0, 0, At, Bq0) BAR
;     LDB(Bq1, 0, 1) BAR WAIT_L(0) MMA(0, 1, At, Bq1) BAR
;     LDA(At, 0, 1) WAIT_V(4) BAR WAIT_L(0) MMA(1, 0, At, Bq0) MMA(1, 1, At, Bq1) BAR }
;   { LDB(Bq0, 1, 0) LDA(At, 1, 0) WAIT_V(2) BAR WAIT_L(0) MMA(0, 0, At, Bq0) BAR
	s_nop 0
	ds_read_b128 v[82:85], v148 offset:16384
	ds_read_b128 v[86:89], v148 offset:17408
	ds_read_b128 v[174:177], v147 offset:16384
	ds_read_b128 v[178:181], v147 offset:17408
	ds_read_b128 v[182:185], v146 offset:16384
	ds_read_b128 v[186:189], v146 offset:17408
	ds_read_b128 v[190:193], v141 offset:16384
	ds_read_b128 v[194:197], v141 offset:17408
	s_waitcnt vmcnt(4)
	s_barrier
	s_waitcnt lgkmcnt(0)
	v_mfma_f32_16x16x32_bf16 v[36:39], v[132:135], v[190:193], v[36:39]
	v_mfma_f32_16x16x32_bf16 v[32:35], v[142:145], v[190:193], v[32:35]
	v_mfma_f32_16x16x32_bf16 v[60:63], v[132:135], v[82:85], v[60:63]
	v_mfma_f32_16x16x32_bf16 v[56:59], v[142:145], v[82:85], v[56:59]
	v_mfma_f32_16x16x32_bf16 v[52:55], v[132:135], v[174:177], v[52:55]
	v_mfma_f32_16x16x32_bf16 v[48:51], v[142:145], v[174:177], v[48:51]
	v_mfma_f32_16x16x32_bf16 v[44:47], v[132:135], v[182:185], v[44:47]
	v_mfma_f32_16x16x32_bf16 v[40:43], v[142:145], v[182:185], v[40:43]
	v_mfma_f32_16x16x32_bf16 v[36:39], v[136:139], v[194:197], v[36:39]
	v_mfma_f32_16x16x32_bf16 v[32:35], v[152:155], v[194:197], v[32:35]
	v_mfma_f32_16x16x32_bf16 v[206:209], v[136:139], v[86:89], v[60:63]
	v_mfma_f32_16x16x32_bf16 v[210:213], v[152:155], v[86:89], v[56:59]
	v_mfma_f32_16x16x32_bf16 v[216:219], v[136:139], v[178:181], v[52:55]
	v_mfma_f32_16x16x32_bf16 v[226:229], v[152:155], v[178:181], v[48:51]
	v_mfma_f32_16x16x32_bf16 v[230:233], v[136:139], v[186:189], v[44:47]
	v_mfma_f32_16x16x32_bf16 v[234:237], v[152:155], v[186:189], v[40:43]
	v_mfma_f32_16x16x32_bf16 v[12:15], v[114:117], v[182:185], v[12:15]
	v_mfma_f32_16x16x32_bf16 v[8:11], v[202:205], v[182:185], v[8:11]
	v_mfma_f32_16x16x32_bf16 v[28:31], v[114:117], v[82:85], v[28:31]
	v_mfma_f32_16x16x32_bf16 v[24:27], v[202:205], v[82:85], v[24:27]
	v_mfma_f32_16x16x32_bf16 v[20:23], v[114:117], v[174:177], v[20:23]
	v_mfma_f32_16x16x32_bf16 v[16:19], v[202:205], v[174:177], v[16:19]
	v_mfma_f32_16x16x32_bf16 v[12:15], v[118:121], v[186:189], v[12:15]
	v_mfma_f32_16x16x32_bf16 v[8:11], v[162:165], v[186:189], v[8:11]
	v_mfma_f32_16x16x32_bf16 v[4:7], v[114:117], v[190:193], v[4:7]
	v_mfma_f32_16x16x32_bf16 v[0:3], v[202:205], v[190:193], v[0:3]
	v_mfma_f32_16x16x32_bf16 v[130:133], v[118:121], v[86:89], v[28:31]
	v_mfma_f32_16x16x32_bf16 v[134:137], v[162:165], v[86:89], v[24:27]
	v_mfma_f32_16x16x32_bf16 v[142:145], v[118:121], v[178:181], v[20:23]
	v_mfma_f32_16x16x32_bf16 v[152:155], v[162:165], v[178:181], v[16:19]
	v_mfma_f32_16x16x32_bf16 v[174:177], v[118:121], v[194:197], v[4:7]
	v_mfma_f32_16x16x32_bf16 v[162:165], v[162:165], v[194:197], v[0:3]
	s_barrier
	s_nop 0
	ds_read_b128 v[0:3], v156
	ds_read_b128 v[4:7], v156 offset:1024
	ds_read_b128 v[178:181], v156 offset:2048
	ds_read_b128 v[182:185], v156 offset:3072
	ds_read_b128 v[16:19], v148 offset:32768
	ds_read_b128 v[20:23], v148 offset:33792
	ds_read_b128 v[40:43], v147 offset:32768
	ds_read_b128 v[44:47], v147 offset:33792
	ds_read_b128 v[56:59], v146 offset:32768
	ds_read_b128 v[60:63], v146 offset:33792
	ds_read_b128 v[186:189], v141 offset:32768
	ds_read_b128 v[190:193], v141 offset:33792
	s_waitcnt vmcnt(2)
	s_barrier
	s_waitcnt lgkmcnt(0)
	v_mfma_f32_16x16x32_bf16 v[24:27], v[0:3], v[16:19], v[126:129]
	v_mfma_f32_16x16x32_bf16 v[114:117], v[4:7], v[20:23], v[24:27]
	v_mfma_f32_16x16x32_bf16 v[24:27], v[178:181], v[16:19], v[122:125]
	v_mfma_f32_16x16x32_bf16 v[118:121], v[182:185], v[20:23], v[24:27]
	v_mfma_f32_16x16x32_bf16 v[24:27], v[0:3], v[40:43], v[166:169]
	v_mfma_f32_16x16x32_bf16 v[82:85], v[4:7], v[44:47], v[24:27]
	v_mfma_f32_16x16x32_bf16 v[24:27], v[178:181], v[40:43], v[198:201]
	v_mfma_f32_16x16x32_bf16 v[86:89], v[182:185], v[44:47], v[24:27]
	v_mfma_f32_16x16x32_bf16 v[24:27], v[0:3], v[56:59], v[110:113]
	v_mfma_f32_16x16x32_bf16 v[48:51], v[4:7], v[60:63], v[24:27]
	v_mfma_f32_16x16x32_bf16 v[24:27], v[178:181], v[56:59], v[106:109]
	v_mfma_f32_16x16x32_bf16 v[52:55], v[182:185], v[60:63], v[24:27]
	v_mfma_f32_16x16x32_bf16 v[24:27], v[0:3], v[186:189], v[102:105]
	v_mfma_f32_16x16x32_bf16 v[28:31], v[178:181], v[186:189], v[98:101]
	v_mfma_f32_16x16x32_bf16 v[24:27], v[4:7], v[190:193], v[24:27]
	v_mfma_f32_16x16x32_bf16 v[28:31], v[182:185], v[190:193], v[28:31]
	s_barrier
; #define LDA(dst, b, h) _Pragma("unroll") for (int m = 0; m < 4; ++m) _Pragma("unroll") for (int k = 0; k < 2; ++k) \
;     dst[m][k] = *(const bf16x8*)(lds + SA_(b, h) + lds_byte(wr * 64 + m * 16 + fr, k * 32 + fq * 8));
; #define LDB(dst, b, h) _Pragma("unroll") for (int n = 0; n < 2; ++n) _Pragma("unroll") for (int k = 0; k < 2; ++k) \
;     dst[n][k] = *(const bf16x8*)(lds + SB_(b, h) + lds_byte(wc * 32 + n * 16 + fr, k * 32 + fq * 8));
; #define MMA(ai, bj, At_, Bt_) { __builtin_amdgcn_s_setprio(1); \
;     _Pragma("unroll") for (int m = 0; m < 4; ++m) _Pragma("unroll") for (int n = 0; n < 2; ++n) _Pragma("unroll") for (int k = 0; k < 2; ++k) \
;       acc[ai][bj][m][n] = MFMA16(Bt_[n][k], At_[m][k], acc[ai][bj][m][n]); \
;     __builtin_amdgcn_s_setprio(0); }
; #define WAIT_V(n) asm volatile("s_waitcnt vmcnt(" #n ")" ::: "memory");
; #define WAIT_L(n) asm volatile("s_waitcnt lgkmcnt(" #n ")" ::: "memory");
; #define BAR __builtin_amdgcn_s_barrier();
; DI void gemm256(const u16* __restrict__ A, int lda, const u16* __restrict__ B0, const u16* __restrict__ B1, int ldb, int nt, acc_t& acc, char* lds) {
;     ...
;     LDB(Bq1, 1, 1) WAIT_V(0) BAR WAIT_L(0) MMA(0, 1, At, Bq1) BAR
;     LDA(At, 1, 1) BAR WAIT_L(0) MMA(1, 0, At, Bq0) MMA(1, 1, At, Bq1) BAR }
;   if (wr == 0) BAR
;   __syncthreads();
	ds_read_b128 v[166:169], v151
	ds_read_b128 v[194:197], v151 offset:1024
	ds_read_b128 v[198:201], v151 offset:2048
	ds_read_b128 v[202:205], v151 offset:3072
	s_waitcnt vmcnt(0)
	s_barrier
	s_waitcnt lgkmcnt(0)
	v_mfma_f32_16x16x32_bf16 v[94:97], v[166:169], v[16:19], v[94:97]
	v_mfma_f32_16x16x32_bf16 v[16:19], v[198:201], v[16:19], v[90:93]
	v_mfma_f32_16x16x32_bf16 v[126:129], v[202:205], v[20:23], v[16:19]
	v_mfma_f32_16x16x32_bf16 v[16:19], v[166:169], v[40:43], v[158:161]
	v_mfma_f32_16x16x32_bf16 v[106:109], v[194:197], v[44:47], v[16:19]
	v_mfma_f32_16x16x32_bf16 v[16:19], v[198:201], v[40:43], v[170:173]
	v_mfma_f32_16x16x32_bf16 v[110:113], v[202:205], v[44:47], v[16:19]
	v_mfma_f32_16x16x32_bf16 v[16:19], v[166:169], v[56:59], v[78:81]
	v_mfma_f32_16x16x32_bf16 v[90:93], v[194:197], v[60:63], v[16:19]
	v_mfma_f32_16x16x32_bf16 v[16:19], v[198:201], v[56:59], v[74:77]
	v_mfma_f32_16x16x32_bf16 v[122:125], v[194:197], v[20:23], v[94:97]
	v_mfma_f32_16x16x32_bf16 v[94:97], v[202:205], v[60:63], v[16:19]
	v_mfma_f32_16x16x32_bf16 v[16:19], v[166:169], v[186:189], v[70:73]
	v_mfma_f32_16x16x32_bf16 v[56:59], v[194:197], v[190:193], v[16:19]
	v_mfma_f32_16x16x32_bf16 v[16:19], v[198:201], v[186:189], v[66:69]
	v_mfma_f32_16x16x32_bf16 v[60:63], v[202:205], v[190:193], v[16:19]
	s_barrier
	ds_read_b128 v[66:69], v148 offset:49152
	ds_read_b128 v[70:73], v148 offset:50176
	ds_read_b128 v[148:151], v147 offset:49152
	ds_read_b128 v[156:159], v147 offset:50176
	ds_read_b128 v[170:173], v146 offset:49152
	ds_read_b128 v[186:189], v146 offset:50176
	ds_read_b128 v[190:193], v141 offset:49152
	ds_read_b128 v[238:241], v141 offset:50176
	s_barrier
	s_waitcnt lgkmcnt(0)
	v_mfma_f32_16x16x32_bf16 v[16:19], v[0:3], v[66:69], v[206:209]
	v_mfma_f32_16x16x32_bf16 v[74:77], v[4:7], v[70:73], v[16:19]
	v_mfma_f32_16x16x32_bf16 v[16:19], v[178:181], v[66:69], v[210:213]
	v_mfma_f32_16x16x32_bf16 v[78:81], v[182:185], v[70:73], v[16:19]
	v_mfma_f32_16x16x32_bf16 v[16:19], v[0:3], v[148:151], v[216:219]
	v_mfma_f32_16x16x32_bf16 v[40:43], v[4:7], v[156:159], v[16:19]
	v_mfma_f32_16x16x32_bf16 v[16:19], v[178:181], v[148:151], v[226:229]
	v_mfma_f32_16x16x32_bf16 v[44:47], v[182:185], v[156:159], v[16:19]
	v_mfma_f32_16x16x32_bf16 v[16:19], v[0:3], v[170:173], v[230:233]
	v_mfma_f32_16x16x32_bf16 v[0:3], v[0:3], v[190:193], v[36:39]
	v_mfma_f32_16x16x32_bf16 v[16:19], v[4:7], v[186:189], v[16:19]
	v_mfma_f32_16x16x32_bf16 v[20:23], v[178:181], v[170:173], v[234:237]
	v_mfma_f32_16x16x32_bf16 v[0:3], v[4:7], v[238:241], v[0:3]
	v_mfma_f32_16x16x32_bf16 v[4:7], v[178:181], v[190:193], v[32:35]
	v_mfma_f32_16x16x32_bf16 v[20:23], v[182:185], v[186:189], v[20:23]
	v_mfma_f32_16x16x32_bf16 v[4:7], v[182:185], v[238:241], v[4:7]
	v_mfma_f32_16x16x32_bf16 v[32:35], v[166:169], v[66:69], v[130:133]
	v_mfma_f32_16x16x32_bf16 v[98:101], v[194:197], v[70:73], v[32:35]
	v_mfma_f32_16x16x32_bf16 v[32:35], v[198:201], v[66:69], v[134:137]
	v_mfma_f32_16x16x32_bf16 v[102:105], v[202:205], v[70:73], v[32:35]
	v_mfma_f32_16x16x32_bf16 v[32:35], v[166:169], v[148:151], v[142:145]
	v_mfma_f32_16x16x32_bf16 v[66:69], v[194:197], v[156:159], v[32:35]
	v_mfma_f32_16x16x32_bf16 v[32:35], v[198:201], v[148:151], v[152:155]
	v_mfma_f32_16x16x32_bf16 v[12:15], v[166:169], v[170:173], v[12:15]
	v_mfma_f32_16x16x32_bf16 v[8:11], v[198:201], v[170:173], v[8:11]
	v_mfma_f32_16x16x32_bf16 v[70:73], v[202:205], v[156:159], v[32:35]
	v_mfma_f32_16x16x32_bf16 v[32:35], v[194:197], v[186:189], v[12:15]
	v_mfma_f32_16x16x32_bf16 v[36:39], v[202:205], v[186:189], v[8:11]
	v_mfma_f32_16x16x32_bf16 v[8:11], v[166:169], v[190:193], v[174:177]
	v_mfma_f32_16x16x32_bf16 v[12:15], v[198:201], v[190:193], v[162:165]
	v_mfma_f32_16x16x32_bf16 v[8:11], v[194:197], v[238:241], v[8:11]
	v_mfma_f32_16x16x32_bf16 v[12:15], v[202:205], v[238:241], v[12:15]
	s_movk_i32 s7, 0x100
	v_cmp_gt_u32_e32 vcc, s7, v140
	s_barrier
	s_and_saveexec_b64 s[28:29], vcc
	s_cbranch_execz .LBB0_1175
	s_barrier

; #define STAGE_A(b, h, kt) { const u16* ap_ = A + (size_t)((h) * ahalf + (unsigned)(kt) * 64u); glds16(ap_ + ao0, l0 + SA_(b, h)); glds16(ap_ + ao1, l0 + SA_(b, h) + 8192); }
; #define STAGE_B(b, h, kt) { const u16* bp_ = ((h) ? B1 : B0) + (unsigned)(kt) * 64u; glds16(bp_ + bo0, l0 + SB_(b, h)); glds16(bp_ + bo1, l0 + SB_(b, h) + 8192); }
; #define LDA(dst, b, h) _Pragma("unroll") for (int m = 0; m < 4; ++m) _Pragma("unroll") for (int k = 0; k < 2; ++k) \
;     dst[m][k] = *(const bf16x8*)(lds + SA_(b, h) + lds_byte(wr * 64 + m * 16 + fr, k * 32 + fq * 8));
; #define LDB(dst, b, h) _Pragma("unroll") for (int n = 0; n < 2; ++n) _Pragma("unroll") for (int k = 0; k < 2; ++k) \
;     dst[n][k] = *(const bf16x8*)(lds + SB_(b, h) + lds_byte(wc * 32 + n * 16 + fr, k * 32 + fq * 8));
; #define MMA(ai, bj, At_, Bt_) { __builtin_amdgcn_s_setprio(1); \
;     _Pragma("unroll") for (int m = 0; m < 4; ++m) _Pragma("unroll") for (int n = 0; n < 2; ++n) _Pragma("unroll") for (int k = 0; k < 2; ++k) \
;       acc[ai][bj][m][n] = MFMA16(Bt_[n][k], At_[m][k], acc[ai][bj][m][n]); \
;     __builtin_amdgcn_s_setprio(0); }
; #define WAIT_L(n) asm volatile("s_waitcnt lgkmcnt(" #n ")" ::: "memory");
; #define BAR __builtin_amdgcn_s_barrier();
; #define SCHED __builtin_amdgcn_sched_barrier(0);
; DI void gemm256(const u16* __restrict__ A, int lda, const u16* __restrict__ B0, const u16* __restrict__ B1, int ldb, int nt, acc_t& acc, char* lds) {
;     ...
;   for (int t = 0; t < nt - 2; t += 2) {
;     LDB(Bq0, 0, 0) SCHED LDA(At, 0, 0) STAGE_A(1, 1, t + 1)
;     WAIT_L(8) BAR WAIT_L(0) MMA(0, 0, At, Bq0) BAR SCHED
;     LDB(Bq1, 0, 1) STAGE_B(0, 0, t + 2)
;     BAR WAIT_L(0) MMA(0, 1, At, Bq1) BAR
;     LDA(At, 0, 1) STAGE_A(0, 0, t + 2)
;     BAR WAIT_L(0) MMA(1, 0, At, Bq0) BAR SCHED
.LBB0_1260:
	ds_read_b128 v[142:145], v166
	ds_read_b128 v[170:173], v166 offset:1024
	ds_read_b128 v[174:177], v166 offset:2048
	ds_read_b128 v[178:181], v166 offset:3072
	v_lshl_add_u64 v[222:223], s[28:29], 0, v[136:137]
	v_readfirstlane_b32 s7, v167
	v_lshl_add_u64 v[168:169], v[222:223], 0, s[76:77]
	s_mov_b32 m0, s7
	ds_read_b128 v[182:185], v150
	ds_read_b128 v[190:193], v149
	ds_read_b128 v[198:201], v148
	ds_read_b128 v[206:209], v147
	global_load_lds_dwordx4 v[168:169], off
	v_add_u32_e32 v168, 0xe000, v140
	v_lshl_add_u64 v[224:225], s[28:29], 0, v[138:139]
	v_readfirstlane_b32 s7, v168
	v_lshl_add_u64 v[216:217], v[224:225], 0, s[76:77]
	s_mov_b32 m0, s7
	s_nop 0
	global_load_lds_dwordx4 v[216:217], off
	s_waitcnt lgkmcnt(4)
	s_barrier
	s_waitcnt lgkmcnt(0)
	ds_read_b128 v[186:189], v150 offset:1024
	ds_read_b128 v[194:197], v149 offset:1024
	ds_read_b128 v[202:205], v148 offset:1024
	ds_read_b128 v[210:213], v147 offset:1024
	v_mfma_f32_16x16x32_bf16 v[126:129], v[142:145], v[182:185], v[126:129]
	v_mfma_f32_16x16x32_bf16 v[122:125], v[174:177], v[182:185], v[122:125]
	v_mfma_f32_16x16x32_bf16 v[118:121], v[142:145], v[190:193], v[118:121]
	v_mfma_f32_16x16x32_bf16 v[114:117], v[174:177], v[190:193], v[114:117]
	v_mfma_f32_16x16x32_bf16 v[110:113], v[142:145], v[198:201], v[110:113]
	v_mfma_f32_16x16x32_bf16 v[106:109], v[174:177], v[198:201], v[106:109]
	v_mfma_f32_16x16x32_bf16 v[102:105], v[142:145], v[206:209], v[102:105]
	v_mfma_f32_16x16x32_bf16 v[98:101], v[174:177], v[206:209], v[98:101]
	s_waitcnt lgkmcnt(0)
	v_mfma_f32_16x16x32_bf16 v[126:129], v[170:173], v[186:189], v[126:129]
	v_mfma_f32_16x16x32_bf16 v[122:125], v[178:181], v[186:189], v[122:125]
	v_mfma_f32_16x16x32_bf16 v[118:121], v[170:173], v[194:197], v[118:121]
	v_mfma_f32_16x16x32_bf16 v[114:117], v[178:181], v[194:197], v[114:117]
	v_mfma_f32_16x16x32_bf16 v[110:113], v[170:173], v[202:205], v[110:113]
	v_mfma_f32_16x16x32_bf16 v[106:109], v[178:181], v[202:205], v[106:109]
	v_mfma_f32_16x16x32_bf16 v[102:105], v[170:173], v[210:213], v[102:105]
	v_mfma_f32_16x16x32_bf16 v[98:101], v[178:181], v[210:213], v[98:101]
	s_barrier
	v_lshl_add_u64 v[238:239], s[28:29], 0, v[132:133]
	v_readfirstlane_b32 s7, v141
	v_lshl_add_u64 v[240:241], v[238:239], 0, s[44:45]
	s_mov_b32 m0, s7
	ds_read_b128 v[216:219], v165
	ds_read_b128 v[226:229], v165 offset:1024
	ds_read_b128 v[230:233], v165 offset:2048
	ds_read_b128 v[234:237], v165 offset:3072
	global_load_lds_dwordx4 v[240:241], off
	v_lshl_add_u64 v[240:241], s[28:29], 0, v[134:135]
	v_readfirstlane_b32 s7, v152
	v_lshl_add_u64 v[242:243], v[240:241], 0, s[44:45]
	s_mov_b32 m0, s7
	s_nop 0
	global_load_lds_dwordx4 v[242:243], off
	s_barrier
	s_waitcnt lgkmcnt(0)
	v_mfma_f32_16x16x32_bf16 v[94:97], v[216:219], v[182:185], v[94:97]
	v_mfma_f32_16x16x32_bf16 v[90:93], v[230:233], v[182:185], v[90:93]
	v_mfma_f32_16x16x32_bf16 v[86:89], v[216:219], v[190:193], v[86:89]
	v_mfma_f32_16x16x32_bf16 v[82:85], v[230:233], v[190:193], v[82:85]
	v_mfma_f32_16x16x32_bf16 v[78:81], v[216:219], v[198:201], v[78:81]
	v_mfma_f32_16x16x32_bf16 v[74:77], v[230:233], v[198:201], v[74:77]
	v_mfma_f32_16x16x32_bf16 v[70:73], v[216:219], v[206:209], v[70:73]
	v_mfma_f32_16x16x32_bf16 v[66:69], v[230:233], v[206:209], v[66:69]
	v_mfma_f32_16x16x32_bf16 v[94:97], v[226:229], v[186:189], v[94:97]
	v_mfma_f32_16x16x32_bf16 v[90:93], v[234:237], v[186:189], v[90:93]
	v_mfma_f32_16x16x32_bf16 v[86:89], v[226:229], v[194:197], v[86:89]
	v_mfma_f32_16x16x32_bf16 v[82:85], v[234:237], v[194:197], v[82:85]
	v_mfma_f32_16x16x32_bf16 v[78:81], v[226:229], v[202:205], v[78:81]
	v_mfma_f32_16x16x32_bf16 v[74:77], v[234:237], v[202:205], v[74:77]
	v_mfma_f32_16x16x32_bf16 v[70:73], v[226:229], v[210:213], v[70:73]
	v_mfma_f32_16x16x32_bf16 v[66:69], v[234:237], v[210:213], v[66:69]
	v_readfirstlane_b32 s7, v140
	v_lshl_add_u64 v[242:243], v[222:223], 0, s[80:81]
	s_mov_b32 m0, s7
	v_readfirstlane_b32 s7, v153
	s_barrier
	ds_read_b128 v[182:185], v150 offset:16384
	ds_read_b128 v[190:193], v149 offset:16384
	ds_read_b128 v[198:201], v148 offset:16384
	ds_read_b128 v[206:209], v147 offset:16384
	global_load_lds_dwordx4 v[242:243], off
	v_lshl_add_u64 v[242:243], v[224:225], 0, s[80:81]
	s_mov_b32 m0, s7
	s_nop 0
	global_load_lds_dwordx4 v[242:243], off
	s_barrier
	s_waitcnt lgkmcnt(0)
	ds_read_b128 v[186:189], v150 offset:17408
	ds_read_b128 v[194:197], v149 offset:17408
	ds_read_b128 v[202:205], v148 offset:17408
	ds_read_b128 v[210:213], v147 offset:17408
	v_mfma_f32_16x16x32_bf16 v[60:63], v[142:145], v[182:185], v[60:63]
	v_mfma_f32_16x16x32_bf16 v[56:59], v[174:177], v[182:185], v[56:59]
	v_mfma_f32_16x16x32_bf16 v[52:55], v[142:145], v[190:193], v[52:55]
	v_mfma_f32_16x16x32_bf16 v[48:51], v[174:177], v[190:193], v[48:51]
	v_mfma_f32_16x16x32_bf16 v[44:47], v[142:145], v[198:201], v[44:47]
	v_mfma_f32_16x16x32_bf16 v[40:43], v[174:177], v[198:201], v[40:43]
	v_mfma_f32_16x16x32_bf16 v[36:39], v[142:145], v[206:209], v[36:39]
	v_mfma_f32_16x16x32_bf16 v[32:35], v[174:177], v[206:209], v[32:35]
	s_waitcnt lgkmcnt(0)
	v_mfma_f32_16x16x32_bf16 v[60:63], v[170:173], v[186:189], v[60:63]
	v_mfma_f32_16x16x32_bf16 v[56:59], v[178:181], v[186:189], v[56:59]
	v_mfma_f32_16x16x32_bf16 v[52:55], v[170:173], v[194:197], v[52:55]
	v_mfma_f32_16x16x32_bf16 v[48:51], v[178:181], v[194:197], v[48:51]
	v_mfma_f32_16x16x32_bf16 v[44:47], v[170:173], v[202:205], v[44:47]
	v_mfma_f32_16x16x32_bf16 v[40:43], v[178:181], v[202:205], v[40:43]
	v_mfma_f32_16x16x32_bf16 v[36:39], v[170:173], v[210:213], v[36:39]
	v_mfma_f32_16x16x32_bf16 v[32:35], v[178:181], v[210:213], v[32:35]
	s_barrier
; #define STAGE_A(b, h, kt) { const u16* ap_ = A + (size_t)((h) * ahalf + (unsigned)(kt) * 64u); glds16(ap_ + ao0, l0 + SA_(b, h)); glds16(ap_ + ao1, l0 + SA_(b, h) + 8192); }
; #define STAGE_B(b, h, kt) { const u16* bp_ = ((h) ? B1 : B0) + (unsigned)(kt) * 64u; glds16(bp_ + bo0, l0 + SB_(b, h)); glds16(bp_ + bo1, l0 + SB_(b, h) + 8192); }
; #define LDA(dst, b, h) _Pragma("unroll") for (int m = 0; m < 4; ++m) _Pragma("unroll") for (int k = 0; k < 2; ++k) \
;     dst[m][k] = *(const bf16x8*)(lds + SA_(b, h) + lds_byte(wr * 64 + m * 16 + fr, k * 32 + fq * 8));
; #define LDB(dst, b, h) _Pragma("unroll") for (int n = 0; n < 2; ++n) _Pragma("unroll") for (int k = 0; k < 2; ++k) \
;     dst[n][k] = *(const bf16x8*)(lds + SB_(b, h) + lds_byte(wc * 32 + n * 16 + fr, k * 32 + fq * 8));
; #define MMA(ai, bj, At_, Bt_) { __builtin_amdgcn_s_setprio(1); \
;     _Pragma("unroll") for (int m = 0; m < 4; ++m) _Pragma("unroll") for (int n = 0; n < 2; ++n) _Pragma("unroll") for (int k = 0; k < 2; ++k) \
;       acc[ai][bj][m][n] = MFMA16(Bt_[n][k], At_[m][k], acc[ai][bj][m][n]); \
;     __builtin_amdgcn_s_setprio(0); }
; #define WAIT_V(n) asm volatile("s_waitcnt vmcnt(" #n ")" ::: "memory");
; #define WAIT_L(n) asm volatile("s_waitcnt lgkmcnt(" #n ")" ::: "memory");
; #define BAR __builtin_amdgcn_s_barrier();
; #define SCHED __builtin_amdgcn_sched_barrier(0);
; DI void gemm256(const u16* __restrict__ A, int lda, const u16* __restrict__ B0, const u16* __restrict__ B1, int ldb, int nt, acc_t& acc, char* lds) {
;     ...
;     BAR WAIT_L(0) MMA(1, 0, At, Bq0) BAR SCHED
;     STAGE_B(0, 1, t + 2)
;     WAIT_V(6) BAR MMA(1, 1, At, Bq1) BAR
;     LDB(Bq0, 1, 0) SCHED LDA(At, 1, 0) STAGE_A(0, 1, t + 2)
;     WAIT_L(8) BAR WAIT_L(0) MMA(0, 0, At, Bq0) BAR SCHED
;     LDB(Bq1, 1, 1) STAGE_B(1, 0, t + 3)
;     BAR WAIT_L(0) MMA(0, 1, At, Bq1) BAR
;     LDA(At, 1, 1) STAGE_A(1, 0, t + 3)
;     BAR WAIT_L(0) MMA(1, 0, At, Bq0) BAR SCHED
	v_readfirstlane_b32 s7, v154
	v_lshl_add_u64 v[142:143], v[238:239], 0, s[46:47]
	s_mov_b32 m0, s7
	v_readfirstlane_b32 s7, v155
	global_load_lds_dwordx4 v[142:143], off
	v_lshl_add_u64 v[142:143], v[240:241], 0, s[46:47]
	s_mov_b32 m0, s7
	s_nop 0
	global_load_lds_dwordx4 v[142:143], off
	s_waitcnt vmcnt(6)
	s_barrier
	v_mfma_f32_16x16x32_bf16 v[28:31], v[216:219], v[182:185], v[28:31]
	v_mfma_f32_16x16x32_bf16 v[24:27], v[230:233], v[182:185], v[24:27]
	v_mfma_f32_16x16x32_bf16 v[20:23], v[216:219], v[190:193], v[20:23]
	v_mfma_f32_16x16x32_bf16 v[16:19], v[230:233], v[190:193], v[16:19]
	v_mfma_f32_16x16x32_bf16 v[12:15], v[216:219], v[198:201], v[12:15]
	v_mfma_f32_16x16x32_bf16 v[8:11], v[230:233], v[198:201], v[8:11]
	v_mfma_f32_16x16x32_bf16 v[4:7], v[216:219], v[206:209], v[4:7]
	v_mfma_f32_16x16x32_bf16 v[0:3], v[230:233], v[206:209], v[0:3]
	v_mfma_f32_16x16x32_bf16 v[28:31], v[226:229], v[186:189], v[28:31]
	v_mfma_f32_16x16x32_bf16 v[24:27], v[234:237], v[186:189], v[24:27]
	v_mfma_f32_16x16x32_bf16 v[20:23], v[226:229], v[194:197], v[20:23]
	v_mfma_f32_16x16x32_bf16 v[16:19], v[234:237], v[194:197], v[16:19]
	v_mfma_f32_16x16x32_bf16 v[12:15], v[226:229], v[202:205], v[12:15]
	v_mfma_f32_16x16x32_bf16 v[8:11], v[234:237], v[202:205], v[8:11]
	v_mfma_f32_16x16x32_bf16 v[4:7], v[226:229], v[210:213], v[4:7]
	v_mfma_f32_16x16x32_bf16 v[0:3], v[234:237], v[210:213], v[0:3]
	s_barrier
	ds_read_b128 v[142:145], v156
	ds_read_b128 v[170:173], v156 offset:1024
	ds_read_b128 v[174:177], v156 offset:2048
	ds_read_b128 v[178:181], v156 offset:3072
	v_readfirstlane_b32 s7, v157
	v_lshl_add_u64 v[216:217], v[222:223], 0, s[4:5]
	s_mov_b32 m0, s7
	v_readfirstlane_b32 s7, v158
	ds_read_b128 v[182:185], v150 offset:32768
	ds_read_b128 v[190:193], v149 offset:32768
	ds_read_b128 v[198:201], v148 offset:32768
	ds_read_b128 v[206:209], v147 offset:32768
	global_load_lds_dwordx4 v[216:217], off
	v_lshl_add_u64 v[216:217], v[224:225], 0, s[4:5]
	s_mov_b32 m0, s7
	s_nop 0
	global_load_lds_dwordx4 v[216:217], off
	s_waitcnt lgkmcnt(4)
	s_barrier
	s_waitcnt lgkmcnt(0)
	ds_read_b128 v[186:189], v150 offset:33792
	ds_read_b128 v[194:197], v149 offset:33792
	ds_read_b128 v[202:205], v148 offset:33792
	ds_read_b128 v[210:213], v147 offset:33792
	v_mfma_f32_16x16x32_bf16 v[126:129], v[142:145], v[182:185], v[126:129]
	v_mfma_f32_16x16x32_bf16 v[122:125], v[174:177], v[182:185], v[122:125]
	v_mfma_f32_16x16x32_bf16 v[118:121], v[142:145], v[190:193], v[118:121]
	v_mfma_f32_16x16x32_bf16 v[114:117], v[174:177], v[190:193], v[114:117]
	v_mfma_f32_16x16x32_bf16 v[110:113], v[142:145], v[198:201], v[110:113]
	v_mfma_f32_16x16x32_bf16 v[106:109], v[174:177], v[198:201], v[106:109]
	v_mfma_f32_16x16x32_bf16 v[102:105], v[142:145], v[206:209], v[102:105]
	v_mfma_f32_16x16x32_bf16 v[98:101], v[174:177], v[206:209], v[98:101]
	s_waitcnt lgkmcnt(0)
	v_mfma_f32_16x16x32_bf16 v[126:129], v[170:173], v[186:189], v[126:129]
	v_mfma_f32_16x16x32_bf16 v[122:125], v[178:181], v[186:189], v[122:125]
	v_mfma_f32_16x16x32_bf16 v[118:121], v[170:173], v[194:197], v[118:121]
	v_mfma_f32_16x16x32_bf16 v[114:117], v[178:181], v[194:197], v[114:117]
	v_mfma_f32_16x16x32_bf16 v[110:113], v[170:173], v[202:205], v[110:113]
	v_mfma_f32_16x16x32_bf16 v[106:109], v[178:181], v[202:205], v[106:109]
	v_mfma_f32_16x16x32_bf16 v[102:105], v[170:173], v[210:213], v[102:105]
	v_mfma_f32_16x16x32_bf16 v[98:101], v[178:181], v[210:213], v[98:101]
	s_barrier
	v_readfirstlane_b32 s7, v159
	v_lshl_add_u64 v[242:243], v[238:239], 0, s[54:55]
	s_mov_b32 m0, s7
	v_readfirstlane_b32 s7, v160
	ds_read_b128 v[216:219], v151
	ds_read_b128 v[226:229], v151 offset:1024
	ds_read_b128 v[230:233], v151 offset:2048
	ds_read_b128 v[234:237], v151 offset:3072
	global_load_lds_dwordx4 v[242:243], off
	v_lshl_add_u64 v[242:243], v[240:241], 0, s[54:55]
	s_mov_b32 m0, s7
	s_nop 0
	global_load_lds_dwordx4 v[242:243], off
	s_barrier
	s_waitcnt lgkmcnt(0)
	v_mfma_f32_16x16x32_bf16 v[94:97], v[216:219], v[182:185], v[94:97]
	v_mfma_f32_16x16x32_bf16 v[90:93], v[230:233], v[182:185], v[90:93]
	v_mfma_f32_16x16x32_bf16 v[86:89], v[216:219], v[190:193], v[86:89]
	v_mfma_f32_16x16x32_bf16 v[82:85], v[230:233], v[190:193], v[82:85]
	v_mfma_f32_16x16x32_bf16 v[78:81], v[216:219], v[198:201], v[78:81]
	v_mfma_f32_16x16x32_bf16 v[74:77], v[230:233], v[198:201], v[74:77]
	v_mfma_f32_16x16x32_bf16 v[70:73], v[216:219], v[206:209], v[70:73]
	v_mfma_f32_16x16x32_bf16 v[66:69], v[230:233], v[206:209], v[66:69]
	v_mfma_f32_16x16x32_bf16 v[94:97], v[226:229], v[186:189], v[94:97]
	v_mfma_f32_16x16x32_bf16 v[90:93], v[234:237], v[186:189], v[90:93]
	v_mfma_f32_16x16x32_bf16 v[86:89], v[226:229], v[194:197], v[86:89]
	v_mfma_f32_16x16x32_bf16 v[82:85], v[234:237], v[194:197], v[82:85]
	v_mfma_f32_16x16x32_bf16 v[78:81], v[226:229], v[202:205], v[78:81]
	v_mfma_f32_16x16x32_bf16 v[74:77], v[234:237], v[202:205], v[74:77]
	v_mfma_f32_16x16x32_bf16 v[70:73], v[226:229], v[210:213], v[70:73]
	v_mfma_f32_16x16x32_bf16 v[66:69], v[234:237], v[210:213], v[66:69]
	v_readfirstlane_b32 s7, v161
	v_lshl_add_u64 v[222:223], v[222:223], 0, s[30:31]
	s_mov_b32 m0, s7
	v_readfirstlane_b32 s7, v162
	s_barrier
	ds_read_b128 v[182:185], v150 offset:49152
	ds_read_b128 v[190:193], v149 offset:49152
	ds_read_b128 v[198:201], v148 offset:49152
	ds_read_b128 v[206:209], v147 offset:49152
	global_load_lds_dwordx4 v[222:223], off
	v_lshl_add_u64 v[222:223], v[224:225], 0, s[30:31]
	s_mov_b32 m0, s7
	s_nop 0
	global_load_lds_dwordx4 v[222:223], off
	s_barrier
; #define STAGE_A(b, h, kt) { const u16* ap_ = A + (size_t)((h) * ahalf + (unsigned)(kt) * 64u); glds16(ap_ + ao0, l0 + SA_(b, h)); glds16(ap_ + ao1, l0 + SA_(b, h) + 8192); }
; #define STAGE_B(b, h, kt) { const u16* bp_ = ((h) ? B1 : B0) + (unsigned)(kt) * 64u; glds16(bp_ + bo0, l0 + SB_(b, h)); glds16(bp_ + bo1, l0 + SB_(b, h) + 8192); }
; #define LDA(dst, b, h) _Pragma("unroll") for (int m = 0; m < 4; ++m) _Pragma("unroll") for (int k = 0; k < 2; ++k) \
;     dst[m][k] = *(const bf16x8*)(lds + SA_(b, h) + lds_byte(wr * 64 + m * 16 + fr, k * 32 + fq * 8));
; #define LDB(dst, b, h) _Pragma("unroll") for (int n = 0; n < 2; ++n) _Pragma("unroll") for (int k = 0; k < 2; ++k) \
;     dst[n][k] = *(const bf16x8*)(lds + SB_(b, h) + lds_byte(wc * 32 + n * 16 + fr, k * 32 + fq * 8));
; #define MMA(ai, bj, At_, Bt_) { __builtin_amdgcn_s_setprio(1); \
;     _Pragma("unroll") for (int m = 0; m < 4; ++m) _Pragma("unroll") for (int n = 0; n < 2; ++n) _Pragma("unroll") for (int k = 0; k < 2; ++k) \
;       acc[ai][bj][m][n] = MFMA16(Bt_[n][k], At_[m][k], acc[ai][bj][m][n]); \
;     __builtin_amdgcn_s_setprio(0); }
; #define WAIT_V(n) asm volatile("s_waitcnt vmcnt(" #n ")" ::: "memory");
; #define WAIT_L(n) asm volatile("s_waitcnt lgkmcnt(" #n ")" ::: "memory");
; #define BAR __builtin_amdgcn_s_barrier();
; #define SCHED __builtin_amdgcn_sched_barrier(0);
; DI void gemm256(const u16* __restrict__ A, int lda, const u16* __restrict__ B0, const u16* __restrict__ B1, int ldb, int nt, acc_t& acc, char* lds) {
;     ...
;     BAR WAIT_L(0) MMA(1, 0, At, Bq0) BAR SCHED
;     STAGE_B(1, 1, t + 3)
;     WAIT_V(6) BAR MMA(1, 1, At, Bq1) BAR
;   }
;   { LDB(Bq0, 0, 0) LDA(At, 0, 0) STAGE_A(1, 1, nt - 1)
;     BAR WAIT_L(0) MMA(0, 0, At, Bq0) BAR
;     LDB(Bq1, 0, 1) BAR WAIT_L(0) MMA(0, 1, At, Bq1) BAR
;     LDA(At, 0, 1) WAIT_V(4) BAR WAIT_L(0) MMA(1, 0, At, Bq0) MMA(1, 1, At, Bq1) BAR }
;   { LDB(Bq0, 1, 0) LDA(At, 1, 0) WAIT_V(2) BAR WAIT_L(0) MMA(0, 0, At, Bq0) BAR
	s_waitcnt lgkmcnt(0)
	ds_read_b128 v[186:189], v150 offset:50176
	ds_read_b128 v[194:197], v149 offset:50176
	ds_read_b128 v[202:205], v148 offset:50176
	ds_read_b128 v[210:213], v147 offset:50176
	v_mfma_f32_16x16x32_bf16 v[60:63], v[142:145], v[182:185], v[60:63]
	v_mfma_f32_16x16x32_bf16 v[56:59], v[174:177], v[182:185], v[56:59]
	v_mfma_f32_16x16x32_bf16 v[52:55], v[142:145], v[190:193], v[52:55]
	v_mfma_f32_16x16x32_bf16 v[48:51], v[174:177], v[190:193], v[48:51]
	v_mfma_f32_16x16x32_bf16 v[44:47], v[142:145], v[198:201], v[44:47]
	v_mfma_f32_16x16x32_bf16 v[40:43], v[174:177], v[198:201], v[40:43]
	v_mfma_f32_16x16x32_bf16 v[36:39], v[142:145], v[206:209], v[36:39]
	v_mfma_f32_16x16x32_bf16 v[32:35], v[174:177], v[206:209], v[32:35]
	s_waitcnt lgkmcnt(0)
	v_mfma_f32_16x16x32_bf16 v[60:63], v[170:173], v[186:189], v[60:63]
	v_mfma_f32_16x16x32_bf16 v[56:59], v[178:181], v[186:189], v[56:59]
	v_mfma_f32_16x16x32_bf16 v[52:55], v[170:173], v[194:197], v[52:55]
	v_mfma_f32_16x16x32_bf16 v[48:51], v[178:181], v[194:197], v[48:51]
	v_mfma_f32_16x16x32_bf16 v[44:47], v[170:173], v[202:205], v[44:47]
	v_mfma_f32_16x16x32_bf16 v[40:43], v[178:181], v[202:205], v[40:43]
	v_mfma_f32_16x16x32_bf16 v[36:39], v[170:173], v[210:213], v[36:39]
	v_mfma_f32_16x16x32_bf16 v[32:35], v[178:181], v[210:213], v[32:35]
	s_barrier
	v_readfirstlane_b32 s7, v163
	v_lshl_add_u64 v[142:143], v[238:239], 0, s[56:57]
	s_mov_b32 m0, s7
	v_readfirstlane_b32 s7, v164
	global_load_lds_dwordx4 v[142:143], off
	v_lshl_add_u64 v[142:143], v[240:241], 0, s[56:57]
	s_mov_b32 m0, s7
	s_nop 0
	global_load_lds_dwordx4 v[142:143], off
	s_waitcnt vmcnt(6)
	s_barrier
	v_mfma_f32_16x16x32_bf16 v[28:31], v[216:219], v[182:185], v[28:31]
	v_mfma_f32_16x16x32_bf16 v[24:27], v[230:233], v[182:185], v[24:27]
	v_mfma_f32_16x16x32_bf16 v[20:23], v[216:219], v[190:193], v[20:23]
	v_mfma_f32_16x16x32_bf16 v[16:19], v[230:233], v[190:193], v[16:19]
	v_mfma_f32_16x16x32_bf16 v[12:15], v[216:219], v[198:201], v[12:15]
	v_mfma_f32_16x16x32_bf16 v[8:11], v[230:233], v[198:201], v[8:11]
	v_mfma_f32_16x16x32_bf16 v[4:7], v[216:219], v[206:209], v[4:7]
	v_mfma_f32_16x16x32_bf16 v[0:3], v[230:233], v[206:209], v[0:3]
	v_mfma_f32_16x16x32_bf16 v[28:31], v[226:229], v[186:189], v[28:31]
	v_mfma_f32_16x16x32_bf16 v[24:27], v[234:237], v[186:189], v[24:27]
	v_mfma_f32_16x16x32_bf16 v[20:23], v[226:229], v[194:197], v[20:23]
	v_mfma_f32_16x16x32_bf16 v[16:19], v[234:237], v[194:197], v[16:19]
	v_mfma_f32_16x16x32_bf16 v[12:15], v[226:229], v[202:205], v[12:15]
	v_mfma_f32_16x16x32_bf16 v[8:11], v[234:237], v[202:205], v[8:11]
	v_mfma_f32_16x16x32_bf16 v[4:7], v[226:229], v[210:213], v[4:7]
	v_mfma_f32_16x16x32_bf16 v[0:3], v[234:237], v[210:213], v[0:3]
	s_add_i32 s3, s3, 2
	s_add_u32 s28, s28, 0x100
	s_addc_u32 s29, s29, 0
	s_cmp_lt_u32 s3, 12
	s_barrier
	s_cbranch_scc1 .LBB0_1260
	s_add_u32 s22, s22, 0x40780
	s_addc_u32 s23, s23, 0
	v_readfirstlane_b32 s3, v167
	v_lshl_add_u64 v[144:145], v[64:65], 1, s[22:23]
	s_mov_b32 m0, s3
	v_readfirstlane_b32 s3, v168
	ds_read_b128 v[132:135], v166
	ds_read_b128 v[136:139], v166 offset:1024
	ds_read_b128 v[140:143], v166 offset:2048
	ds_read_b128 v[152:155], v166 offset:3072
	ds_read_b128 v[158:161], v150
	ds_read_b128 v[170:173], v150 offset:1024
	ds_read_b128 v[174:177], v149
	ds_read_b128 v[178:181], v149 offset:1024
	ds_read_b128 v[182:185], v148
	ds_read_b128 v[186:189], v148 offset:1024
	ds_read_b128 v[190:193], v147
	ds_read_b128 v[194:197], v147 offset:1024
	global_load_lds_dwordx4 v[144:145], off
	v_lshl_add_u64 v[130:131], v[130:131], 1, s[22:23]
	s_mov_b32 m0, s3
	s_nop 0
	global_load_lds_dwordx4 v[130:131], off
	s_barrier
	s_waitcnt lgkmcnt(0)
	v_mfma_f32_16x16x32_bf16 v[126:129], v[132:135], v[158:161], v[126:129]
	v_mfma_f32_16x16x32_bf16 v[122:125], v[140:143], v[158:161], v[122:125]
	v_mfma_f32_16x16x32_bf16 v[118:121], v[132:135], v[174:177], v[118:121]
	v_mfma_f32_16x16x32_bf16 v[114:117], v[140:143], v[174:177], v[114:117]
	v_mfma_f32_16x16x32_bf16 v[110:113], v[132:135], v[182:185], v[110:113]
	v_mfma_f32_16x16x32_bf16 v[106:109], v[140:143], v[182:185], v[106:109]
	v_mfma_f32_16x16x32_bf16 v[102:105], v[132:135], v[190:193], v[102:105]
	v_mfma_f32_16x16x32_bf16 v[126:129], v[136:139], v[170:173], v[126:129]
	v_mfma_f32_16x16x32_bf16 v[122:125], v[152:155], v[170:173], v[122:125]
	v_mfma_f32_16x16x32_bf16 v[118:121], v[136:139], v[178:181], v[118:121]
	v_mfma_f32_16x16x32_bf16 v[114:117], v[152:155], v[178:181], v[114:117]
	v_mfma_f32_16x16x32_bf16 v[110:113], v[136:139], v[186:189], v[110:113]
	v_mfma_f32_16x16x32_bf16 v[106:109], v[152:155], v[186:189], v[106:109]
	v_mfma_f32_16x16x32_bf16 v[102:105], v[136:139], v[194:197], v[102:105]
	v_mfma_f32_16x16x32_bf16 v[98:101], v[140:143], v[190:193], v[98:101]
	v_mfma_f32_16x16x32_bf16 v[98:101], v[152:155], v[194:197], v[98:101]
	s_barrier
	ds_read_b128 v[166:169], v165
	ds_read_b128 v[198:201], v165 offset:1024
	ds_read_b128 v[202:205], v165 offset:2048
	ds_read_b128 v[162:165], v165 offset:3072
	s_barrier
	s_waitcnt lgkmcnt(0)
	v_mfma_f32_16x16x32_bf16 v[94:97], v[166:169], v[158:161], v[94:97]
	v_mfma_f32_16x16x32_bf16 v[90:93], v[202:205], v[158:161], v[90:93]
	v_mfma_f32_16x16x32_bf16 v[86:89], v[166:169], v[174:177], v[86:89]
	v_mfma_f32_16x16x32_bf16 v[82:85], v[202:205], v[174:177], v[82:85]
	v_mfma_f32_16x16x32_bf16 v[78:81], v[166:169], v[182:185], v[78:81]
	v_mfma_f32_16x16x32_bf16 v[74:77], v[202:205], v[182:185], v[74:77]
	v_mfma_f32_16x16x32_bf16 v[70:73], v[166:169], v[190:193], v[70:73]
	v_mfma_f32_16x16x32_bf16 v[66:69], v[202:205], v[190:193], v[66:69]
	v_mfma_f32_16x16x32_bf16 v[94:97], v[198:201], v[170:173], v[94:97]
	v_mfma_f32_16x16x32_bf16 v[90:93], v[162:165], v[170:173], v[90:93]
	v_mfma_f32_16x16x32_bf16 v[86:89], v[198:201], v[178:181], v[86:89]
	v_mfma_f32_16x16x32_bf16 v[82:85], v[162:165], v[178:181], v[82:85]
	v_mfma_f32_16x16x32_bf16 v[78:81], v[198:201], v[186:189], v[78:81]
	v_mfma_f32_16x16x32_bf16 v[74:77], v[162:165], v[186:189], v[74:77]
	v_mfma_f32_16x16x32_bf16 v[70:73], v[198:201], v[194:197], v[70:73]
	v_mfma_f32_16x16x32_bf16 v[66:69], v[162:165], v[194:197], v[66:69]
	s_barrier
; #define LDA(dst, b, h) _Pragma("unroll") for (int m = 0; m < 4; ++m) _Pragma("unroll") for (int k = 0; k < 2; ++k) \
;     dst[m][k] = *(const bf16x8*)(lds + SA_(b, h) + lds_byte(wr * 64 + m * 16 + fr, k * 32 + fq * 8));
; #define LDB(dst, b, h) _Pragma("unroll") for (int n = 0; n < 2; ++n) _Pragma("unroll") for (int k = 0; k < 2; ++k) \
;     dst[n][k] = *(const bf16x8*)(lds + SB_(b, h) + lds_byte(wc * 32 + n * 16 + fr, k * 32 + fq * 8));
; #define MMA(ai, bj, At_, Bt_) { __builtin_amdgcn_s_setprio(1); \
;     _Pragma("unroll") for (int m = 0; m < 4; ++m) _Pragma("unroll") for (int n = 0; n < 2; ++n) _Pragma("unroll") for (int k = 0; k < 2; ++k) \
;       acc[ai][bj][m][n] = MFMA16(Bt_[n][k], At_[m][k], acc[ai][bj][m][n]); \
;     __builtin_amdgcn_s_setprio(0); }
; #define WAIT_V(n) asm volatile("s_waitcnt vmcnt(" #n ")" ::: "memory");
; #define WAIT_L(n) asm volatile("s_waitcnt lgkmcnt(" #n ")" ::: "memory");
; #define BAR __builtin_amdgcn_s_barrier();
; DI void gemm256(const u16* __restrict__ A, int lda, const u16* __restrict__ B0, const u16* __restrict__ B1, int ldb, int nt, acc_t& acc, char* lds) {
;     ...
;     BAR WAIT_L(0) MMA(0, 0, At, Bq0) BAR
;     LDB(Bq1, 0, 1) BAR WAIT_L(0) MMA(0, 1, At, Bq1) BAR
;     LDA(At, 0, 1) WAIT_V(4) BAR WAIT_L(0) MMA(1, 0, At, Bq0) MMA(1, 1, At, Bq1) BAR }
;   { LDB(Bq0, 1, 0) LDA(At, 1, 0) WAIT_V(2) BAR WAIT_L(0) MMA(0, 0, At, Bq0) BAR
	ds_read_b128 v[158:161], v150 offset:16384
	ds_read_b128 v[170:173], v150 offset:17408
	ds_read_b128 v[174:177], v149 offset:16384
	ds_read_b128 v[178:181], v149 offset:17408
	ds_read_b128 v[182:185], v148 offset:16384
	ds_read_b128 v[186:189], v148 offset:17408
	ds_read_b128 v[190:193], v147 offset:16384
	ds_read_b128 v[194:197], v147 offset:17408
	s_waitcnt vmcnt(4)
	s_barrier
	s_waitcnt lgkmcnt(0)
	v_mfma_f32_16x16x32_bf16 v[36:39], v[132:135], v[190:193], v[36:39]
	v_mfma_f32_16x16x32_bf16 v[32:35], v[140:143], v[190:193], v[32:35]
	v_mfma_f32_16x16x32_bf16 v[60:63], v[132:135], v[158:161], v[60:63]
	v_mfma_f32_16x16x32_bf16 v[56:59], v[140:143], v[158:161], v[56:59]
	v_mfma_f32_16x16x32_bf16 v[52:55], v[132:135], v[174:177], v[52:55]
	v_mfma_f32_16x16x32_bf16 v[48:51], v[140:143], v[174:177], v[48:51]
	v_mfma_f32_16x16x32_bf16 v[44:47], v[132:135], v[182:185], v[44:47]
	v_mfma_f32_16x16x32_bf16 v[40:43], v[140:143], v[182:185], v[40:43]
	v_mfma_f32_16x16x32_bf16 v[130:133], v[136:139], v[194:197], v[36:39]
	v_mfma_f32_16x16x32_bf16 v[142:145], v[152:155], v[194:197], v[32:35]
	v_mfma_f32_16x16x32_bf16 v[206:209], v[136:139], v[170:173], v[60:63]
	v_mfma_f32_16x16x32_bf16 v[210:213], v[152:155], v[170:173], v[56:59]
	v_mfma_f32_16x16x32_bf16 v[216:219], v[136:139], v[178:181], v[52:55]
	v_mfma_f32_16x16x32_bf16 v[226:229], v[152:155], v[178:181], v[48:51]
	v_mfma_f32_16x16x32_bf16 v[230:233], v[136:139], v[186:189], v[44:47]
	v_mfma_f32_16x16x32_bf16 v[234:237], v[152:155], v[186:189], v[40:43]
	v_mfma_f32_16x16x32_bf16 v[28:31], v[166:169], v[158:161], v[28:31]
	v_mfma_f32_16x16x32_bf16 v[24:27], v[202:205], v[158:161], v[24:27]
	v_mfma_f32_16x16x32_bf16 v[20:23], v[166:169], v[174:177], v[20:23]
	v_mfma_f32_16x16x32_bf16 v[16:19], v[202:205], v[174:177], v[16:19]
	v_mfma_f32_16x16x32_bf16 v[12:15], v[166:169], v[182:185], v[12:15]
	v_mfma_f32_16x16x32_bf16 v[8:11], v[202:205], v[182:185], v[8:11]
	v_mfma_f32_16x16x32_bf16 v[4:7], v[166:169], v[190:193], v[4:7]
	v_mfma_f32_16x16x32_bf16 v[0:3], v[202:205], v[190:193], v[0:3]
	v_mfma_f32_16x16x32_bf16 v[152:155], v[198:201], v[170:173], v[28:31]
	v_mfma_f32_16x16x32_bf16 v[158:161], v[162:165], v[170:173], v[24:27]
	v_mfma_f32_16x16x32_bf16 v[170:173], v[198:201], v[178:181], v[20:23]
	v_mfma_f32_16x16x32_bf16 v[174:177], v[162:165], v[178:181], v[16:19]
	v_mfma_f32_16x16x32_bf16 v[178:181], v[198:201], v[186:189], v[12:15]
	v_mfma_f32_16x16x32_bf16 v[182:185], v[162:165], v[186:189], v[8:11]
	v_mfma_f32_16x16x32_bf16 v[166:169], v[198:201], v[194:197], v[4:7]
	v_mfma_f32_16x16x32_bf16 v[162:165], v[162:165], v[194:197], v[0:3]
	s_barrier
	ds_read_b128 v[186:189], v156
	ds_read_b128 v[190:193], v156 offset:1024
	ds_read_b128 v[194:197], v156 offset:2048
	ds_read_b128 v[198:201], v156 offset:3072
	ds_read_b128 v[10:13], v150 offset:32768
	ds_read_b128 v[22:25], v150 offset:33792
	ds_read_b128 v[26:29], v149 offset:32768
	ds_read_b128 v[38:41], v149 offset:33792
	ds_read_b128 v[42:45], v148 offset:32768
	ds_read_b128 v[54:57], v148 offset:33792
	ds_read_b128 v[58:61], v147 offset:32768
	ds_read_b128 v[134:137], v147 offset:33792
	s_waitcnt vmcnt(2)
	s_barrier
	s_waitcnt lgkmcnt(0)
	v_mfma_f32_16x16x32_bf16 v[6:9], v[186:189], v[26:29], v[118:121]
	v_mfma_f32_16x16x32_bf16 v[14:17], v[190:193], v[38:41], v[6:9]
	v_mfma_f32_16x16x32_bf16 v[6:9], v[194:197], v[26:29], v[114:117]
	v_mfma_f32_16x16x32_bf16 v[18:21], v[198:201], v[38:41], v[6:9]
	v_mfma_f32_16x16x32_bf16 v[6:9], v[186:189], v[42:45], v[110:113]
	v_mfma_f32_16x16x32_bf16 v[30:33], v[190:193], v[54:57], v[6:9]
	v_mfma_f32_16x16x32_bf16 v[6:9], v[194:197], v[42:45], v[106:109]
	v_mfma_f32_16x16x32_bf16 v[0:3], v[186:189], v[10:13], v[126:129]
	v_mfma_f32_16x16x32_bf16 v[34:37], v[198:201], v[54:57], v[6:9]
	v_mfma_f32_16x16x32_bf16 v[6:9], v[186:189], v[58:61], v[102:105]
	v_mfma_f32_16x16x32_bf16 v[138:141], v[190:193], v[22:25], v[0:3]
	v_mfma_f32_16x16x32_bf16 v[0:3], v[194:197], v[10:13], v[122:125]
	v_mfma_f32_16x16x32_bf16 v[46:49], v[190:193], v[134:137], v[6:9]
	v_mfma_f32_16x16x32_bf16 v[6:9], v[194:197], v[58:61], v[98:101]
	v_mfma_f32_16x16x32_bf16 v[2:5], v[198:201], v[22:25], v[0:3]
	v_mfma_f32_16x16x32_bf16 v[50:53], v[198:201], v[134:137], v[6:9]
	s_barrier
; #define LDA(dst, b, h) _Pragma("unroll") for (int m = 0; m < 4; ++m) _Pragma("unroll") for (int k = 0; k < 2; ++k) \
;     dst[m][k] = *(const bf16x8*)(lds + SA_(b, h) + lds_byte(wr * 64 + m * 16 + fr, k * 32 + fq * 8));
; #define LDB(dst, b, h) _Pragma("unroll") for (int n = 0; n < 2; ++n) _Pragma("unroll") for (int k = 0; k < 2; ++k) \
;     dst[n][k] = *(const bf16x8*)(lds + SB_(b, h) + lds_byte(wc * 32 + n * 16 + fr, k * 32 + fq * 8));
; #define MMA(ai, bj, At_, Bt_) { __builtin_amdgcn_s_setprio(1); \
;     _Pragma("unroll") for (int m = 0; m < 4; ++m) _Pragma("unroll") for (int n = 0; n < 2; ++n) _Pragma("unroll") for (int k = 0; k < 2; ++k) \
;       acc[ai][bj][m][n] = MFMA16(Bt_[n][k], At_[m][k], acc[ai][bj][m][n]); \
;     __builtin_amdgcn_s_setprio(0); }
; #define WAIT_V(n) asm volatile("s_waitcnt vmcnt(" #n ")" ::: "memory");
; #define WAIT_L(n) asm volatile("s_waitcnt lgkmcnt(" #n ")" ::: "memory");
; #define BAR __builtin_amdgcn_s_barrier();
; DI void gemm256(const u16* __restrict__ A, int lda, const u16* __restrict__ B0, const u16* __restrict__ B1, int ldb, int nt, acc_t& acc, char* lds) {
;     ...
;     LDB(Bq1, 1, 1) WAIT_V(0) BAR WAIT_L(0) MMA(0, 1, At, Bq1) BAR
;     LDA(At, 1, 1) BAR WAIT_L(0) MMA(1, 0, At, Bq0) MMA(1, 1, At, Bq1) BAR }
;   if (wr == 0) BAR
;   __syncthreads();
	ds_read_b128 v[202:205], v151
	ds_read_b128 v[238:241], v151 offset:1024
	ds_read_b128 v[242:245], v151 offset:2048
	ds_read_b128 v[246:249], v151 offset:3072
	s_waitcnt vmcnt(0)
	s_barrier
	s_waitcnt lgkmcnt(0)
	v_mfma_f32_16x16x32_bf16 v[6:9], v[202:205], v[10:13], v[94:97]
	v_mfma_f32_16x16x32_bf16 v[10:13], v[242:245], v[10:13], v[90:93]
	v_mfma_f32_16x16x32_bf16 v[6:9], v[238:241], v[22:25], v[6:9]
	v_mfma_f32_16x16x32_bf16 v[10:13], v[246:249], v[22:25], v[10:13]
	v_mfma_f32_16x16x32_bf16 v[22:25], v[202:205], v[26:29], v[86:89]
	v_mfma_f32_16x16x32_bf16 v[26:29], v[242:245], v[26:29], v[82:85]
	v_mfma_f32_16x16x32_bf16 v[22:25], v[238:241], v[38:41], v[22:25]
	v_mfma_f32_16x16x32_bf16 v[26:29], v[246:249], v[38:41], v[26:29]
	v_mfma_f32_16x16x32_bf16 v[38:41], v[202:205], v[42:45], v[78:81]
	v_mfma_f32_16x16x32_bf16 v[42:45], v[242:245], v[42:45], v[74:77]
	v_mfma_f32_16x16x32_bf16 v[38:41], v[238:241], v[54:57], v[38:41]
	v_mfma_f32_16x16x32_bf16 v[42:45], v[246:249], v[54:57], v[42:45]
	v_mfma_f32_16x16x32_bf16 v[54:57], v[202:205], v[58:61], v[70:73]
	v_mfma_f32_16x16x32_bf16 v[58:61], v[242:245], v[58:61], v[66:69]
	v_mfma_f32_16x16x32_bf16 v[54:57], v[238:241], v[134:137], v[54:57]
	v_mfma_f32_16x16x32_bf16 v[58:61], v[246:249], v[134:137], v[58:61]
	s_barrier
	ds_read_b128 v[76:79], v150 offset:49152
	ds_read_b128 v[80:83], v150 offset:50176
	ds_read_b128 v[88:91], v149 offset:49152
	ds_read_b128 v[110:113], v149 offset:50176
	ds_read_b128 v[114:117], v148 offset:49152
	ds_read_b128 v[148:151], v148 offset:50176
	ds_read_b128 v[222:225], v147 offset:49152
	ds_read_b128 v[98:101], v147 offset:50176
	s_barrier
	s_waitcnt lgkmcnt(0)
	v_mfma_f32_16x16x32_bf16 v[72:75], v[186:189], v[88:91], v[216:219]
	v_mfma_f32_16x16x32_bf16 v[84:87], v[190:193], v[110:113], v[72:75]
	v_mfma_f32_16x16x32_bf16 v[72:75], v[194:197], v[88:91], v[226:229]
	v_mfma_f32_16x16x32_bf16 v[94:97], v[198:201], v[110:113], v[72:75]
	v_mfma_f32_16x16x32_bf16 v[72:75], v[186:189], v[114:117], v[230:233]
	v_mfma_f32_16x16x32_bf16 v[118:121], v[190:193], v[148:151], v[72:75]
	v_mfma_f32_16x16x32_bf16 v[72:75], v[194:197], v[114:117], v[234:237]
	v_mfma_f32_16x16x32_bf16 v[66:69], v[186:189], v[76:79], v[206:209]
	v_mfma_f32_16x16x32_bf16 v[126:129], v[198:201], v[148:151], v[72:75]
	v_mfma_f32_16x16x32_bf16 v[72:75], v[186:189], v[222:225], v[130:133]
	v_mfma_f32_16x16x32_bf16 v[134:137], v[190:193], v[80:83], v[66:69]
	v_mfma_f32_16x16x32_bf16 v[66:69], v[194:197], v[76:79], v[210:213]
	v_mfma_f32_16x16x32_bf16 v[106:109], v[190:193], v[98:101], v[72:75]
	v_mfma_f32_16x16x32_bf16 v[72:75], v[194:197], v[222:225], v[142:145]
	v_mfma_f32_16x16x32_bf16 v[68:71], v[198:201], v[80:83], v[66:69]
	v_mfma_f32_16x16x32_bf16 v[142:145], v[198:201], v[98:101], v[72:75]
	v_mfma_f32_16x16x32_bf16 v[72:75], v[202:205], v[76:79], v[152:155]
	v_mfma_f32_16x16x32_bf16 v[76:79], v[242:245], v[76:79], v[158:161]
	v_mfma_f32_16x16x32_bf16 v[130:133], v[246:249], v[80:83], v[76:79]
	v_mfma_f32_16x16x32_bf16 v[76:79], v[202:205], v[88:91], v[170:173]
	v_mfma_f32_16x16x32_bf16 v[102:105], v[238:241], v[110:113], v[76:79]
	v_mfma_f32_16x16x32_bf16 v[76:79], v[242:245], v[88:91], v[174:177]
	v_mfma_f32_16x16x32_bf16 v[110:113], v[246:249], v[110:113], v[76:79]
	v_mfma_f32_16x16x32_bf16 v[76:79], v[202:205], v[114:117], v[178:181]
	v_mfma_f32_16x16x32_bf16 v[122:125], v[238:241], v[148:151], v[76:79]
	v_mfma_f32_16x16x32_bf16 v[76:79], v[242:245], v[114:117], v[182:185]
	v_mfma_f32_16x16x32_bf16 v[114:117], v[246:249], v[148:151], v[76:79]
	v_mfma_f32_16x16x32_bf16 v[76:79], v[202:205], v[222:225], v[166:169]
	v_mfma_f32_16x16x32_bf16 v[90:93], v[238:241], v[98:101], v[76:79]
	v_mfma_f32_16x16x32_bf16 v[76:79], v[242:245], v[222:225], v[162:165]
	v_mfma_f32_16x16x32_bf16 v[72:75], v[238:241], v[80:83], v[72:75]
	v_mfma_f32_16x16x32_bf16 v[78:81], v[246:249], v[98:101], v[76:79]
	s_movk_i32 s3, 0x100
	v_cmp_gt_u32_e32 vcc, s3, v146
	s_barrier
	s_and_saveexec_b64 s[22:23], vcc
	s_cbranch_execz .LBB0_1263
	s_barrier

; #define STAGE_A(b, h, kt) { const u16* ap_ = A + (size_t)((h) * ahalf + (unsigned)(kt) * 64u); glds16(ap_ + ao0, l0 + SA_(b, h)); glds16(ap_ + ao1, l0 + SA_(b, h) + 8192); }
; #define STAGE_B(b, h, kt) { const u16* bp_ = ((h) ? B1 : B0) + (unsigned)(kt) * 64u; glds16(bp_ + bo0, l0 + SB_(b, h)); glds16(bp_ + bo1, l0 + SB_(b, h) + 8192); }
; #define LDA(dst, b, h) _Pragma("unroll") for (int m = 0; m < 4; ++m) _Pragma("unroll") for (int k = 0; k < 2; ++k) \
;     dst[m][k] = *(const bf16x8*)(lds + SA_(b, h) + lds_byte(wr * 64 + m * 16 + fr, k * 32 + fq * 8));
; #define LDB(dst, b, h) _Pragma("unroll") for (int n = 0; n < 2; ++n) _Pragma("unroll") for (int k = 0; k < 2; ++k) \
;     dst[n][k] = *(const bf16x8*)(lds + SB_(b, h) + lds_byte(wc * 32 + n * 16 + fr, k * 32 + fq * 8));
; #define MMA(ai, bj, At_, Bt_) { __builtin_amdgcn_s_setprio(1); \
;     _Pragma("unroll") for (int m = 0; m < 4; ++m) _Pragma("unroll") for (int n = 0; n < 2; ++n) _Pragma("unroll") for (int k = 0; k < 2; ++k) \
;       acc[ai][bj][m][n] = MFMA16(Bt_[n][k], At_[m][k], acc[ai][bj][m][n]); \
;     __builtin_amdgcn_s_setprio(0); }
; #define WAIT_L(n) asm volatile("s_waitcnt lgkmcnt(" #n ")" ::: "memory");
; #define BAR __builtin_amdgcn_s_barrier();
; #define SCHED __builtin_amdgcn_sched_barrier(0);
; DI void gemm256(const u16* __restrict__ A, int lda, const u16* __restrict__ B0, const u16* __restrict__ B1, int ldb, int nt, acc_t& acc, char* lds) {
;     ...
;   for (int t = 0; t < nt - 2; t += 2) {
;     LDB(Bq0, 0, 0) SCHED LDA(At, 0, 0) STAGE_A(1, 1, t + 1)
;     WAIT_L(8) BAR WAIT_L(0) MMA(0, 0, At, Bq0) BAR SCHED
;     LDB(Bq1, 0, 1) STAGE_B(0, 0, t + 2)
;     BAR WAIT_L(0) MMA(0, 1, At, Bq1) BAR
;     LDA(At, 0, 1) STAGE_A(0, 0, t + 2)
;     BAR WAIT_L(0) MMA(1, 0, At, Bq0) BAR SCHED
.LBB0_1266:
	ds_read_b128 v[142:145], v157
	ds_read_b128 v[160:163], v157 offset:1024
	ds_read_b128 v[164:167], v157 offset:2048
	ds_read_b128 v[168:171], v157 offset:3072
	v_lshl_add_u64 v[212:213], s[8:9], 0, v[134:135]
	v_readfirstlane_b32 s3, v158
	v_lshl_add_u64 v[204:205], v[212:213], 0, s[28:29]
	s_mov_b32 m0, s3
	v_lshl_add_u64 v[222:223], s[8:9], 0, v[136:137]
	v_readfirstlane_b32 s3, v159
	ds_read_b128 v[172:175], v151
	ds_read_b128 v[180:183], v150
	ds_read_b128 v[188:191], v149
	ds_read_b128 v[196:199], v148
	global_load_lds_dwordx4 v[204:205], off
	v_lshl_add_u64 v[204:205], v[222:223], 0, s[28:29]
	s_mov_b32 m0, s3
	s_nop 0
	global_load_lds_dwordx4 v[204:205], off
	s_waitcnt lgkmcnt(4)
	s_barrier
	s_waitcnt lgkmcnt(0)
	ds_read_b128 v[176:179], v151 offset:1024
	ds_read_b128 v[184:187], v150 offset:1024
	ds_read_b128 v[192:195], v149 offset:1024
	ds_read_b128 v[200:203], v148 offset:1024
	v_mfma_f32_16x16x32_bf16 v[0:3], v[142:145], v[172:175], v[0:3]
	v_mfma_f32_16x16x32_bf16 v[4:7], v[164:167], v[172:175], v[4:7]
	v_mfma_f32_16x16x32_bf16 v[16:19], v[142:145], v[180:183], v[16:19]
	v_mfma_f32_16x16x32_bf16 v[20:23], v[164:167], v[180:183], v[20:23]
	v_mfma_f32_16x16x32_bf16 v[32:35], v[142:145], v[188:191], v[32:35]
	v_mfma_f32_16x16x32_bf16 v[36:39], v[164:167], v[188:191], v[36:39]
	v_mfma_f32_16x16x32_bf16 v[48:51], v[142:145], v[196:199], v[48:51]
	v_mfma_f32_16x16x32_bf16 v[52:55], v[164:167], v[196:199], v[52:55]
	s_waitcnt lgkmcnt(0)
	v_mfma_f32_16x16x32_bf16 v[0:3], v[160:163], v[176:179], v[0:3]
	v_mfma_f32_16x16x32_bf16 v[4:7], v[168:171], v[176:179], v[4:7]
	v_mfma_f32_16x16x32_bf16 v[16:19], v[160:163], v[184:187], v[16:19]
	v_mfma_f32_16x16x32_bf16 v[20:23], v[168:171], v[184:187], v[20:23]
	v_mfma_f32_16x16x32_bf16 v[32:35], v[160:163], v[192:195], v[32:35]
	v_mfma_f32_16x16x32_bf16 v[36:39], v[168:171], v[192:195], v[36:39]
	v_mfma_f32_16x16x32_bf16 v[48:51], v[160:163], v[200:203], v[48:51]
	v_mfma_f32_16x16x32_bf16 v[52:55], v[168:171], v[200:203], v[52:55]
	s_barrier
	v_lshl_add_u64 v[238:239], s[8:9], 0, v[130:131]
	v_readfirstlane_b32 s3, v227
	v_lshl_add_u64 v[240:241], v[238:239], 0, s[44:45]
	s_mov_b32 m0, s3
	ds_read_b128 v[204:207], v156
	ds_read_b128 v[208:211], v156 offset:1024
	ds_read_b128 v[216:219], v156 offset:2048
	ds_read_b128 v[234:237], v156 offset:3072
	global_load_lds_dwordx4 v[240:241], off
	v_lshl_add_u64 v[240:241], s[8:9], 0, v[132:133]
	v_readfirstlane_b32 s3, v228
	v_lshl_add_u64 v[242:243], v[240:241], 0, s[44:45]
	s_mov_b32 m0, s3
	s_nop 0
	global_load_lds_dwordx4 v[242:243], off
	s_barrier
	s_waitcnt lgkmcnt(0)
	v_mfma_f32_16x16x32_bf16 v[8:11], v[204:207], v[172:175], v[8:11]
	v_mfma_f32_16x16x32_bf16 v[12:15], v[216:219], v[172:175], v[12:15]
	v_mfma_f32_16x16x32_bf16 v[24:27], v[204:207], v[180:183], v[24:27]
	v_mfma_f32_16x16x32_bf16 v[28:31], v[216:219], v[180:183], v[28:31]
	v_mfma_f32_16x16x32_bf16 v[40:43], v[204:207], v[188:191], v[40:43]
	v_mfma_f32_16x16x32_bf16 v[44:47], v[216:219], v[188:191], v[44:47]
	v_mfma_f32_16x16x32_bf16 v[56:59], v[204:207], v[196:199], v[56:59]
	v_mfma_f32_16x16x32_bf16 v[60:63], v[216:219], v[196:199], v[60:63]
	v_mfma_f32_16x16x32_bf16 v[8:11], v[208:211], v[176:179], v[8:11]
	v_mfma_f32_16x16x32_bf16 v[12:15], v[234:237], v[176:179], v[12:15]
	v_mfma_f32_16x16x32_bf16 v[24:27], v[208:211], v[184:187], v[24:27]
	v_mfma_f32_16x16x32_bf16 v[28:31], v[234:237], v[184:187], v[28:31]
	v_mfma_f32_16x16x32_bf16 v[40:43], v[208:211], v[192:195], v[40:43]
	v_mfma_f32_16x16x32_bf16 v[44:47], v[234:237], v[192:195], v[44:47]
	v_mfma_f32_16x16x32_bf16 v[56:59], v[208:211], v[200:203], v[56:59]
	v_mfma_f32_16x16x32_bf16 v[60:63], v[234:237], v[200:203], v[60:63]
	v_readfirstlane_b32 s3, v226
	v_lshl_add_u64 v[242:243], v[212:213], 0, s[70:71]
	s_mov_b32 m0, s3
	v_readfirstlane_b32 s3, v229
	s_barrier
	ds_read_b128 v[172:175], v151 offset:16384
	ds_read_b128 v[180:183], v150 offset:16384
	ds_read_b128 v[188:191], v149 offset:16384
	ds_read_b128 v[196:199], v148 offset:16384
	global_load_lds_dwordx4 v[242:243], off
	v_lshl_add_u64 v[242:243], v[222:223], 0, s[70:71]
	s_mov_b32 m0, s3
	s_nop 0
	global_load_lds_dwordx4 v[242:243], off
	s_barrier
	s_waitcnt lgkmcnt(0)
	ds_read_b128 v[176:179], v151 offset:17408
	ds_read_b128 v[184:187], v150 offset:17408
	ds_read_b128 v[192:195], v149 offset:17408
	ds_read_b128 v[200:203], v148 offset:17408
	v_mfma_f32_16x16x32_bf16 v[66:69], v[142:145], v[172:175], v[66:69]
	v_mfma_f32_16x16x32_bf16 v[70:73], v[164:167], v[172:175], v[70:73]
	v_mfma_f32_16x16x32_bf16 v[86:89], v[142:145], v[180:183], v[86:89]
	v_mfma_f32_16x16x32_bf16 v[94:97], v[164:167], v[180:183], v[94:97]
	v_mfma_f32_16x16x32_bf16 v[118:121], v[142:145], v[188:191], v[118:121]
	v_mfma_f32_16x16x32_bf16 v[126:129], v[164:167], v[188:191], v[126:129]
	v_mfma_f32_16x16x32_bf16 v[106:109], v[142:145], v[196:199], v[106:109]
	v_mfma_f32_16x16x32_bf16 v[98:101], v[164:167], v[196:199], v[98:101]
	s_waitcnt lgkmcnt(0)
	v_mfma_f32_16x16x32_bf16 v[66:69], v[160:163], v[176:179], v[66:69]
	v_mfma_f32_16x16x32_bf16 v[70:73], v[168:171], v[176:179], v[70:73]
	v_mfma_f32_16x16x32_bf16 v[86:89], v[160:163], v[184:187], v[86:89]
	v_mfma_f32_16x16x32_bf16 v[94:97], v[168:171], v[184:187], v[94:97]
	v_mfma_f32_16x16x32_bf16 v[118:121], v[160:163], v[192:195], v[118:121]
	v_mfma_f32_16x16x32_bf16 v[126:129], v[168:171], v[192:195], v[126:129]
	v_mfma_f32_16x16x32_bf16 v[106:109], v[160:163], v[200:203], v[106:109]
	v_mfma_f32_16x16x32_bf16 v[98:101], v[168:171], v[200:203], v[98:101]
	s_barrier
; #define STAGE_A(b, h, kt) { const u16* ap_ = A + (size_t)((h) * ahalf + (unsigned)(kt) * 64u); glds16(ap_ + ao0, l0 + SA_(b, h)); glds16(ap_ + ao1, l0 + SA_(b, h) + 8192); }
; #define STAGE_B(b, h, kt) { const u16* bp_ = ((h) ? B1 : B0) + (unsigned)(kt) * 64u; glds16(bp_ + bo0, l0 + SB_(b, h)); glds16(bp_ + bo1, l0 + SB_(b, h) + 8192); }
; #define LDA(dst, b, h) _Pragma("unroll") for (int m = 0; m < 4; ++m) _Pragma("unroll") for (int k = 0; k < 2; ++k) \
;     dst[m][k] = *(const bf16x8*)(lds + SA_(b, h) + lds_byte(wr * 64 + m * 16 + fr, k * 32 + fq * 8));
; #define LDB(dst, b, h) _Pragma("unroll") for (int n = 0; n < 2; ++n) _Pragma("unroll") for (int k = 0; k < 2; ++k) \
;     dst[n][k] = *(const bf16x8*)(lds + SB_(b, h) + lds_byte(wc * 32 + n * 16 + fr, k * 32 + fq * 8));
; #define MMA(ai, bj, At_, Bt_) { __builtin_amdgcn_s_setprio(1); \
;     _Pragma("unroll") for (int m = 0; m < 4; ++m) _Pragma("unroll") for (int n = 0; n < 2; ++n) _Pragma("unroll") for (int k = 0; k < 2; ++k) \
;       acc[ai][bj][m][n] = MFMA16(Bt_[n][k], At_[m][k], acc[ai][bj][m][n]); \
;     __builtin_amdgcn_s_setprio(0); }
; #define WAIT_V(n) asm volatile("s_waitcnt vmcnt(" #n ")" ::: "memory");
; #define WAIT_L(n) asm volatile("s_waitcnt lgkmcnt(" #n ")" ::: "memory");
; #define BAR __builtin_amdgcn_s_barrier();
; #define SCHED __builtin_amdgcn_sched_barrier(0);
; DI void gemm256(const u16* __restrict__ A, int lda, const u16* __restrict__ B0, const u16* __restrict__ B1, int ldb, int nt, acc_t& acc, char* lds) {
;     ...
;     BAR WAIT_L(0) MMA(1, 0, At, Bq0) BAR SCHED
;     STAGE_B(0, 1, t + 2)
;     WAIT_V(6) BAR MMA(1, 1, At, Bq1) BAR
;     LDB(Bq0, 1, 0) SCHED LDA(At, 1, 0) STAGE_A(0, 1, t + 2)
;     WAIT_L(8) BAR WAIT_L(0) MMA(0, 0, At, Bq0) BAR SCHED
;     LDB(Bq1, 1, 1) STAGE_B(1, 0, t + 3)
;     BAR WAIT_L(0) MMA(0, 1, At, Bq1) BAR
;     LDA(At, 1, 1) STAGE_A(1, 0, t + 3)
;     BAR WAIT_L(0) MMA(1, 0, At, Bq0) BAR SCHED
	v_readfirstlane_b32 s3, v230
	v_lshl_add_u64 v[142:143], v[238:239], 0, s[46:47]
	s_mov_b32 m0, s3
	v_readfirstlane_b32 s3, v231
	global_load_lds_dwordx4 v[142:143], off
	v_lshl_add_u64 v[142:143], v[240:241], 0, s[46:47]
	s_mov_b32 m0, s3
	s_nop 0
	global_load_lds_dwordx4 v[142:143], off
	s_waitcnt vmcnt(6)
	s_barrier
	v_mfma_f32_16x16x32_bf16 v[74:77], v[204:207], v[172:175], v[74:77]
	v_mfma_f32_16x16x32_bf16 v[82:85], v[216:219], v[172:175], v[82:85]
	v_mfma_f32_16x16x32_bf16 v[102:105], v[204:207], v[180:183], v[102:105]
	v_mfma_f32_16x16x32_bf16 v[110:113], v[216:219], v[180:183], v[110:113]
	v_mfma_f32_16x16x32_bf16 v[122:125], v[204:207], v[188:191], v[122:125]
	v_mfma_f32_16x16x32_bf16 v[114:117], v[216:219], v[188:191], v[114:117]
	v_mfma_f32_16x16x32_bf16 v[90:93], v[204:207], v[196:199], v[90:93]
	v_mfma_f32_16x16x32_bf16 v[78:81], v[216:219], v[196:199], v[78:81]
	v_mfma_f32_16x16x32_bf16 v[74:77], v[208:211], v[176:179], v[74:77]
	v_mfma_f32_16x16x32_bf16 v[82:85], v[234:237], v[176:179], v[82:85]
	v_mfma_f32_16x16x32_bf16 v[102:105], v[208:211], v[184:187], v[102:105]
	v_mfma_f32_16x16x32_bf16 v[110:113], v[234:237], v[184:187], v[110:113]
	v_mfma_f32_16x16x32_bf16 v[122:125], v[208:211], v[192:195], v[122:125]
	v_mfma_f32_16x16x32_bf16 v[114:117], v[234:237], v[192:195], v[114:117]
	v_mfma_f32_16x16x32_bf16 v[90:93], v[208:211], v[200:203], v[90:93]
	v_mfma_f32_16x16x32_bf16 v[78:81], v[234:237], v[200:203], v[78:81]
	s_barrier
	ds_read_b128 v[142:145], v155
	ds_read_b128 v[160:163], v155 offset:1024
	ds_read_b128 v[164:167], v155 offset:2048
	ds_read_b128 v[168:171], v155 offset:3072
	v_readfirstlane_b32 s3, v232
	v_lshl_add_u64 v[204:205], v[212:213], 0, s[48:49]
	s_mov_b32 m0, s3
	v_readfirstlane_b32 s3, v233
	ds_read_b128 v[172:175], v151 offset:32768
	ds_read_b128 v[180:183], v150 offset:32768
	ds_read_b128 v[188:191], v149 offset:32768
	ds_read_b128 v[196:199], v148 offset:32768
	global_load_lds_dwordx4 v[204:205], off
	v_lshl_add_u64 v[204:205], v[222:223], 0, s[48:49]
	s_mov_b32 m0, s3
	s_nop 0
	global_load_lds_dwordx4 v[204:205], off
	s_waitcnt lgkmcnt(4)
	s_barrier
	s_waitcnt lgkmcnt(0)
	ds_read_b128 v[176:179], v151 offset:33792
	ds_read_b128 v[184:187], v150 offset:33792
	ds_read_b128 v[192:195], v149 offset:33792
	ds_read_b128 v[200:203], v148 offset:33792
	v_mfma_f32_16x16x32_bf16 v[0:3], v[142:145], v[172:175], v[0:3]
	v_mfma_f32_16x16x32_bf16 v[4:7], v[164:167], v[172:175], v[4:7]
	v_mfma_f32_16x16x32_bf16 v[16:19], v[142:145], v[180:183], v[16:19]
	v_mfma_f32_16x16x32_bf16 v[20:23], v[164:167], v[180:183], v[20:23]
	v_mfma_f32_16x16x32_bf16 v[32:35], v[142:145], v[188:191], v[32:35]
	v_mfma_f32_16x16x32_bf16 v[36:39], v[164:167], v[188:191], v[36:39]
	v_mfma_f32_16x16x32_bf16 v[48:51], v[142:145], v[196:199], v[48:51]
	v_mfma_f32_16x16x32_bf16 v[52:55], v[164:167], v[196:199], v[52:55]
	s_waitcnt lgkmcnt(0)
	v_mfma_f32_16x16x32_bf16 v[0:3], v[160:163], v[176:179], v[0:3]
	v_mfma_f32_16x16x32_bf16 v[4:7], v[168:171], v[176:179], v[4:7]
	v_mfma_f32_16x16x32_bf16 v[16:19], v[160:163], v[184:187], v[16:19]
	v_mfma_f32_16x16x32_bf16 v[20:23], v[168:171], v[184:187], v[20:23]
	v_mfma_f32_16x16x32_bf16 v[32:35], v[160:163], v[192:195], v[32:35]
	v_mfma_f32_16x16x32_bf16 v[36:39], v[168:171], v[192:195], v[36:39]
	v_mfma_f32_16x16x32_bf16 v[48:51], v[160:163], v[200:203], v[48:51]
	v_mfma_f32_16x16x32_bf16 v[52:55], v[168:171], v[200:203], v[52:55]
	s_barrier
	v_readfirstlane_b32 s3, v138
	v_lshl_add_u64 v[242:243], v[238:239], 0, s[52:53]
	s_mov_b32 m0, s3
	v_readfirstlane_b32 s3, v139
	ds_read_b128 v[204:207], v154
	ds_read_b128 v[208:211], v154 offset:1024
	ds_read_b128 v[216:219], v154 offset:2048
	ds_read_b128 v[234:237], v154 offset:3072
	global_load_lds_dwordx4 v[242:243], off
	v_lshl_add_u64 v[242:243], v[240:241], 0, s[52:53]
	s_mov_b32 m0, s3
	s_nop 0
	global_load_lds_dwordx4 v[242:243], off
	s_barrier
	s_waitcnt lgkmcnt(0)
	v_mfma_f32_16x16x32_bf16 v[8:11], v[204:207], v[172:175], v[8:11]
	v_mfma_f32_16x16x32_bf16 v[12:15], v[216:219], v[172:175], v[12:15]
	v_mfma_f32_16x16x32_bf16 v[24:27], v[204:207], v[180:183], v[24:27]
	v_mfma_f32_16x16x32_bf16 v[28:31], v[216:219], v[180:183], v[28:31]
	v_mfma_f32_16x16x32_bf16 v[40:43], v[204:207], v[188:191], v[40:43]
	v_mfma_f32_16x16x32_bf16 v[44:47], v[216:219], v[188:191], v[44:47]
	v_mfma_f32_16x16x32_bf16 v[56:59], v[204:207], v[196:199], v[56:59]
	v_mfma_f32_16x16x32_bf16 v[60:63], v[216:219], v[196:199], v[60:63]
	v_mfma_f32_16x16x32_bf16 v[8:11], v[208:211], v[176:179], v[8:11]
	v_mfma_f32_16x16x32_bf16 v[12:15], v[234:237], v[176:179], v[12:15]
	v_mfma_f32_16x16x32_bf16 v[24:27], v[208:211], v[184:187], v[24:27]
	v_mfma_f32_16x16x32_bf16 v[28:31], v[234:237], v[184:187], v[28:31]
	v_mfma_f32_16x16x32_bf16 v[40:43], v[208:211], v[192:195], v[40:43]
	v_mfma_f32_16x16x32_bf16 v[44:47], v[234:237], v[192:195], v[44:47]
	v_mfma_f32_16x16x32_bf16 v[56:59], v[208:211], v[200:203], v[56:59]
	v_mfma_f32_16x16x32_bf16 v[60:63], v[234:237], v[200:203], v[60:63]
	v_readfirstlane_b32 s3, v140
	v_lshl_add_u64 v[212:213], v[212:213], 0, s[72:73]
	s_mov_b32 m0, s3
	v_readfirstlane_b32 s3, v141
	s_barrier
	ds_read_b128 v[172:175], v151 offset:49152
	ds_read_b128 v[180:183], v150 offset:49152
	ds_read_b128 v[188:191], v149 offset:49152
	ds_read_b128 v[196:199], v148 offset:49152
	global_load_lds_dwordx4 v[212:213], off
	v_lshl_add_u64 v[212:213], v[222:223], 0, s[72:73]
	s_mov_b32 m0, s3
	s_nop 0
	global_load_lds_dwordx4 v[212:213], off
	s_barrier
; #define STAGE_A(b, h, kt) { const u16* ap_ = A + (size_t)((h) * ahalf + (unsigned)(kt) * 64u); glds16(ap_ + ao0, l0 + SA_(b, h)); glds16(ap_ + ao1, l0 + SA_(b, h) + 8192); }
; #define STAGE_B(b, h, kt) { const u16* bp_ = ((h) ? B1 : B0) + (unsigned)(kt) * 64u; glds16(bp_ + bo0, l0 + SB_(b, h)); glds16(bp_ + bo1, l0 + SB_(b, h) + 8192); }
; #define LDA(dst, b, h) _Pragma("unroll") for (int m = 0; m < 4; ++m) _Pragma("unroll") for (int k = 0; k < 2; ++k) \
;     dst[m][k] = *(const bf16x8*)(lds + SA_(b, h) + lds_byte(wr * 64 + m * 16 + fr, k * 32 + fq * 8));
; #define LDB(dst, b, h) _Pragma("unroll") for (int n = 0; n < 2; ++n) _Pragma("unroll") for (int k = 0; k < 2; ++k) \
;     dst[n][k] = *(const bf16x8*)(lds + SB_(b, h) + lds_byte(wc * 32 + n * 16 + fr, k * 32 + fq * 8));
; #define MMA(ai, bj, At_, Bt_) { __builtin_amdgcn_s_setprio(1); \
;     _Pragma("unroll") for (int m = 0; m < 4; ++m) _Pragma("unroll") for (int n = 0; n < 2; ++n) _Pragma("unroll") for (int k = 0; k < 2; ++k) \
;       acc[ai][bj][m][n] = MFMA16(Bt_[n][k], At_[m][k], acc[ai][bj][m][n]); \
;     __builtin_amdgcn_s_setprio(0); }
; #define WAIT_V(n) asm volatile("s_waitcnt vmcnt(" #n ")" ::: "memory");
; #define WAIT_L(n) asm volatile("s_waitcnt lgkmcnt(" #n ")" ::: "memory");
; #define BAR __builtin_amdgcn_s_barrier();
; #define SCHED __builtin_amdgcn_sched_barrier(0);
; DI void gemm256(const u16* __restrict__ A, int lda, const u16* __restrict__ B0, const u16* __restrict__ B1, int ldb, int nt, acc_t& acc, char* lds) {
;     ...
;     BAR WAIT_L(0) MMA(1, 0, At, Bq0) BAR SCHED
;     STAGE_B(1, 1, t + 3)
;     WAIT_V(6) BAR MMA(1, 1, At, Bq1) BAR
;   }
;   { LDB(Bq0, 0, 0) LDA(At, 0, 0) STAGE_A(1, 1, nt - 1)
;     BAR WAIT_L(0) MMA(0, 0, At, Bq0) BAR
;     LDB(Bq1, 0, 1) BAR WAIT_L(0) MMA(0, 1, At, Bq1) BAR
;     LDA(At, 0, 1) WAIT_V(4) BAR WAIT_L(0) MMA(1, 0, At, Bq0) MMA(1, 1, At, Bq1) BAR }
;   { LDB(Bq0, 1, 0) LDA(At, 1, 0) WAIT_V(2) BAR WAIT_L(0) MMA(0, 0, At, Bq0) BAR
	s_waitcnt lgkmcnt(0)
	ds_read_b128 v[176:179], v151 offset:50176
	ds_read_b128 v[184:187], v150 offset:50176
	ds_read_b128 v[192:195], v149 offset:50176
	ds_read_b128 v[200:203], v148 offset:50176
	v_mfma_f32_16x16x32_bf16 v[66:69], v[142:145], v[172:175], v[66:69]
	v_mfma_f32_16x16x32_bf16 v[70:73], v[164:167], v[172:175], v[70:73]
	v_mfma_f32_16x16x32_bf16 v[86:89], v[142:145], v[180:183], v[86:89]
	v_mfma_f32_16x16x32_bf16 v[94:97], v[164:167], v[180:183], v[94:97]
	v_mfma_f32_16x16x32_bf16 v[118:121], v[142:145], v[188:191], v[118:121]
	v_mfma_f32_16x16x32_bf16 v[126:129], v[164:167], v[188:191], v[126:129]
	v_mfma_f32_16x16x32_bf16 v[106:109], v[142:145], v[196:199], v[106:109]
	v_mfma_f32_16x16x32_bf16 v[98:101], v[164:167], v[196:199], v[98:101]
	s_waitcnt lgkmcnt(0)
	v_mfma_f32_16x16x32_bf16 v[66:69], v[160:163], v[176:179], v[66:69]
	v_mfma_f32_16x16x32_bf16 v[70:73], v[168:171], v[176:179], v[70:73]
	v_mfma_f32_16x16x32_bf16 v[86:89], v[160:163], v[184:187], v[86:89]
	v_mfma_f32_16x16x32_bf16 v[94:97], v[168:171], v[184:187], v[94:97]
	v_mfma_f32_16x16x32_bf16 v[118:121], v[160:163], v[192:195], v[118:121]
	v_mfma_f32_16x16x32_bf16 v[126:129], v[168:171], v[192:195], v[126:129]
	v_mfma_f32_16x16x32_bf16 v[106:109], v[160:163], v[200:203], v[106:109]
	v_mfma_f32_16x16x32_bf16 v[98:101], v[168:171], v[200:203], v[98:101]
	s_barrier
	v_readfirstlane_b32 s3, v152
	v_lshl_add_u64 v[142:143], v[238:239], 0, s[54:55]
	s_mov_b32 m0, s3
	v_readfirstlane_b32 s3, v153
	global_load_lds_dwordx4 v[142:143], off
	v_lshl_add_u64 v[142:143], v[240:241], 0, s[54:55]
	s_mov_b32 m0, s3
	s_nop 0
	global_load_lds_dwordx4 v[142:143], off
	s_waitcnt vmcnt(6)
	s_barrier
	v_mfma_f32_16x16x32_bf16 v[74:77], v[204:207], v[172:175], v[74:77]
	v_mfma_f32_16x16x32_bf16 v[82:85], v[216:219], v[172:175], v[82:85]
	v_mfma_f32_16x16x32_bf16 v[102:105], v[204:207], v[180:183], v[102:105]
	v_mfma_f32_16x16x32_bf16 v[110:113], v[216:219], v[180:183], v[110:113]
	v_mfma_f32_16x16x32_bf16 v[122:125], v[204:207], v[188:191], v[122:125]
	v_mfma_f32_16x16x32_bf16 v[114:117], v[216:219], v[188:191], v[114:117]
	v_mfma_f32_16x16x32_bf16 v[90:93], v[204:207], v[196:199], v[90:93]
	v_mfma_f32_16x16x32_bf16 v[78:81], v[216:219], v[196:199], v[78:81]
	v_mfma_f32_16x16x32_bf16 v[74:77], v[208:211], v[176:179], v[74:77]
	v_mfma_f32_16x16x32_bf16 v[82:85], v[234:237], v[176:179], v[82:85]
	v_mfma_f32_16x16x32_bf16 v[102:105], v[208:211], v[184:187], v[102:105]
	v_mfma_f32_16x16x32_bf16 v[110:113], v[234:237], v[184:187], v[110:113]
	v_mfma_f32_16x16x32_bf16 v[122:125], v[208:211], v[192:195], v[122:125]
	v_mfma_f32_16x16x32_bf16 v[114:117], v[234:237], v[192:195], v[114:117]
	v_mfma_f32_16x16x32_bf16 v[90:93], v[208:211], v[200:203], v[90:93]
	v_mfma_f32_16x16x32_bf16 v[78:81], v[234:237], v[200:203], v[78:81]
	s_add_i32 s2, s2, 2
	s_add_u32 s8, s8, 0x100
	s_addc_u32 s9, s9, 0
	s_cmp_lt_u32 s2, 40
	s_barrier
	s_cbranch_scc1 .LBB0_1266
	s_add_u32 s2, s22, 0xb1580
	s_addc_u32 s3, s23, 0
	v_readfirstlane_b32 s7, v158
	v_lshl_add_u64 v[152:153], v[64:65], 1, s[2:3]
	s_mov_b32 m0, s7
	v_lshl_add_u64 v[146:147], v[146:147], 1, s[2:3]
	v_readfirstlane_b32 s2, v159
	ds_read_b128 v[130:133], v157
	ds_read_b128 v[134:137], v157 offset:1024
	ds_read_b128 v[138:141], v157 offset:2048
	ds_read_b128 v[142:145], v157 offset:3072
	ds_read_b128 v[160:163], v151
	ds_read_b128 v[164:167], v151 offset:1024
	ds_read_b128 v[168:171], v150
	ds_read_b128 v[172:175], v150 offset:1024
	ds_read_b128 v[176:179], v149
	ds_read_b128 v[180:183], v149 offset:1024
	ds_read_b128 v[184:187], v148
	ds_read_b128 v[188:191], v148 offset:1024
	global_load_lds_dwordx4 v[152:153], off
	s_mov_b32 m0, s2
	s_nop 0
	global_load_lds_dwordx4 v[146:147], off
	s_barrier
	s_waitcnt lgkmcnt(0)
	v_mfma_f32_16x16x32_bf16 v[0:3], v[130:133], v[160:163], v[0:3]
	v_mfma_f32_16x16x32_bf16 v[4:7], v[138:141], v[160:163], v[4:7]
	v_mfma_f32_16x16x32_bf16 v[16:19], v[130:133], v[168:171], v[16:19]
	v_mfma_f32_16x16x32_bf16 v[20:23], v[138:141], v[168:171], v[20:23]
	v_mfma_f32_16x16x32_bf16 v[32:35], v[130:133], v[176:179], v[32:35]
	v_mfma_f32_16x16x32_bf16 v[36:39], v[138:141], v[176:179], v[36:39]
	v_mfma_f32_16x16x32_bf16 v[48:51], v[130:133], v[184:187], v[48:51]
	v_mfma_f32_16x16x32_bf16 v[52:55], v[138:141], v[184:187], v[52:55]
	v_mfma_f32_16x16x32_bf16 v[0:3], v[134:137], v[164:167], v[0:3]
	v_mfma_f32_16x16x32_bf16 v[4:7], v[142:145], v[164:167], v[4:7]
	v_mfma_f32_16x16x32_bf16 v[16:19], v[134:137], v[172:175], v[16:19]
	v_mfma_f32_16x16x32_bf16 v[20:23], v[142:145], v[172:175], v[20:23]
	v_mfma_f32_16x16x32_bf16 v[32:35], v[134:137], v[180:183], v[32:35]
	v_mfma_f32_16x16x32_bf16 v[36:39], v[142:145], v[180:183], v[36:39]
	v_mfma_f32_16x16x32_bf16 v[48:51], v[134:137], v[188:191], v[48:51]
	v_mfma_f32_16x16x32_bf16 v[52:55], v[142:145], v[188:191], v[52:55]
	s_barrier
	ds_read_b128 v[192:195], v156
	ds_read_b128 v[196:199], v156 offset:1024
	ds_read_b128 v[200:203], v156 offset:2048
	ds_read_b128 v[156:159], v156 offset:3072
	s_barrier
	s_waitcnt lgkmcnt(0)
	v_mfma_f32_16x16x32_bf16 v[8:11], v[192:195], v[160:163], v[8:11]
	v_mfma_f32_16x16x32_bf16 v[12:15], v[200:203], v[160:163], v[12:15]
	v_mfma_f32_16x16x32_bf16 v[24:27], v[192:195], v[168:171], v[24:27]
	v_mfma_f32_16x16x32_bf16 v[28:31], v[200:203], v[168:171], v[28:31]
	v_mfma_f32_16x16x32_bf16 v[40:43], v[192:195], v[176:179], v[40:43]
	v_mfma_f32_16x16x32_bf16 v[44:47], v[200:203], v[176:179], v[44:47]
	v_mfma_f32_16x16x32_bf16 v[56:59], v[192:195], v[184:187], v[56:59]
	v_mfma_f32_16x16x32_bf16 v[60:63], v[200:203], v[184:187], v[60:63]
	v_mfma_f32_16x16x32_bf16 v[8:11], v[196:199], v[164:167], v[8:11]
	v_mfma_f32_16x16x32_bf16 v[12:15], v[156:159], v[164:167], v[12:15]
	v_mfma_f32_16x16x32_bf16 v[24:27], v[196:199], v[172:175], v[24:27]
	v_mfma_f32_16x16x32_bf16 v[28:31], v[156:159], v[172:175], v[28:31]
	v_mfma_f32_16x16x32_bf16 v[40:43], v[196:199], v[180:183], v[40:43]
	v_mfma_f32_16x16x32_bf16 v[44:47], v[156:159], v[180:183], v[44:47]
	v_mfma_f32_16x16x32_bf16 v[56:59], v[196:199], v[188:191], v[56:59]
	v_mfma_f32_16x16x32_bf16 v[60:63], v[156:159], v[188:191], v[60:63]
	s_barrier
; #define LDA(dst, b, h) _Pragma("unroll") for (int m = 0; m < 4; ++m) _Pragma("unroll") for (int k = 0; k < 2; ++k) \
;     dst[m][k] = *(const bf16x8*)(lds + SA_(b, h) + lds_byte(wr * 64 + m * 16 + fr, k * 32 + fq * 8));
; #define LDB(dst, b, h) _Pragma("unroll") for (int n = 0; n < 2; ++n) _Pragma("unroll") for (int k = 0; k < 2; ++k) \
;     dst[n][k] = *(const bf16x8*)(lds + SB_(b, h) + lds_byte(wc * 32 + n * 16 + fr, k * 32 + fq * 8));
; #define MMA(ai, bj, At_, Bt_) { __builtin_amdgcn_s_setprio(1); \
;     _Pragma("unroll") for (int m = 0; m < 4; ++m) _Pragma("unroll") for (int n = 0; n < 2; ++n) _Pragma("unroll") for (int k = 0; k < 2; ++k) \
;       acc[ai][bj][m][n] = MFMA16(Bt_[n][k], At_[m][k], acc[ai][bj][m][n]); \
;     __builtin_amdgcn_s_setprio(0); }
; #define WAIT_V(n) asm volatile("s_waitcnt vmcnt(" #n ")" ::: "memory");
; #define WAIT_L(n) asm volatile("s_waitcnt lgkmcnt(" #n ")" ::: "memory");
; #define BAR __builtin_amdgcn_s_barrier();
; DI void gemm256(const u16* __restrict__ A, int lda, const u16* __restrict__ B0, const u16* __restrict__ B1, int ldb, int nt, acc_t& acc, char* lds) {
;     ...
;     BAR WAIT_L(0) MMA(0, 0, At, Bq0) BAR
;     LDB(Bq1, 0, 1) BAR WAIT_L(0) MMA(0, 1, At, Bq1) BAR
;     LDA(At, 0, 1) WAIT_V(4) BAR WAIT_L(0) MMA(1, 0, At, Bq0) MMA(1, 1, At, Bq1) BAR }
;   { LDB(Bq0, 1, 0) LDA(At, 1, 0) WAIT_V(2) BAR WAIT_L(0) MMA(0, 0, At, Bq0) BAR
	ds_read_b128 v[160:163], v151 offset:16384
	ds_read_b128 v[164:167], v151 offset:17408
	ds_read_b128 v[168:171], v150 offset:16384
	ds_read_b128 v[172:175], v150 offset:17408
	ds_read_b128 v[176:179], v149 offset:16384
	ds_read_b128 v[180:183], v149 offset:17408
	ds_read_b128 v[184:187], v148 offset:16384
	ds_read_b128 v[188:191], v148 offset:17408
	s_waitcnt vmcnt(4)
	s_barrier
	s_waitcnt lgkmcnt(0)
	v_mfma_f32_16x16x32_bf16 v[66:69], v[130:133], v[160:163], v[66:69]
	v_mfma_f32_16x16x32_bf16 v[204:207], v[134:137], v[164:167], v[66:69]
	v_mfma_f32_16x16x32_bf16 v[66:69], v[138:141], v[160:163], v[70:73]
	v_mfma_f32_16x16x32_bf16 v[208:211], v[142:145], v[164:167], v[66:69]
	v_mfma_f32_16x16x32_bf16 v[66:69], v[130:133], v[168:171], v[86:89]
	v_mfma_f32_16x16x32_bf16 v[216:219], v[134:137], v[172:175], v[66:69]
	v_mfma_f32_16x16x32_bf16 v[66:69], v[138:141], v[168:171], v[94:97]
	v_mfma_f32_16x16x32_bf16 v[226:229], v[142:145], v[172:175], v[66:69]
	v_mfma_f32_16x16x32_bf16 v[66:69], v[130:133], v[176:179], v[118:121]
	v_mfma_f32_16x16x32_bf16 v[230:233], v[134:137], v[180:183], v[66:69]
	v_mfma_f32_16x16x32_bf16 v[66:69], v[138:141], v[176:179], v[126:129]
	v_mfma_f32_16x16x32_bf16 v[234:237], v[142:145], v[180:183], v[66:69]
	v_mfma_f32_16x16x32_bf16 v[66:69], v[130:133], v[184:187], v[106:109]
	v_mfma_f32_16x16x32_bf16 v[134:137], v[134:137], v[188:191], v[66:69]
	v_mfma_f32_16x16x32_bf16 v[66:69], v[138:141], v[184:187], v[98:101]
	v_mfma_f32_16x16x32_bf16 v[138:141], v[142:145], v[188:191], v[66:69]
	v_mfma_f32_16x16x32_bf16 v[66:69], v[192:195], v[160:163], v[74:77]
	v_mfma_f32_16x16x32_bf16 v[142:145], v[196:199], v[164:167], v[66:69]
	v_mfma_f32_16x16x32_bf16 v[66:69], v[200:203], v[160:163], v[82:85]
	v_mfma_f32_16x16x32_bf16 v[160:163], v[156:159], v[164:167], v[66:69]
	v_mfma_f32_16x16x32_bf16 v[66:69], v[192:195], v[168:171], v[102:105]
	v_mfma_f32_16x16x32_bf16 v[164:167], v[196:199], v[172:175], v[66:69]
	v_mfma_f32_16x16x32_bf16 v[66:69], v[200:203], v[168:171], v[110:113]
	v_mfma_f32_16x16x32_bf16 v[168:171], v[156:159], v[172:175], v[66:69]
	v_mfma_f32_16x16x32_bf16 v[66:69], v[192:195], v[176:179], v[122:125]
	v_mfma_f32_16x16x32_bf16 v[122:125], v[196:199], v[180:183], v[66:69]
	v_mfma_f32_16x16x32_bf16 v[66:69], v[200:203], v[176:179], v[114:117]
	v_mfma_f32_16x16x32_bf16 v[172:175], v[156:159], v[180:183], v[66:69]
	v_mfma_f32_16x16x32_bf16 v[66:69], v[192:195], v[184:187], v[90:93]
	v_mfma_f32_16x16x32_bf16 v[176:179], v[196:199], v[188:191], v[66:69]
	v_mfma_f32_16x16x32_bf16 v[66:69], v[200:203], v[184:187], v[78:81]
	v_mfma_f32_16x16x32_bf16 v[156:159], v[156:159], v[188:191], v[66:69]
	s_barrier
	ds_read_b128 v[180:183], v155
	ds_read_b128 v[184:187], v155 offset:1024
	ds_read_b128 v[188:191], v155 offset:2048
	ds_read_b128 v[192:195], v155 offset:3072
	s_nop 0
	ds_read_b128 v[66:69], v151 offset:32768
	ds_read_b128 v[70:73], v151 offset:33792
	ds_read_b128 v[82:85], v150 offset:32768
	ds_read_b128 v[86:89], v150 offset:33792
	ds_read_b128 v[196:199], v149 offset:32768
	ds_read_b128 v[200:203], v149 offset:33792
	ds_read_b128 v[238:241], v148 offset:32768
	ds_read_b128 v[242:245], v148 offset:33792
	s_waitcnt vmcnt(2)
	s_barrier
	s_waitcnt lgkmcnt(0)
	v_mfma_f32_16x16x32_bf16 v[0:3], v[180:183], v[66:69], v[0:3]
	v_mfma_f32_16x16x32_bf16 v[126:129], v[184:187], v[70:73], v[0:3]
	v_mfma_f32_16x16x32_bf16 v[0:3], v[188:191], v[66:69], v[4:7]
	v_mfma_f32_16x16x32_bf16 v[130:133], v[192:195], v[70:73], v[0:3]
	v_mfma_f32_16x16x32_bf16 v[0:3], v[180:183], v[82:85], v[16:19]
	v_mfma_f32_16x16x32_bf16 v[110:113], v[184:187], v[86:89], v[0:3]
	v_mfma_f32_16x16x32_bf16 v[0:3], v[188:191], v[82:85], v[20:23]
	v_mfma_f32_16x16x32_bf16 v[106:109], v[192:195], v[86:89], v[0:3]
	v_mfma_f32_16x16x32_bf16 v[0:3], v[180:183], v[196:199], v[32:35]
	v_mfma_f32_16x16x32_bf16 v[94:97], v[184:187], v[200:203], v[0:3]
	v_mfma_f32_16x16x32_bf16 v[0:3], v[188:191], v[196:199], v[36:39]
	v_mfma_f32_16x16x32_bf16 v[90:93], v[192:195], v[200:203], v[0:3]
	v_mfma_f32_16x16x32_bf16 v[0:3], v[180:183], v[238:241], v[48:51]
	v_mfma_f32_16x16x32_bf16 v[78:81], v[184:187], v[242:245], v[0:3]
	v_mfma_f32_16x16x32_bf16 v[0:3], v[188:191], v[238:241], v[52:55]
	v_mfma_f32_16x16x32_bf16 v[74:77], v[192:195], v[242:245], v[0:3]
	s_barrier
; #define LDA(dst, b, h) _Pragma("unroll") for (int m = 0; m < 4; ++m) _Pragma("unroll") for (int k = 0; k < 2; ++k) \
;     dst[m][k] = *(const bf16x8*)(lds + SA_(b, h) + lds_byte(wr * 64 + m * 16 + fr, k * 32 + fq * 8));
; #define LDB(dst, b, h) _Pragma("unroll") for (int n = 0; n < 2; ++n) _Pragma("unroll") for (int k = 0; k < 2; ++k) \
;     dst[n][k] = *(const bf16x8*)(lds + SB_(b, h) + lds_byte(wc * 32 + n * 16 + fr, k * 32 + fq * 8));
; #define MMA(ai, bj, At_, Bt_) { __builtin_amdgcn_s_setprio(1); \
;     _Pragma("unroll") for (int m = 0; m < 4; ++m) _Pragma("unroll") for (int n = 0; n < 2; ++n) _Pragma("unroll") for (int k = 0; k < 2; ++k) \
;       acc[ai][bj][m][n] = MFMA16(Bt_[n][k], At_[m][k], acc[ai][bj][m][n]); \
;     __builtin_amdgcn_s_setprio(0); }
; #define WAIT_V(n) asm volatile("s_waitcnt vmcnt(" #n ")" ::: "memory");
; #define WAIT_L(n) asm volatile("s_waitcnt lgkmcnt(" #n ")" ::: "memory");
; #define BAR __builtin_amdgcn_s_barrier();
; DI void gemm256(const u16* __restrict__ A, int lda, const u16* __restrict__ B0, const u16* __restrict__ B1, int ldb, int nt, acc_t& acc, char* lds) {
;     ...
;     LDB(Bq1, 1, 1) WAIT_V(0) BAR WAIT_L(0) MMA(0, 1, At, Bq1) BAR
;     LDA(At, 1, 1) BAR WAIT_L(0) MMA(1, 0, At, Bq0) MMA(1, 1, At, Bq1) BAR }
;   if (wr == 0) BAR
;   __syncthreads();
	s_nop 4
	ds_read_b128 v[0:3], v154
	ds_read_b128 v[4:7], v154 offset:1024
	ds_read_b128 v[246:249], v154 offset:2048
	ds_read_b128 v[152:155], v154 offset:3072
	s_waitcnt vmcnt(0)
	s_barrier
	s_waitcnt lgkmcnt(0)
	v_mfma_f32_16x16x32_bf16 v[8:11], v[0:3], v[66:69], v[8:11]
	v_mfma_f32_16x16x32_bf16 v[118:121], v[4:7], v[70:73], v[8:11]
	v_mfma_f32_16x16x32_bf16 v[8:11], v[246:249], v[66:69], v[12:15]
	v_mfma_f32_16x16x32_bf16 v[114:117], v[152:155], v[70:73], v[8:11]
	v_mfma_f32_16x16x32_bf16 v[8:11], v[0:3], v[82:85], v[24:27]
	v_mfma_f32_16x16x32_bf16 v[102:105], v[4:7], v[86:89], v[8:11]
	v_mfma_f32_16x16x32_bf16 v[8:11], v[246:249], v[82:85], v[28:31]
	v_mfma_f32_16x16x32_bf16 v[98:101], v[152:155], v[86:89], v[8:11]
	v_mfma_f32_16x16x32_bf16 v[8:11], v[0:3], v[196:199], v[40:43]
	v_mfma_f32_16x16x32_bf16 v[86:89], v[4:7], v[200:203], v[8:11]
	v_mfma_f32_16x16x32_bf16 v[8:11], v[246:249], v[196:199], v[44:47]
	v_mfma_f32_16x16x32_bf16 v[82:85], v[152:155], v[200:203], v[8:11]
	v_mfma_f32_16x16x32_bf16 v[8:11], v[0:3], v[238:241], v[56:59]
	v_mfma_f32_16x16x32_bf16 v[70:73], v[4:7], v[242:245], v[8:11]
	v_mfma_f32_16x16x32_bf16 v[8:11], v[246:249], v[238:241], v[60:63]
	v_mfma_f32_16x16x32_bf16 v[66:69], v[152:155], v[242:245], v[8:11]
	s_barrier
	ds_read_b128 v[16:19], v151 offset:49152
	ds_read_b128 v[20:23], v151 offset:50176
	ds_read_b128 v[32:35], v150 offset:49152
	ds_read_b128 v[196:199], v150 offset:50176
	ds_read_b128 v[200:203], v149 offset:49152
	ds_read_b128 v[238:241], v149 offset:50176
	ds_read_b128 v[242:245], v148 offset:49152
	ds_read_b128 v[146:149], v148 offset:50176
	s_barrier
	s_waitcnt lgkmcnt(0)
	v_mfma_f32_16x16x32_bf16 v[8:11], v[180:183], v[16:19], v[204:207]
	v_mfma_f32_16x16x32_bf16 v[60:63], v[184:187], v[20:23], v[8:11]
	v_mfma_f32_16x16x32_bf16 v[8:11], v[188:191], v[16:19], v[208:211]
	v_mfma_f32_16x16x32_bf16 v[56:59], v[192:195], v[20:23], v[8:11]
	v_mfma_f32_16x16x32_bf16 v[8:11], v[180:183], v[32:35], v[216:219]
	v_mfma_f32_16x16x32_bf16 v[44:47], v[184:187], v[196:199], v[8:11]
	v_mfma_f32_16x16x32_bf16 v[8:11], v[188:191], v[32:35], v[226:229]
	v_mfma_f32_16x16x32_bf16 v[40:43], v[192:195], v[196:199], v[8:11]
	v_mfma_f32_16x16x32_bf16 v[8:11], v[180:183], v[200:203], v[230:233]
	v_mfma_f32_16x16x32_bf16 v[28:31], v[184:187], v[238:241], v[8:11]
	v_mfma_f32_16x16x32_bf16 v[8:11], v[188:191], v[200:203], v[234:237]
	v_mfma_f32_16x16x32_bf16 v[24:27], v[192:195], v[238:241], v[8:11]
	v_mfma_f32_16x16x32_bf16 v[8:11], v[180:183], v[242:245], v[134:137]
	v_mfma_f32_16x16x32_bf16 v[12:15], v[184:187], v[146:149], v[8:11]
	v_mfma_f32_16x16x32_bf16 v[8:11], v[188:191], v[242:245], v[138:141]
	v_mfma_f32_16x16x32_bf16 v[8:11], v[192:195], v[146:149], v[8:11]
	v_mfma_f32_16x16x32_bf16 v[36:39], v[0:3], v[16:19], v[142:145]
	v_mfma_f32_16x16x32_bf16 v[16:19], v[246:249], v[16:19], v[160:163]
	v_mfma_f32_16x16x32_bf16 v[48:51], v[152:155], v[20:23], v[16:19]
	v_mfma_f32_16x16x32_bf16 v[16:19], v[0:3], v[32:35], v[164:167]
	v_mfma_f32_16x16x32_bf16 v[52:55], v[4:7], v[20:23], v[36:39]
	v_mfma_f32_16x16x32_bf16 v[36:39], v[4:7], v[196:199], v[16:19]
	v_mfma_f32_16x16x32_bf16 v[16:19], v[246:249], v[32:35], v[168:171]
	v_mfma_f32_16x16x32_bf16 v[32:35], v[152:155], v[196:199], v[16:19]
	v_mfma_f32_16x16x32_bf16 v[16:19], v[0:3], v[200:203], v[122:125]
	v_mfma_f32_16x16x32_bf16 v[0:3], v[0:3], v[242:245], v[176:179]
	v_mfma_f32_16x16x32_bf16 v[20:23], v[4:7], v[238:241], v[16:19]
	v_mfma_f32_16x16x32_bf16 v[16:19], v[246:249], v[200:203], v[172:175]
	v_mfma_f32_16x16x32_bf16 v[4:7], v[4:7], v[146:149], v[0:3]
	v_mfma_f32_16x16x32_bf16 v[0:3], v[246:249], v[242:245], v[156:159]
	v_mfma_f32_16x16x32_bf16 v[16:19], v[152:155], v[238:241], v[16:19]
	v_mfma_f32_16x16x32_bf16 v[0:3], v[152:155], v[146:149], v[0:3]
	s_movk_i32 s2, 0x100
	v_cmp_gt_u32_e32 vcc, s2, v225
	s_barrier
	s_and_saveexec_b64 s[8:9], vcc
	s_cbranch_execz .LBB0_1240
	s_barrier
	s_branch .LBB0_1240
